# v36 + GEMM K-loops: drop mid-block s_setprio 0/1 pairs and the redundant post-barrier lgkmcnt(0)
# speedup vs baseline: 1.0020x; 1.0020x over previous
; #define PG8_STAGE(bufoff, gbase, voff) do { _Pragma("unroll") for (int _i = 0; _i < 2; ++_i) \
;         __builtin_amdgcn_global_load_lds((const unsigned*)((const char*)(gbase) + (voff)[_i]), (PG8_LAS unsigned*)(lds + (bufoff) + ldsw + _i * 8192), 16, 0, 0); } while (0)
; #define PG8_LDA(dst, b, h) do { _Pragma("unroll") for (int m = 0; m < 4; ++m) _Pragma("unroll") for (int k = 0; k < 2; ++k) dst[m][k] = *(const PG8_LAS bf16x8*)(lds + PG8_SA(b, h) + aoff + m * 2048 + k * 1024); } while (0)
; #define PG8_LDB(dst, b, h) do { _Pragma("unroll") for (int n = 0; n < 2; ++n) _Pragma("unroll") for (int k = 0; k < 2; ++k) dst[n][k] = *(const PG8_LAS bf16x8*)(lds + PG8_SB(b, h) + boff + n * 2048 + k * 1024); } while (0)
; #define PG8_MMA(ai, bj, At, Bt) do { __builtin_amdgcn_s_setprio(1); _Pragma("unroll") for (int m = 0; m < 4; ++m) _Pragma("unroll") for (int n = 0; n < 2; ++n) _Pragma("unroll") for (int k = 0; k < 2; ++k) \
;         acc[ai][bj][m][n] = __builtin_amdgcn_mfma_f32_16x16x32_bf16(Bt[n][k], At[m][k], acc[ai][bj][m][n], 0, 0, 0); __builtin_amdgcn_s_setprio(0); } while (0)
; #define PG8_WAIT_V(n) asm volatile("s_waitcnt vmcnt(" #n ")" ::: "memory")
; #define PG8_BAR __builtin_amdgcn_s_barrier()
; template <class Epi, class Sched, bool ALIGN_EPI = false, bool SP2 = false>
; __device__ __forceinline__ void gemm_phase(PG8_LAS unsigned char* lds, const Gemm g, const Sched& S, const Epi& E) {
;     ...
;         for (int t = 0; t < nt; t += 2) {
;             const bool last = (t == nt - 2);
;             const char* a1 = cA + (size_t)(t + 1) * kstep;
;             const char* a2 = last ? nA : cA + (size_t)(t + 2) * kstep; const char* b2 = last ? nB : cB + (size_t)(t + 2) * kstep;
;             const char* a3 = a2 + kstep; const char* b3 = b2 + kstep;
;             if (last && has_next) S.a_ready(nxt);
;             if constexpr (SP2) {
;             PG8_LDB(B0, 0, 0); PG8_LDB(B1, 0, 1); PG8_SCHED; PG8_LDA(At, 0, 0); PG8_STAGE(PG8_SA(1, 1), a1 + hstepA, voffA);
;             PG8_WAIT_V(8); PG8_WAIT_L(0); PG8_BAR; PG8_MMA(0, 0, At, B0); PG8_MMA(0, 1, At, B1); PG8_BAR; PG8_SCHED;
;             PG8_LDA(At, 0, 1); PG8_STAGE(PG8_SB(0, 0), b2, voffB); PG8_STAGE(PG8_SB(0, 1), b2 + hstepB, voffB); PG8_STAGE(PG8_SA(0, 0), a2, voffA);
;             PG8_WAIT_V(8); PG8_WAIT_L(0); PG8_BAR; PG8_MMA(1, 0, At, B0); PG8_MMA(1, 1, At, B1); PG8_BAR; PG8_SCHED;
.LBB0_165:
	ds_read_b128 v[152:155], v146
	ds_read_b128 v[156:159], v146 offset:1024
	ds_read_b128 v[160:163], v146 offset:2048
	ds_read_b128 v[164:167], v146 offset:3072
	ds_read_b128 v[168:171], v147
	ds_read_b128 v[172:175], v147 offset:1024
	ds_read_b128 v[176:179], v147 offset:2048
	ds_read_b128 v[180:183], v147 offset:3072
	s_add_i32 s61, s40, 2
	s_add_u32 s41, s38, 0xffff0080
	s_addc_u32 s42, s39, -1
	s_cmp_eq_u32 s52, s40
	s_cselect_b32 s40, s58, s59
	s_cselect_b32 s43, s19, s42
	s_cselect_b32 s42, s23, s41
	s_cselect_b32 s41, s29, s60
	v_lshl_add_u64 v[142:143], s[38:39], 0, v[136:137]
	s_add_i32 m0, s33, 0xc000
	ds_read_b128 v[184:187], v148
	ds_read_b128 v[188:191], v148 offset:1024
	ds_read_b128 v[192:195], v148 offset:2048
	ds_read_b128 v[196:199], v148 offset:3072
	ds_read_b128 v[200:203], v148 offset:4096
	ds_read_b128 v[204:207], v148 offset:5120
	ds_read_b128 v[208:211], v148 offset:6144
	ds_read_b128 v[212:215], v148 offset:7168
	global_load_lds_dwordx4 v[142:143], off
	v_lshl_add_u64 v[142:143], s[38:39], 0, v[138:139]
	s_add_i32 m0, s33, 0xe000
	s_nop 0
	global_load_lds_dwordx4 v[142:143], off
	s_waitcnt vmcnt(8)
	s_waitcnt lgkmcnt(0)
	s_barrier
	s_setprio 1
	v_mfma_f32_16x16x32_bf16 v[124:127], v[152:155], v[184:187], v[124:127]
	v_mfma_f32_16x16x32_bf16 v[120:123], v[160:163], v[184:187], v[120:123]
	v_mfma_f32_16x16x32_bf16 v[108:111], v[152:155], v[192:195], v[108:111]
	v_mfma_f32_16x16x32_bf16 v[104:107], v[160:163], v[192:195], v[104:107]
	v_mfma_f32_16x16x32_bf16 v[92:95], v[152:155], v[200:203], v[92:95]
	v_mfma_f32_16x16x32_bf16 v[88:91], v[160:163], v[200:203], v[88:91]
	v_mfma_f32_16x16x32_bf16 v[76:79], v[152:155], v[208:211], v[76:79]
	v_mfma_f32_16x16x32_bf16 v[72:75], v[160:163], v[208:211], v[72:75]
	v_mfma_f32_16x16x32_bf16 v[124:127], v[156:159], v[188:191], v[124:127]
	v_mfma_f32_16x16x32_bf16 v[120:123], v[164:167], v[188:191], v[120:123]
	v_mfma_f32_16x16x32_bf16 v[108:111], v[156:159], v[196:199], v[108:111]
	v_mfma_f32_16x16x32_bf16 v[104:107], v[164:167], v[196:199], v[104:107]
	v_mfma_f32_16x16x32_bf16 v[92:95], v[156:159], v[204:207], v[92:95]
	v_mfma_f32_16x16x32_bf16 v[88:91], v[164:167], v[204:207], v[88:91]
	v_mfma_f32_16x16x32_bf16 v[76:79], v[156:159], v[212:215], v[76:79]
	v_mfma_f32_16x16x32_bf16 v[72:75], v[164:167], v[212:215], v[72:75]
	v_mfma_f32_16x16x32_bf16 v[116:119], v[168:171], v[184:187], v[116:119]
	v_mfma_f32_16x16x32_bf16 v[112:115], v[176:179], v[184:187], v[112:115]
	v_mfma_f32_16x16x32_bf16 v[100:103], v[168:171], v[192:195], v[100:103]
	v_mfma_f32_16x16x32_bf16 v[96:99], v[176:179], v[192:195], v[96:99]
	v_mfma_f32_16x16x32_bf16 v[84:87], v[168:171], v[200:203], v[84:87]
	v_mfma_f32_16x16x32_bf16 v[80:83], v[176:179], v[200:203], v[80:83]
	v_mfma_f32_16x16x32_bf16 v[68:71], v[168:171], v[208:211], v[68:71]
	v_mfma_f32_16x16x32_bf16 v[64:67], v[176:179], v[208:211], v[64:67]
	v_mfma_f32_16x16x32_bf16 v[116:119], v[172:175], v[188:191], v[116:119]
	v_mfma_f32_16x16x32_bf16 v[112:115], v[180:183], v[188:191], v[112:115]
	v_mfma_f32_16x16x32_bf16 v[100:103], v[172:175], v[196:199], v[100:103]
	v_mfma_f32_16x16x32_bf16 v[96:99], v[180:183], v[196:199], v[96:99]
	v_mfma_f32_16x16x32_bf16 v[84:87], v[172:175], v[204:207], v[84:87]
	v_mfma_f32_16x16x32_bf16 v[80:83], v[180:183], v[204:207], v[80:83]
	v_mfma_f32_16x16x32_bf16 v[68:71], v[172:175], v[212:215], v[68:71]
	v_mfma_f32_16x16x32_bf16 v[64:67], v[180:183], v[212:215], v[64:67]
	s_setprio 0
	s_barrier
	s_add_i32 s62, s53, s17
	v_lshl_add_u64 v[142:143], s[40:41], 0, v[130:131]
	s_mov_b32 m0, s62
	ds_read_b128 v[184:187], v148 offset:16384
	ds_read_b128 v[188:191], v148 offset:17408
	ds_read_b128 v[192:195], v148 offset:18432
	ds_read_b128 v[196:199], v148 offset:19456
	ds_read_b128 v[200:203], v148 offset:20480
	ds_read_b128 v[204:207], v148 offset:21504
	ds_read_b128 v[208:211], v148 offset:22528
	ds_read_b128 v[212:215], v148 offset:23552
	global_load_lds_dwordx4 v[142:143], off
	s_add_i32 m0, s62, 0x2000
	s_add_u32 s62, s40, 0x10000
	v_lshl_add_u64 v[218:219], s[40:41], 0, v[134:135]
	s_addc_u32 s63, s41, 0
	s_add_i32 s64, s54, s17
	global_load_lds_dwordx4 v[218:219], off
	v_lshl_add_u64 v[220:221], s[62:63], 0, v[130:131]
	s_mov_b32 m0, s64
	v_lshl_add_u64 v[222:223], s[42:43], 0, v[132:133]
	global_load_lds_dwordx4 v[220:221], off
	v_lshl_add_u64 v[220:221], s[62:63], 0, v[134:135]
	s_add_i32 m0, s64, 0x2000
	s_nop 0
	global_load_lds_dwordx4 v[220:221], off
	v_lshl_add_u64 v[220:221], s[42:43], 0, v[128:129]
	s_mov_b32 m0, s33
	s_nop 0
	global_load_lds_dwordx4 v[220:221], off
	s_mov_b32 m0, s37
	s_nop 0
	global_load_lds_dwordx4 v[222:223], off
	s_waitcnt vmcnt(8)
	s_waitcnt lgkmcnt(0)
	s_barrier
; #define PG8_STAGE(bufoff, gbase, voff) do { _Pragma("unroll") for (int _i = 0; _i < 2; ++_i) \
;         __builtin_amdgcn_global_load_lds((const unsigned*)((const char*)(gbase) + (voff)[_i]), (PG8_LAS unsigned*)(lds + (bufoff) + ldsw + _i * 8192), 16, 0, 0); } while (0)
; #define PG8_LDA(dst, b, h) do { _Pragma("unroll") for (int m = 0; m < 4; ++m) _Pragma("unroll") for (int k = 0; k < 2; ++k) dst[m][k] = *(const PG8_LAS bf16x8*)(lds + PG8_SA(b, h) + aoff + m * 2048 + k * 1024); } while (0)
; #define PG8_LDB(dst, b, h) do { _Pragma("unroll") for (int n = 0; n < 2; ++n) _Pragma("unroll") for (int k = 0; k < 2; ++k) dst[n][k] = *(const PG8_LAS bf16x8*)(lds + PG8_SB(b, h) + boff + n * 2048 + k * 1024); } while (0)
; #define PG8_MMA(ai, bj, At, Bt) do { __builtin_amdgcn_s_setprio(1); _Pragma("unroll") for (int m = 0; m < 4; ++m) _Pragma("unroll") for (int n = 0; n < 2; ++n) _Pragma("unroll") for (int k = 0; k < 2; ++k) \
;         acc[ai][bj][m][n] = __builtin_amdgcn_mfma_f32_16x16x32_bf16(Bt[n][k], At[m][k], acc[ai][bj][m][n], 0, 0, 0); __builtin_amdgcn_s_setprio(0); } while (0)
; #define PG8_WAIT_V(n) asm volatile("s_waitcnt vmcnt(" #n ")" ::: "memory")
; #define PG8_WAIT_L(n) asm volatile("s_waitcnt lgkmcnt(" #n ")" ::: "memory")
; #define PG8_BAR __builtin_amdgcn_s_barrier()
; #define PG8_SCHED __builtin_amdgcn_sched_barrier(0)
; template <class Epi, class Sched, bool ALIGN_EPI = false, bool SP2 = false>
; __device__ __forceinline__ void gemm_phase(PG8_LAS unsigned char* lds, const Gemm g, const Sched& S, const Epi& E) {
;     ...
;             PG8_WAIT_V(8); PG8_WAIT_L(0); PG8_BAR; PG8_MMA(1, 0, At, B0); PG8_MMA(1, 1, At, B1); PG8_BAR; PG8_SCHED;
;             PG8_LDB(B0, 1, 0); PG8_LDB(B1, 1, 1); PG8_SCHED; PG8_LDA(At, 1, 0); PG8_STAGE(PG8_SA(0, 1), a2 + hstepA, voffA);
;             PG8_WAIT_V(8); PG8_WAIT_L(0); PG8_BAR; PG8_MMA(0, 0, At, B0); PG8_MMA(0, 1, At, B1); PG8_BAR; PG8_SCHED;
	s_setprio 1
	v_mfma_f32_16x16x32_bf16 v[60:63], v[152:155], v[184:187], v[60:63]
	v_mfma_f32_16x16x32_bf16 v[56:59], v[160:163], v[184:187], v[56:59]
	v_mfma_f32_16x16x32_bf16 v[44:47], v[152:155], v[192:195], v[44:47]
	v_mfma_f32_16x16x32_bf16 v[40:43], v[160:163], v[192:195], v[40:43]
	v_mfma_f32_16x16x32_bf16 v[28:31], v[152:155], v[200:203], v[28:31]
	v_mfma_f32_16x16x32_bf16 v[24:27], v[160:163], v[200:203], v[24:27]
	v_mfma_f32_16x16x32_bf16 v[12:15], v[152:155], v[208:211], v[12:15]
	v_mfma_f32_16x16x32_bf16 v[8:11], v[160:163], v[208:211], v[8:11]
	v_mfma_f32_16x16x32_bf16 v[60:63], v[156:159], v[188:191], v[60:63]
	v_mfma_f32_16x16x32_bf16 v[56:59], v[164:167], v[188:191], v[56:59]
	v_mfma_f32_16x16x32_bf16 v[44:47], v[156:159], v[196:199], v[44:47]
	v_mfma_f32_16x16x32_bf16 v[40:43], v[164:167], v[196:199], v[40:43]
	v_mfma_f32_16x16x32_bf16 v[28:31], v[156:159], v[204:207], v[28:31]
	v_mfma_f32_16x16x32_bf16 v[24:27], v[164:167], v[204:207], v[24:27]
	v_mfma_f32_16x16x32_bf16 v[12:15], v[156:159], v[212:215], v[12:15]
	v_mfma_f32_16x16x32_bf16 v[8:11], v[164:167], v[212:215], v[8:11]
	v_mfma_f32_16x16x32_bf16 v[52:55], v[168:171], v[184:187], v[52:55]
	v_mfma_f32_16x16x32_bf16 v[48:51], v[176:179], v[184:187], v[48:51]
	v_mfma_f32_16x16x32_bf16 v[36:39], v[168:171], v[192:195], v[36:39]
	v_mfma_f32_16x16x32_bf16 v[32:35], v[176:179], v[192:195], v[32:35]
	v_mfma_f32_16x16x32_bf16 v[20:23], v[168:171], v[200:203], v[20:23]
	v_mfma_f32_16x16x32_bf16 v[16:19], v[176:179], v[200:203], v[16:19]
	v_mfma_f32_16x16x32_bf16 v[4:7], v[168:171], v[208:211], v[4:7]
	v_mfma_f32_16x16x32_bf16 v[0:3], v[176:179], v[208:211], v[0:3]
	v_mfma_f32_16x16x32_bf16 v[52:55], v[172:175], v[188:191], v[52:55]
	v_mfma_f32_16x16x32_bf16 v[48:51], v[180:183], v[188:191], v[48:51]
	v_mfma_f32_16x16x32_bf16 v[36:39], v[172:175], v[196:199], v[36:39]
	v_mfma_f32_16x16x32_bf16 v[32:35], v[180:183], v[196:199], v[32:35]
	v_mfma_f32_16x16x32_bf16 v[20:23], v[172:175], v[204:207], v[20:23]
	v_mfma_f32_16x16x32_bf16 v[16:19], v[180:183], v[204:207], v[16:19]
	v_mfma_f32_16x16x32_bf16 v[4:7], v[172:175], v[212:215], v[4:7]
	v_mfma_f32_16x16x32_bf16 v[0:3], v[180:183], v[212:215], v[0:3]
	s_setprio 0
	s_barrier
	s_add_i32 s62, 0, 0x18000
	v_add_u32_e32 v140, s62, v145
	s_add_i32 s63, 0, 0x1c000
	ds_read_b128 v[152:155], v140
	ds_read_b128 v[156:159], v140 offset:1024
	ds_read_b128 v[160:163], v140 offset:2048
	ds_read_b128 v[164:167], v140 offset:3072
	v_add_u32_e32 v140, s63, v145
	ds_read_b128 v[168:171], v140
	ds_read_b128 v[172:175], v140 offset:1024
	ds_read_b128 v[176:179], v140 offset:2048
	ds_read_b128 v[180:183], v140 offset:3072
	s_add_u32 s42, s42, 0x10000
	s_addc_u32 s43, s43, 0
	s_mov_b32 m0, s46
	v_lshl_add_u64 v[224:225], s[42:43], 0, v[128:129]
	ds_read_b128 v[184:187], v148 offset:32768
	ds_read_b128 v[188:191], v148 offset:33792
	ds_read_b128 v[192:195], v148 offset:34816
	ds_read_b128 v[196:199], v148 offset:35840
	ds_read_b128 v[200:203], v148 offset:36864
	ds_read_b128 v[204:207], v148 offset:37888
	ds_read_b128 v[208:211], v148 offset:38912
	ds_read_b128 v[212:215], v148 offset:39936
	global_load_lds_dwordx4 v[224:225], off
	v_lshl_add_u64 v[224:225], s[42:43], 0, v[132:133]
	s_mov_b32 m0, s47
	s_nop 0
	global_load_lds_dwordx4 v[224:225], off
	s_waitcnt vmcnt(8)
	s_waitcnt lgkmcnt(0)
	s_barrier
	s_setprio 1
	v_mfma_f32_16x16x32_bf16 v[124:127], v[152:155], v[184:187], v[124:127]
	v_mfma_f32_16x16x32_bf16 v[120:123], v[160:163], v[184:187], v[120:123]
	v_mfma_f32_16x16x32_bf16 v[108:111], v[152:155], v[192:195], v[108:111]
	v_mfma_f32_16x16x32_bf16 v[104:107], v[160:163], v[192:195], v[104:107]
	v_mfma_f32_16x16x32_bf16 v[92:95], v[152:155], v[200:203], v[92:95]
	v_mfma_f32_16x16x32_bf16 v[88:91], v[160:163], v[200:203], v[88:91]
	v_mfma_f32_16x16x32_bf16 v[76:79], v[152:155], v[208:211], v[76:79]
	v_mfma_f32_16x16x32_bf16 v[72:75], v[160:163], v[208:211], v[72:75]
	v_mfma_f32_16x16x32_bf16 v[124:127], v[156:159], v[188:191], v[124:127]
	v_mfma_f32_16x16x32_bf16 v[120:123], v[164:167], v[188:191], v[120:123]
	v_mfma_f32_16x16x32_bf16 v[108:111], v[156:159], v[196:199], v[108:111]
	v_mfma_f32_16x16x32_bf16 v[104:107], v[164:167], v[196:199], v[104:107]
	v_mfma_f32_16x16x32_bf16 v[92:95], v[156:159], v[204:207], v[92:95]
	v_mfma_f32_16x16x32_bf16 v[88:91], v[164:167], v[204:207], v[88:91]
	v_mfma_f32_16x16x32_bf16 v[76:79], v[156:159], v[212:215], v[76:79]
	v_mfma_f32_16x16x32_bf16 v[72:75], v[164:167], v[212:215], v[72:75]
	v_mfma_f32_16x16x32_bf16 v[116:119], v[168:171], v[184:187], v[116:119]
	v_mfma_f32_16x16x32_bf16 v[112:115], v[176:179], v[184:187], v[112:115]
	v_mfma_f32_16x16x32_bf16 v[100:103], v[168:171], v[192:195], v[100:103]
	v_mfma_f32_16x16x32_bf16 v[96:99], v[176:179], v[192:195], v[96:99]
	v_mfma_f32_16x16x32_bf16 v[84:87], v[168:171], v[200:203], v[84:87]
	v_mfma_f32_16x16x32_bf16 v[80:83], v[176:179], v[200:203], v[80:83]
	v_mfma_f32_16x16x32_bf16 v[68:71], v[168:171], v[208:211], v[68:71]
	v_mfma_f32_16x16x32_bf16 v[64:67], v[176:179], v[208:211], v[64:67]
	v_mfma_f32_16x16x32_bf16 v[116:119], v[172:175], v[188:191], v[116:119]
	v_mfma_f32_16x16x32_bf16 v[112:115], v[180:183], v[188:191], v[112:115]
	v_mfma_f32_16x16x32_bf16 v[100:103], v[172:175], v[196:199], v[100:103]
	v_mfma_f32_16x16x32_bf16 v[96:99], v[180:183], v[196:199], v[96:99]
	v_mfma_f32_16x16x32_bf16 v[84:87], v[172:175], v[204:207], v[84:87]
	v_mfma_f32_16x16x32_bf16 v[80:83], v[180:183], v[204:207], v[80:83]
	v_mfma_f32_16x16x32_bf16 v[68:71], v[172:175], v[212:215], v[68:71]
	v_mfma_f32_16x16x32_bf16 v[64:67], v[180:183], v[212:215], v[64:67]
	s_setprio 0
	s_barrier
; #define PG8_STAGE(bufoff, gbase, voff) do { _Pragma("unroll") for (int _i = 0; _i < 2; ++_i) \
;         __builtin_amdgcn_global_load_lds((const unsigned*)((const char*)(gbase) + (voff)[_i]), (PG8_LAS unsigned*)(lds + (bufoff) + ldsw + _i * 8192), 16, 0, 0); } while (0)
; #define PG8_LDA(dst, b, h) do { _Pragma("unroll") for (int m = 0; m < 4; ++m) _Pragma("unroll") for (int k = 0; k < 2; ++k) dst[m][k] = *(const PG8_LAS bf16x8*)(lds + PG8_SA(b, h) + aoff + m * 2048 + k * 1024); } while (0)
; #define PG8_MMA(ai, bj, At, Bt) do { __builtin_amdgcn_s_setprio(1); _Pragma("unroll") for (int m = 0; m < 4; ++m) _Pragma("unroll") for (int n = 0; n < 2; ++n) _Pragma("unroll") for (int k = 0; k < 2; ++k) \
;         acc[ai][bj][m][n] = __builtin_amdgcn_mfma_f32_16x16x32_bf16(Bt[n][k], At[m][k], acc[ai][bj][m][n], 0, 0, 0); __builtin_amdgcn_s_setprio(0); } while (0)
; #define PG8_WAIT_V(n) asm volatile("s_waitcnt vmcnt(" #n ")" ::: "memory")
; #define PG8_WAIT_L(n) asm volatile("s_waitcnt lgkmcnt(" #n ")" ::: "memory")
; #define PG8_BAR __builtin_amdgcn_s_barrier()
; #define PG8_SCHED __builtin_amdgcn_sched_barrier(0)
; template <class Epi, class Sched, bool ALIGN_EPI = false, bool SP2 = false>
; __device__ __forceinline__ void gemm_phase(PG8_LAS unsigned char* lds, const Gemm g, const Sched& S, const Epi& E) {
;     ...
;         for (int t = 0; t < nt; t += 2) {
;     ...
;             PG8_WAIT_V(8); PG8_WAIT_L(0); PG8_BAR; PG8_MMA(0, 0, At, B0); PG8_MMA(0, 1, At, B1); PG8_BAR; PG8_SCHED;
;             PG8_LDA(At, 1, 1); PG8_STAGE(PG8_SB(1, 0), b3, voffB); PG8_STAGE(PG8_SB(1, 1), b3 + hstepB, voffB); PG8_STAGE(PG8_SA(1, 0), a3, voffA);
;             PG8_WAIT_V(8); PG8_WAIT_L(0); PG8_BAR; PG8_MMA(1, 0, At, B0); PG8_MMA(1, 1, At, B1); PG8_BAR; PG8_SCHED;
	s_add_i32 s42, s62, s17
	v_lshl_add_u64 v[142:143], v[142:143], 0, s[8:9]
	s_mov_b32 m0, s42
	ds_read_b128 v[184:187], v148 offset:49152
	ds_read_b128 v[188:191], v148 offset:50176
	ds_read_b128 v[192:195], v148 offset:51200
	ds_read_b128 v[196:199], v148 offset:52224
	ds_read_b128 v[200:203], v148 offset:53248
	ds_read_b128 v[204:207], v148 offset:54272
	ds_read_b128 v[208:211], v148 offset:55296
	ds_read_b128 v[212:215], v148 offset:56320
	global_load_lds_dwordx4 v[142:143], off
	s_add_i32 m0, s42, 0x2000
	s_add_u32 s40, s40, 0x10080
	v_lshl_add_u64 v[142:143], v[218:219], 0, s[8:9]
	s_addc_u32 s41, s41, 0
	s_add_i32 s42, s63, s17
	global_load_lds_dwordx4 v[142:143], off
	v_lshl_add_u64 v[142:143], s[40:41], 0, v[130:131]
	s_mov_b32 m0, s42
	s_nop 0
	global_load_lds_dwordx4 v[142:143], off
	v_lshl_add_u64 v[142:143], s[40:41], 0, v[134:135]
	s_add_i32 m0, s42, 0x2000
	s_nop 0
	global_load_lds_dwordx4 v[142:143], off
	v_lshl_add_u64 v[142:143], v[220:221], 0, s[8:9]
	s_mov_b32 m0, s50
	s_nop 0
	global_load_lds_dwordx4 v[142:143], off
	v_lshl_add_u64 v[142:143], v[222:223], 0, s[8:9]
	s_mov_b32 m0, s51
	s_nop 0
	global_load_lds_dwordx4 v[142:143], off
	s_waitcnt vmcnt(8)
	s_waitcnt lgkmcnt(0)
	s_barrier
	s_setprio 1
	v_mfma_f32_16x16x32_bf16 v[60:63], v[152:155], v[184:187], v[60:63]
	v_mfma_f32_16x16x32_bf16 v[56:59], v[160:163], v[184:187], v[56:59]
	v_mfma_f32_16x16x32_bf16 v[44:47], v[152:155], v[192:195], v[44:47]
	v_mfma_f32_16x16x32_bf16 v[40:43], v[160:163], v[192:195], v[40:43]
	v_mfma_f32_16x16x32_bf16 v[28:31], v[152:155], v[200:203], v[28:31]
	v_mfma_f32_16x16x32_bf16 v[24:27], v[160:163], v[200:203], v[24:27]
	v_mfma_f32_16x16x32_bf16 v[12:15], v[152:155], v[208:211], v[12:15]
	v_mfma_f32_16x16x32_bf16 v[8:11], v[160:163], v[208:211], v[8:11]
	v_mfma_f32_16x16x32_bf16 v[60:63], v[156:159], v[188:191], v[60:63]
	v_mfma_f32_16x16x32_bf16 v[56:59], v[164:167], v[188:191], v[56:59]
	v_mfma_f32_16x16x32_bf16 v[44:47], v[156:159], v[196:199], v[44:47]
	v_mfma_f32_16x16x32_bf16 v[40:43], v[164:167], v[196:199], v[40:43]
	v_mfma_f32_16x16x32_bf16 v[28:31], v[156:159], v[204:207], v[28:31]
	v_mfma_f32_16x16x32_bf16 v[24:27], v[164:167], v[204:207], v[24:27]
	v_mfma_f32_16x16x32_bf16 v[12:15], v[156:159], v[212:215], v[12:15]
	v_mfma_f32_16x16x32_bf16 v[8:11], v[164:167], v[212:215], v[8:11]
	v_mfma_f32_16x16x32_bf16 v[52:55], v[168:171], v[184:187], v[52:55]
	v_mfma_f32_16x16x32_bf16 v[48:51], v[176:179], v[184:187], v[48:51]
	v_mfma_f32_16x16x32_bf16 v[36:39], v[168:171], v[192:195], v[36:39]
	v_mfma_f32_16x16x32_bf16 v[32:35], v[176:179], v[192:195], v[32:35]
	v_mfma_f32_16x16x32_bf16 v[20:23], v[168:171], v[200:203], v[20:23]
	v_mfma_f32_16x16x32_bf16 v[16:19], v[176:179], v[200:203], v[16:19]
	v_mfma_f32_16x16x32_bf16 v[4:7], v[168:171], v[208:211], v[4:7]
	v_mfma_f32_16x16x32_bf16 v[0:3], v[176:179], v[208:211], v[0:3]
	v_mfma_f32_16x16x32_bf16 v[52:55], v[172:175], v[188:191], v[52:55]
	v_mfma_f32_16x16x32_bf16 v[48:51], v[180:183], v[188:191], v[48:51]
	v_mfma_f32_16x16x32_bf16 v[36:39], v[172:175], v[196:199], v[36:39]
	v_mfma_f32_16x16x32_bf16 v[32:35], v[180:183], v[196:199], v[32:35]
	v_mfma_f32_16x16x32_bf16 v[20:23], v[172:175], v[204:207], v[20:23]
	v_mfma_f32_16x16x32_bf16 v[16:19], v[180:183], v[204:207], v[16:19]
	v_mfma_f32_16x16x32_bf16 v[4:7], v[172:175], v[212:215], v[4:7]
	v_mfma_f32_16x16x32_bf16 v[0:3], v[180:183], v[212:215], v[0:3]
	s_setprio 0
	s_barrier
	s_add_u32 s38, s38, 0x100
	s_addc_u32 s39, s39, 0
	s_add_u32 s59, s59, 0x100
	s_addc_u32 s60, s60, 0
	s_cmp_ge_i32 s61, s48
	s_mov_b32 s40, s61
	s_cbranch_scc0 .LBB0_165

; #define PG8_STAGE(bufoff, gbase, voff) do { _Pragma("unroll") for (int _i = 0; _i < 2; ++_i) \
;         __builtin_amdgcn_global_load_lds((const unsigned*)((const char*)(gbase) + (voff)[_i]), (PG8_LAS unsigned*)(lds + (bufoff) + ldsw + _i * 8192), 16, 0, 0); } while (0)
; #define PG8_LDA(dst, b, h) do { _Pragma("unroll") for (int m = 0; m < 4; ++m) _Pragma("unroll") for (int k = 0; k < 2; ++k) dst[m][k] = *(const PG8_LAS bf16x8*)(lds + PG8_SA(b, h) + aoff + m * 2048 + k * 1024); } while (0)
; #define PG8_LDB(dst, b, h) do { _Pragma("unroll") for (int n = 0; n < 2; ++n) _Pragma("unroll") for (int k = 0; k < 2; ++k) dst[n][k] = *(const PG8_LAS bf16x8*)(lds + PG8_SB(b, h) + boff + n * 2048 + k * 1024); } while (0)
; #define PG8_MMA(ai, bj, At, Bt) do { __builtin_amdgcn_s_setprio(1); _Pragma("unroll") for (int m = 0; m < 4; ++m) _Pragma("unroll") for (int n = 0; n < 2; ++n) _Pragma("unroll") for (int k = 0; k < 2; ++k) \
;         acc[ai][bj][m][n] = __builtin_amdgcn_mfma_f32_16x16x32_bf16(Bt[n][k], At[m][k], acc[ai][bj][m][n], 0, 0, 0); __builtin_amdgcn_s_setprio(0); } while (0)
; #define PG8_WAIT_V(n) asm volatile("s_waitcnt vmcnt(" #n ")" ::: "memory")
; #define PG8_BAR __builtin_amdgcn_s_barrier()
; template <class Epi, class Sched, bool ALIGN_EPI = false, bool SP2 = false>
; __device__ __forceinline__ void gemm_phase(PG8_LAS unsigned char* lds, const Gemm g, const Sched& S, const Epi& E) {
;     ...
;         for (int t = 0; t < nt; t += 2) {
;             const bool last = (t == nt - 2);
;             const char* a1 = cA + (size_t)(t + 1) * kstep;
;             const char* a2 = last ? nA : cA + (size_t)(t + 2) * kstep; const char* b2 = last ? nB : cB + (size_t)(t + 2) * kstep;
;             const char* a3 = a2 + kstep; const char* b3 = b2 + kstep;
;             if (last && has_next) S.a_ready(nxt);
;             if constexpr (SP2) {
;             PG8_LDB(B0, 0, 0); PG8_LDB(B1, 0, 1); PG8_SCHED; PG8_LDA(At, 0, 0); PG8_STAGE(PG8_SA(1, 1), a1 + hstepA, voffA);
;             PG8_WAIT_V(8); PG8_WAIT_L(0); PG8_BAR; PG8_MMA(0, 0, At, B0); PG8_MMA(0, 1, At, B1); PG8_BAR; PG8_SCHED;
;             PG8_LDA(At, 0, 1); PG8_STAGE(PG8_SB(0, 0), b2, voffB); PG8_STAGE(PG8_SB(0, 1), b2 + hstepB, voffB); PG8_STAGE(PG8_SA(0, 0), a2, voffA);
;             PG8_WAIT_V(8); PG8_WAIT_L(0); PG8_BAR; PG8_MMA(1, 0, At, B0); PG8_MMA(1, 1, At, B1); PG8_BAR; PG8_SCHED;
.LBB0_301:
	s_add_i32 s59, s48, 2
	s_add_u32 s46, s42, 0xfffc0080
	s_addc_u32 s47, s43, -1
	s_add_i32 s62, 0, 0x10000
	s_cmp_eq_u32 s16, s48
	s_cselect_b32 s49, s29, s47
	s_cselect_b32 s48, s33, s46
	s_cselect_b32 s47, s41, s58
	s_cselect_b32 s46, s45, s55
	s_add_i32 s64, 0, 0x14000
	v_add_u32_e32 v150, s62, v158
	v_add_u32_e32 v154, s64, v158
	ds_read_b128 v[138:141], v150
	ds_read_b128 v[142:145], v150 offset:1024
	ds_read_b128 v[146:149], v150 offset:2048
	ds_read_b128 v[150:153], v150 offset:3072
	ds_read_b128 v[160:163], v154
	ds_read_b128 v[164:167], v154 offset:1024
	ds_read_b128 v[168:171], v154 offset:2048
	ds_read_b128 v[172:175], v154 offset:3072
	v_lshl_add_u64 v[154:155], s[42:43], 0, v[134:135]
	s_add_i32 m0, s3, 0xc000
	ds_read_b128 v[176:179], v159
	ds_read_b128 v[180:183], v159 offset:1024
	ds_read_b128 v[184:187], v159 offset:2048
	ds_read_b128 v[188:191], v159 offset:3072
	ds_read_b128 v[200:203], v159 offset:4096
	ds_read_b128 v[204:207], v159 offset:5120
	ds_read_b128 v[208:211], v159 offset:6144
	ds_read_b128 v[212:215], v159 offset:7168
	global_load_lds_dwordx4 v[154:155], off
	v_lshl_add_u64 v[154:155], s[42:43], 0, v[136:137]
	s_add_i32 m0, s3, 0xe000
	s_nop 0
	global_load_lds_dwordx4 v[154:155], off
	s_waitcnt vmcnt(8)
	s_waitcnt lgkmcnt(0)
	s_barrier
	s_setprio 1
	v_mfma_f32_16x16x32_bf16 v[124:127], v[138:141], v[176:179], v[124:127]
	v_mfma_f32_16x16x32_bf16 v[120:123], v[146:149], v[176:179], v[120:123]
	v_mfma_f32_16x16x32_bf16 v[108:111], v[138:141], v[184:187], v[108:111]
	v_mfma_f32_16x16x32_bf16 v[104:107], v[146:149], v[184:187], v[104:107]
	v_mfma_f32_16x16x32_bf16 v[92:95], v[138:141], v[200:203], v[92:95]
	v_mfma_f32_16x16x32_bf16 v[88:91], v[146:149], v[200:203], v[88:91]
	v_mfma_f32_16x16x32_bf16 v[76:79], v[138:141], v[208:211], v[76:79]
	v_mfma_f32_16x16x32_bf16 v[72:75], v[146:149], v[208:211], v[72:75]
	v_mfma_f32_16x16x32_bf16 v[124:127], v[142:145], v[180:183], v[124:127]
	v_mfma_f32_16x16x32_bf16 v[120:123], v[150:153], v[180:183], v[120:123]
	v_mfma_f32_16x16x32_bf16 v[108:111], v[142:145], v[188:191], v[108:111]
	v_mfma_f32_16x16x32_bf16 v[104:107], v[150:153], v[188:191], v[104:107]
	v_mfma_f32_16x16x32_bf16 v[92:95], v[142:145], v[204:207], v[92:95]
	v_mfma_f32_16x16x32_bf16 v[88:91], v[150:153], v[204:207], v[88:91]
	v_mfma_f32_16x16x32_bf16 v[76:79], v[142:145], v[212:215], v[76:79]
	v_mfma_f32_16x16x32_bf16 v[72:75], v[150:153], v[212:215], v[72:75]
	v_mfma_f32_16x16x32_bf16 v[112:115], v[160:163], v[176:179], v[112:115]
	v_mfma_f32_16x16x32_bf16 v[116:119], v[168:171], v[176:179], v[116:119]
	v_mfma_f32_16x16x32_bf16 v[100:103], v[160:163], v[184:187], v[100:103]
	v_mfma_f32_16x16x32_bf16 v[96:99], v[168:171], v[184:187], v[96:99]
	v_mfma_f32_16x16x32_bf16 v[84:87], v[160:163], v[200:203], v[84:87]
	v_mfma_f32_16x16x32_bf16 v[80:83], v[168:171], v[200:203], v[80:83]
	v_mfma_f32_16x16x32_bf16 v[68:71], v[160:163], v[208:211], v[68:71]
	v_mfma_f32_16x16x32_bf16 v[64:67], v[168:171], v[208:211], v[64:67]
	v_mfma_f32_16x16x32_bf16 v[112:115], v[164:167], v[180:183], v[112:115]
	v_mfma_f32_16x16x32_bf16 v[116:119], v[172:175], v[180:183], v[116:119]
	v_mfma_f32_16x16x32_bf16 v[100:103], v[164:167], v[188:191], v[100:103]
	v_mfma_f32_16x16x32_bf16 v[96:99], v[172:175], v[188:191], v[96:99]
	v_mfma_f32_16x16x32_bf16 v[84:87], v[164:167], v[204:207], v[84:87]
	v_mfma_f32_16x16x32_bf16 v[80:83], v[172:175], v[204:207], v[80:83]
	v_mfma_f32_16x16x32_bf16 v[68:71], v[164:167], v[212:215], v[68:71]
	v_mfma_f32_16x16x32_bf16 v[64:67], v[172:175], v[212:215], v[64:67]
	s_setprio 0
	s_barrier
	s_add_i32 s62, s62, s2
	v_lshl_add_u64 v[154:155], s[46:47], 0, v[194:195]
	s_mov_b32 m0, s62
	ds_read_b128 v[176:179], v159 offset:16384
	ds_read_b128 v[180:183], v159 offset:17408
	ds_read_b128 v[184:187], v159 offset:18432
	ds_read_b128 v[188:191], v159 offset:19456
	ds_read_b128 v[200:203], v159 offset:20480
	ds_read_b128 v[204:207], v159 offset:21504
	ds_read_b128 v[208:211], v159 offset:22528
	ds_read_b128 v[212:215], v159 offset:23552
	global_load_lds_dwordx4 v[154:155], off
	s_add_i32 m0, s62, 0x2000
	s_add_u32 s62, s46, 0x40000
	v_lshl_add_u64 v[192:193], s[46:47], 0, v[132:133]
	s_addc_u32 s63, s47, 0
	s_add_i32 s64, s64, s2
	global_load_lds_dwordx4 v[192:193], off
	v_lshl_add_u64 v[228:229], s[62:63], 0, v[194:195]
	s_mov_b32 m0, s64
	v_lshl_add_u64 v[230:231], s[48:49], 0, v[130:131]
	global_load_lds_dwordx4 v[228:229], off
	v_lshl_add_u64 v[228:229], s[62:63], 0, v[132:133]
	s_add_i32 m0, s64, 0x2000
	s_nop 0
	global_load_lds_dwordx4 v[228:229], off
	v_lshl_add_u64 v[228:229], s[48:49], 0, v[128:129]
	s_mov_b32 m0, s3
	s_nop 0
	global_load_lds_dwordx4 v[228:229], off
	s_mov_b32 m0, s8
	s_nop 0
	global_load_lds_dwordx4 v[230:231], off
	s_waitcnt vmcnt(8)
	s_waitcnt lgkmcnt(0)
	s_barrier
; #define PG8_STAGE(bufoff, gbase, voff) do { _Pragma("unroll") for (int _i = 0; _i < 2; ++_i) \
;         __builtin_amdgcn_global_load_lds((const unsigned*)((const char*)(gbase) + (voff)[_i]), (PG8_LAS unsigned*)(lds + (bufoff) + ldsw + _i * 8192), 16, 0, 0); } while (0)
; #define PG8_LDA(dst, b, h) do { _Pragma("unroll") for (int m = 0; m < 4; ++m) _Pragma("unroll") for (int k = 0; k < 2; ++k) dst[m][k] = *(const PG8_LAS bf16x8*)(lds + PG8_SA(b, h) + aoff + m * 2048 + k * 1024); } while (0)
; #define PG8_LDB(dst, b, h) do { _Pragma("unroll") for (int n = 0; n < 2; ++n) _Pragma("unroll") for (int k = 0; k < 2; ++k) dst[n][k] = *(const PG8_LAS bf16x8*)(lds + PG8_SB(b, h) + boff + n * 2048 + k * 1024); } while (0)
; #define PG8_MMA(ai, bj, At, Bt) do { __builtin_amdgcn_s_setprio(1); _Pragma("unroll") for (int m = 0; m < 4; ++m) _Pragma("unroll") for (int n = 0; n < 2; ++n) _Pragma("unroll") for (int k = 0; k < 2; ++k) \
;         acc[ai][bj][m][n] = __builtin_amdgcn_mfma_f32_16x16x32_bf16(Bt[n][k], At[m][k], acc[ai][bj][m][n], 0, 0, 0); __builtin_amdgcn_s_setprio(0); } while (0)
; #define PG8_WAIT_V(n) asm volatile("s_waitcnt vmcnt(" #n ")" ::: "memory")
; #define PG8_WAIT_L(n) asm volatile("s_waitcnt lgkmcnt(" #n ")" ::: "memory")
; #define PG8_BAR __builtin_amdgcn_s_barrier()
; #define PG8_SCHED __builtin_amdgcn_sched_barrier(0)
; template <class Epi, class Sched, bool ALIGN_EPI = false, bool SP2 = false>
; __device__ __forceinline__ void gemm_phase(PG8_LAS unsigned char* lds, const Gemm g, const Sched& S, const Epi& E) {
;     ...
;             PG8_WAIT_V(8); PG8_WAIT_L(0); PG8_BAR; PG8_MMA(1, 0, At, B0); PG8_MMA(1, 1, At, B1); PG8_BAR; PG8_SCHED;
;             PG8_LDB(B0, 1, 0); PG8_LDB(B1, 1, 1); PG8_SCHED; PG8_LDA(At, 1, 0); PG8_STAGE(PG8_SA(0, 1), a2 + hstepA, voffA);
;             PG8_WAIT_V(8); PG8_WAIT_L(0); PG8_BAR; PG8_MMA(0, 0, At, B0); PG8_MMA(0, 1, At, B1); PG8_BAR; PG8_SCHED;
	s_setprio 1
	v_mfma_f32_16x16x32_bf16 v[60:63], v[138:141], v[176:179], v[60:63]
	v_mfma_f32_16x16x32_bf16 v[56:59], v[146:149], v[176:179], v[56:59]
	v_mfma_f32_16x16x32_bf16 v[44:47], v[138:141], v[184:187], v[44:47]
	v_mfma_f32_16x16x32_bf16 v[40:43], v[146:149], v[184:187], v[40:43]
	v_mfma_f32_16x16x32_bf16 v[28:31], v[138:141], v[200:203], v[28:31]
	v_mfma_f32_16x16x32_bf16 v[24:27], v[146:149], v[200:203], v[24:27]
	v_mfma_f32_16x16x32_bf16 v[12:15], v[138:141], v[208:211], v[12:15]
	v_mfma_f32_16x16x32_bf16 v[8:11], v[146:149], v[208:211], v[8:11]
	v_mfma_f32_16x16x32_bf16 v[60:63], v[142:145], v[180:183], v[60:63]
	v_mfma_f32_16x16x32_bf16 v[56:59], v[150:153], v[180:183], v[56:59]
	v_mfma_f32_16x16x32_bf16 v[44:47], v[142:145], v[188:191], v[44:47]
	v_mfma_f32_16x16x32_bf16 v[40:43], v[150:153], v[188:191], v[40:43]
	v_mfma_f32_16x16x32_bf16 v[28:31], v[142:145], v[204:207], v[28:31]
	v_mfma_f32_16x16x32_bf16 v[24:27], v[150:153], v[204:207], v[24:27]
	v_mfma_f32_16x16x32_bf16 v[12:15], v[142:145], v[212:215], v[12:15]
	v_mfma_f32_16x16x32_bf16 v[8:11], v[150:153], v[212:215], v[8:11]
	v_mfma_f32_16x16x32_bf16 v[52:55], v[160:163], v[176:179], v[52:55]
	v_mfma_f32_16x16x32_bf16 v[48:51], v[168:171], v[176:179], v[48:51]
	v_mfma_f32_16x16x32_bf16 v[36:39], v[160:163], v[184:187], v[36:39]
	v_mfma_f32_16x16x32_bf16 v[32:35], v[168:171], v[184:187], v[32:35]
	v_mfma_f32_16x16x32_bf16 v[20:23], v[160:163], v[200:203], v[20:23]
	v_mfma_f32_16x16x32_bf16 v[16:19], v[168:171], v[200:203], v[16:19]
	v_mfma_f32_16x16x32_bf16 v[4:7], v[160:163], v[208:211], v[4:7]
	v_mfma_f32_16x16x32_bf16 v[0:3], v[168:171], v[208:211], v[0:3]
	v_mfma_f32_16x16x32_bf16 v[52:55], v[164:167], v[180:183], v[52:55]
	v_mfma_f32_16x16x32_bf16 v[48:51], v[172:175], v[180:183], v[48:51]
	v_mfma_f32_16x16x32_bf16 v[36:39], v[164:167], v[188:191], v[36:39]
	v_mfma_f32_16x16x32_bf16 v[32:35], v[172:175], v[188:191], v[32:35]
	v_mfma_f32_16x16x32_bf16 v[20:23], v[164:167], v[204:207], v[20:23]
	v_mfma_f32_16x16x32_bf16 v[16:19], v[172:175], v[204:207], v[16:19]
	v_mfma_f32_16x16x32_bf16 v[4:7], v[164:167], v[212:215], v[4:7]
	v_mfma_f32_16x16x32_bf16 v[0:3], v[172:175], v[212:215], v[0:3]
	s_setprio 0
	s_barrier
	s_add_i32 s62, 0, 0x18000
	s_add_i32 s63, 0, 0x1c000
	v_add_u32_e32 v150, s62, v158
	v_add_u32_e32 v172, s63, v158
	ds_read_b128 v[138:141], v150
	ds_read_b128 v[142:145], v150 offset:1024
	ds_read_b128 v[146:149], v150 offset:2048
	ds_read_b128 v[150:153], v150 offset:3072
	ds_read_b128 v[160:163], v172
	ds_read_b128 v[164:167], v172 offset:1024
	ds_read_b128 v[168:171], v172 offset:2048
	ds_read_b128 v[172:175], v172 offset:3072
	s_add_u32 s48, s48, 0x40000
	s_addc_u32 s49, s49, 0
	s_mov_b32 m0, s9
	v_lshl_add_u64 v[232:233], s[48:49], 0, v[128:129]
	ds_read_b128 v[176:179], v159 offset:32768
	ds_read_b128 v[180:183], v159 offset:33792
	ds_read_b128 v[184:187], v159 offset:34816
	ds_read_b128 v[188:191], v159 offset:35840
	ds_read_b128 v[200:203], v159 offset:36864
	ds_read_b128 v[204:207], v159 offset:37888
	ds_read_b128 v[208:211], v159 offset:38912
	ds_read_b128 v[212:215], v159 offset:39936
	global_load_lds_dwordx4 v[232:233], off
	v_lshl_add_u64 v[232:233], s[48:49], 0, v[130:131]
	s_mov_b32 m0, s10
	s_nop 0
	global_load_lds_dwordx4 v[232:233], off
	s_waitcnt vmcnt(8)
	s_waitcnt lgkmcnt(0)
	s_barrier
	s_setprio 1
	v_mfma_f32_16x16x32_bf16 v[124:127], v[138:141], v[176:179], v[124:127]
	v_mfma_f32_16x16x32_bf16 v[120:123], v[146:149], v[176:179], v[120:123]
	v_mfma_f32_16x16x32_bf16 v[108:111], v[138:141], v[184:187], v[108:111]
	v_mfma_f32_16x16x32_bf16 v[104:107], v[146:149], v[184:187], v[104:107]
	v_mfma_f32_16x16x32_bf16 v[92:95], v[138:141], v[200:203], v[92:95]
	v_mfma_f32_16x16x32_bf16 v[88:91], v[146:149], v[200:203], v[88:91]
	v_mfma_f32_16x16x32_bf16 v[76:79], v[138:141], v[208:211], v[76:79]
	v_mfma_f32_16x16x32_bf16 v[72:75], v[146:149], v[208:211], v[72:75]
	v_mfma_f32_16x16x32_bf16 v[124:127], v[142:145], v[180:183], v[124:127]
	v_mfma_f32_16x16x32_bf16 v[120:123], v[150:153], v[180:183], v[120:123]
	v_mfma_f32_16x16x32_bf16 v[108:111], v[142:145], v[188:191], v[108:111]
	v_mfma_f32_16x16x32_bf16 v[104:107], v[150:153], v[188:191], v[104:107]
	v_mfma_f32_16x16x32_bf16 v[92:95], v[142:145], v[204:207], v[92:95]
	v_mfma_f32_16x16x32_bf16 v[88:91], v[150:153], v[204:207], v[88:91]
	v_mfma_f32_16x16x32_bf16 v[76:79], v[142:145], v[212:215], v[76:79]
	v_mfma_f32_16x16x32_bf16 v[72:75], v[150:153], v[212:215], v[72:75]
	v_mfma_f32_16x16x32_bf16 v[112:115], v[160:163], v[176:179], v[112:115]
	v_mfma_f32_16x16x32_bf16 v[116:119], v[168:171], v[176:179], v[116:119]
	v_mfma_f32_16x16x32_bf16 v[100:103], v[160:163], v[184:187], v[100:103]
	v_mfma_f32_16x16x32_bf16 v[96:99], v[168:171], v[184:187], v[96:99]
	v_mfma_f32_16x16x32_bf16 v[84:87], v[160:163], v[200:203], v[84:87]
	v_mfma_f32_16x16x32_bf16 v[80:83], v[168:171], v[200:203], v[80:83]
	v_mfma_f32_16x16x32_bf16 v[68:71], v[160:163], v[208:211], v[68:71]
	v_mfma_f32_16x16x32_bf16 v[64:67], v[168:171], v[208:211], v[64:67]
	v_mfma_f32_16x16x32_bf16 v[112:115], v[164:167], v[180:183], v[112:115]
	v_mfma_f32_16x16x32_bf16 v[116:119], v[172:175], v[180:183], v[116:119]
	v_mfma_f32_16x16x32_bf16 v[100:103], v[164:167], v[188:191], v[100:103]
	v_mfma_f32_16x16x32_bf16 v[96:99], v[172:175], v[188:191], v[96:99]
	v_mfma_f32_16x16x32_bf16 v[84:87], v[164:167], v[204:207], v[84:87]
	v_mfma_f32_16x16x32_bf16 v[80:83], v[172:175], v[204:207], v[80:83]
	v_mfma_f32_16x16x32_bf16 v[68:71], v[164:167], v[212:215], v[68:71]
	v_mfma_f32_16x16x32_bf16 v[64:67], v[172:175], v[212:215], v[64:67]
	s_setprio 0
	s_barrier
; #define PG8_STAGE(bufoff, gbase, voff) do { _Pragma("unroll") for (int _i = 0; _i < 2; ++_i) \
;         __builtin_amdgcn_global_load_lds((const unsigned*)((const char*)(gbase) + (voff)[_i]), (PG8_LAS unsigned*)(lds + (bufoff) + ldsw + _i * 8192), 16, 0, 0); } while (0)
; #define PG8_LDA(dst, b, h) do { _Pragma("unroll") for (int m = 0; m < 4; ++m) _Pragma("unroll") for (int k = 0; k < 2; ++k) dst[m][k] = *(const PG8_LAS bf16x8*)(lds + PG8_SA(b, h) + aoff + m * 2048 + k * 1024); } while (0)
; #define PG8_MMA(ai, bj, At, Bt) do { __builtin_amdgcn_s_setprio(1); _Pragma("unroll") for (int m = 0; m < 4; ++m) _Pragma("unroll") for (int n = 0; n < 2; ++n) _Pragma("unroll") for (int k = 0; k < 2; ++k) \
;         acc[ai][bj][m][n] = __builtin_amdgcn_mfma_f32_16x16x32_bf16(Bt[n][k], At[m][k], acc[ai][bj][m][n], 0, 0, 0); __builtin_amdgcn_s_setprio(0); } while (0)
; #define PG8_WAIT_V(n) asm volatile("s_waitcnt vmcnt(" #n ")" ::: "memory")
; #define PG8_WAIT_L(n) asm volatile("s_waitcnt lgkmcnt(" #n ")" ::: "memory")
; #define PG8_BAR __builtin_amdgcn_s_barrier()
; #define PG8_SCHED __builtin_amdgcn_sched_barrier(0)
; template <class Epi, class Sched, bool ALIGN_EPI = false, bool SP2 = false>
; __device__ __forceinline__ void gemm_phase(PG8_LAS unsigned char* lds, const Gemm g, const Sched& S, const Epi& E) {
;     ...
;         for (int t = 0; t < nt; t += 2) {
;     ...
;             PG8_WAIT_V(8); PG8_WAIT_L(0); PG8_BAR; PG8_MMA(0, 0, At, B0); PG8_MMA(0, 1, At, B1); PG8_BAR; PG8_SCHED;
;             PG8_LDA(At, 1, 1); PG8_STAGE(PG8_SB(1, 0), b3, voffB); PG8_STAGE(PG8_SB(1, 1), b3 + hstepB, voffB); PG8_STAGE(PG8_SA(1, 0), a3, voffA);
;             PG8_WAIT_V(8); PG8_WAIT_L(0); PG8_BAR; PG8_MMA(1, 0, At, B0); PG8_MMA(1, 1, At, B1); PG8_BAR; PG8_SCHED;
	s_add_i32 s48, s62, s2
	v_lshl_add_u64 v[154:155], v[154:155], 0, s[26:27]
	s_mov_b32 m0, s48
	ds_read_b128 v[176:179], v159 offset:49152
	ds_read_b128 v[180:183], v159 offset:50176
	ds_read_b128 v[184:187], v159 offset:51200
	ds_read_b128 v[188:191], v159 offset:52224
	ds_read_b128 v[200:203], v159 offset:53248
	ds_read_b128 v[204:207], v159 offset:54272
	ds_read_b128 v[208:211], v159 offset:55296
	ds_read_b128 v[212:215], v159 offset:56320
	global_load_lds_dwordx4 v[154:155], off
	s_add_i32 m0, s48, 0x2000
	s_add_u32 s46, s46, 0x40080
	v_lshl_add_u64 v[154:155], v[192:193], 0, s[26:27]
	s_addc_u32 s47, s47, 0
	s_add_i32 s48, s63, s2
	global_load_lds_dwordx4 v[154:155], off
	v_lshl_add_u64 v[154:155], s[46:47], 0, v[194:195]
	s_mov_b32 m0, s48
	s_nop 0
	global_load_lds_dwordx4 v[154:155], off
	v_lshl_add_u64 v[154:155], s[46:47], 0, v[132:133]
	s_add_i32 m0, s48, 0x2000
	s_nop 0
	global_load_lds_dwordx4 v[154:155], off
	v_lshl_add_u64 v[154:155], v[228:229], 0, s[26:27]
	s_mov_b32 m0, s14
	s_nop 0
	global_load_lds_dwordx4 v[154:155], off
	v_lshl_add_u64 v[154:155], v[230:231], 0, s[26:27]
	s_mov_b32 m0, s15
	s_nop 0
	global_load_lds_dwordx4 v[154:155], off
	s_waitcnt vmcnt(8)
	s_waitcnt lgkmcnt(0)
	s_barrier
	s_setprio 1
	v_mfma_f32_16x16x32_bf16 v[60:63], v[138:141], v[176:179], v[60:63]
	v_mfma_f32_16x16x32_bf16 v[56:59], v[146:149], v[176:179], v[56:59]
	v_mfma_f32_16x16x32_bf16 v[44:47], v[138:141], v[184:187], v[44:47]
	v_mfma_f32_16x16x32_bf16 v[40:43], v[146:149], v[184:187], v[40:43]
	v_mfma_f32_16x16x32_bf16 v[28:31], v[138:141], v[200:203], v[28:31]
	v_mfma_f32_16x16x32_bf16 v[24:27], v[146:149], v[200:203], v[24:27]
	v_mfma_f32_16x16x32_bf16 v[12:15], v[138:141], v[208:211], v[12:15]
	v_mfma_f32_16x16x32_bf16 v[8:11], v[146:149], v[208:211], v[8:11]
	v_mfma_f32_16x16x32_bf16 v[60:63], v[142:145], v[180:183], v[60:63]
	v_mfma_f32_16x16x32_bf16 v[56:59], v[150:153], v[180:183], v[56:59]
	v_mfma_f32_16x16x32_bf16 v[44:47], v[142:145], v[188:191], v[44:47]
	v_mfma_f32_16x16x32_bf16 v[40:43], v[150:153], v[188:191], v[40:43]
	v_mfma_f32_16x16x32_bf16 v[28:31], v[142:145], v[204:207], v[28:31]
	v_mfma_f32_16x16x32_bf16 v[24:27], v[150:153], v[204:207], v[24:27]
	v_mfma_f32_16x16x32_bf16 v[12:15], v[142:145], v[212:215], v[12:15]
	v_mfma_f32_16x16x32_bf16 v[8:11], v[150:153], v[212:215], v[8:11]
	v_mfma_f32_16x16x32_bf16 v[52:55], v[160:163], v[176:179], v[52:55]
	v_mfma_f32_16x16x32_bf16 v[48:51], v[168:171], v[176:179], v[48:51]
	v_mfma_f32_16x16x32_bf16 v[36:39], v[160:163], v[184:187], v[36:39]
	v_mfma_f32_16x16x32_bf16 v[32:35], v[168:171], v[184:187], v[32:35]
	v_mfma_f32_16x16x32_bf16 v[20:23], v[160:163], v[200:203], v[20:23]
	v_mfma_f32_16x16x32_bf16 v[16:19], v[168:171], v[200:203], v[16:19]
	v_mfma_f32_16x16x32_bf16 v[4:7], v[160:163], v[208:211], v[4:7]
	v_mfma_f32_16x16x32_bf16 v[0:3], v[168:171], v[208:211], v[0:3]
	v_mfma_f32_16x16x32_bf16 v[52:55], v[164:167], v[180:183], v[52:55]
	v_mfma_f32_16x16x32_bf16 v[48:51], v[172:175], v[180:183], v[48:51]
	v_mfma_f32_16x16x32_bf16 v[36:39], v[164:167], v[188:191], v[36:39]
	v_mfma_f32_16x16x32_bf16 v[32:35], v[172:175], v[188:191], v[32:35]
	v_mfma_f32_16x16x32_bf16 v[20:23], v[164:167], v[204:207], v[20:23]
	v_mfma_f32_16x16x32_bf16 v[16:19], v[172:175], v[204:207], v[16:19]
	v_mfma_f32_16x16x32_bf16 v[4:7], v[164:167], v[212:215], v[4:7]
	v_mfma_f32_16x16x32_bf16 v[0:3], v[172:175], v[212:215], v[0:3]
	s_setprio 0
	s_barrier
	s_add_u32 s42, s42, 0x100
	s_addc_u32 s43, s43, 0
	s_add_u32 s55, s55, 0x100
	s_addc_u32 s58, s58, 0
	s_cmp_ge_i32 s59, s11
	s_mov_b32 s48, s59
	s_cbranch_scc0 .LBB0_301
	s_and_b64 vcc, exec, s[76:77]
	s_cbranch_vccz .LBB0_304

; #define PG8_STAGE(bufoff, gbase, voff) do { _Pragma("unroll") for (int _i = 0; _i < 2; ++_i) \
;         __builtin_amdgcn_global_load_lds((const unsigned*)((const char*)(gbase) + (voff)[_i]), (PG8_LAS unsigned*)(lds + (bufoff) + ldsw + _i * 8192), 16, 0, 0); } while (0)
; #define PG8_LDA(dst, b, h) do { _Pragma("unroll") for (int m = 0; m < 4; ++m) _Pragma("unroll") for (int k = 0; k < 2; ++k) dst[m][k] = *(const PG8_LAS bf16x8*)(lds + PG8_SA(b, h) + aoff + m * 2048 + k * 1024); } while (0)
; #define PG8_LDB(dst, b, h) do { _Pragma("unroll") for (int n = 0; n < 2; ++n) _Pragma("unroll") for (int k = 0; k < 2; ++k) dst[n][k] = *(const PG8_LAS bf16x8*)(lds + PG8_SB(b, h) + boff + n * 2048 + k * 1024); } while (0)
; #define PG8_MMA(ai, bj, At, Bt) do { __builtin_amdgcn_s_setprio(1); _Pragma("unroll") for (int m = 0; m < 4; ++m) _Pragma("unroll") for (int n = 0; n < 2; ++n) _Pragma("unroll") for (int k = 0; k < 2; ++k) \
;         acc[ai][bj][m][n] = __builtin_amdgcn_mfma_f32_16x16x32_bf16(Bt[n][k], At[m][k], acc[ai][bj][m][n], 0, 0, 0); __builtin_amdgcn_s_setprio(0); } while (0)
; #define PG8_WAIT_V(n) asm volatile("s_waitcnt vmcnt(" #n ")" ::: "memory")
; #define PG8_BAR __builtin_amdgcn_s_barrier()
; template <class Epi, class Sched, bool ALIGN_EPI = false, bool SP2 = false>
; __device__ __forceinline__ void gemm_phase(PG8_LAS unsigned char* lds, const Gemm g, const Sched& S, const Epi& E) {
;     ...
;         for (int t = 0; t < nt; t += 2) {
;             const bool last = (t == nt - 2);
;             const char* a1 = cA + (size_t)(t + 1) * kstep;
;             const char* a2 = last ? nA : cA + (size_t)(t + 2) * kstep; const char* b2 = last ? nB : cB + (size_t)(t + 2) * kstep;
;             const char* a3 = a2 + kstep; const char* b3 = b2 + kstep;
;             if (last && has_next) S.a_ready(nxt);
;             if constexpr (SP2) {
;             PG8_LDB(B0, 0, 0); PG8_LDB(B1, 0, 1); PG8_SCHED; PG8_LDA(At, 0, 0); PG8_STAGE(PG8_SA(1, 1), a1 + hstepA, voffA);
;             PG8_WAIT_V(8); PG8_WAIT_L(0); PG8_BAR; PG8_MMA(0, 0, At, B0); PG8_MMA(0, 1, At, B1); PG8_BAR; PG8_SCHED;
;             PG8_LDA(At, 0, 1); PG8_STAGE(PG8_SB(0, 0), b2, voffB); PG8_STAGE(PG8_SB(0, 1), b2 + hstepB, voffB); PG8_STAGE(PG8_SA(0, 0), a2, voffA);
;             PG8_WAIT_V(8); PG8_WAIT_L(0); PG8_BAR; PG8_MMA(1, 0, At, B0); PG8_MMA(1, 1, At, B1); PG8_BAR; PG8_SCHED;
.LBB0_502:
	s_add_i32 s48, s44, 2
	s_add_u32 s45, s42, 0xfffe0080
	s_addc_u32 s46, s43, -1
	s_add_i32 s49, 0, 0x10000
	s_cmp_eq_u32 s58, s44
	s_cselect_b32 s47, s15, s46
	s_cselect_b32 s46, s16, s45
	v_add_u32_e32 v150, s49, v154
	s_cselect_b32 s45, s17, s41
	s_cselect_b32 s44, s33, s35
	s_add_i32 s62, 0, 0x14000
	ds_read_b128 v[138:141], v150
	ds_read_b128 v[142:145], v150 offset:1024
	ds_read_b128 v[146:149], v150 offset:2048
	ds_read_b128 v[156:159], v150 offset:3072
	v_add_u32_e32 v150, s62, v154
	ds_read_b128 v[160:163], v150
	ds_read_b128 v[164:167], v150 offset:1024
	ds_read_b128 v[168:171], v150 offset:2048
	ds_read_b128 v[172:175], v150 offset:3072
	v_lshl_add_u64 v[150:151], s[42:43], 0, v[134:135]
	s_add_i32 m0, s9, 0xc000
	ds_read_b128 v[176:179], v155
	ds_read_b128 v[180:183], v155 offset:1024
	ds_read_b128 v[184:187], v155 offset:2048
	ds_read_b128 v[188:191], v155 offset:3072
	ds_read_b128 v[200:203], v155 offset:4096
	ds_read_b128 v[204:207], v155 offset:5120
	ds_read_b128 v[208:211], v155 offset:6144
	ds_read_b128 v[212:215], v155 offset:7168
	global_load_lds_dwordx4 v[150:151], off
	v_lshl_add_u64 v[150:151], s[42:43], 0, v[136:137]
	s_add_i32 m0, s9, 0xe000
	s_nop 0
	global_load_lds_dwordx4 v[150:151], off
	s_waitcnt vmcnt(8)
	s_waitcnt lgkmcnt(0)
	s_barrier
	s_setprio 1
	v_mfma_f32_16x16x32_bf16 v[120:123], v[138:141], v[176:179], v[120:123]
	v_mfma_f32_16x16x32_bf16 v[124:127], v[146:149], v[176:179], v[124:127]
	v_mfma_f32_16x16x32_bf16 v[108:111], v[138:141], v[184:187], v[108:111]
	v_mfma_f32_16x16x32_bf16 v[104:107], v[146:149], v[184:187], v[104:107]
	v_mfma_f32_16x16x32_bf16 v[92:95], v[138:141], v[200:203], v[92:95]
	v_mfma_f32_16x16x32_bf16 v[88:91], v[146:149], v[200:203], v[88:91]
	v_mfma_f32_16x16x32_bf16 v[76:79], v[138:141], v[208:211], v[76:79]
	v_mfma_f32_16x16x32_bf16 v[72:75], v[146:149], v[208:211], v[72:75]
	v_mfma_f32_16x16x32_bf16 v[120:123], v[142:145], v[180:183], v[120:123]
	v_mfma_f32_16x16x32_bf16 v[124:127], v[156:159], v[180:183], v[124:127]
	v_mfma_f32_16x16x32_bf16 v[108:111], v[142:145], v[188:191], v[108:111]
	v_mfma_f32_16x16x32_bf16 v[104:107], v[156:159], v[188:191], v[104:107]
	v_mfma_f32_16x16x32_bf16 v[92:95], v[142:145], v[204:207], v[92:95]
	v_mfma_f32_16x16x32_bf16 v[88:91], v[156:159], v[204:207], v[88:91]
	v_mfma_f32_16x16x32_bf16 v[76:79], v[142:145], v[212:215], v[76:79]
	v_mfma_f32_16x16x32_bf16 v[72:75], v[156:159], v[212:215], v[72:75]
	v_mfma_f32_16x16x32_bf16 v[116:119], v[160:163], v[176:179], v[116:119]
	v_mfma_f32_16x16x32_bf16 v[112:115], v[168:171], v[176:179], v[112:115]
	v_mfma_f32_16x16x32_bf16 v[100:103], v[160:163], v[184:187], v[100:103]
	v_mfma_f32_16x16x32_bf16 v[96:99], v[168:171], v[184:187], v[96:99]
	v_mfma_f32_16x16x32_bf16 v[84:87], v[160:163], v[200:203], v[84:87]
	v_mfma_f32_16x16x32_bf16 v[80:83], v[168:171], v[200:203], v[80:83]
	v_mfma_f32_16x16x32_bf16 v[68:71], v[160:163], v[208:211], v[68:71]
	v_mfma_f32_16x16x32_bf16 v[64:67], v[168:171], v[208:211], v[64:67]
	v_mfma_f32_16x16x32_bf16 v[116:119], v[164:167], v[180:183], v[116:119]
	v_mfma_f32_16x16x32_bf16 v[112:115], v[172:175], v[180:183], v[112:115]
	v_mfma_f32_16x16x32_bf16 v[100:103], v[164:167], v[188:191], v[100:103]
	v_mfma_f32_16x16x32_bf16 v[96:99], v[172:175], v[188:191], v[96:99]
	v_mfma_f32_16x16x32_bf16 v[84:87], v[164:167], v[204:207], v[84:87]
	v_mfma_f32_16x16x32_bf16 v[80:83], v[172:175], v[204:207], v[80:83]
	v_mfma_f32_16x16x32_bf16 v[68:71], v[164:167], v[212:215], v[68:71]
	v_mfma_f32_16x16x32_bf16 v[64:67], v[172:175], v[212:215], v[64:67]
	s_setprio 0
	s_barrier
	s_add_i32 s49, s49, s8
	v_lshl_add_u64 v[150:151], s[44:45], 0, v[194:195]
	s_mov_b32 m0, s49
	ds_read_b128 v[176:179], v155 offset:16384
	ds_read_b128 v[180:183], v155 offset:17408
	ds_read_b128 v[184:187], v155 offset:18432
	ds_read_b128 v[188:191], v155 offset:19456
	ds_read_b128 v[200:203], v155 offset:20480
	ds_read_b128 v[204:207], v155 offset:21504
	ds_read_b128 v[208:211], v155 offset:22528
	ds_read_b128 v[212:215], v155 offset:23552
	global_load_lds_dwordx4 v[150:151], off
	s_add_i32 m0, s49, 0x2000
	s_add_u32 s52, s44, 0x10000
	v_lshl_add_u64 v[192:193], s[44:45], 0, v[132:133]
	s_addc_u32 s53, s45, 0
	s_add_i32 s49, s62, s8
	global_load_lds_dwordx4 v[192:193], off
	v_lshl_add_u64 v[228:229], s[52:53], 0, v[194:195]
	s_mov_b32 m0, s49
	v_lshl_add_u64 v[230:231], s[46:47], 0, v[130:131]
	global_load_lds_dwordx4 v[228:229], off
	v_lshl_add_u64 v[228:229], s[52:53], 0, v[132:133]
	s_add_i32 m0, s49, 0x2000
	s_nop 0
	global_load_lds_dwordx4 v[228:229], off
	v_lshl_add_u64 v[228:229], s[46:47], 0, v[128:129]
	s_mov_b32 m0, s9
	s_nop 0
	global_load_lds_dwordx4 v[228:229], off
	s_mov_b32 m0, s28
	s_nop 0
	global_load_lds_dwordx4 v[230:231], off
	s_waitcnt vmcnt(8)
	s_waitcnt lgkmcnt(0)
	s_barrier
; #define PG8_STAGE(bufoff, gbase, voff) do { _Pragma("unroll") for (int _i = 0; _i < 2; ++_i) \
;         __builtin_amdgcn_global_load_lds((const unsigned*)((const char*)(gbase) + (voff)[_i]), (PG8_LAS unsigned*)(lds + (bufoff) + ldsw + _i * 8192), 16, 0, 0); } while (0)
; #define PG8_LDA(dst, b, h) do { _Pragma("unroll") for (int m = 0; m < 4; ++m) _Pragma("unroll") for (int k = 0; k < 2; ++k) dst[m][k] = *(const PG8_LAS bf16x8*)(lds + PG8_SA(b, h) + aoff + m * 2048 + k * 1024); } while (0)
; #define PG8_LDB(dst, b, h) do { _Pragma("unroll") for (int n = 0; n < 2; ++n) _Pragma("unroll") for (int k = 0; k < 2; ++k) dst[n][k] = *(const PG8_LAS bf16x8*)(lds + PG8_SB(b, h) + boff + n * 2048 + k * 1024); } while (0)
; #define PG8_MMA(ai, bj, At, Bt) do { __builtin_amdgcn_s_setprio(1); _Pragma("unroll") for (int m = 0; m < 4; ++m) _Pragma("unroll") for (int n = 0; n < 2; ++n) _Pragma("unroll") for (int k = 0; k < 2; ++k) \
;         acc[ai][bj][m][n] = __builtin_amdgcn_mfma_f32_16x16x32_bf16(Bt[n][k], At[m][k], acc[ai][bj][m][n], 0, 0, 0); __builtin_amdgcn_s_setprio(0); } while (0)
; #define PG8_WAIT_V(n) asm volatile("s_waitcnt vmcnt(" #n ")" ::: "memory")
; #define PG8_WAIT_L(n) asm volatile("s_waitcnt lgkmcnt(" #n ")" ::: "memory")
; #define PG8_BAR __builtin_amdgcn_s_barrier()
; #define PG8_SCHED __builtin_amdgcn_sched_barrier(0)
; template <class Epi, class Sched, bool ALIGN_EPI = false, bool SP2 = false>
; __device__ __forceinline__ void gemm_phase(PG8_LAS unsigned char* lds, const Gemm g, const Sched& S, const Epi& E) {
;     ...
;             PG8_WAIT_V(8); PG8_WAIT_L(0); PG8_BAR; PG8_MMA(1, 0, At, B0); PG8_MMA(1, 1, At, B1); PG8_BAR; PG8_SCHED;
;             PG8_LDB(B0, 1, 0); PG8_LDB(B1, 1, 1); PG8_SCHED; PG8_LDA(At, 1, 0); PG8_STAGE(PG8_SA(0, 1), a2 + hstepA, voffA);
;             PG8_WAIT_V(8); PG8_WAIT_L(0); PG8_BAR; PG8_MMA(0, 0, At, B0); PG8_MMA(0, 1, At, B1); PG8_BAR; PG8_SCHED;
	s_setprio 1
	v_mfma_f32_16x16x32_bf16 v[60:63], v[138:141], v[176:179], v[60:63]
	v_mfma_f32_16x16x32_bf16 v[56:59], v[146:149], v[176:179], v[56:59]
	v_mfma_f32_16x16x32_bf16 v[44:47], v[138:141], v[184:187], v[44:47]
	v_mfma_f32_16x16x32_bf16 v[40:43], v[146:149], v[184:187], v[40:43]
	v_mfma_f32_16x16x32_bf16 v[28:31], v[138:141], v[200:203], v[28:31]
	v_mfma_f32_16x16x32_bf16 v[24:27], v[146:149], v[200:203], v[24:27]
	v_mfma_f32_16x16x32_bf16 v[12:15], v[138:141], v[208:211], v[12:15]
	v_mfma_f32_16x16x32_bf16 v[8:11], v[146:149], v[208:211], v[8:11]
	v_mfma_f32_16x16x32_bf16 v[60:63], v[142:145], v[180:183], v[60:63]
	v_mfma_f32_16x16x32_bf16 v[56:59], v[156:159], v[180:183], v[56:59]
	v_mfma_f32_16x16x32_bf16 v[44:47], v[142:145], v[188:191], v[44:47]
	v_mfma_f32_16x16x32_bf16 v[40:43], v[156:159], v[188:191], v[40:43]
	v_mfma_f32_16x16x32_bf16 v[28:31], v[142:145], v[204:207], v[28:31]
	v_mfma_f32_16x16x32_bf16 v[24:27], v[156:159], v[204:207], v[24:27]
	v_mfma_f32_16x16x32_bf16 v[12:15], v[142:145], v[212:215], v[12:15]
	v_mfma_f32_16x16x32_bf16 v[8:11], v[156:159], v[212:215], v[8:11]
	v_mfma_f32_16x16x32_bf16 v[52:55], v[160:163], v[176:179], v[52:55]
	v_mfma_f32_16x16x32_bf16 v[48:51], v[168:171], v[176:179], v[48:51]
	v_mfma_f32_16x16x32_bf16 v[36:39], v[160:163], v[184:187], v[36:39]
	v_mfma_f32_16x16x32_bf16 v[32:35], v[168:171], v[184:187], v[32:35]
	v_mfma_f32_16x16x32_bf16 v[20:23], v[160:163], v[200:203], v[20:23]
	v_mfma_f32_16x16x32_bf16 v[16:19], v[168:171], v[200:203], v[16:19]
	v_mfma_f32_16x16x32_bf16 v[4:7], v[160:163], v[208:211], v[4:7]
	v_mfma_f32_16x16x32_bf16 v[0:3], v[168:171], v[208:211], v[0:3]
	v_mfma_f32_16x16x32_bf16 v[52:55], v[164:167], v[180:183], v[52:55]
	v_mfma_f32_16x16x32_bf16 v[48:51], v[172:175], v[180:183], v[48:51]
	v_mfma_f32_16x16x32_bf16 v[36:39], v[164:167], v[188:191], v[36:39]
	v_mfma_f32_16x16x32_bf16 v[32:35], v[172:175], v[188:191], v[32:35]
	v_mfma_f32_16x16x32_bf16 v[20:23], v[164:167], v[204:207], v[20:23]
	v_mfma_f32_16x16x32_bf16 v[16:19], v[172:175], v[204:207], v[16:19]
	v_mfma_f32_16x16x32_bf16 v[4:7], v[164:167], v[212:215], v[4:7]
	v_mfma_f32_16x16x32_bf16 v[0:3], v[172:175], v[212:215], v[0:3]
	s_setprio 0
	s_barrier
	s_add_i32 s49, 0, 0x18000
	s_add_i32 s52, 0, 0x1c000
	v_add_u32_e32 v156, s49, v154
	v_add_u32_e32 v172, s52, v154
	ds_read_b128 v[138:141], v156
	ds_read_b128 v[142:145], v156 offset:1024
	ds_read_b128 v[146:149], v156 offset:2048
	ds_read_b128 v[156:159], v156 offset:3072
	ds_read_b128 v[160:163], v172
	ds_read_b128 v[164:167], v172 offset:1024
	ds_read_b128 v[168:171], v172 offset:2048
	ds_read_b128 v[172:175], v172 offset:3072
	s_add_u32 s46, s46, 0x20000
	s_addc_u32 s47, s47, 0
	s_mov_b32 m0, s10
	v_lshl_add_u64 v[232:233], s[46:47], 0, v[128:129]
	ds_read_b128 v[176:179], v155 offset:32768
	ds_read_b128 v[180:183], v155 offset:33792
	ds_read_b128 v[184:187], v155 offset:34816
	ds_read_b128 v[188:191], v155 offset:35840
	ds_read_b128 v[200:203], v155 offset:36864
	ds_read_b128 v[204:207], v155 offset:37888
	ds_read_b128 v[208:211], v155 offset:38912
	ds_read_b128 v[212:215], v155 offset:39936
	global_load_lds_dwordx4 v[232:233], off
	v_lshl_add_u64 v[232:233], s[46:47], 0, v[130:131]
	s_mov_b32 m0, s11
	s_nop 0
	global_load_lds_dwordx4 v[232:233], off
	s_waitcnt vmcnt(8)
	s_waitcnt lgkmcnt(0)
	s_barrier
	s_setprio 1
	v_mfma_f32_16x16x32_bf16 v[120:123], v[138:141], v[176:179], v[120:123]
	v_mfma_f32_16x16x32_bf16 v[124:127], v[146:149], v[176:179], v[124:127]
	v_mfma_f32_16x16x32_bf16 v[108:111], v[138:141], v[184:187], v[108:111]
	v_mfma_f32_16x16x32_bf16 v[104:107], v[146:149], v[184:187], v[104:107]
	v_mfma_f32_16x16x32_bf16 v[92:95], v[138:141], v[200:203], v[92:95]
	v_mfma_f32_16x16x32_bf16 v[88:91], v[146:149], v[200:203], v[88:91]
	v_mfma_f32_16x16x32_bf16 v[76:79], v[138:141], v[208:211], v[76:79]
	v_mfma_f32_16x16x32_bf16 v[72:75], v[146:149], v[208:211], v[72:75]
	v_mfma_f32_16x16x32_bf16 v[120:123], v[142:145], v[180:183], v[120:123]
	v_mfma_f32_16x16x32_bf16 v[124:127], v[156:159], v[180:183], v[124:127]
	v_mfma_f32_16x16x32_bf16 v[108:111], v[142:145], v[188:191], v[108:111]
	v_mfma_f32_16x16x32_bf16 v[104:107], v[156:159], v[188:191], v[104:107]
	v_mfma_f32_16x16x32_bf16 v[92:95], v[142:145], v[204:207], v[92:95]
	v_mfma_f32_16x16x32_bf16 v[88:91], v[156:159], v[204:207], v[88:91]
	v_mfma_f32_16x16x32_bf16 v[76:79], v[142:145], v[212:215], v[76:79]
	v_mfma_f32_16x16x32_bf16 v[72:75], v[156:159], v[212:215], v[72:75]
	v_mfma_f32_16x16x32_bf16 v[116:119], v[160:163], v[176:179], v[116:119]
	v_mfma_f32_16x16x32_bf16 v[112:115], v[168:171], v[176:179], v[112:115]
	v_mfma_f32_16x16x32_bf16 v[100:103], v[160:163], v[184:187], v[100:103]
	v_mfma_f32_16x16x32_bf16 v[96:99], v[168:171], v[184:187], v[96:99]
	v_mfma_f32_16x16x32_bf16 v[84:87], v[160:163], v[200:203], v[84:87]
	v_mfma_f32_16x16x32_bf16 v[80:83], v[168:171], v[200:203], v[80:83]
	v_mfma_f32_16x16x32_bf16 v[68:71], v[160:163], v[208:211], v[68:71]
	v_mfma_f32_16x16x32_bf16 v[64:67], v[168:171], v[208:211], v[64:67]
	v_mfma_f32_16x16x32_bf16 v[116:119], v[164:167], v[180:183], v[116:119]
	v_mfma_f32_16x16x32_bf16 v[112:115], v[172:175], v[180:183], v[112:115]
	v_mfma_f32_16x16x32_bf16 v[100:103], v[164:167], v[188:191], v[100:103]
	v_mfma_f32_16x16x32_bf16 v[96:99], v[172:175], v[188:191], v[96:99]
	v_mfma_f32_16x16x32_bf16 v[84:87], v[164:167], v[204:207], v[84:87]
	v_mfma_f32_16x16x32_bf16 v[80:83], v[172:175], v[204:207], v[80:83]
	v_mfma_f32_16x16x32_bf16 v[68:71], v[164:167], v[212:215], v[68:71]
	v_mfma_f32_16x16x32_bf16 v[64:67], v[172:175], v[212:215], v[64:67]
	s_setprio 0
	s_barrier
; #define PG8_STAGE(bufoff, gbase, voff) do { _Pragma("unroll") for (int _i = 0; _i < 2; ++_i) \
;         __builtin_amdgcn_global_load_lds((const unsigned*)((const char*)(gbase) + (voff)[_i]), (PG8_LAS unsigned*)(lds + (bufoff) + ldsw + _i * 8192), 16, 0, 0); } while (0)
; #define PG8_LDA(dst, b, h) do { _Pragma("unroll") for (int m = 0; m < 4; ++m) _Pragma("unroll") for (int k = 0; k < 2; ++k) dst[m][k] = *(const PG8_LAS bf16x8*)(lds + PG8_SA(b, h) + aoff + m * 2048 + k * 1024); } while (0)
; #define PG8_MMA(ai, bj, At, Bt) do { __builtin_amdgcn_s_setprio(1); _Pragma("unroll") for (int m = 0; m < 4; ++m) _Pragma("unroll") for (int n = 0; n < 2; ++n) _Pragma("unroll") for (int k = 0; k < 2; ++k) \
;         acc[ai][bj][m][n] = __builtin_amdgcn_mfma_f32_16x16x32_bf16(Bt[n][k], At[m][k], acc[ai][bj][m][n], 0, 0, 0); __builtin_amdgcn_s_setprio(0); } while (0)
; #define PG8_WAIT_V(n) asm volatile("s_waitcnt vmcnt(" #n ")" ::: "memory")
; #define PG8_WAIT_L(n) asm volatile("s_waitcnt lgkmcnt(" #n ")" ::: "memory")
; #define PG8_BAR __builtin_amdgcn_s_barrier()
; #define PG8_SCHED __builtin_amdgcn_sched_barrier(0)
; template <class Epi, class Sched, bool ALIGN_EPI = false, bool SP2 = false>
; __device__ __forceinline__ void gemm_phase(PG8_LAS unsigned char* lds, const Gemm g, const Sched& S, const Epi& E) {
;     ...
;         for (int t = 0; t < nt; t += 2) {
;     ...
;             PG8_LDA(At, 1, 1); PG8_STAGE(PG8_SB(1, 0), b3, voffB); PG8_STAGE(PG8_SB(1, 1), b3 + hstepB, voffB); PG8_STAGE(PG8_SA(1, 0), a3, voffA);
;             PG8_WAIT_V(8); PG8_WAIT_L(0); PG8_BAR; PG8_MMA(1, 0, At, B0); PG8_MMA(1, 1, At, B1); PG8_BAR; PG8_SCHED;
	s_add_i32 s46, s49, s8
	v_lshl_add_u64 v[150:151], v[150:151], 0, s[26:27]
	s_mov_b32 m0, s46
	ds_read_b128 v[176:179], v155 offset:49152
	ds_read_b128 v[180:183], v155 offset:50176
	ds_read_b128 v[184:187], v155 offset:51200
	ds_read_b128 v[188:191], v155 offset:52224
	ds_read_b128 v[200:203], v155 offset:53248
	ds_read_b128 v[204:207], v155 offset:54272
	ds_read_b128 v[208:211], v155 offset:55296
	ds_read_b128 v[212:215], v155 offset:56320
	global_load_lds_dwordx4 v[150:151], off
	s_add_i32 m0, s46, 0x2000
	s_add_u32 s44, s44, 0x10080
	v_lshl_add_u64 v[150:151], v[192:193], 0, s[26:27]
	s_addc_u32 s45, s45, 0
	s_add_i32 s46, s52, s8
	global_load_lds_dwordx4 v[150:151], off
	v_lshl_add_u64 v[150:151], s[44:45], 0, v[194:195]
	s_mov_b32 m0, s46
	s_nop 0
	global_load_lds_dwordx4 v[150:151], off
	v_lshl_add_u64 v[150:151], s[44:45], 0, v[132:133]
	s_add_i32 m0, s46, 0x2000
	s_nop 0
	global_load_lds_dwordx4 v[150:151], off
	v_lshl_add_u64 v[150:151], v[228:229], 0, s[26:27]
	s_mov_b32 m0, s3
	s_nop 0
	global_load_lds_dwordx4 v[150:151], off
	v_lshl_add_u64 v[150:151], v[230:231], 0, s[26:27]
	s_mov_b32 m0, s55
	s_nop 0
	global_load_lds_dwordx4 v[150:151], off
	s_waitcnt vmcnt(8)
	s_waitcnt lgkmcnt(0)
	s_barrier
	s_setprio 1
	v_mfma_f32_16x16x32_bf16 v[60:63], v[138:141], v[176:179], v[60:63]
	v_mfma_f32_16x16x32_bf16 v[56:59], v[146:149], v[176:179], v[56:59]
	v_mfma_f32_16x16x32_bf16 v[44:47], v[138:141], v[184:187], v[44:47]
	v_mfma_f32_16x16x32_bf16 v[40:43], v[146:149], v[184:187], v[40:43]
	v_mfma_f32_16x16x32_bf16 v[28:31], v[138:141], v[200:203], v[28:31]
	v_mfma_f32_16x16x32_bf16 v[24:27], v[146:149], v[200:203], v[24:27]
	v_mfma_f32_16x16x32_bf16 v[12:15], v[138:141], v[208:211], v[12:15]
	v_mfma_f32_16x16x32_bf16 v[8:11], v[146:149], v[208:211], v[8:11]
	v_mfma_f32_16x16x32_bf16 v[60:63], v[142:145], v[180:183], v[60:63]
	v_mfma_f32_16x16x32_bf16 v[56:59], v[156:159], v[180:183], v[56:59]
	v_mfma_f32_16x16x32_bf16 v[44:47], v[142:145], v[188:191], v[44:47]
	v_mfma_f32_16x16x32_bf16 v[40:43], v[156:159], v[188:191], v[40:43]
	v_mfma_f32_16x16x32_bf16 v[28:31], v[142:145], v[204:207], v[28:31]
	v_mfma_f32_16x16x32_bf16 v[24:27], v[156:159], v[204:207], v[24:27]
	v_mfma_f32_16x16x32_bf16 v[12:15], v[142:145], v[212:215], v[12:15]
	v_mfma_f32_16x16x32_bf16 v[8:11], v[156:159], v[212:215], v[8:11]
	v_mfma_f32_16x16x32_bf16 v[52:55], v[160:163], v[176:179], v[52:55]
	v_mfma_f32_16x16x32_bf16 v[48:51], v[168:171], v[176:179], v[48:51]
	v_mfma_f32_16x16x32_bf16 v[36:39], v[160:163], v[184:187], v[36:39]
	v_mfma_f32_16x16x32_bf16 v[32:35], v[168:171], v[184:187], v[32:35]
	v_mfma_f32_16x16x32_bf16 v[20:23], v[160:163], v[200:203], v[20:23]
	v_mfma_f32_16x16x32_bf16 v[16:19], v[168:171], v[200:203], v[16:19]
	v_mfma_f32_16x16x32_bf16 v[4:7], v[160:163], v[208:211], v[4:7]
	v_mfma_f32_16x16x32_bf16 v[0:3], v[168:171], v[208:211], v[0:3]
	v_mfma_f32_16x16x32_bf16 v[52:55], v[164:167], v[180:183], v[52:55]
	v_mfma_f32_16x16x32_bf16 v[48:51], v[172:175], v[180:183], v[48:51]
	v_mfma_f32_16x16x32_bf16 v[36:39], v[164:167], v[188:191], v[36:39]
	v_mfma_f32_16x16x32_bf16 v[32:35], v[172:175], v[188:191], v[32:35]
	v_mfma_f32_16x16x32_bf16 v[20:23], v[164:167], v[204:207], v[20:23]
	v_mfma_f32_16x16x32_bf16 v[16:19], v[172:175], v[204:207], v[16:19]
	v_mfma_f32_16x16x32_bf16 v[4:7], v[164:167], v[212:215], v[4:7]
	v_mfma_f32_16x16x32_bf16 v[0:3], v[172:175], v[212:215], v[0:3]
	s_setprio 0
	s_barrier
	s_add_u32 s42, s42, 0x100
	s_addc_u32 s43, s43, 0
	s_add_u32 s35, s35, 0x100
	s_addc_u32 s41, s41, 0
	s_cmp_ge_i32 s48, s13
	s_mov_b32 s44, s48
	s_cbranch_scc0 .LBB0_502

; #define PG8_STAGE(bufoff, gbase, voff) do { _Pragma("unroll") for (int _i = 0; _i < 2; ++_i) \
;         __builtin_amdgcn_global_load_lds((const unsigned*)((const char*)(gbase) + (voff)[_i]), (PG8_LAS unsigned*)(lds + (bufoff) + ldsw + _i * 8192), 16, 0, 0); } while (0)
; #define PG8_LDA(dst, b, h) do { _Pragma("unroll") for (int m = 0; m < 4; ++m) _Pragma("unroll") for (int k = 0; k < 2; ++k) dst[m][k] = *(const PG8_LAS bf16x8*)(lds + PG8_SA(b, h) + aoff + m * 2048 + k * 1024); } while (0)
; #define PG8_LDB(dst, b, h) do { _Pragma("unroll") for (int n = 0; n < 2; ++n) _Pragma("unroll") for (int k = 0; k < 2; ++k) dst[n][k] = *(const PG8_LAS bf16x8*)(lds + PG8_SB(b, h) + boff + n * 2048 + k * 1024); } while (0)
; #define PG8_MMA(ai, bj, At, Bt) do { __builtin_amdgcn_s_setprio(1); _Pragma("unroll") for (int m = 0; m < 4; ++m) _Pragma("unroll") for (int n = 0; n < 2; ++n) _Pragma("unroll") for (int k = 0; k < 2; ++k) \
;         acc[ai][bj][m][n] = __builtin_amdgcn_mfma_f32_16x16x32_bf16(Bt[n][k], At[m][k], acc[ai][bj][m][n], 0, 0, 0); __builtin_amdgcn_s_setprio(0); } while (0)
; #define PG8_WAIT_V(n) asm volatile("s_waitcnt vmcnt(" #n ")" ::: "memory")
; #define PG8_WAIT_L(n) asm volatile("s_waitcnt lgkmcnt(" #n ")" ::: "memory")
; template <class Epi, class Sched, bool ALIGN_EPI = false, bool SP2 = false>
; __device__ __forceinline__ void gemm_phase(PG8_LAS unsigned char* lds, const Gemm g, const Sched& S, const Epi& E) {
;     ...
;             const bool last = (t == nt - 2);
;             const char* a1 = cA + (size_t)(t + 1) * kstep;
;             const char* a2 = last ? nA : cA + (size_t)(t + 2) * kstep; const char* b2 = last ? nB : cB + (size_t)(t + 2) * kstep;
;             const char* a3 = a2 + kstep; const char* b3 = b2 + kstep;
;             if (last && has_next) S.a_ready(nxt);
;             if constexpr (SP2) {
;             PG8_LDB(B0, 0, 0); PG8_LDB(B1, 0, 1); PG8_SCHED; PG8_LDA(At, 0, 0); PG8_STAGE(PG8_SA(1, 1), a1 + hstepA, voffA);
;             PG8_WAIT_V(8); PG8_WAIT_L(0); PG8_BAR; PG8_MMA(0, 0, At, B0); PG8_MMA(0, 1, At, B1); PG8_BAR; PG8_SCHED;
;             PG8_LDA(At, 0, 1); PG8_STAGE(PG8_SB(0, 0), b2, voffB); PG8_STAGE(PG8_SB(0, 1), b2 + hstepB, voffB); PG8_STAGE(PG8_SA(0, 0), a2, voffA);
;             PG8_WAIT_V(8); PG8_WAIT_L(0); PG8_BAR; PG8_MMA(1, 0, At, B0); PG8_MMA(1, 1, At, B1); PG8_BAR; PG8_SCHED;
.LBB0_569:
	s_add_i32 s58, s55, 2
	s_add_u32 s59, s84, 0xfffe0080
	s_addc_u32 s62, s85, -1
	s_add_i32 s64, 0, 0x10000
	s_cmp_eq_u32 s15, s55
	s_cselect_b32 s87, s28, s62
	s_cselect_b32 s86, s29, s59
	s_cselect_b32 s63, s33, s53
	s_cselect_b32 s62, s47, s49
	s_add_i32 s55, 0, 0x14000
	v_add_u32_e32 v154, s64, v148
	v_add_u32_e32 v170, s55, v148
	ds_read_b128 v[138:141], v154
	ds_read_b128 v[142:145], v154 offset:1024
	ds_read_b128 v[150:153], v154 offset:2048
	ds_read_b128 v[154:157], v154 offset:3072
	ds_read_b128 v[158:161], v170
	ds_read_b128 v[162:165], v170 offset:1024
	ds_read_b128 v[166:169], v170 offset:2048
	ds_read_b128 v[170:173], v170 offset:3072
	v_lshl_add_u64 v[212:213], s[84:85], 0, v[134:135]
	s_add_i32 m0, s3, 0xc000
	ds_read_b128 v[174:177], v149
	ds_read_b128 v[178:181], v149 offset:1024
	ds_read_b128 v[182:185], v149 offset:2048
	ds_read_b128 v[186:189], v149 offset:3072
	ds_read_b128 v[190:193], v149 offset:4096
	ds_read_b128 v[200:203], v149 offset:5120
	ds_read_b128 v[204:207], v149 offset:6144
	ds_read_b128 v[208:211], v149 offset:7168
	global_load_lds_dwordx4 v[212:213], off
	v_lshl_add_u64 v[212:213], s[84:85], 0, v[136:137]
	s_add_i32 m0, s3, 0xe000
	s_nop 0
	global_load_lds_dwordx4 v[212:213], off
	s_waitcnt vmcnt(8)
	s_waitcnt lgkmcnt(0)
	s_barrier
	s_setprio 1
	v_mfma_f32_16x16x32_bf16 v[124:127], v[138:141], v[174:177], v[124:127]
	v_mfma_f32_16x16x32_bf16 v[120:123], v[150:153], v[174:177], v[120:123]
	v_mfma_f32_16x16x32_bf16 v[108:111], v[138:141], v[182:185], v[108:111]
	v_mfma_f32_16x16x32_bf16 v[104:107], v[150:153], v[182:185], v[104:107]
	v_mfma_f32_16x16x32_bf16 v[92:95], v[138:141], v[190:193], v[92:95]
	v_mfma_f32_16x16x32_bf16 v[88:91], v[150:153], v[190:193], v[88:91]
	v_mfma_f32_16x16x32_bf16 v[76:79], v[138:141], v[204:207], v[76:79]
	v_mfma_f32_16x16x32_bf16 v[72:75], v[150:153], v[204:207], v[72:75]
	v_mfma_f32_16x16x32_bf16 v[124:127], v[142:145], v[178:181], v[124:127]
	v_mfma_f32_16x16x32_bf16 v[120:123], v[154:157], v[178:181], v[120:123]
	v_mfma_f32_16x16x32_bf16 v[108:111], v[142:145], v[186:189], v[108:111]
	v_mfma_f32_16x16x32_bf16 v[104:107], v[154:157], v[186:189], v[104:107]
	v_mfma_f32_16x16x32_bf16 v[92:95], v[142:145], v[200:203], v[92:95]
	v_mfma_f32_16x16x32_bf16 v[88:91], v[154:157], v[200:203], v[88:91]
	v_mfma_f32_16x16x32_bf16 v[76:79], v[142:145], v[208:211], v[76:79]
	v_mfma_f32_16x16x32_bf16 v[72:75], v[154:157], v[208:211], v[72:75]
	v_mfma_f32_16x16x32_bf16 v[116:119], v[158:161], v[174:177], v[116:119]
	v_mfma_f32_16x16x32_bf16 v[112:115], v[166:169], v[174:177], v[112:115]
	v_mfma_f32_16x16x32_bf16 v[100:103], v[158:161], v[182:185], v[100:103]
	v_mfma_f32_16x16x32_bf16 v[96:99], v[166:169], v[182:185], v[96:99]
	v_mfma_f32_16x16x32_bf16 v[84:87], v[158:161], v[190:193], v[84:87]
	v_mfma_f32_16x16x32_bf16 v[80:83], v[166:169], v[190:193], v[80:83]
	v_mfma_f32_16x16x32_bf16 v[68:71], v[158:161], v[204:207], v[68:71]
	v_mfma_f32_16x16x32_bf16 v[64:67], v[166:169], v[204:207], v[64:67]
	v_mfma_f32_16x16x32_bf16 v[116:119], v[162:165], v[178:181], v[116:119]
	v_mfma_f32_16x16x32_bf16 v[112:115], v[170:173], v[178:181], v[112:115]
	v_mfma_f32_16x16x32_bf16 v[100:103], v[162:165], v[186:189], v[100:103]
	v_mfma_f32_16x16x32_bf16 v[96:99], v[170:173], v[186:189], v[96:99]
	v_mfma_f32_16x16x32_bf16 v[84:87], v[162:165], v[200:203], v[84:87]
	v_mfma_f32_16x16x32_bf16 v[80:83], v[170:173], v[200:203], v[80:83]
	v_mfma_f32_16x16x32_bf16 v[68:71], v[162:165], v[208:211], v[68:71]
	v_mfma_f32_16x16x32_bf16 v[64:67], v[170:173], v[208:211], v[64:67]
	s_setprio 0
	s_barrier
	s_add_i32 s59, s64, s2
	v_lshl_add_u64 v[212:213], s[62:63], 0, v[194:195]
	s_mov_b32 m0, s59
	ds_read_b128 v[174:177], v149 offset:16384
	ds_read_b128 v[178:181], v149 offset:17408
	ds_read_b128 v[182:185], v149 offset:18432
	ds_read_b128 v[186:189], v149 offset:19456
	ds_read_b128 v[190:193], v149 offset:20480
	ds_read_b128 v[200:203], v149 offset:21504
	ds_read_b128 v[204:207], v149 offset:22528
	ds_read_b128 v[208:211], v149 offset:23552
	global_load_lds_dwordx4 v[212:213], off
	s_add_i32 m0, s59, 0x2000
	s_add_u32 s78, s62, 0x8000
	v_lshl_add_u64 v[214:215], s[62:63], 0, v[132:133]
	s_addc_u32 s79, s63, 0
	s_add_i32 s55, s55, s2
	global_load_lds_dwordx4 v[214:215], off
	v_lshl_add_u64 v[228:229], s[78:79], 0, v[194:195]
	s_mov_b32 m0, s55
	v_lshl_add_u64 v[230:231], s[86:87], 0, v[130:131]
	global_load_lds_dwordx4 v[228:229], off
	v_lshl_add_u64 v[228:229], s[78:79], 0, v[132:133]
	s_add_i32 m0, s55, 0x2000
	s_nop 0
	global_load_lds_dwordx4 v[228:229], off
	v_lshl_add_u64 v[228:229], s[86:87], 0, v[128:129]
	s_mov_b32 m0, s3
	s_nop 0
	global_load_lds_dwordx4 v[228:229], off
	s_mov_b32 m0, s8
	s_nop 0
	global_load_lds_dwordx4 v[230:231], off
	s_waitcnt vmcnt(8)
	s_waitcnt lgkmcnt(0)
	s_barrier
; #define PG8_STAGE(bufoff, gbase, voff) do { _Pragma("unroll") for (int _i = 0; _i < 2; ++_i) \
;         __builtin_amdgcn_global_load_lds((const unsigned*)((const char*)(gbase) + (voff)[_i]), (PG8_LAS unsigned*)(lds + (bufoff) + ldsw + _i * 8192), 16, 0, 0); } while (0)
; #define PG8_LDA(dst, b, h) do { _Pragma("unroll") for (int m = 0; m < 4; ++m) _Pragma("unroll") for (int k = 0; k < 2; ++k) dst[m][k] = *(const PG8_LAS bf16x8*)(lds + PG8_SA(b, h) + aoff + m * 2048 + k * 1024); } while (0)
; #define PG8_LDB(dst, b, h) do { _Pragma("unroll") for (int n = 0; n < 2; ++n) _Pragma("unroll") for (int k = 0; k < 2; ++k) dst[n][k] = *(const PG8_LAS bf16x8*)(lds + PG8_SB(b, h) + boff + n * 2048 + k * 1024); } while (0)
; #define PG8_MMA(ai, bj, At, Bt) do { __builtin_amdgcn_s_setprio(1); _Pragma("unroll") for (int m = 0; m < 4; ++m) _Pragma("unroll") for (int n = 0; n < 2; ++n) _Pragma("unroll") for (int k = 0; k < 2; ++k) \
;         acc[ai][bj][m][n] = __builtin_amdgcn_mfma_f32_16x16x32_bf16(Bt[n][k], At[m][k], acc[ai][bj][m][n], 0, 0, 0); __builtin_amdgcn_s_setprio(0); } while (0)
; #define PG8_WAIT_V(n) asm volatile("s_waitcnt vmcnt(" #n ")" ::: "memory")
; #define PG8_WAIT_L(n) asm volatile("s_waitcnt lgkmcnt(" #n ")" ::: "memory")
; #define PG8_BAR __builtin_amdgcn_s_barrier()
; #define PG8_SCHED __builtin_amdgcn_sched_barrier(0)
; template <class Epi, class Sched, bool ALIGN_EPI = false, bool SP2 = false>
; __device__ __forceinline__ void gemm_phase(PG8_LAS unsigned char* lds, const Gemm g, const Sched& S, const Epi& E) {
;     ...
;             PG8_WAIT_V(8); PG8_WAIT_L(0); PG8_BAR; PG8_MMA(1, 0, At, B0); PG8_MMA(1, 1, At, B1); PG8_BAR; PG8_SCHED;
;             PG8_LDB(B0, 1, 0); PG8_LDB(B1, 1, 1); PG8_SCHED; PG8_LDA(At, 1, 0); PG8_STAGE(PG8_SA(0, 1), a2 + hstepA, voffA);
;             PG8_WAIT_V(8); PG8_WAIT_L(0); PG8_BAR; PG8_MMA(0, 0, At, B0); PG8_MMA(0, 1, At, B1); PG8_BAR; PG8_SCHED;
	s_setprio 1
	v_mfma_f32_16x16x32_bf16 v[60:63], v[138:141], v[174:177], v[60:63]
	v_mfma_f32_16x16x32_bf16 v[56:59], v[150:153], v[174:177], v[56:59]
	v_mfma_f32_16x16x32_bf16 v[44:47], v[138:141], v[182:185], v[44:47]
	v_mfma_f32_16x16x32_bf16 v[40:43], v[150:153], v[182:185], v[40:43]
	v_mfma_f32_16x16x32_bf16 v[28:31], v[138:141], v[190:193], v[28:31]
	v_mfma_f32_16x16x32_bf16 v[24:27], v[150:153], v[190:193], v[24:27]
	v_mfma_f32_16x16x32_bf16 v[12:15], v[138:141], v[204:207], v[12:15]
	v_mfma_f32_16x16x32_bf16 v[8:11], v[150:153], v[204:207], v[8:11]
	v_mfma_f32_16x16x32_bf16 v[60:63], v[142:145], v[178:181], v[60:63]
	v_mfma_f32_16x16x32_bf16 v[56:59], v[154:157], v[178:181], v[56:59]
	v_mfma_f32_16x16x32_bf16 v[44:47], v[142:145], v[186:189], v[44:47]
	v_mfma_f32_16x16x32_bf16 v[40:43], v[154:157], v[186:189], v[40:43]
	v_mfma_f32_16x16x32_bf16 v[28:31], v[142:145], v[200:203], v[28:31]
	v_mfma_f32_16x16x32_bf16 v[24:27], v[154:157], v[200:203], v[24:27]
	v_mfma_f32_16x16x32_bf16 v[12:15], v[142:145], v[208:211], v[12:15]
	v_mfma_f32_16x16x32_bf16 v[8:11], v[154:157], v[208:211], v[8:11]
	v_mfma_f32_16x16x32_bf16 v[52:55], v[158:161], v[174:177], v[52:55]
	v_mfma_f32_16x16x32_bf16 v[48:51], v[166:169], v[174:177], v[48:51]
	v_mfma_f32_16x16x32_bf16 v[36:39], v[158:161], v[182:185], v[36:39]
	v_mfma_f32_16x16x32_bf16 v[32:35], v[166:169], v[182:185], v[32:35]
	v_mfma_f32_16x16x32_bf16 v[20:23], v[158:161], v[190:193], v[20:23]
	v_mfma_f32_16x16x32_bf16 v[16:19], v[166:169], v[190:193], v[16:19]
	v_mfma_f32_16x16x32_bf16 v[4:7], v[158:161], v[204:207], v[4:7]
	v_mfma_f32_16x16x32_bf16 v[0:3], v[166:169], v[204:207], v[0:3]
	v_mfma_f32_16x16x32_bf16 v[52:55], v[162:165], v[178:181], v[52:55]
	v_mfma_f32_16x16x32_bf16 v[48:51], v[170:173], v[178:181], v[48:51]
	v_mfma_f32_16x16x32_bf16 v[36:39], v[162:165], v[186:189], v[36:39]
	v_mfma_f32_16x16x32_bf16 v[32:35], v[170:173], v[186:189], v[32:35]
	v_mfma_f32_16x16x32_bf16 v[20:23], v[162:165], v[200:203], v[20:23]
	v_mfma_f32_16x16x32_bf16 v[16:19], v[170:173], v[200:203], v[16:19]
	v_mfma_f32_16x16x32_bf16 v[4:7], v[162:165], v[208:211], v[4:7]
	v_mfma_f32_16x16x32_bf16 v[0:3], v[170:173], v[208:211], v[0:3]
	s_setprio 0
	s_barrier
	s_add_i32 s55, 0, 0x18000
	s_add_i32 s59, 0, 0x1c000
	v_add_u32_e32 v154, s55, v148
	v_add_u32_e32 v170, s59, v148
	ds_read_b128 v[138:141], v154
	ds_read_b128 v[142:145], v154 offset:1024
	ds_read_b128 v[150:153], v154 offset:2048
	ds_read_b128 v[154:157], v154 offset:3072
	ds_read_b128 v[158:161], v170
	ds_read_b128 v[162:165], v170 offset:1024
	ds_read_b128 v[166:169], v170 offset:2048
	ds_read_b128 v[170:173], v170 offset:3072
	s_add_u32 s78, s86, 0x20000
	s_addc_u32 s79, s87, 0
	s_mov_b32 m0, s9
	v_lshl_add_u64 v[232:233], s[78:79], 0, v[128:129]
	ds_read_b128 v[174:177], v149 offset:32768
	ds_read_b128 v[178:181], v149 offset:33792
	ds_read_b128 v[182:185], v149 offset:34816
	ds_read_b128 v[186:189], v149 offset:35840
	ds_read_b128 v[190:193], v149 offset:36864
	ds_read_b128 v[200:203], v149 offset:37888
	ds_read_b128 v[204:207], v149 offset:38912
	ds_read_b128 v[208:211], v149 offset:39936
	global_load_lds_dwordx4 v[232:233], off
	v_lshl_add_u64 v[232:233], s[78:79], 0, v[130:131]
	s_mov_b32 m0, s10
	s_nop 0
	global_load_lds_dwordx4 v[232:233], off
	s_waitcnt vmcnt(8)
	s_waitcnt lgkmcnt(0)
	s_barrier
	s_setprio 1
	v_mfma_f32_16x16x32_bf16 v[124:127], v[138:141], v[174:177], v[124:127]
	v_mfma_f32_16x16x32_bf16 v[120:123], v[150:153], v[174:177], v[120:123]
	v_mfma_f32_16x16x32_bf16 v[108:111], v[138:141], v[182:185], v[108:111]
	v_mfma_f32_16x16x32_bf16 v[104:107], v[150:153], v[182:185], v[104:107]
	v_mfma_f32_16x16x32_bf16 v[92:95], v[138:141], v[190:193], v[92:95]
	v_mfma_f32_16x16x32_bf16 v[88:91], v[150:153], v[190:193], v[88:91]
	v_mfma_f32_16x16x32_bf16 v[76:79], v[138:141], v[204:207], v[76:79]
	v_mfma_f32_16x16x32_bf16 v[72:75], v[150:153], v[204:207], v[72:75]
	v_mfma_f32_16x16x32_bf16 v[124:127], v[142:145], v[178:181], v[124:127]
	v_mfma_f32_16x16x32_bf16 v[120:123], v[154:157], v[178:181], v[120:123]
	v_mfma_f32_16x16x32_bf16 v[108:111], v[142:145], v[186:189], v[108:111]
	v_mfma_f32_16x16x32_bf16 v[104:107], v[154:157], v[186:189], v[104:107]
	v_mfma_f32_16x16x32_bf16 v[92:95], v[142:145], v[200:203], v[92:95]
	v_mfma_f32_16x16x32_bf16 v[88:91], v[154:157], v[200:203], v[88:91]
	v_mfma_f32_16x16x32_bf16 v[76:79], v[142:145], v[208:211], v[76:79]
	v_mfma_f32_16x16x32_bf16 v[72:75], v[154:157], v[208:211], v[72:75]
	v_mfma_f32_16x16x32_bf16 v[116:119], v[158:161], v[174:177], v[116:119]
	v_mfma_f32_16x16x32_bf16 v[112:115], v[166:169], v[174:177], v[112:115]
	v_mfma_f32_16x16x32_bf16 v[100:103], v[158:161], v[182:185], v[100:103]
	v_mfma_f32_16x16x32_bf16 v[96:99], v[166:169], v[182:185], v[96:99]
	v_mfma_f32_16x16x32_bf16 v[84:87], v[158:161], v[190:193], v[84:87]
	v_mfma_f32_16x16x32_bf16 v[80:83], v[166:169], v[190:193], v[80:83]
	v_mfma_f32_16x16x32_bf16 v[68:71], v[158:161], v[204:207], v[68:71]
	v_mfma_f32_16x16x32_bf16 v[64:67], v[166:169], v[204:207], v[64:67]
	v_mfma_f32_16x16x32_bf16 v[116:119], v[162:165], v[178:181], v[116:119]
	v_mfma_f32_16x16x32_bf16 v[112:115], v[170:173], v[178:181], v[112:115]
	v_mfma_f32_16x16x32_bf16 v[100:103], v[162:165], v[186:189], v[100:103]
	v_mfma_f32_16x16x32_bf16 v[96:99], v[170:173], v[186:189], v[96:99]
	v_mfma_f32_16x16x32_bf16 v[84:87], v[162:165], v[200:203], v[84:87]
	v_mfma_f32_16x16x32_bf16 v[80:83], v[170:173], v[200:203], v[80:83]
	v_mfma_f32_16x16x32_bf16 v[68:71], v[162:165], v[208:211], v[68:71]
	v_mfma_f32_16x16x32_bf16 v[64:67], v[170:173], v[208:211], v[64:67]
	s_setprio 0
	s_barrier
; #define PG8_STAGE(bufoff, gbase, voff) do { _Pragma("unroll") for (int _i = 0; _i < 2; ++_i) \
;         __builtin_amdgcn_global_load_lds((const unsigned*)((const char*)(gbase) + (voff)[_i]), (PG8_LAS unsigned*)(lds + (bufoff) + ldsw + _i * 8192), 16, 0, 0); } while (0)
; #define PG8_LDA(dst, b, h) do { _Pragma("unroll") for (int m = 0; m < 4; ++m) _Pragma("unroll") for (int k = 0; k < 2; ++k) dst[m][k] = *(const PG8_LAS bf16x8*)(lds + PG8_SA(b, h) + aoff + m * 2048 + k * 1024); } while (0)
; #define PG8_MMA(ai, bj, At, Bt) do { __builtin_amdgcn_s_setprio(1); _Pragma("unroll") for (int m = 0; m < 4; ++m) _Pragma("unroll") for (int n = 0; n < 2; ++n) _Pragma("unroll") for (int k = 0; k < 2; ++k) \
;         acc[ai][bj][m][n] = __builtin_amdgcn_mfma_f32_16x16x32_bf16(Bt[n][k], At[m][k], acc[ai][bj][m][n], 0, 0, 0); __builtin_amdgcn_s_setprio(0); } while (0)
; #define PG8_WAIT_V(n) asm volatile("s_waitcnt vmcnt(" #n ")" ::: "memory")
; #define PG8_WAIT_L(n) asm volatile("s_waitcnt lgkmcnt(" #n ")" ::: "memory")
; #define PG8_BAR __builtin_amdgcn_s_barrier()
; #define PG8_SCHED __builtin_amdgcn_sched_barrier(0)
; template <class Epi, class Sched, bool ALIGN_EPI = false, bool SP2 = false>
; __device__ __forceinline__ void gemm_phase(PG8_LAS unsigned char* lds, const Gemm g, const Sched& S, const Epi& E) {
;     ...
;         for (int t = 0; t < nt; t += 2) {
;     ...
;             PG8_LDA(At, 1, 1); PG8_STAGE(PG8_SB(1, 0), b3, voffB); PG8_STAGE(PG8_SB(1, 1), b3 + hstepB, voffB); PG8_STAGE(PG8_SA(1, 0), a3, voffA);
;             PG8_WAIT_V(8); PG8_WAIT_L(0); PG8_BAR; PG8_MMA(1, 0, At, B0); PG8_MMA(1, 1, At, B1); PG8_BAR; PG8_SCHED;
	s_add_i32 s55, s55, s2
	v_lshl_add_u64 v[212:213], v[212:213], 0, s[26:27]
	s_mov_b32 m0, s55
	ds_read_b128 v[174:177], v149 offset:49152
	ds_read_b128 v[178:181], v149 offset:50176
	ds_read_b128 v[182:185], v149 offset:51200
	ds_read_b128 v[186:189], v149 offset:52224
	ds_read_b128 v[190:193], v149 offset:53248
	ds_read_b128 v[200:203], v149 offset:54272
	ds_read_b128 v[204:207], v149 offset:55296
	ds_read_b128 v[208:211], v149 offset:56320
	global_load_lds_dwordx4 v[212:213], off
	s_add_i32 m0, s55, 0x2000
	s_add_u32 s62, s62, 0x8080
	v_lshl_add_u64 v[212:213], v[214:215], 0, s[26:27]
	s_addc_u32 s63, s63, 0
	s_add_i32 s55, s59, s2
	global_load_lds_dwordx4 v[212:213], off
	v_lshl_add_u64 v[212:213], s[62:63], 0, v[194:195]
	s_mov_b32 m0, s55
	s_nop 0
	global_load_lds_dwordx4 v[212:213], off
	v_lshl_add_u64 v[212:213], s[62:63], 0, v[132:133]
	s_add_i32 m0, s55, 0x2000
	s_nop 0
	global_load_lds_dwordx4 v[212:213], off
	v_lshl_add_u64 v[212:213], v[228:229], 0, s[26:27]
	s_mov_b32 m0, s13
	s_nop 0
	global_load_lds_dwordx4 v[212:213], off
	v_lshl_add_u64 v[212:213], v[230:231], 0, s[26:27]
	s_mov_b32 m0, s14
	s_nop 0
	global_load_lds_dwordx4 v[212:213], off
	s_waitcnt vmcnt(8)
	s_waitcnt lgkmcnt(0)
	s_barrier
	s_setprio 1
	v_mfma_f32_16x16x32_bf16 v[60:63], v[138:141], v[174:177], v[60:63]
	v_mfma_f32_16x16x32_bf16 v[56:59], v[150:153], v[174:177], v[56:59]
	v_mfma_f32_16x16x32_bf16 v[44:47], v[138:141], v[182:185], v[44:47]
	v_mfma_f32_16x16x32_bf16 v[40:43], v[150:153], v[182:185], v[40:43]
	v_mfma_f32_16x16x32_bf16 v[28:31], v[138:141], v[190:193], v[28:31]
	v_mfma_f32_16x16x32_bf16 v[24:27], v[150:153], v[190:193], v[24:27]
	v_mfma_f32_16x16x32_bf16 v[12:15], v[138:141], v[204:207], v[12:15]
	v_mfma_f32_16x16x32_bf16 v[8:11], v[150:153], v[204:207], v[8:11]
	v_mfma_f32_16x16x32_bf16 v[60:63], v[142:145], v[178:181], v[60:63]
	v_mfma_f32_16x16x32_bf16 v[56:59], v[154:157], v[178:181], v[56:59]
	v_mfma_f32_16x16x32_bf16 v[44:47], v[142:145], v[186:189], v[44:47]
	v_mfma_f32_16x16x32_bf16 v[40:43], v[154:157], v[186:189], v[40:43]
	v_mfma_f32_16x16x32_bf16 v[28:31], v[142:145], v[200:203], v[28:31]
	v_mfma_f32_16x16x32_bf16 v[24:27], v[154:157], v[200:203], v[24:27]
	v_mfma_f32_16x16x32_bf16 v[12:15], v[142:145], v[208:211], v[12:15]
	v_mfma_f32_16x16x32_bf16 v[8:11], v[154:157], v[208:211], v[8:11]
	v_mfma_f32_16x16x32_bf16 v[52:55], v[158:161], v[174:177], v[52:55]
	v_mfma_f32_16x16x32_bf16 v[48:51], v[166:169], v[174:177], v[48:51]
	v_mfma_f32_16x16x32_bf16 v[36:39], v[158:161], v[182:185], v[36:39]
	v_mfma_f32_16x16x32_bf16 v[32:35], v[166:169], v[182:185], v[32:35]
	v_mfma_f32_16x16x32_bf16 v[20:23], v[158:161], v[190:193], v[20:23]
	v_mfma_f32_16x16x32_bf16 v[16:19], v[166:169], v[190:193], v[16:19]
	v_mfma_f32_16x16x32_bf16 v[4:7], v[158:161], v[204:207], v[4:7]
	v_mfma_f32_16x16x32_bf16 v[0:3], v[166:169], v[204:207], v[0:3]
	v_mfma_f32_16x16x32_bf16 v[52:55], v[162:165], v[178:181], v[52:55]
	v_mfma_f32_16x16x32_bf16 v[48:51], v[170:173], v[178:181], v[48:51]
	v_mfma_f32_16x16x32_bf16 v[36:39], v[162:165], v[186:189], v[36:39]
	v_mfma_f32_16x16x32_bf16 v[32:35], v[170:173], v[186:189], v[32:35]
	v_mfma_f32_16x16x32_bf16 v[20:23], v[162:165], v[200:203], v[20:23]
	v_mfma_f32_16x16x32_bf16 v[16:19], v[170:173], v[200:203], v[16:19]
	v_mfma_f32_16x16x32_bf16 v[4:7], v[162:165], v[208:211], v[4:7]
	v_mfma_f32_16x16x32_bf16 v[0:3], v[170:173], v[208:211], v[0:3]
	s_setprio 0
	s_barrier
	s_add_u32 s84, s84, 0x100
	s_addc_u32 s85, s85, 0
	s_add_u32 s49, s49, 0x100
	s_addc_u32 s53, s53, 0
	s_cmp_ge_i32 s58, s11
	s_mov_b32 s55, s58
	s_cbranch_scc0 .LBB0_569

; #define PG8_STAGE(bufoff, gbase, voff) do { _Pragma("unroll") for (int _i = 0; _i < 2; ++_i) \
;         __builtin_amdgcn_global_load_lds((const unsigned*)((const char*)(gbase) + (voff)[_i]), (PG8_LAS unsigned*)(lds + (bufoff) + ldsw + _i * 8192), 16, 0, 0); } while (0)
; #define PG8_LDA(dst, b, h) do { _Pragma("unroll") for (int m = 0; m < 4; ++m) _Pragma("unroll") for (int k = 0; k < 2; ++k) dst[m][k] = *(const PG8_LAS bf16x8*)(lds + PG8_SA(b, h) + aoff + m * 2048 + k * 1024); } while (0)
; #define PG8_LDB(dst, b, h) do { _Pragma("unroll") for (int n = 0; n < 2; ++n) _Pragma("unroll") for (int k = 0; k < 2; ++k) dst[n][k] = *(const PG8_LAS bf16x8*)(lds + PG8_SB(b, h) + boff + n * 2048 + k * 1024); } while (0)
; #define PG8_MMA(ai, bj, At, Bt) do { __builtin_amdgcn_s_setprio(1); _Pragma("unroll") for (int m = 0; m < 4; ++m) _Pragma("unroll") for (int n = 0; n < 2; ++n) _Pragma("unroll") for (int k = 0; k < 2; ++k) \
;         acc[ai][bj][m][n] = __builtin_amdgcn_mfma_f32_16x16x32_bf16(Bt[n][k], At[m][k], acc[ai][bj][m][n], 0, 0, 0); __builtin_amdgcn_s_setprio(0); } while (0)
; #define PG8_WAIT_V(n) asm volatile("s_waitcnt vmcnt(" #n ")" ::: "memory")
; #define PG8_WAIT_L(n) asm volatile("s_waitcnt lgkmcnt(" #n ")" ::: "memory")
; template <class Epi, class Sched, bool ALIGN_EPI = false, bool SP2 = false>
; __device__ __forceinline__ void gemm_phase(PG8_LAS unsigned char* lds, const Gemm g, const Sched& S, const Epi& E) {
;     ...
;             const bool last = (t == nt - 2);
;             const char* a1 = cA + (size_t)(t + 1) * kstep;
;             const char* a2 = last ? nA : cA + (size_t)(t + 2) * kstep; const char* b2 = last ? nB : cB + (size_t)(t + 2) * kstep;
;             const char* a3 = a2 + kstep; const char* b3 = b2 + kstep;
;             if (last && has_next) S.a_ready(nxt);
;             if constexpr (SP2) {
;             PG8_LDB(B0, 0, 0); PG8_LDB(B1, 0, 1); PG8_SCHED; PG8_LDA(At, 0, 0); PG8_STAGE(PG8_SA(1, 1), a1 + hstepA, voffA);
;             PG8_WAIT_V(8); PG8_WAIT_L(0); PG8_BAR; PG8_MMA(0, 0, At, B0); PG8_MMA(0, 1, At, B1); PG8_BAR; PG8_SCHED;
;             PG8_LDA(At, 0, 1); PG8_STAGE(PG8_SB(0, 0), b2, voffB); PG8_STAGE(PG8_SB(0, 1), b2 + hstepB, voffB); PG8_STAGE(PG8_SA(0, 0), a2, voffA);
;             PG8_WAIT_V(8); PG8_WAIT_L(0); PG8_BAR; PG8_MMA(1, 0, At, B0); PG8_MMA(1, 1, At, B1); PG8_BAR; PG8_SCHED;
.LBB0_618:
	s_add_i32 s79, s62, 2
	s_add_u32 s63, s42, 0xffff8080
	s_addc_u32 s74, s43, -1
	s_add_i32 s75, 0, 0x10000
	s_cmp_eq_u32 s55, s62
	s_cselect_b32 s85, s41, s74
	s_cselect_b32 s84, s53, s63
	s_cselect_b32 s63, s59, s78
	s_cselect_b32 s62, s64, s69
	s_add_i32 s74, 0, 0x14000
	v_add_u32_e32 v156, s75, v154
	v_add_u32_e32 v172, s74, v154
	ds_read_b128 v[128:131], v156
	ds_read_b128 v[144:147], v156 offset:1024
	ds_read_b128 v[148:151], v156 offset:2048
	ds_read_b128 v[156:159], v156 offset:3072
	ds_read_b128 v[160:163], v172
	ds_read_b128 v[164:167], v172 offset:1024
	ds_read_b128 v[168:171], v172 offset:2048
	ds_read_b128 v[172:175], v172 offset:3072
	v_lshl_add_u64 v[192:193], s[42:43], 0, v[140:141]
	s_add_i32 m0, s12, 0xc000
	ds_read_b128 v[176:179], v155
	ds_read_b128 v[180:183], v155 offset:1024
	ds_read_b128 v[184:187], v155 offset:2048
	ds_read_b128 v[188:191], v155 offset:3072
	ds_read_b128 v[200:203], v155 offset:4096
	ds_read_b128 v[204:207], v155 offset:5120
	ds_read_b128 v[208:211], v155 offset:6144
	ds_read_b128 v[212:215], v155 offset:7168
	global_load_lds_dwordx4 v[192:193], off
	v_lshl_add_u64 v[192:193], s[42:43], 0, v[142:143]
	s_add_i32 m0, s12, 0xe000
	s_nop 0
	global_load_lds_dwordx4 v[192:193], off
	s_waitcnt vmcnt(8)
	s_waitcnt lgkmcnt(0)
	s_barrier
	s_setprio 1
	v_mfma_f32_16x16x32_bf16 v[124:127], v[128:131], v[176:179], v[124:127]
	v_mfma_f32_16x16x32_bf16 v[120:123], v[148:151], v[176:179], v[120:123]
	v_mfma_f32_16x16x32_bf16 v[116:119], v[128:131], v[184:187], v[116:119]
	v_mfma_f32_16x16x32_bf16 v[112:115], v[148:151], v[184:187], v[112:115]
	v_mfma_f32_16x16x32_bf16 v[108:111], v[128:131], v[200:203], v[108:111]
	v_mfma_f32_16x16x32_bf16 v[104:107], v[148:151], v[200:203], v[104:107]
	v_mfma_f32_16x16x32_bf16 v[100:103], v[128:131], v[208:211], v[100:103]
	v_mfma_f32_16x16x32_bf16 v[96:99], v[148:151], v[208:211], v[96:99]
	v_mfma_f32_16x16x32_bf16 v[124:127], v[144:147], v[180:183], v[124:127]
	v_mfma_f32_16x16x32_bf16 v[120:123], v[156:159], v[180:183], v[120:123]
	v_mfma_f32_16x16x32_bf16 v[116:119], v[144:147], v[188:191], v[116:119]
	v_mfma_f32_16x16x32_bf16 v[112:115], v[156:159], v[188:191], v[112:115]
	v_mfma_f32_16x16x32_bf16 v[108:111], v[144:147], v[204:207], v[108:111]
	v_mfma_f32_16x16x32_bf16 v[104:107], v[156:159], v[204:207], v[104:107]
	v_mfma_f32_16x16x32_bf16 v[100:103], v[144:147], v[212:215], v[100:103]
	v_mfma_f32_16x16x32_bf16 v[96:99], v[156:159], v[212:215], v[96:99]
	v_mfma_f32_16x16x32_bf16 v[60:63], v[160:163], v[176:179], v[60:63]
	v_mfma_f32_16x16x32_bf16 v[56:59], v[168:171], v[176:179], v[56:59]
	v_mfma_f32_16x16x32_bf16 v[52:55], v[160:163], v[184:187], v[52:55]
	v_mfma_f32_16x16x32_bf16 v[48:51], v[168:171], v[184:187], v[48:51]
	v_mfma_f32_16x16x32_bf16 v[44:47], v[160:163], v[200:203], v[44:47]
	v_mfma_f32_16x16x32_bf16 v[40:43], v[168:171], v[200:203], v[40:43]
	v_mfma_f32_16x16x32_bf16 v[36:39], v[160:163], v[208:211], v[36:39]
	v_mfma_f32_16x16x32_bf16 v[32:35], v[168:171], v[208:211], v[32:35]
	v_mfma_f32_16x16x32_bf16 v[60:63], v[164:167], v[180:183], v[60:63]
	v_mfma_f32_16x16x32_bf16 v[56:59], v[172:175], v[180:183], v[56:59]
	v_mfma_f32_16x16x32_bf16 v[52:55], v[164:167], v[188:191], v[52:55]
	v_mfma_f32_16x16x32_bf16 v[48:51], v[172:175], v[188:191], v[48:51]
	v_mfma_f32_16x16x32_bf16 v[44:47], v[164:167], v[204:207], v[44:47]
	v_mfma_f32_16x16x32_bf16 v[40:43], v[172:175], v[204:207], v[40:43]
	v_mfma_f32_16x16x32_bf16 v[36:39], v[164:167], v[212:215], v[36:39]
	v_mfma_f32_16x16x32_bf16 v[32:35], v[172:175], v[212:215], v[32:35]
	s_setprio 0
	s_barrier
	s_add_i32 s75, s75, s2
	v_lshl_add_u64 v[192:193], s[62:63], 0, v[136:137]
	s_mov_b32 m0, s75
	ds_read_b128 v[176:179], v155 offset:16384
	ds_read_b128 v[180:183], v155 offset:17408
	ds_read_b128 v[184:187], v155 offset:18432
	ds_read_b128 v[188:191], v155 offset:19456
	ds_read_b128 v[200:203], v155 offset:20480
	ds_read_b128 v[204:207], v155 offset:21504
	ds_read_b128 v[208:211], v155 offset:22528
	ds_read_b128 v[212:215], v155 offset:23552
	global_load_lds_dwordx4 v[192:193], off
	s_add_i32 m0, s75, 0x2000
	s_add_u32 s86, s62, 0x20000
	v_lshl_add_u64 v[228:229], s[62:63], 0, v[132:133]
	s_addc_u32 s87, s63, 0
	s_add_i32 s74, s74, s2
	global_load_lds_dwordx4 v[228:229], off
	v_lshl_add_u64 v[230:231], s[86:87], 0, v[136:137]
	s_mov_b32 m0, s74
	v_lshl_add_u64 v[232:233], s[84:85], 0, v[134:135]
	global_load_lds_dwordx4 v[230:231], off
	v_lshl_add_u64 v[230:231], s[86:87], 0, v[132:133]
	s_add_i32 m0, s74, 0x2000
	s_nop 0
	global_load_lds_dwordx4 v[230:231], off
	v_lshl_add_u64 v[230:231], s[84:85], 0, v[138:139]
	s_mov_b32 m0, s12
	s_nop 0
	global_load_lds_dwordx4 v[230:231], off
	s_mov_b32 m0, s13
	s_nop 0
	global_load_lds_dwordx4 v[232:233], off
	s_waitcnt vmcnt(8)
	s_waitcnt lgkmcnt(0)
	s_barrier
; #define PG8_STAGE(bufoff, gbase, voff) do { _Pragma("unroll") for (int _i = 0; _i < 2; ++_i) \
;         __builtin_amdgcn_global_load_lds((const unsigned*)((const char*)(gbase) + (voff)[_i]), (PG8_LAS unsigned*)(lds + (bufoff) + ldsw + _i * 8192), 16, 0, 0); } while (0)
; #define PG8_LDA(dst, b, h) do { _Pragma("unroll") for (int m = 0; m < 4; ++m) _Pragma("unroll") for (int k = 0; k < 2; ++k) dst[m][k] = *(const PG8_LAS bf16x8*)(lds + PG8_SA(b, h) + aoff + m * 2048 + k * 1024); } while (0)
; #define PG8_LDB(dst, b, h) do { _Pragma("unroll") for (int n = 0; n < 2; ++n) _Pragma("unroll") for (int k = 0; k < 2; ++k) dst[n][k] = *(const PG8_LAS bf16x8*)(lds + PG8_SB(b, h) + boff + n * 2048 + k * 1024); } while (0)
; #define PG8_MMA(ai, bj, At, Bt) do { __builtin_amdgcn_s_setprio(1); _Pragma("unroll") for (int m = 0; m < 4; ++m) _Pragma("unroll") for (int n = 0; n < 2; ++n) _Pragma("unroll") for (int k = 0; k < 2; ++k) \
;         acc[ai][bj][m][n] = __builtin_amdgcn_mfma_f32_16x16x32_bf16(Bt[n][k], At[m][k], acc[ai][bj][m][n], 0, 0, 0); __builtin_amdgcn_s_setprio(0); } while (0)
; #define PG8_WAIT_V(n) asm volatile("s_waitcnt vmcnt(" #n ")" ::: "memory")
; #define PG8_WAIT_L(n) asm volatile("s_waitcnt lgkmcnt(" #n ")" ::: "memory")
; #define PG8_BAR __builtin_amdgcn_s_barrier()
; #define PG8_SCHED __builtin_amdgcn_sched_barrier(0)
; template <class Epi, class Sched, bool ALIGN_EPI = false, bool SP2 = false>
; __device__ __forceinline__ void gemm_phase(PG8_LAS unsigned char* lds, const Gemm g, const Sched& S, const Epi& E) {
;     ...
;             PG8_WAIT_V(8); PG8_WAIT_L(0); PG8_BAR; PG8_MMA(1, 0, At, B0); PG8_MMA(1, 1, At, B1); PG8_BAR; PG8_SCHED;
;             PG8_LDB(B0, 1, 0); PG8_LDB(B1, 1, 1); PG8_SCHED; PG8_LDA(At, 1, 0); PG8_STAGE(PG8_SA(0, 1), a2 + hstepA, voffA);
;             PG8_WAIT_V(8); PG8_WAIT_L(0); PG8_BAR; PG8_MMA(0, 0, At, B0); PG8_MMA(0, 1, At, B1); PG8_BAR; PG8_SCHED;
	s_setprio 1
	v_mfma_f32_16x16x32_bf16 v[92:95], v[128:131], v[176:179], v[92:95]
	v_mfma_f32_16x16x32_bf16 v[88:91], v[148:151], v[176:179], v[88:91]
	v_mfma_f32_16x16x32_bf16 v[84:87], v[128:131], v[184:187], v[84:87]
	v_mfma_f32_16x16x32_bf16 v[80:83], v[148:151], v[184:187], v[80:83]
	v_mfma_f32_16x16x32_bf16 v[76:79], v[128:131], v[200:203], v[76:79]
	v_mfma_f32_16x16x32_bf16 v[72:75], v[148:151], v[200:203], v[72:75]
	v_mfma_f32_16x16x32_bf16 v[68:71], v[128:131], v[208:211], v[68:71]
	v_mfma_f32_16x16x32_bf16 v[64:67], v[148:151], v[208:211], v[64:67]
	v_mfma_f32_16x16x32_bf16 v[92:95], v[144:147], v[180:183], v[92:95]
	v_mfma_f32_16x16x32_bf16 v[88:91], v[156:159], v[180:183], v[88:91]
	v_mfma_f32_16x16x32_bf16 v[84:87], v[144:147], v[188:191], v[84:87]
	v_mfma_f32_16x16x32_bf16 v[80:83], v[156:159], v[188:191], v[80:83]
	v_mfma_f32_16x16x32_bf16 v[76:79], v[144:147], v[204:207], v[76:79]
	v_mfma_f32_16x16x32_bf16 v[72:75], v[156:159], v[204:207], v[72:75]
	v_mfma_f32_16x16x32_bf16 v[68:71], v[144:147], v[212:215], v[68:71]
	v_mfma_f32_16x16x32_bf16 v[64:67], v[156:159], v[212:215], v[64:67]
	v_mfma_f32_16x16x32_bf16 v[28:31], v[160:163], v[176:179], v[28:31]
	v_mfma_f32_16x16x32_bf16 v[24:27], v[168:171], v[176:179], v[24:27]
	v_mfma_f32_16x16x32_bf16 v[20:23], v[160:163], v[184:187], v[20:23]
	v_mfma_f32_16x16x32_bf16 v[16:19], v[168:171], v[184:187], v[16:19]
	v_mfma_f32_16x16x32_bf16 v[12:15], v[160:163], v[200:203], v[12:15]
	v_mfma_f32_16x16x32_bf16 v[8:11], v[168:171], v[200:203], v[8:11]
	v_mfma_f32_16x16x32_bf16 v[4:7], v[160:163], v[208:211], v[4:7]
	v_mfma_f32_16x16x32_bf16 v[0:3], v[168:171], v[208:211], v[0:3]
	v_mfma_f32_16x16x32_bf16 v[28:31], v[164:167], v[180:183], v[28:31]
	v_mfma_f32_16x16x32_bf16 v[24:27], v[172:175], v[180:183], v[24:27]
	v_mfma_f32_16x16x32_bf16 v[20:23], v[164:167], v[188:191], v[20:23]
	v_mfma_f32_16x16x32_bf16 v[16:19], v[172:175], v[188:191], v[16:19]
	v_mfma_f32_16x16x32_bf16 v[12:15], v[164:167], v[204:207], v[12:15]
	v_mfma_f32_16x16x32_bf16 v[8:11], v[172:175], v[204:207], v[8:11]
	v_mfma_f32_16x16x32_bf16 v[4:7], v[164:167], v[212:215], v[4:7]
	v_mfma_f32_16x16x32_bf16 v[0:3], v[172:175], v[212:215], v[0:3]
	s_setprio 0
	s_barrier
	s_add_i32 s74, 0, 0x18000
	s_add_i32 s75, 0, 0x1c000
	v_add_u32_e32 v156, s74, v154
	v_add_u32_e32 v172, s75, v154
	ds_read_b128 v[128:131], v156
	ds_read_b128 v[144:147], v156 offset:1024
	ds_read_b128 v[148:151], v156 offset:2048
	ds_read_b128 v[156:159], v156 offset:3072
	ds_read_b128 v[160:163], v172
	ds_read_b128 v[164:167], v172 offset:1024
	ds_read_b128 v[168:171], v172 offset:2048
	ds_read_b128 v[172:175], v172 offset:3072
	s_add_u32 s84, s84, 0x8000
	s_addc_u32 s85, s85, 0
	s_mov_b32 m0, s14
	v_lshl_add_u64 v[234:235], s[84:85], 0, v[138:139]
	ds_read_b128 v[176:179], v155 offset:32768
	ds_read_b128 v[180:183], v155 offset:33792
	ds_read_b128 v[184:187], v155 offset:34816
	ds_read_b128 v[188:191], v155 offset:35840
	ds_read_b128 v[200:203], v155 offset:36864
	ds_read_b128 v[204:207], v155 offset:37888
	ds_read_b128 v[208:211], v155 offset:38912
	ds_read_b128 v[212:215], v155 offset:39936
	global_load_lds_dwordx4 v[234:235], off
	v_lshl_add_u64 v[234:235], s[84:85], 0, v[134:135]
	s_mov_b32 m0, s15
	s_nop 0
	global_load_lds_dwordx4 v[234:235], off
	s_waitcnt vmcnt(8)
	s_waitcnt lgkmcnt(0)
	s_barrier
	s_setprio 1
	v_mfma_f32_16x16x32_bf16 v[124:127], v[128:131], v[176:179], v[124:127]
	v_mfma_f32_16x16x32_bf16 v[120:123], v[148:151], v[176:179], v[120:123]
	v_mfma_f32_16x16x32_bf16 v[116:119], v[128:131], v[184:187], v[116:119]
	v_mfma_f32_16x16x32_bf16 v[112:115], v[148:151], v[184:187], v[112:115]
	v_mfma_f32_16x16x32_bf16 v[108:111], v[128:131], v[200:203], v[108:111]
	v_mfma_f32_16x16x32_bf16 v[104:107], v[148:151], v[200:203], v[104:107]
	v_mfma_f32_16x16x32_bf16 v[100:103], v[128:131], v[208:211], v[100:103]
	v_mfma_f32_16x16x32_bf16 v[96:99], v[148:151], v[208:211], v[96:99]
	v_mfma_f32_16x16x32_bf16 v[124:127], v[144:147], v[180:183], v[124:127]
	v_mfma_f32_16x16x32_bf16 v[120:123], v[156:159], v[180:183], v[120:123]
	v_mfma_f32_16x16x32_bf16 v[116:119], v[144:147], v[188:191], v[116:119]
	v_mfma_f32_16x16x32_bf16 v[112:115], v[156:159], v[188:191], v[112:115]
	v_mfma_f32_16x16x32_bf16 v[108:111], v[144:147], v[204:207], v[108:111]
	v_mfma_f32_16x16x32_bf16 v[104:107], v[156:159], v[204:207], v[104:107]
	v_mfma_f32_16x16x32_bf16 v[100:103], v[144:147], v[212:215], v[100:103]
	v_mfma_f32_16x16x32_bf16 v[96:99], v[156:159], v[212:215], v[96:99]
	v_mfma_f32_16x16x32_bf16 v[60:63], v[160:163], v[176:179], v[60:63]
	v_mfma_f32_16x16x32_bf16 v[56:59], v[168:171], v[176:179], v[56:59]
	v_mfma_f32_16x16x32_bf16 v[52:55], v[160:163], v[184:187], v[52:55]
	v_mfma_f32_16x16x32_bf16 v[48:51], v[168:171], v[184:187], v[48:51]
	v_mfma_f32_16x16x32_bf16 v[44:47], v[160:163], v[200:203], v[44:47]
	v_mfma_f32_16x16x32_bf16 v[40:43], v[168:171], v[200:203], v[40:43]
	v_mfma_f32_16x16x32_bf16 v[36:39], v[160:163], v[208:211], v[36:39]
	v_mfma_f32_16x16x32_bf16 v[32:35], v[168:171], v[208:211], v[32:35]
	v_mfma_f32_16x16x32_bf16 v[60:63], v[164:167], v[180:183], v[60:63]
	v_mfma_f32_16x16x32_bf16 v[56:59], v[172:175], v[180:183], v[56:59]
	v_mfma_f32_16x16x32_bf16 v[52:55], v[164:167], v[188:191], v[52:55]
	v_mfma_f32_16x16x32_bf16 v[48:51], v[172:175], v[188:191], v[48:51]
	v_mfma_f32_16x16x32_bf16 v[44:47], v[164:167], v[204:207], v[44:47]
	v_mfma_f32_16x16x32_bf16 v[40:43], v[172:175], v[204:207], v[40:43]
	v_mfma_f32_16x16x32_bf16 v[36:39], v[164:167], v[212:215], v[36:39]
	v_mfma_f32_16x16x32_bf16 v[32:35], v[172:175], v[212:215], v[32:35]
	s_setprio 0
	s_barrier
; #define PG8_STAGE(bufoff, gbase, voff) do { _Pragma("unroll") for (int _i = 0; _i < 2; ++_i) \
;         __builtin_amdgcn_global_load_lds((const unsigned*)((const char*)(gbase) + (voff)[_i]), (PG8_LAS unsigned*)(lds + (bufoff) + ldsw + _i * 8192), 16, 0, 0); } while (0)
; #define PG8_LDA(dst, b, h) do { _Pragma("unroll") for (int m = 0; m < 4; ++m) _Pragma("unroll") for (int k = 0; k < 2; ++k) dst[m][k] = *(const PG8_LAS bf16x8*)(lds + PG8_SA(b, h) + aoff + m * 2048 + k * 1024); } while (0)
; #define PG8_MMA(ai, bj, At, Bt) do { __builtin_amdgcn_s_setprio(1); _Pragma("unroll") for (int m = 0; m < 4; ++m) _Pragma("unroll") for (int n = 0; n < 2; ++n) _Pragma("unroll") for (int k = 0; k < 2; ++k) \
;         acc[ai][bj][m][n] = __builtin_amdgcn_mfma_f32_16x16x32_bf16(Bt[n][k], At[m][k], acc[ai][bj][m][n], 0, 0, 0); __builtin_amdgcn_s_setprio(0); } while (0)
; #define PG8_WAIT_V(n) asm volatile("s_waitcnt vmcnt(" #n ")" ::: "memory")
; #define PG8_WAIT_L(n) asm volatile("s_waitcnt lgkmcnt(" #n ")" ::: "memory")
; #define PG8_BAR __builtin_amdgcn_s_barrier()
; #define PG8_SCHED __builtin_amdgcn_sched_barrier(0)
; template <class Epi, class Sched, bool ALIGN_EPI = false, bool SP2 = false>
; __device__ __forceinline__ void gemm_phase(PG8_LAS unsigned char* lds, const Gemm g, const Sched& S, const Epi& E) {
;     ...
;         for (int t = 0; t < nt; t += 2) {
;     ...
;             PG8_LDA(At, 1, 1); PG8_STAGE(PG8_SB(1, 0), b3, voffB); PG8_STAGE(PG8_SB(1, 1), b3 + hstepB, voffB); PG8_STAGE(PG8_SA(1, 0), a3, voffA);
;             PG8_WAIT_V(8); PG8_WAIT_L(0); PG8_BAR; PG8_MMA(1, 0, At, B0); PG8_MMA(1, 1, At, B1); PG8_BAR; PG8_SCHED;
	s_add_i32 s74, s74, s2
	v_lshl_add_u64 v[192:193], v[192:193], 0, s[26:27]
	s_mov_b32 m0, s74
	ds_read_b128 v[176:179], v155 offset:49152
	ds_read_b128 v[180:183], v155 offset:50176
	ds_read_b128 v[184:187], v155 offset:51200
	ds_read_b128 v[188:191], v155 offset:52224
	ds_read_b128 v[200:203], v155 offset:53248
	ds_read_b128 v[204:207], v155 offset:54272
	ds_read_b128 v[208:211], v155 offset:55296
	ds_read_b128 v[212:215], v155 offset:56320
	global_load_lds_dwordx4 v[192:193], off
	s_add_i32 m0, s74, 0x2000
	s_add_u32 s62, s62, 0x20080
	v_lshl_add_u64 v[192:193], v[228:229], 0, s[26:27]
	s_addc_u32 s63, s63, 0
	s_add_i32 s74, s75, s2
	global_load_lds_dwordx4 v[192:193], off
	v_lshl_add_u64 v[192:193], s[62:63], 0, v[136:137]
	s_mov_b32 m0, s74
	s_nop 0
	global_load_lds_dwordx4 v[192:193], off
	v_lshl_add_u64 v[192:193], s[62:63], 0, v[132:133]
	s_add_i32 m0, s74, 0x2000
	s_nop 0
	global_load_lds_dwordx4 v[192:193], off
	v_lshl_add_u64 v[192:193], v[230:231], 0, s[26:27]
	s_mov_b32 m0, s29
	s_nop 0
	global_load_lds_dwordx4 v[192:193], off
	v_lshl_add_u64 v[192:193], v[232:233], 0, s[26:27]
	s_mov_b32 m0, s33
	s_nop 0
	global_load_lds_dwordx4 v[192:193], off
	s_waitcnt vmcnt(8)
	s_waitcnt lgkmcnt(0)
	s_barrier
	s_setprio 1
	v_mfma_f32_16x16x32_bf16 v[92:95], v[128:131], v[176:179], v[92:95]
	v_mfma_f32_16x16x32_bf16 v[88:91], v[148:151], v[176:179], v[88:91]
	v_mfma_f32_16x16x32_bf16 v[84:87], v[128:131], v[184:187], v[84:87]
	v_mfma_f32_16x16x32_bf16 v[80:83], v[148:151], v[184:187], v[80:83]
	v_mfma_f32_16x16x32_bf16 v[76:79], v[128:131], v[200:203], v[76:79]
	v_mfma_f32_16x16x32_bf16 v[72:75], v[148:151], v[200:203], v[72:75]
	v_mfma_f32_16x16x32_bf16 v[68:71], v[128:131], v[208:211], v[68:71]
	v_mfma_f32_16x16x32_bf16 v[64:67], v[148:151], v[208:211], v[64:67]
	v_mfma_f32_16x16x32_bf16 v[92:95], v[144:147], v[180:183], v[92:95]
	v_mfma_f32_16x16x32_bf16 v[88:91], v[156:159], v[180:183], v[88:91]
	v_mfma_f32_16x16x32_bf16 v[84:87], v[144:147], v[188:191], v[84:87]
	v_mfma_f32_16x16x32_bf16 v[80:83], v[156:159], v[188:191], v[80:83]
	v_mfma_f32_16x16x32_bf16 v[76:79], v[144:147], v[204:207], v[76:79]
	v_mfma_f32_16x16x32_bf16 v[72:75], v[156:159], v[204:207], v[72:75]
	v_mfma_f32_16x16x32_bf16 v[68:71], v[144:147], v[212:215], v[68:71]
	v_mfma_f32_16x16x32_bf16 v[64:67], v[156:159], v[212:215], v[64:67]
	v_mfma_f32_16x16x32_bf16 v[28:31], v[160:163], v[176:179], v[28:31]
	v_mfma_f32_16x16x32_bf16 v[24:27], v[168:171], v[176:179], v[24:27]
	v_mfma_f32_16x16x32_bf16 v[20:23], v[160:163], v[184:187], v[20:23]
	v_mfma_f32_16x16x32_bf16 v[16:19], v[168:171], v[184:187], v[16:19]
	v_mfma_f32_16x16x32_bf16 v[12:15], v[160:163], v[200:203], v[12:15]
	v_mfma_f32_16x16x32_bf16 v[8:11], v[168:171], v[200:203], v[8:11]
	v_mfma_f32_16x16x32_bf16 v[4:7], v[160:163], v[208:211], v[4:7]
	v_mfma_f32_16x16x32_bf16 v[0:3], v[168:171], v[208:211], v[0:3]
	v_mfma_f32_16x16x32_bf16 v[28:31], v[164:167], v[180:183], v[28:31]
	v_mfma_f32_16x16x32_bf16 v[24:27], v[172:175], v[180:183], v[24:27]
	v_mfma_f32_16x16x32_bf16 v[20:23], v[164:167], v[188:191], v[20:23]
	v_mfma_f32_16x16x32_bf16 v[16:19], v[172:175], v[188:191], v[16:19]
	v_mfma_f32_16x16x32_bf16 v[12:15], v[164:167], v[204:207], v[12:15]
	v_mfma_f32_16x16x32_bf16 v[8:11], v[172:175], v[204:207], v[8:11]
	v_mfma_f32_16x16x32_bf16 v[4:7], v[164:167], v[212:215], v[4:7]
	v_mfma_f32_16x16x32_bf16 v[0:3], v[172:175], v[212:215], v[0:3]
	s_setprio 0
	s_barrier
	s_add_u32 s42, s42, 0x100
	s_addc_u32 s43, s43, 0
	s_add_u32 s69, s69, 0x100
	s_addc_u32 s78, s78, 0
	s_cmp_ge_i32 s79, s16
	s_mov_b32 s62, s79
	s_cbranch_scc0 .LBB0_618

; #define PG8_STAGE(bufoff, gbase, voff) do { _Pragma("unroll") for (int _i = 0; _i < 2; ++_i) \
;         __builtin_amdgcn_global_load_lds((const unsigned*)((const char*)(gbase) + (voff)[_i]), (PG8_LAS unsigned*)(lds + (bufoff) + ldsw + _i * 8192), 16, 0, 0); } while (0)
; #define PG8_LDA(dst, b, h) do { _Pragma("unroll") for (int m = 0; m < 4; ++m) _Pragma("unroll") for (int k = 0; k < 2; ++k) dst[m][k] = *(const PG8_LAS bf16x8*)(lds + PG8_SA(b, h) + aoff + m * 2048 + k * 1024); } while (0)
; #define PG8_LDB(dst, b, h) do { _Pragma("unroll") for (int n = 0; n < 2; ++n) _Pragma("unroll") for (int k = 0; k < 2; ++k) dst[n][k] = *(const PG8_LAS bf16x8*)(lds + PG8_SB(b, h) + boff + n * 2048 + k * 1024); } while (0)
; #define PG8_MMA(ai, bj, At, Bt) do { __builtin_amdgcn_s_setprio(1); _Pragma("unroll") for (int m = 0; m < 4; ++m) _Pragma("unroll") for (int n = 0; n < 2; ++n) _Pragma("unroll") for (int k = 0; k < 2; ++k) \
;         acc[ai][bj][m][n] = __builtin_amdgcn_mfma_f32_16x16x32_bf16(Bt[n][k], At[m][k], acc[ai][bj][m][n], 0, 0, 0); __builtin_amdgcn_s_setprio(0); } while (0)
; #define PG8_WAIT_V(n) asm volatile("s_waitcnt vmcnt(" #n ")" ::: "memory")
; #define PG8_WAIT_L(n) asm volatile("s_waitcnt lgkmcnt(" #n ")" ::: "memory")
; template <class Epi, class Sched, bool ALIGN_EPI = false, bool SP2 = false>
; __device__ __forceinline__ void gemm_phase(PG8_LAS unsigned char* lds, const Gemm g, const Sched& S, const Epi& E) {
;     ...
;             const bool last = (t == nt - 2);
;             const char* a1 = cA + (size_t)(t + 1) * kstep;
;             const char* a2 = last ? nA : cA + (size_t)(t + 2) * kstep; const char* b2 = last ? nB : cB + (size_t)(t + 2) * kstep;
;             const char* a3 = a2 + kstep; const char* b3 = b2 + kstep;
;             if (last && has_next) S.a_ready(nxt);
;             if constexpr (SP2) {
;             PG8_LDB(B0, 0, 0); PG8_LDB(B1, 0, 1); PG8_SCHED; PG8_LDA(At, 0, 0); PG8_STAGE(PG8_SA(1, 1), a1 + hstepA, voffA);
;             PG8_WAIT_V(8); PG8_WAIT_L(0); PG8_BAR; PG8_MMA(0, 0, At, B0); PG8_MMA(0, 1, At, B1); PG8_BAR; PG8_SCHED;
;             PG8_LDA(At, 0, 1); PG8_STAGE(PG8_SB(0, 0), b2, voffB); PG8_STAGE(PG8_SB(0, 1), b2 + hstepB, voffB); PG8_STAGE(PG8_SA(0, 0), a2, voffA);
;             PG8_WAIT_V(8); PG8_WAIT_L(0); PG8_BAR; PG8_MMA(1, 0, At, B0); PG8_MMA(1, 1, At, B1); PG8_BAR; PG8_SCHED;
.LBB0_929:
	s_add_i32 s59, s58, 2
	s_add_u32 s62, s84, 0xfffc0080
	s_addc_u32 s63, s85, -1
	s_add_i32 s64, 0, 0x10000
	s_cmp_eq_u32 s16, s58
	s_cselect_b32 s87, s28, s63
	s_cselect_b32 s86, s29, s62
	v_add_u32_e32 v136, s64, v170
	s_cselect_b32 s63, s33, s55
	s_cselect_b32 s62, s43, s45
	s_add_i32 s58, 0, 0x14000
	ds_read_b128 v[128:131], v136
	ds_read_b128 v[132:135], v136 offset:1024
	ds_read_b128 v[150:153], v136 offset:2048
	ds_read_b128 v[154:157], v136 offset:3072
	v_add_u32_e32 v136, s58, v170
	ds_read_b128 v[158:161], v136
	ds_read_b128 v[162:165], v136 offset:1024
	ds_read_b128 v[172:175], v136 offset:2048
	ds_read_b128 v[176:179], v136 offset:3072
	v_lshl_add_u64 v[136:137], s[84:85], 0, v[146:147]
	s_add_i32 m0, s3, 0xc000
	ds_read_b128 v[180:183], v171
	ds_read_b128 v[184:187], v171 offset:1024
	ds_read_b128 v[188:191], v171 offset:2048
	ds_read_b128 v[200:203], v171 offset:3072
	ds_read_b128 v[204:207], v171 offset:4096
	ds_read_b128 v[208:211], v171 offset:5120
	ds_read_b128 v[212:215], v171 offset:6144
	ds_read_b128 v[228:231], v171 offset:7168
	global_load_lds_dwordx4 v[136:137], off
	v_lshl_add_u64 v[136:137], s[84:85], 0, v[148:149]
	s_add_i32 m0, s3, 0xe000
	s_nop 0
	global_load_lds_dwordx4 v[136:137], off
	s_waitcnt vmcnt(8)
	s_waitcnt lgkmcnt(0)
	s_barrier
	s_setprio 1
	v_mfma_f32_16x16x32_bf16 v[124:127], v[128:131], v[180:183], v[124:127]
	v_mfma_f32_16x16x32_bf16 v[120:123], v[150:153], v[180:183], v[120:123]
	v_mfma_f32_16x16x32_bf16 v[108:111], v[128:131], v[188:191], v[108:111]
	v_mfma_f32_16x16x32_bf16 v[104:107], v[150:153], v[188:191], v[104:107]
	v_mfma_f32_16x16x32_bf16 v[92:95], v[128:131], v[204:207], v[92:95]
	v_mfma_f32_16x16x32_bf16 v[88:91], v[150:153], v[204:207], v[88:91]
	v_mfma_f32_16x16x32_bf16 v[76:79], v[128:131], v[212:215], v[76:79]
	v_mfma_f32_16x16x32_bf16 v[72:75], v[150:153], v[212:215], v[72:75]
	v_mfma_f32_16x16x32_bf16 v[124:127], v[132:135], v[184:187], v[124:127]
	v_mfma_f32_16x16x32_bf16 v[120:123], v[154:157], v[184:187], v[120:123]
	v_mfma_f32_16x16x32_bf16 v[108:111], v[132:135], v[200:203], v[108:111]
	v_mfma_f32_16x16x32_bf16 v[104:107], v[154:157], v[200:203], v[104:107]
	v_mfma_f32_16x16x32_bf16 v[92:95], v[132:135], v[208:211], v[92:95]
	v_mfma_f32_16x16x32_bf16 v[88:91], v[154:157], v[208:211], v[88:91]
	v_mfma_f32_16x16x32_bf16 v[76:79], v[132:135], v[228:231], v[76:79]
	v_mfma_f32_16x16x32_bf16 v[72:75], v[154:157], v[228:231], v[72:75]
	v_mfma_f32_16x16x32_bf16 v[116:119], v[158:161], v[180:183], v[116:119]
	v_mfma_f32_16x16x32_bf16 v[112:115], v[172:175], v[180:183], v[112:115]
	v_mfma_f32_16x16x32_bf16 v[100:103], v[158:161], v[188:191], v[100:103]
	v_mfma_f32_16x16x32_bf16 v[96:99], v[172:175], v[188:191], v[96:99]
	v_mfma_f32_16x16x32_bf16 v[84:87], v[158:161], v[204:207], v[84:87]
	v_mfma_f32_16x16x32_bf16 v[80:83], v[172:175], v[204:207], v[80:83]
	v_mfma_f32_16x16x32_bf16 v[68:71], v[158:161], v[212:215], v[68:71]
	v_mfma_f32_16x16x32_bf16 v[64:67], v[172:175], v[212:215], v[64:67]
	v_mfma_f32_16x16x32_bf16 v[116:119], v[162:165], v[184:187], v[116:119]
	v_mfma_f32_16x16x32_bf16 v[112:115], v[176:179], v[184:187], v[112:115]
	v_mfma_f32_16x16x32_bf16 v[100:103], v[162:165], v[200:203], v[100:103]
	v_mfma_f32_16x16x32_bf16 v[96:99], v[176:179], v[200:203], v[96:99]
	v_mfma_f32_16x16x32_bf16 v[84:87], v[162:165], v[208:211], v[84:87]
	v_mfma_f32_16x16x32_bf16 v[80:83], v[176:179], v[208:211], v[80:83]
	v_mfma_f32_16x16x32_bf16 v[68:71], v[162:165], v[228:231], v[68:71]
	v_mfma_f32_16x16x32_bf16 v[64:67], v[176:179], v[228:231], v[64:67]
	s_setprio 0
	s_barrier
	s_add_i32 s64, s64, s2
	v_lshl_add_u64 v[136:137], s[62:63], 0, v[140:141]
	s_mov_b32 m0, s64
	ds_read_b128 v[180:183], v171 offset:16384
	ds_read_b128 v[184:187], v171 offset:17408
	ds_read_b128 v[188:191], v171 offset:18432
	ds_read_b128 v[200:203], v171 offset:19456
	ds_read_b128 v[204:207], v171 offset:20480
	ds_read_b128 v[208:211], v171 offset:21504
	ds_read_b128 v[212:215], v171 offset:22528
	ds_read_b128 v[228:231], v171 offset:23552
	global_load_lds_dwordx4 v[136:137], off
	s_add_i32 m0, s64, 0x2000
	s_add_u32 s78, s62, 0x40000
	v_lshl_add_u64 v[166:167], s[62:63], 0, v[144:145]
	s_addc_u32 s79, s63, 0
	s_add_i32 s58, s58, s2
	global_load_lds_dwordx4 v[166:167], off
	v_lshl_add_u64 v[192:193], s[78:79], 0, v[140:141]
	s_mov_b32 m0, s58
	v_lshl_add_u64 v[232:233], s[86:87], 0, v[142:143]
	global_load_lds_dwordx4 v[192:193], off
	v_lshl_add_u64 v[192:193], s[78:79], 0, v[144:145]
	s_add_i32 m0, s58, 0x2000
	s_nop 0
	global_load_lds_dwordx4 v[192:193], off
	v_lshl_add_u64 v[192:193], s[86:87], 0, v[138:139]
	s_mov_b32 m0, s3
	s_nop 0
	global_load_lds_dwordx4 v[192:193], off
	s_mov_b32 m0, s8
	s_nop 0
	global_load_lds_dwordx4 v[232:233], off
	s_waitcnt vmcnt(8)
	s_waitcnt lgkmcnt(0)
	s_barrier
; #define PG8_STAGE(bufoff, gbase, voff) do { _Pragma("unroll") for (int _i = 0; _i < 2; ++_i) \
;         __builtin_amdgcn_global_load_lds((const unsigned*)((const char*)(gbase) + (voff)[_i]), (PG8_LAS unsigned*)(lds + (bufoff) + ldsw + _i * 8192), 16, 0, 0); } while (0)
; #define PG8_LDA(dst, b, h) do { _Pragma("unroll") for (int m = 0; m < 4; ++m) _Pragma("unroll") for (int k = 0; k < 2; ++k) dst[m][k] = *(const PG8_LAS bf16x8*)(lds + PG8_SA(b, h) + aoff + m * 2048 + k * 1024); } while (0)
; #define PG8_LDB(dst, b, h) do { _Pragma("unroll") for (int n = 0; n < 2; ++n) _Pragma("unroll") for (int k = 0; k < 2; ++k) dst[n][k] = *(const PG8_LAS bf16x8*)(lds + PG8_SB(b, h) + boff + n * 2048 + k * 1024); } while (0)
; #define PG8_MMA(ai, bj, At, Bt) do { __builtin_amdgcn_s_setprio(1); _Pragma("unroll") for (int m = 0; m < 4; ++m) _Pragma("unroll") for (int n = 0; n < 2; ++n) _Pragma("unroll") for (int k = 0; k < 2; ++k) \
;         acc[ai][bj][m][n] = __builtin_amdgcn_mfma_f32_16x16x32_bf16(Bt[n][k], At[m][k], acc[ai][bj][m][n], 0, 0, 0); __builtin_amdgcn_s_setprio(0); } while (0)
; #define PG8_WAIT_V(n) asm volatile("s_waitcnt vmcnt(" #n ")" ::: "memory")
; #define PG8_WAIT_L(n) asm volatile("s_waitcnt lgkmcnt(" #n ")" ::: "memory")
; #define PG8_BAR __builtin_amdgcn_s_barrier()
; #define PG8_SCHED __builtin_amdgcn_sched_barrier(0)
; template <class Epi, class Sched, bool ALIGN_EPI = false, bool SP2 = false>
; __device__ __forceinline__ void gemm_phase(PG8_LAS unsigned char* lds, const Gemm g, const Sched& S, const Epi& E) {
;     ...
;             PG8_WAIT_V(8); PG8_WAIT_L(0); PG8_BAR; PG8_MMA(1, 0, At, B0); PG8_MMA(1, 1, At, B1); PG8_BAR; PG8_SCHED;
;             PG8_LDB(B0, 1, 0); PG8_LDB(B1, 1, 1); PG8_SCHED; PG8_LDA(At, 1, 0); PG8_STAGE(PG8_SA(0, 1), a2 + hstepA, voffA);
;             PG8_WAIT_V(8); PG8_WAIT_L(0); PG8_BAR; PG8_MMA(0, 0, At, B0); PG8_MMA(0, 1, At, B1); PG8_BAR; PG8_SCHED;
	s_setprio 1
	v_mfma_f32_16x16x32_bf16 v[60:63], v[128:131], v[180:183], v[60:63]
	v_mfma_f32_16x16x32_bf16 v[56:59], v[150:153], v[180:183], v[56:59]
	v_mfma_f32_16x16x32_bf16 v[44:47], v[128:131], v[188:191], v[44:47]
	v_mfma_f32_16x16x32_bf16 v[40:43], v[150:153], v[188:191], v[40:43]
	v_mfma_f32_16x16x32_bf16 v[28:31], v[128:131], v[204:207], v[28:31]
	v_mfma_f32_16x16x32_bf16 v[24:27], v[150:153], v[204:207], v[24:27]
	v_mfma_f32_16x16x32_bf16 v[12:15], v[128:131], v[212:215], v[12:15]
	v_mfma_f32_16x16x32_bf16 v[8:11], v[150:153], v[212:215], v[8:11]
	v_mfma_f32_16x16x32_bf16 v[60:63], v[132:135], v[184:187], v[60:63]
	v_mfma_f32_16x16x32_bf16 v[56:59], v[154:157], v[184:187], v[56:59]
	v_mfma_f32_16x16x32_bf16 v[44:47], v[132:135], v[200:203], v[44:47]
	v_mfma_f32_16x16x32_bf16 v[40:43], v[154:157], v[200:203], v[40:43]
	v_mfma_f32_16x16x32_bf16 v[28:31], v[132:135], v[208:211], v[28:31]
	v_mfma_f32_16x16x32_bf16 v[24:27], v[154:157], v[208:211], v[24:27]
	v_mfma_f32_16x16x32_bf16 v[12:15], v[132:135], v[228:231], v[12:15]
	v_mfma_f32_16x16x32_bf16 v[8:11], v[154:157], v[228:231], v[8:11]
	v_mfma_f32_16x16x32_bf16 v[52:55], v[158:161], v[180:183], v[52:55]
	v_mfma_f32_16x16x32_bf16 v[48:51], v[172:175], v[180:183], v[48:51]
	v_mfma_f32_16x16x32_bf16 v[36:39], v[158:161], v[188:191], v[36:39]
	v_mfma_f32_16x16x32_bf16 v[32:35], v[172:175], v[188:191], v[32:35]
	v_mfma_f32_16x16x32_bf16 v[20:23], v[158:161], v[204:207], v[20:23]
	v_mfma_f32_16x16x32_bf16 v[16:19], v[172:175], v[204:207], v[16:19]
	v_mfma_f32_16x16x32_bf16 v[4:7], v[158:161], v[212:215], v[4:7]
	v_mfma_f32_16x16x32_bf16 v[0:3], v[172:175], v[212:215], v[0:3]
	v_mfma_f32_16x16x32_bf16 v[52:55], v[162:165], v[184:187], v[52:55]
	v_mfma_f32_16x16x32_bf16 v[48:51], v[176:179], v[184:187], v[48:51]
	v_mfma_f32_16x16x32_bf16 v[36:39], v[162:165], v[200:203], v[36:39]
	v_mfma_f32_16x16x32_bf16 v[32:35], v[176:179], v[200:203], v[32:35]
	v_mfma_f32_16x16x32_bf16 v[20:23], v[162:165], v[208:211], v[20:23]
	v_mfma_f32_16x16x32_bf16 v[16:19], v[176:179], v[208:211], v[16:19]
	v_mfma_f32_16x16x32_bf16 v[4:7], v[162:165], v[228:231], v[4:7]
	v_mfma_f32_16x16x32_bf16 v[0:3], v[176:179], v[228:231], v[0:3]
	s_setprio 0
	s_barrier
	s_add_i32 s58, 0, 0x18000
	s_add_i32 s64, 0, 0x1c000
	v_add_u32_e32 v154, s58, v170
	v_add_u32_e32 v176, s64, v170
	ds_read_b128 v[128:131], v154
	ds_read_b128 v[132:135], v154 offset:1024
	ds_read_b128 v[150:153], v154 offset:2048
	ds_read_b128 v[154:157], v154 offset:3072
	ds_read_b128 v[158:161], v176
	ds_read_b128 v[162:165], v176 offset:1024
	ds_read_b128 v[172:175], v176 offset:2048
	ds_read_b128 v[176:179], v176 offset:3072
	s_add_u32 s78, s86, 0x40000
	s_addc_u32 s79, s87, 0
	s_mov_b32 m0, s9
	v_lshl_add_u64 v[234:235], s[78:79], 0, v[138:139]
	ds_read_b128 v[180:183], v171 offset:32768
	ds_read_b128 v[184:187], v171 offset:33792
	ds_read_b128 v[188:191], v171 offset:34816
	ds_read_b128 v[200:203], v171 offset:35840
	ds_read_b128 v[204:207], v171 offset:36864
	ds_read_b128 v[208:211], v171 offset:37888
	ds_read_b128 v[212:215], v171 offset:38912
	ds_read_b128 v[228:231], v171 offset:39936
	global_load_lds_dwordx4 v[234:235], off
	v_lshl_add_u64 v[234:235], s[78:79], 0, v[142:143]
	s_mov_b32 m0, s10
	s_nop 0
	global_load_lds_dwordx4 v[234:235], off
	s_waitcnt vmcnt(8)
	s_waitcnt lgkmcnt(0)
	s_barrier
	s_setprio 1
	v_mfma_f32_16x16x32_bf16 v[124:127], v[128:131], v[180:183], v[124:127]
	v_mfma_f32_16x16x32_bf16 v[120:123], v[150:153], v[180:183], v[120:123]
	v_mfma_f32_16x16x32_bf16 v[108:111], v[128:131], v[188:191], v[108:111]
	v_mfma_f32_16x16x32_bf16 v[104:107], v[150:153], v[188:191], v[104:107]
	v_mfma_f32_16x16x32_bf16 v[92:95], v[128:131], v[204:207], v[92:95]
	v_mfma_f32_16x16x32_bf16 v[88:91], v[150:153], v[204:207], v[88:91]
	v_mfma_f32_16x16x32_bf16 v[76:79], v[128:131], v[212:215], v[76:79]
	v_mfma_f32_16x16x32_bf16 v[72:75], v[150:153], v[212:215], v[72:75]
	v_mfma_f32_16x16x32_bf16 v[124:127], v[132:135], v[184:187], v[124:127]
	v_mfma_f32_16x16x32_bf16 v[120:123], v[154:157], v[184:187], v[120:123]
	v_mfma_f32_16x16x32_bf16 v[108:111], v[132:135], v[200:203], v[108:111]
	v_mfma_f32_16x16x32_bf16 v[104:107], v[154:157], v[200:203], v[104:107]
	v_mfma_f32_16x16x32_bf16 v[92:95], v[132:135], v[208:211], v[92:95]
	v_mfma_f32_16x16x32_bf16 v[88:91], v[154:157], v[208:211], v[88:91]
	v_mfma_f32_16x16x32_bf16 v[76:79], v[132:135], v[228:231], v[76:79]
	v_mfma_f32_16x16x32_bf16 v[72:75], v[154:157], v[228:231], v[72:75]
	v_mfma_f32_16x16x32_bf16 v[116:119], v[158:161], v[180:183], v[116:119]
	v_mfma_f32_16x16x32_bf16 v[112:115], v[172:175], v[180:183], v[112:115]
	v_mfma_f32_16x16x32_bf16 v[100:103], v[158:161], v[188:191], v[100:103]
	v_mfma_f32_16x16x32_bf16 v[96:99], v[172:175], v[188:191], v[96:99]
	v_mfma_f32_16x16x32_bf16 v[84:87], v[158:161], v[204:207], v[84:87]
	v_mfma_f32_16x16x32_bf16 v[80:83], v[172:175], v[204:207], v[80:83]
	v_mfma_f32_16x16x32_bf16 v[68:71], v[158:161], v[212:215], v[68:71]
	v_mfma_f32_16x16x32_bf16 v[64:67], v[172:175], v[212:215], v[64:67]
	v_mfma_f32_16x16x32_bf16 v[116:119], v[162:165], v[184:187], v[116:119]
	v_mfma_f32_16x16x32_bf16 v[112:115], v[176:179], v[184:187], v[112:115]
	v_mfma_f32_16x16x32_bf16 v[100:103], v[162:165], v[200:203], v[100:103]
	v_mfma_f32_16x16x32_bf16 v[96:99], v[176:179], v[200:203], v[96:99]
	v_mfma_f32_16x16x32_bf16 v[84:87], v[162:165], v[208:211], v[84:87]
	v_mfma_f32_16x16x32_bf16 v[80:83], v[176:179], v[208:211], v[80:83]
	v_mfma_f32_16x16x32_bf16 v[68:71], v[162:165], v[228:231], v[68:71]
	v_mfma_f32_16x16x32_bf16 v[64:67], v[176:179], v[228:231], v[64:67]
	s_setprio 0
	s_barrier
; #define PG8_STAGE(bufoff, gbase, voff) do { _Pragma("unroll") for (int _i = 0; _i < 2; ++_i) \
;         __builtin_amdgcn_global_load_lds((const unsigned*)((const char*)(gbase) + (voff)[_i]), (PG8_LAS unsigned*)(lds + (bufoff) + ldsw + _i * 8192), 16, 0, 0); } while (0)
; #define PG8_LDA(dst, b, h) do { _Pragma("unroll") for (int m = 0; m < 4; ++m) _Pragma("unroll") for (int k = 0; k < 2; ++k) dst[m][k] = *(const PG8_LAS bf16x8*)(lds + PG8_SA(b, h) + aoff + m * 2048 + k * 1024); } while (0)
; #define PG8_MMA(ai, bj, At, Bt) do { __builtin_amdgcn_s_setprio(1); _Pragma("unroll") for (int m = 0; m < 4; ++m) _Pragma("unroll") for (int n = 0; n < 2; ++n) _Pragma("unroll") for (int k = 0; k < 2; ++k) \
;         acc[ai][bj][m][n] = __builtin_amdgcn_mfma_f32_16x16x32_bf16(Bt[n][k], At[m][k], acc[ai][bj][m][n], 0, 0, 0); __builtin_amdgcn_s_setprio(0); } while (0)
; #define PG8_WAIT_V(n) asm volatile("s_waitcnt vmcnt(" #n ")" ::: "memory")
; #define PG8_WAIT_L(n) asm volatile("s_waitcnt lgkmcnt(" #n ")" ::: "memory")
; #define PG8_BAR __builtin_amdgcn_s_barrier()
; #define PG8_SCHED __builtin_amdgcn_sched_barrier(0)
; template <class Epi, class Sched, bool ALIGN_EPI = false, bool SP2 = false>
; __device__ __forceinline__ void gemm_phase(PG8_LAS unsigned char* lds, const Gemm g, const Sched& S, const Epi& E) {
;     ...
;         for (int t = 0; t < nt; t += 2) {
;     ...
;             PG8_LDA(At, 1, 1); PG8_STAGE(PG8_SB(1, 0), b3, voffB); PG8_STAGE(PG8_SB(1, 1), b3 + hstepB, voffB); PG8_STAGE(PG8_SA(1, 0), a3, voffA);
;             PG8_WAIT_V(8); PG8_WAIT_L(0); PG8_BAR; PG8_MMA(1, 0, At, B0); PG8_MMA(1, 1, At, B1); PG8_BAR; PG8_SCHED;
	s_add_i32 s58, s58, s2
	v_lshl_add_u64 v[136:137], v[136:137], 0, s[26:27]
	s_mov_b32 m0, s58
	ds_read_b128 v[180:183], v171 offset:49152
	ds_read_b128 v[184:187], v171 offset:50176
	ds_read_b128 v[188:191], v171 offset:51200
	ds_read_b128 v[200:203], v171 offset:52224
	ds_read_b128 v[204:207], v171 offset:53248
	ds_read_b128 v[208:211], v171 offset:54272
	ds_read_b128 v[212:215], v171 offset:55296
	ds_read_b128 v[228:231], v171 offset:56320
	global_load_lds_dwordx4 v[136:137], off
	s_add_i32 m0, s58, 0x2000
	s_add_u32 s62, s62, 0x40080
	v_lshl_add_u64 v[136:137], v[166:167], 0, s[26:27]
	s_addc_u32 s63, s63, 0
	s_add_i32 s58, s64, s2
	global_load_lds_dwordx4 v[136:137], off
	v_lshl_add_u64 v[136:137], s[62:63], 0, v[140:141]
	s_mov_b32 m0, s58
	s_nop 0
	global_load_lds_dwordx4 v[136:137], off
	v_lshl_add_u64 v[136:137], s[62:63], 0, v[144:145]
	s_add_i32 m0, s58, 0x2000
	s_nop 0
	global_load_lds_dwordx4 v[136:137], off
	v_lshl_add_u64 v[136:137], v[192:193], 0, s[26:27]
	s_mov_b32 m0, s14
	s_nop 0
	global_load_lds_dwordx4 v[136:137], off
	v_lshl_add_u64 v[136:137], v[232:233], 0, s[26:27]
	s_mov_b32 m0, s15
	s_nop 0
	global_load_lds_dwordx4 v[136:137], off
	s_waitcnt vmcnt(8)
	s_waitcnt lgkmcnt(0)
	s_barrier
	s_setprio 1
	v_mfma_f32_16x16x32_bf16 v[60:63], v[128:131], v[180:183], v[60:63]
	v_mfma_f32_16x16x32_bf16 v[56:59], v[150:153], v[180:183], v[56:59]
	v_mfma_f32_16x16x32_bf16 v[44:47], v[128:131], v[188:191], v[44:47]
	v_mfma_f32_16x16x32_bf16 v[40:43], v[150:153], v[188:191], v[40:43]
	v_mfma_f32_16x16x32_bf16 v[28:31], v[128:131], v[204:207], v[28:31]
	v_mfma_f32_16x16x32_bf16 v[24:27], v[150:153], v[204:207], v[24:27]
	v_mfma_f32_16x16x32_bf16 v[12:15], v[128:131], v[212:215], v[12:15]
	v_mfma_f32_16x16x32_bf16 v[8:11], v[150:153], v[212:215], v[8:11]
	v_mfma_f32_16x16x32_bf16 v[60:63], v[132:135], v[184:187], v[60:63]
	v_mfma_f32_16x16x32_bf16 v[56:59], v[154:157], v[184:187], v[56:59]
	v_mfma_f32_16x16x32_bf16 v[44:47], v[132:135], v[200:203], v[44:47]
	v_mfma_f32_16x16x32_bf16 v[40:43], v[154:157], v[200:203], v[40:43]
	v_mfma_f32_16x16x32_bf16 v[28:31], v[132:135], v[208:211], v[28:31]
	v_mfma_f32_16x16x32_bf16 v[24:27], v[154:157], v[208:211], v[24:27]
	v_mfma_f32_16x16x32_bf16 v[12:15], v[132:135], v[228:231], v[12:15]
	v_mfma_f32_16x16x32_bf16 v[8:11], v[154:157], v[228:231], v[8:11]
	v_mfma_f32_16x16x32_bf16 v[52:55], v[158:161], v[180:183], v[52:55]
	v_mfma_f32_16x16x32_bf16 v[48:51], v[172:175], v[180:183], v[48:51]
	v_mfma_f32_16x16x32_bf16 v[36:39], v[158:161], v[188:191], v[36:39]
	v_mfma_f32_16x16x32_bf16 v[32:35], v[172:175], v[188:191], v[32:35]
	v_mfma_f32_16x16x32_bf16 v[20:23], v[158:161], v[204:207], v[20:23]
	v_mfma_f32_16x16x32_bf16 v[16:19], v[172:175], v[204:207], v[16:19]
	v_mfma_f32_16x16x32_bf16 v[4:7], v[158:161], v[212:215], v[4:7]
	v_mfma_f32_16x16x32_bf16 v[0:3], v[172:175], v[212:215], v[0:3]
	v_mfma_f32_16x16x32_bf16 v[52:55], v[162:165], v[184:187], v[52:55]
	v_mfma_f32_16x16x32_bf16 v[48:51], v[176:179], v[184:187], v[48:51]
	v_mfma_f32_16x16x32_bf16 v[36:39], v[162:165], v[200:203], v[36:39]
	v_mfma_f32_16x16x32_bf16 v[32:35], v[176:179], v[200:203], v[32:35]
	v_mfma_f32_16x16x32_bf16 v[20:23], v[162:165], v[208:211], v[20:23]
	v_mfma_f32_16x16x32_bf16 v[16:19], v[176:179], v[208:211], v[16:19]
	v_mfma_f32_16x16x32_bf16 v[4:7], v[162:165], v[228:231], v[4:7]
	v_mfma_f32_16x16x32_bf16 v[0:3], v[176:179], v[228:231], v[0:3]
	s_setprio 0
	s_barrier
	s_add_u32 s84, s84, 0x100
	s_addc_u32 s85, s85, 0
	s_add_u32 s45, s45, 0x100
	s_addc_u32 s55, s55, 0
	s_cmp_ge_i32 s59, s11
	s_mov_b32 s58, s59
	s_cbranch_scc0 .LBB0_929

; #define PG8_STAGE(bufoff, gbase, voff) do { _Pragma("unroll") for (int _i = 0; _i < 2; ++_i) \
;         __builtin_amdgcn_global_load_lds((const unsigned*)((const char*)(gbase) + (voff)[_i]), (PG8_LAS unsigned*)(lds + (bufoff) + ldsw + _i * 8192), 16, 0, 0); } while (0)
; #define PG8_LDA(dst, b, h) do { _Pragma("unroll") for (int m = 0; m < 4; ++m) _Pragma("unroll") for (int k = 0; k < 2; ++k) dst[m][k] = *(const PG8_LAS bf16x8*)(lds + PG8_SA(b, h) + aoff + m * 2048 + k * 1024); } while (0)
; #define PG8_LDB(dst, b, h) do { _Pragma("unroll") for (int n = 0; n < 2; ++n) _Pragma("unroll") for (int k = 0; k < 2; ++k) dst[n][k] = *(const PG8_LAS bf16x8*)(lds + PG8_SB(b, h) + boff + n * 2048 + k * 1024); } while (0)
; #define PG8_MMA(ai, bj, At, Bt) do { __builtin_amdgcn_s_setprio(1); _Pragma("unroll") for (int m = 0; m < 4; ++m) _Pragma("unroll") for (int n = 0; n < 2; ++n) _Pragma("unroll") for (int k = 0; k < 2; ++k) \
;         acc[ai][bj][m][n] = __builtin_amdgcn_mfma_f32_16x16x32_bf16(Bt[n][k], At[m][k], acc[ai][bj][m][n], 0, 0, 0); __builtin_amdgcn_s_setprio(0); } while (0)
; #define PG8_WAIT_V(n) asm volatile("s_waitcnt vmcnt(" #n ")" ::: "memory")
; #define PG8_WAIT_L(n) asm volatile("s_waitcnt lgkmcnt(" #n ")" ::: "memory")
; template <class Epi, class Sched, bool ALIGN_EPI = false, bool SP2 = false>
; __device__ __forceinline__ void gemm_phase(PG8_LAS unsigned char* lds, const Gemm g, const Sched& S, const Epi& E) {
;     ...
;             const bool last = (t == nt - 2);
;             const char* a1 = cA + (size_t)(t + 1) * kstep;
;             const char* a2 = last ? nA : cA + (size_t)(t + 2) * kstep; const char* b2 = last ? nB : cB + (size_t)(t + 2) * kstep;
;             const char* a3 = a2 + kstep; const char* b3 = b2 + kstep;
;             if (last && has_next) S.a_ready(nxt);
;             if constexpr (SP2) {
;             PG8_LDB(B0, 0, 0); PG8_LDB(B1, 0, 1); PG8_SCHED; PG8_LDA(At, 0, 0); PG8_STAGE(PG8_SA(1, 1), a1 + hstepA, voffA);
;             PG8_WAIT_V(8); PG8_WAIT_L(0); PG8_BAR; PG8_MMA(0, 0, At, B0); PG8_MMA(0, 1, At, B1); PG8_BAR; PG8_SCHED;
;             PG8_LDA(At, 0, 1); PG8_STAGE(PG8_SB(0, 0), b2, voffB); PG8_STAGE(PG8_SB(0, 1), b2 + hstepB, voffB); PG8_STAGE(PG8_SA(0, 0), a2, voffA);
;             PG8_WAIT_V(8); PG8_WAIT_L(0); PG8_BAR; PG8_MMA(1, 0, At, B0); PG8_MMA(1, 1, At, B1); PG8_BAR; PG8_SCHED;
.LBB0_1019:
	s_add_i32 s64, s62, 2
	s_add_u32 s63, s84, 0xfffc0080
	s_addc_u32 s69, s85, -1
	s_add_i32 s74, 0, 0x10000
	s_cmp_eq_u32 s33, s62
	s_cselect_b32 s87, s49, s69
	s_cselect_b32 s86, s53, s63
	s_cselect_b32 s63, s55, s61
	s_cselect_b32 s62, s58, s59
	s_add_i32 s69, 0, 0x14000
	v_add_u32_e32 v156, s74, v142
	v_add_u32_e32 v172, s69, v142
	ds_read_b128 v[144:147], v156
	ds_read_b128 v[148:151], v156 offset:1024
	ds_read_b128 v[152:155], v156 offset:2048
	ds_read_b128 v[156:159], v156 offset:3072
	ds_read_b128 v[160:163], v172
	ds_read_b128 v[164:167], v172 offset:1024
	ds_read_b128 v[168:171], v172 offset:2048
	ds_read_b128 v[172:175], v172 offset:3072
	v_lshl_add_u64 v[192:193], s[84:85], 0, v[136:137]
	s_add_i32 m0, s11, 0xc000
	ds_read_b128 v[176:179], v143
	ds_read_b128 v[180:183], v143 offset:1024
	ds_read_b128 v[184:187], v143 offset:2048
	ds_read_b128 v[188:191], v143 offset:3072
	ds_read_b128 v[200:203], v143 offset:4096
	ds_read_b128 v[204:207], v143 offset:5120
	ds_read_b128 v[208:211], v143 offset:6144
	ds_read_b128 v[212:215], v143 offset:7168
	global_load_lds_dwordx4 v[192:193], off
	v_lshl_add_u64 v[192:193], s[84:85], 0, v[138:139]
	s_add_i32 m0, s11, 0xe000
	s_nop 0
	global_load_lds_dwordx4 v[192:193], off
	s_waitcnt vmcnt(8)
	s_waitcnt lgkmcnt(0)
	s_barrier
	s_setprio 1
	v_mfma_f32_16x16x32_bf16 v[120:123], v[144:147], v[176:179], v[120:123]
	v_mfma_f32_16x16x32_bf16 v[124:127], v[152:155], v[176:179], v[124:127]
	v_mfma_f32_16x16x32_bf16 v[116:119], v[144:147], v[184:187], v[116:119]
	v_mfma_f32_16x16x32_bf16 v[112:115], v[152:155], v[184:187], v[112:115]
	v_mfma_f32_16x16x32_bf16 v[108:111], v[144:147], v[200:203], v[108:111]
	v_mfma_f32_16x16x32_bf16 v[104:107], v[152:155], v[200:203], v[104:107]
	v_mfma_f32_16x16x32_bf16 v[100:103], v[144:147], v[208:211], v[100:103]
	v_mfma_f32_16x16x32_bf16 v[96:99], v[152:155], v[208:211], v[96:99]
	v_mfma_f32_16x16x32_bf16 v[120:123], v[148:151], v[180:183], v[120:123]
	v_mfma_f32_16x16x32_bf16 v[124:127], v[156:159], v[180:183], v[124:127]
	v_mfma_f32_16x16x32_bf16 v[116:119], v[148:151], v[188:191], v[116:119]
	v_mfma_f32_16x16x32_bf16 v[112:115], v[156:159], v[188:191], v[112:115]
	v_mfma_f32_16x16x32_bf16 v[108:111], v[148:151], v[204:207], v[108:111]
	v_mfma_f32_16x16x32_bf16 v[104:107], v[156:159], v[204:207], v[104:107]
	v_mfma_f32_16x16x32_bf16 v[100:103], v[148:151], v[212:215], v[100:103]
	v_mfma_f32_16x16x32_bf16 v[96:99], v[156:159], v[212:215], v[96:99]
	v_mfma_f32_16x16x32_bf16 v[60:63], v[160:163], v[176:179], v[60:63]
	v_mfma_f32_16x16x32_bf16 v[56:59], v[168:171], v[176:179], v[56:59]
	v_mfma_f32_16x16x32_bf16 v[52:55], v[160:163], v[184:187], v[52:55]
	v_mfma_f32_16x16x32_bf16 v[48:51], v[168:171], v[184:187], v[48:51]
	v_mfma_f32_16x16x32_bf16 v[44:47], v[160:163], v[200:203], v[44:47]
	v_mfma_f32_16x16x32_bf16 v[40:43], v[168:171], v[200:203], v[40:43]
	v_mfma_f32_16x16x32_bf16 v[36:39], v[160:163], v[208:211], v[36:39]
	v_mfma_f32_16x16x32_bf16 v[32:35], v[168:171], v[208:211], v[32:35]
	v_mfma_f32_16x16x32_bf16 v[60:63], v[164:167], v[180:183], v[60:63]
	v_mfma_f32_16x16x32_bf16 v[56:59], v[172:175], v[180:183], v[56:59]
	v_mfma_f32_16x16x32_bf16 v[52:55], v[164:167], v[188:191], v[52:55]
	v_mfma_f32_16x16x32_bf16 v[48:51], v[172:175], v[188:191], v[48:51]
	v_mfma_f32_16x16x32_bf16 v[44:47], v[164:167], v[204:207], v[44:47]
	v_mfma_f32_16x16x32_bf16 v[40:43], v[172:175], v[204:207], v[40:43]
	v_mfma_f32_16x16x32_bf16 v[36:39], v[164:167], v[212:215], v[36:39]
	v_mfma_f32_16x16x32_bf16 v[32:35], v[172:175], v[212:215], v[32:35]
	s_setprio 0
	s_barrier
	s_add_i32 s74, s74, s2
	v_lshl_add_u64 v[192:193], s[62:63], 0, v[132:133]
	s_mov_b32 m0, s74
	ds_read_b128 v[176:179], v143 offset:16384
	ds_read_b128 v[180:183], v143 offset:17408
	ds_read_b128 v[184:187], v143 offset:18432
	ds_read_b128 v[188:191], v143 offset:19456
	ds_read_b128 v[200:203], v143 offset:20480
	ds_read_b128 v[204:207], v143 offset:21504
	ds_read_b128 v[208:211], v143 offset:22528
	ds_read_b128 v[212:215], v143 offset:23552
	global_load_lds_dwordx4 v[192:193], off
	s_add_i32 m0, s74, 0x2000
	s_add_u32 s78, s62, 0x40000
	v_lshl_add_u64 v[228:229], s[62:63], 0, v[128:129]
	s_addc_u32 s79, s63, 0
	s_add_i32 s69, s69, s2
	global_load_lds_dwordx4 v[228:229], off
	v_lshl_add_u64 v[230:231], s[78:79], 0, v[132:133]
	s_mov_b32 m0, s69
	v_lshl_add_u64 v[232:233], s[86:87], 0, v[130:131]
	global_load_lds_dwordx4 v[230:231], off
	v_lshl_add_u64 v[230:231], s[78:79], 0, v[128:129]
	s_add_i32 m0, s69, 0x2000
	s_nop 0
	global_load_lds_dwordx4 v[230:231], off
	v_lshl_add_u64 v[230:231], s[86:87], 0, v[134:135]
	s_mov_b32 m0, s11
	s_nop 0
	global_load_lds_dwordx4 v[230:231], off
	s_mov_b32 m0, s12
	s_nop 0
	global_load_lds_dwordx4 v[232:233], off
	s_waitcnt vmcnt(8)
	s_waitcnt lgkmcnt(0)
	s_barrier
; #define PG8_STAGE(bufoff, gbase, voff) do { _Pragma("unroll") for (int _i = 0; _i < 2; ++_i) \
;         __builtin_amdgcn_global_load_lds((const unsigned*)((const char*)(gbase) + (voff)[_i]), (PG8_LAS unsigned*)(lds + (bufoff) + ldsw + _i * 8192), 16, 0, 0); } while (0)
; #define PG8_LDA(dst, b, h) do { _Pragma("unroll") for (int m = 0; m < 4; ++m) _Pragma("unroll") for (int k = 0; k < 2; ++k) dst[m][k] = *(const PG8_LAS bf16x8*)(lds + PG8_SA(b, h) + aoff + m * 2048 + k * 1024); } while (0)
; #define PG8_LDB(dst, b, h) do { _Pragma("unroll") for (int n = 0; n < 2; ++n) _Pragma("unroll") for (int k = 0; k < 2; ++k) dst[n][k] = *(const PG8_LAS bf16x8*)(lds + PG8_SB(b, h) + boff + n * 2048 + k * 1024); } while (0)
; #define PG8_MMA(ai, bj, At, Bt) do { __builtin_amdgcn_s_setprio(1); _Pragma("unroll") for (int m = 0; m < 4; ++m) _Pragma("unroll") for (int n = 0; n < 2; ++n) _Pragma("unroll") for (int k = 0; k < 2; ++k) \
;         acc[ai][bj][m][n] = __builtin_amdgcn_mfma_f32_16x16x32_bf16(Bt[n][k], At[m][k], acc[ai][bj][m][n], 0, 0, 0); __builtin_amdgcn_s_setprio(0); } while (0)
; #define PG8_WAIT_V(n) asm volatile("s_waitcnt vmcnt(" #n ")" ::: "memory")
; #define PG8_WAIT_L(n) asm volatile("s_waitcnt lgkmcnt(" #n ")" ::: "memory")
; #define PG8_BAR __builtin_amdgcn_s_barrier()
; #define PG8_SCHED __builtin_amdgcn_sched_barrier(0)
; template <class Epi, class Sched, bool ALIGN_EPI = false, bool SP2 = false>
; __device__ __forceinline__ void gemm_phase(PG8_LAS unsigned char* lds, const Gemm g, const Sched& S, const Epi& E) {
;     ...
;             PG8_WAIT_V(8); PG8_WAIT_L(0); PG8_BAR; PG8_MMA(1, 0, At, B0); PG8_MMA(1, 1, At, B1); PG8_BAR; PG8_SCHED;
;             PG8_LDB(B0, 1, 0); PG8_LDB(B1, 1, 1); PG8_SCHED; PG8_LDA(At, 1, 0); PG8_STAGE(PG8_SA(0, 1), a2 + hstepA, voffA);
;             PG8_WAIT_V(8); PG8_WAIT_L(0); PG8_BAR; PG8_MMA(0, 0, At, B0); PG8_MMA(0, 1, At, B1); PG8_BAR; PG8_SCHED;
	s_setprio 1
	v_mfma_f32_16x16x32_bf16 v[92:95], v[144:147], v[176:179], v[92:95]
	v_mfma_f32_16x16x32_bf16 v[88:91], v[152:155], v[176:179], v[88:91]
	v_mfma_f32_16x16x32_bf16 v[84:87], v[144:147], v[184:187], v[84:87]
	v_mfma_f32_16x16x32_bf16 v[80:83], v[152:155], v[184:187], v[80:83]
	v_mfma_f32_16x16x32_bf16 v[76:79], v[144:147], v[200:203], v[76:79]
	v_mfma_f32_16x16x32_bf16 v[72:75], v[152:155], v[200:203], v[72:75]
	v_mfma_f32_16x16x32_bf16 v[68:71], v[144:147], v[208:211], v[68:71]
	v_mfma_f32_16x16x32_bf16 v[64:67], v[152:155], v[208:211], v[64:67]
	v_mfma_f32_16x16x32_bf16 v[92:95], v[148:151], v[180:183], v[92:95]
	v_mfma_f32_16x16x32_bf16 v[88:91], v[156:159], v[180:183], v[88:91]
	v_mfma_f32_16x16x32_bf16 v[84:87], v[148:151], v[188:191], v[84:87]
	v_mfma_f32_16x16x32_bf16 v[80:83], v[156:159], v[188:191], v[80:83]
	v_mfma_f32_16x16x32_bf16 v[76:79], v[148:151], v[204:207], v[76:79]
	v_mfma_f32_16x16x32_bf16 v[72:75], v[156:159], v[204:207], v[72:75]
	v_mfma_f32_16x16x32_bf16 v[68:71], v[148:151], v[212:215], v[68:71]
	v_mfma_f32_16x16x32_bf16 v[64:67], v[156:159], v[212:215], v[64:67]
	v_mfma_f32_16x16x32_bf16 v[28:31], v[160:163], v[176:179], v[28:31]
	v_mfma_f32_16x16x32_bf16 v[24:27], v[168:171], v[176:179], v[24:27]
	v_mfma_f32_16x16x32_bf16 v[20:23], v[160:163], v[184:187], v[20:23]
	v_mfma_f32_16x16x32_bf16 v[16:19], v[168:171], v[184:187], v[16:19]
	v_mfma_f32_16x16x32_bf16 v[12:15], v[160:163], v[200:203], v[12:15]
	v_mfma_f32_16x16x32_bf16 v[8:11], v[168:171], v[200:203], v[8:11]
	v_mfma_f32_16x16x32_bf16 v[4:7], v[160:163], v[208:211], v[4:7]
	v_mfma_f32_16x16x32_bf16 v[0:3], v[168:171], v[208:211], v[0:3]
	v_mfma_f32_16x16x32_bf16 v[28:31], v[164:167], v[180:183], v[28:31]
	v_mfma_f32_16x16x32_bf16 v[24:27], v[172:175], v[180:183], v[24:27]
	v_mfma_f32_16x16x32_bf16 v[20:23], v[164:167], v[188:191], v[20:23]
	v_mfma_f32_16x16x32_bf16 v[16:19], v[172:175], v[188:191], v[16:19]
	v_mfma_f32_16x16x32_bf16 v[12:15], v[164:167], v[204:207], v[12:15]
	v_mfma_f32_16x16x32_bf16 v[8:11], v[172:175], v[204:207], v[8:11]
	v_mfma_f32_16x16x32_bf16 v[4:7], v[164:167], v[212:215], v[4:7]
	v_mfma_f32_16x16x32_bf16 v[0:3], v[172:175], v[212:215], v[0:3]
	s_setprio 0
	s_barrier
	s_add_i32 s69, 0, 0x18000
	s_add_i32 s74, 0, 0x1c000
	v_add_u32_e32 v156, s69, v142
	v_add_u32_e32 v172, s74, v142
	ds_read_b128 v[144:147], v156
	ds_read_b128 v[148:151], v156 offset:1024
	ds_read_b128 v[152:155], v156 offset:2048
	ds_read_b128 v[156:159], v156 offset:3072
	ds_read_b128 v[160:163], v172
	ds_read_b128 v[164:167], v172 offset:1024
	ds_read_b128 v[168:171], v172 offset:2048
	ds_read_b128 v[172:175], v172 offset:3072
	s_add_u32 s78, s86, 0x40000
	s_addc_u32 s79, s87, 0
	s_mov_b32 m0, s13
	v_lshl_add_u64 v[234:235], s[78:79], 0, v[134:135]
	ds_read_b128 v[176:179], v143 offset:32768
	ds_read_b128 v[180:183], v143 offset:33792
	ds_read_b128 v[184:187], v143 offset:34816
	ds_read_b128 v[188:191], v143 offset:35840
	ds_read_b128 v[200:203], v143 offset:36864
	ds_read_b128 v[204:207], v143 offset:37888
	ds_read_b128 v[208:211], v143 offset:38912
	ds_read_b128 v[212:215], v143 offset:39936
	global_load_lds_dwordx4 v[234:235], off
	v_lshl_add_u64 v[234:235], s[78:79], 0, v[130:131]
	s_mov_b32 m0, s14
	s_nop 0
	global_load_lds_dwordx4 v[234:235], off
	s_waitcnt vmcnt(8)
	s_waitcnt lgkmcnt(0)
	s_barrier
	s_setprio 1
	v_mfma_f32_16x16x32_bf16 v[120:123], v[144:147], v[176:179], v[120:123]
	v_mfma_f32_16x16x32_bf16 v[124:127], v[152:155], v[176:179], v[124:127]
	v_mfma_f32_16x16x32_bf16 v[116:119], v[144:147], v[184:187], v[116:119]
	v_mfma_f32_16x16x32_bf16 v[112:115], v[152:155], v[184:187], v[112:115]
	v_mfma_f32_16x16x32_bf16 v[108:111], v[144:147], v[200:203], v[108:111]
	v_mfma_f32_16x16x32_bf16 v[104:107], v[152:155], v[200:203], v[104:107]
	v_mfma_f32_16x16x32_bf16 v[100:103], v[144:147], v[208:211], v[100:103]
	v_mfma_f32_16x16x32_bf16 v[96:99], v[152:155], v[208:211], v[96:99]
	v_mfma_f32_16x16x32_bf16 v[120:123], v[148:151], v[180:183], v[120:123]
	v_mfma_f32_16x16x32_bf16 v[124:127], v[156:159], v[180:183], v[124:127]
	v_mfma_f32_16x16x32_bf16 v[116:119], v[148:151], v[188:191], v[116:119]
	v_mfma_f32_16x16x32_bf16 v[112:115], v[156:159], v[188:191], v[112:115]
	v_mfma_f32_16x16x32_bf16 v[108:111], v[148:151], v[204:207], v[108:111]
	v_mfma_f32_16x16x32_bf16 v[104:107], v[156:159], v[204:207], v[104:107]
	v_mfma_f32_16x16x32_bf16 v[100:103], v[148:151], v[212:215], v[100:103]
	v_mfma_f32_16x16x32_bf16 v[96:99], v[156:159], v[212:215], v[96:99]
	v_mfma_f32_16x16x32_bf16 v[60:63], v[160:163], v[176:179], v[60:63]
	v_mfma_f32_16x16x32_bf16 v[56:59], v[168:171], v[176:179], v[56:59]
	v_mfma_f32_16x16x32_bf16 v[52:55], v[160:163], v[184:187], v[52:55]
	v_mfma_f32_16x16x32_bf16 v[48:51], v[168:171], v[184:187], v[48:51]
	v_mfma_f32_16x16x32_bf16 v[44:47], v[160:163], v[200:203], v[44:47]
	v_mfma_f32_16x16x32_bf16 v[40:43], v[168:171], v[200:203], v[40:43]
	v_mfma_f32_16x16x32_bf16 v[36:39], v[160:163], v[208:211], v[36:39]
	v_mfma_f32_16x16x32_bf16 v[32:35], v[168:171], v[208:211], v[32:35]
	v_mfma_f32_16x16x32_bf16 v[60:63], v[164:167], v[180:183], v[60:63]
	v_mfma_f32_16x16x32_bf16 v[56:59], v[172:175], v[180:183], v[56:59]
	v_mfma_f32_16x16x32_bf16 v[52:55], v[164:167], v[188:191], v[52:55]
	v_mfma_f32_16x16x32_bf16 v[48:51], v[172:175], v[188:191], v[48:51]
	v_mfma_f32_16x16x32_bf16 v[44:47], v[164:167], v[204:207], v[44:47]
	v_mfma_f32_16x16x32_bf16 v[40:43], v[172:175], v[204:207], v[40:43]
	v_mfma_f32_16x16x32_bf16 v[36:39], v[164:167], v[212:215], v[36:39]
	v_mfma_f32_16x16x32_bf16 v[32:35], v[172:175], v[212:215], v[32:35]
	s_setprio 0
	s_barrier
; #define PG8_STAGE(bufoff, gbase, voff) do { _Pragma("unroll") for (int _i = 0; _i < 2; ++_i) \
;         __builtin_amdgcn_global_load_lds((const unsigned*)((const char*)(gbase) + (voff)[_i]), (PG8_LAS unsigned*)(lds + (bufoff) + ldsw + _i * 8192), 16, 0, 0); } while (0)
; #define PG8_LDA(dst, b, h) do { _Pragma("unroll") for (int m = 0; m < 4; ++m) _Pragma("unroll") for (int k = 0; k < 2; ++k) dst[m][k] = *(const PG8_LAS bf16x8*)(lds + PG8_SA(b, h) + aoff + m * 2048 + k * 1024); } while (0)
; #define PG8_MMA(ai, bj, At, Bt) do { __builtin_amdgcn_s_setprio(1); _Pragma("unroll") for (int m = 0; m < 4; ++m) _Pragma("unroll") for (int n = 0; n < 2; ++n) _Pragma("unroll") for (int k = 0; k < 2; ++k) \
;         acc[ai][bj][m][n] = __builtin_amdgcn_mfma_f32_16x16x32_bf16(Bt[n][k], At[m][k], acc[ai][bj][m][n], 0, 0, 0); __builtin_amdgcn_s_setprio(0); } while (0)
; #define PG8_WAIT_V(n) asm volatile("s_waitcnt vmcnt(" #n ")" ::: "memory")
; #define PG8_WAIT_L(n) asm volatile("s_waitcnt lgkmcnt(" #n ")" ::: "memory")
; #define PG8_BAR __builtin_amdgcn_s_barrier()
; #define PG8_SCHED __builtin_amdgcn_sched_barrier(0)
; template <class Epi, class Sched, bool ALIGN_EPI = false, bool SP2 = false>
; __device__ __forceinline__ void gemm_phase(PG8_LAS unsigned char* lds, const Gemm g, const Sched& S, const Epi& E) {
;     ...
;         for (int t = 0; t < nt; t += 2) {
;     ...
;             PG8_LDA(At, 1, 1); PG8_STAGE(PG8_SB(1, 0), b3, voffB); PG8_STAGE(PG8_SB(1, 1), b3 + hstepB, voffB); PG8_STAGE(PG8_SA(1, 0), a3, voffA);
;             PG8_WAIT_V(8); PG8_WAIT_L(0); PG8_BAR; PG8_MMA(1, 0, At, B0); PG8_MMA(1, 1, At, B1); PG8_BAR; PG8_SCHED;
	s_add_i32 s69, s69, s2
	v_lshl_add_u64 v[192:193], v[192:193], 0, s[26:27]
	s_mov_b32 m0, s69
	ds_read_b128 v[176:179], v143 offset:49152
	ds_read_b128 v[180:183], v143 offset:50176
	ds_read_b128 v[184:187], v143 offset:51200
	ds_read_b128 v[188:191], v143 offset:52224
	ds_read_b128 v[200:203], v143 offset:53248
	ds_read_b128 v[204:207], v143 offset:54272
	ds_read_b128 v[208:211], v143 offset:55296
	ds_read_b128 v[212:215], v143 offset:56320
	global_load_lds_dwordx4 v[192:193], off
	s_add_i32 m0, s69, 0x2000
	s_add_u32 s62, s62, 0x40080
	v_lshl_add_u64 v[192:193], v[228:229], 0, s[26:27]
	s_addc_u32 s63, s63, 0
	s_add_i32 s69, s74, s2
	global_load_lds_dwordx4 v[192:193], off
	v_lshl_add_u64 v[192:193], s[62:63], 0, v[132:133]
	s_mov_b32 m0, s69
	s_nop 0
	global_load_lds_dwordx4 v[192:193], off
	v_lshl_add_u64 v[192:193], s[62:63], 0, v[128:129]
	s_add_i32 m0, s69, 0x2000
	s_nop 0
	global_load_lds_dwordx4 v[192:193], off
	v_lshl_add_u64 v[192:193], v[230:231], 0, s[26:27]
	s_mov_b32 m0, s28
	s_nop 0
	global_load_lds_dwordx4 v[192:193], off
	v_lshl_add_u64 v[192:193], v[232:233], 0, s[26:27]
	s_mov_b32 m0, s29
	s_nop 0
	global_load_lds_dwordx4 v[192:193], off
	s_waitcnt vmcnt(8)
	s_waitcnt lgkmcnt(0)
	s_barrier
	s_setprio 1
	v_mfma_f32_16x16x32_bf16 v[92:95], v[144:147], v[176:179], v[92:95]
	v_mfma_f32_16x16x32_bf16 v[88:91], v[152:155], v[176:179], v[88:91]
	v_mfma_f32_16x16x32_bf16 v[84:87], v[144:147], v[184:187], v[84:87]
	v_mfma_f32_16x16x32_bf16 v[80:83], v[152:155], v[184:187], v[80:83]
	v_mfma_f32_16x16x32_bf16 v[76:79], v[144:147], v[200:203], v[76:79]
	v_mfma_f32_16x16x32_bf16 v[72:75], v[152:155], v[200:203], v[72:75]
	v_mfma_f32_16x16x32_bf16 v[68:71], v[144:147], v[208:211], v[68:71]
	v_mfma_f32_16x16x32_bf16 v[64:67], v[152:155], v[208:211], v[64:67]
	v_mfma_f32_16x16x32_bf16 v[92:95], v[148:151], v[180:183], v[92:95]
	v_mfma_f32_16x16x32_bf16 v[88:91], v[156:159], v[180:183], v[88:91]
	v_mfma_f32_16x16x32_bf16 v[84:87], v[148:151], v[188:191], v[84:87]
	v_mfma_f32_16x16x32_bf16 v[80:83], v[156:159], v[188:191], v[80:83]
	v_mfma_f32_16x16x32_bf16 v[76:79], v[148:151], v[204:207], v[76:79]
	v_mfma_f32_16x16x32_bf16 v[72:75], v[156:159], v[204:207], v[72:75]
	v_mfma_f32_16x16x32_bf16 v[68:71], v[148:151], v[212:215], v[68:71]
	v_mfma_f32_16x16x32_bf16 v[64:67], v[156:159], v[212:215], v[64:67]
	v_mfma_f32_16x16x32_bf16 v[28:31], v[160:163], v[176:179], v[28:31]
	v_mfma_f32_16x16x32_bf16 v[24:27], v[168:171], v[176:179], v[24:27]
	v_mfma_f32_16x16x32_bf16 v[20:23], v[160:163], v[184:187], v[20:23]
	v_mfma_f32_16x16x32_bf16 v[16:19], v[168:171], v[184:187], v[16:19]
	v_mfma_f32_16x16x32_bf16 v[12:15], v[160:163], v[200:203], v[12:15]
	v_mfma_f32_16x16x32_bf16 v[8:11], v[168:171], v[200:203], v[8:11]
	v_mfma_f32_16x16x32_bf16 v[4:7], v[160:163], v[208:211], v[4:7]
	v_mfma_f32_16x16x32_bf16 v[0:3], v[168:171], v[208:211], v[0:3]
	v_mfma_f32_16x16x32_bf16 v[28:31], v[164:167], v[180:183], v[28:31]
	v_mfma_f32_16x16x32_bf16 v[24:27], v[172:175], v[180:183], v[24:27]
	v_mfma_f32_16x16x32_bf16 v[20:23], v[164:167], v[188:191], v[20:23]
	v_mfma_f32_16x16x32_bf16 v[16:19], v[172:175], v[188:191], v[16:19]
	v_mfma_f32_16x16x32_bf16 v[12:15], v[164:167], v[204:207], v[12:15]
	v_mfma_f32_16x16x32_bf16 v[8:11], v[172:175], v[204:207], v[8:11]
	v_mfma_f32_16x16x32_bf16 v[4:7], v[164:167], v[212:215], v[4:7]
	v_mfma_f32_16x16x32_bf16 v[0:3], v[172:175], v[212:215], v[0:3]
	s_setprio 0
	s_barrier
	s_add_u32 s84, s84, 0x100
	s_addc_u32 s85, s85, 0
	s_add_u32 s59, s59, 0x100
	s_addc_u32 s61, s61, 0
	s_cmp_ge_i32 s64, s15
	s_mov_b32 s62, s64
	s_cbranch_scc0 .LBB0_1019

; #define PG8_STAGE(bufoff, gbase, voff) do { _Pragma("unroll") for (int _i = 0; _i < 2; ++_i) \
;         __builtin_amdgcn_global_load_lds((const unsigned*)((const char*)(gbase) + (voff)[_i]), (PG8_LAS unsigned*)(lds + (bufoff) + ldsw + _i * 8192), 16, 0, 0); } while (0)
; #define PG8_LDA(dst, b, h) do { _Pragma("unroll") for (int m = 0; m < 4; ++m) _Pragma("unroll") for (int k = 0; k < 2; ++k) dst[m][k] = *(const PG8_LAS bf16x8*)(lds + PG8_SA(b, h) + aoff + m * 2048 + k * 1024); } while (0)
; #define PG8_LDB(dst, b, h) do { _Pragma("unroll") for (int n = 0; n < 2; ++n) _Pragma("unroll") for (int k = 0; k < 2; ++k) dst[n][k] = *(const PG8_LAS bf16x8*)(lds + PG8_SB(b, h) + boff + n * 2048 + k * 1024); } while (0)
; #define PG8_MMA(ai, bj, At, Bt) do { __builtin_amdgcn_s_setprio(1); _Pragma("unroll") for (int m = 0; m < 4; ++m) _Pragma("unroll") for (int n = 0; n < 2; ++n) _Pragma("unroll") for (int k = 0; k < 2; ++k) \
;         acc[ai][bj][m][n] = __builtin_amdgcn_mfma_f32_16x16x32_bf16(Bt[n][k], At[m][k], acc[ai][bj][m][n], 0, 0, 0); __builtin_amdgcn_s_setprio(0); } while (0)
; #define PG8_WAIT_V(n) asm volatile("s_waitcnt vmcnt(" #n ")" ::: "memory")
; #define PG8_WAIT_L(n) asm volatile("s_waitcnt lgkmcnt(" #n ")" ::: "memory")
; template <class Epi, class Sched, bool ALIGN_EPI = false, bool SP2 = false>
; __device__ __forceinline__ void gemm_phase(PG8_LAS unsigned char* lds, const Gemm g, const Sched& S, const Epi& E) {
;     ...
;             const bool last = (t == nt - 2);
;             const char* a1 = cA + (size_t)(t + 1) * kstep;
;             const char* a2 = last ? nA : cA + (size_t)(t + 2) * kstep; const char* b2 = last ? nB : cB + (size_t)(t + 2) * kstep;
;             const char* a3 = a2 + kstep; const char* b3 = b2 + kstep;
;             if (last && has_next) S.a_ready(nxt);
;             if constexpr (SP2) {
;             PG8_LDB(B0, 0, 0); PG8_LDB(B1, 0, 1); PG8_SCHED; PG8_LDA(At, 0, 0); PG8_STAGE(PG8_SA(1, 1), a1 + hstepA, voffA);
;             PG8_WAIT_V(8); PG8_WAIT_L(0); PG8_BAR; PG8_MMA(0, 0, At, B0); PG8_MMA(0, 1, At, B1); PG8_BAR; PG8_SCHED;
;             PG8_LDA(At, 0, 1); PG8_STAGE(PG8_SB(0, 0), b2, voffB); PG8_STAGE(PG8_SB(0, 1), b2 + hstepB, voffB); PG8_STAGE(PG8_SA(0, 0), a2, voffA);
;             PG8_WAIT_V(8); PG8_WAIT_L(0); PG8_BAR; PG8_MMA(1, 0, At, B0); PG8_MMA(1, 1, At, B1); PG8_BAR; PG8_SCHED;
.LBB0_1218:
	s_add_i32 s79, s44, 2
	s_add_u32 s83, s42, 0x80
	s_addc_u32 s45, s43, 0
	s_add_i32 s74, 0, 0x10000
	s_cmp_eq_u32 s15, s44
	s_cselect_b32 s45, s35, s45
	s_cselect_b32 s44, s41, s83
	s_cselect_b32 vcc_hi, s61, s69
	s_cselect_b32 vcc_lo, s62, s63
	s_add_i32 s75, 0, 0x14000
	v_add_u32_e32 v150, s74, v178
	v_add_u32_e32 v166, s75, v178
	ds_read_b128 v[128:131], v150
	ds_read_b128 v[132:135], v150 offset:1024
	ds_read_b128 v[146:149], v150 offset:2048
	ds_read_b128 v[150:153], v150 offset:3072
	ds_read_b128 v[154:157], v166
	ds_read_b128 v[158:161], v166 offset:1024
	ds_read_b128 v[162:165], v166 offset:2048
	ds_read_b128 v[166:169], v166 offset:3072
	v_lshl_add_u64 v[174:175], s[42:43], 0, v[142:143]
	s_add_i32 m0, s85, 0xc000
	ds_read_b128 v[170:173], v179
	ds_read_b128 v[180:183], v179 offset:1024
	ds_read_b128 v[184:187], v179 offset:2048
	ds_read_b128 v[188:191], v179 offset:3072
	ds_read_b128 v[200:203], v179 offset:4096
	ds_read_b128 v[204:207], v179 offset:5120
	ds_read_b128 v[208:211], v179 offset:6144
	ds_read_b128 v[212:215], v179 offset:7168
	global_load_lds_dwordx4 v[174:175], off
	v_lshl_add_u64 v[174:175], s[42:43], 0, v[144:145]
	s_add_i32 m0, s85, 0xe000
	s_nop 0
	global_load_lds_dwordx4 v[174:175], off
	s_waitcnt vmcnt(8)
	s_waitcnt lgkmcnt(0)
	s_barrier
	s_setprio 1
	v_mfma_f32_16x16x32_bf16 v[120:123], v[128:131], v[170:173], v[120:123]
	v_mfma_f32_16x16x32_bf16 v[124:127], v[146:149], v[170:173], v[124:127]
	v_mfma_f32_16x16x32_bf16 v[108:111], v[128:131], v[184:187], v[108:111]
	v_mfma_f32_16x16x32_bf16 v[104:107], v[146:149], v[184:187], v[104:107]
	v_mfma_f32_16x16x32_bf16 v[92:95], v[128:131], v[200:203], v[92:95]
	v_mfma_f32_16x16x32_bf16 v[88:91], v[146:149], v[200:203], v[88:91]
	v_mfma_f32_16x16x32_bf16 v[76:79], v[128:131], v[208:211], v[76:79]
	v_mfma_f32_16x16x32_bf16 v[72:75], v[146:149], v[208:211], v[72:75]
	v_mfma_f32_16x16x32_bf16 v[120:123], v[132:135], v[180:183], v[120:123]
	v_mfma_f32_16x16x32_bf16 v[124:127], v[150:153], v[180:183], v[124:127]
	v_mfma_f32_16x16x32_bf16 v[108:111], v[132:135], v[188:191], v[108:111]
	v_mfma_f32_16x16x32_bf16 v[104:107], v[150:153], v[188:191], v[104:107]
	v_mfma_f32_16x16x32_bf16 v[92:95], v[132:135], v[204:207], v[92:95]
	v_mfma_f32_16x16x32_bf16 v[88:91], v[150:153], v[204:207], v[88:91]
	v_mfma_f32_16x16x32_bf16 v[76:79], v[132:135], v[212:215], v[76:79]
	v_mfma_f32_16x16x32_bf16 v[72:75], v[150:153], v[212:215], v[72:75]
	v_mfma_f32_16x16x32_bf16 v[116:119], v[154:157], v[170:173], v[116:119]
	v_mfma_f32_16x16x32_bf16 v[112:115], v[162:165], v[170:173], v[112:115]
	v_mfma_f32_16x16x32_bf16 v[100:103], v[154:157], v[184:187], v[100:103]
	v_mfma_f32_16x16x32_bf16 v[96:99], v[162:165], v[184:187], v[96:99]
	v_mfma_f32_16x16x32_bf16 v[84:87], v[154:157], v[200:203], v[84:87]
	v_mfma_f32_16x16x32_bf16 v[80:83], v[162:165], v[200:203], v[80:83]
	v_mfma_f32_16x16x32_bf16 v[68:71], v[154:157], v[208:211], v[68:71]
	v_mfma_f32_16x16x32_bf16 v[64:67], v[162:165], v[208:211], v[64:67]
	v_mfma_f32_16x16x32_bf16 v[116:119], v[158:161], v[180:183], v[116:119]
	v_mfma_f32_16x16x32_bf16 v[112:115], v[166:169], v[180:183], v[112:115]
	v_mfma_f32_16x16x32_bf16 v[100:103], v[158:161], v[188:191], v[100:103]
	v_mfma_f32_16x16x32_bf16 v[96:99], v[166:169], v[188:191], v[96:99]
	v_mfma_f32_16x16x32_bf16 v[84:87], v[158:161], v[204:207], v[84:87]
	v_mfma_f32_16x16x32_bf16 v[80:83], v[166:169], v[204:207], v[80:83]
	v_mfma_f32_16x16x32_bf16 v[68:71], v[158:161], v[212:215], v[68:71]
	v_mfma_f32_16x16x32_bf16 v[64:67], v[166:169], v[212:215], v[64:67]
	s_setprio 0
	s_barrier
	s_add_i32 s74, s74, s8
	v_lshl_add_u64 v[174:175], vcc, 0, v[194:195]
	s_mov_b32 m0, s74
	ds_read_b128 v[170:173], v179 offset:16384
	ds_read_b128 v[180:183], v179 offset:17408
	ds_read_b128 v[184:187], v179 offset:18432
	ds_read_b128 v[188:191], v179 offset:19456
	ds_read_b128 v[200:203], v179 offset:20480
	ds_read_b128 v[204:207], v179 offset:21504
	ds_read_b128 v[208:211], v179 offset:22528
	ds_read_b128 v[212:215], v179 offset:23552
	global_load_lds_dwordx4 v[174:175], off
	s_add_i32 m0, s74, 0x2000
	v_lshl_add_u64 v[192:193], vcc, 0, v[140:141]
	s_add_u32 vcc_lo, vcc_lo, s82
	s_addc_u32 vcc_hi, vcc_hi, 0
	s_add_i32 s74, s75, s8
	global_load_lds_dwordx4 v[192:193], off
	v_lshl_add_u64 v[228:229], vcc, 0, v[194:195]
	s_mov_b32 m0, s74
	v_lshl_add_u64 v[230:231], vcc, 0, v[140:141]
	global_load_lds_dwordx4 v[228:229], off
	s_add_i32 m0, s74, 0x2000
	v_lshl_add_u64 v[232:233], s[44:45], 0, v[136:137]
	global_load_lds_dwordx4 v[230:231], off
	s_mov_b32 m0, s85
	v_lshl_add_u64 v[234:235], s[44:45], 0, v[138:139]
	global_load_lds_dwordx4 v[232:233], off
	s_mov_b32 m0, s10
	s_nop 0
	global_load_lds_dwordx4 v[234:235], off
	s_waitcnt vmcnt(8)
	s_waitcnt lgkmcnt(0)
	s_barrier
; #define PG8_STAGE(bufoff, gbase, voff) do { _Pragma("unroll") for (int _i = 0; _i < 2; ++_i) \
;         __builtin_amdgcn_global_load_lds((const unsigned*)((const char*)(gbase) + (voff)[_i]), (PG8_LAS unsigned*)(lds + (bufoff) + ldsw + _i * 8192), 16, 0, 0); } while (0)
; #define PG8_LDA(dst, b, h) do { _Pragma("unroll") for (int m = 0; m < 4; ++m) _Pragma("unroll") for (int k = 0; k < 2; ++k) dst[m][k] = *(const PG8_LAS bf16x8*)(lds + PG8_SA(b, h) + aoff + m * 2048 + k * 1024); } while (0)
; #define PG8_LDB(dst, b, h) do { _Pragma("unroll") for (int n = 0; n < 2; ++n) _Pragma("unroll") for (int k = 0; k < 2; ++k) dst[n][k] = *(const PG8_LAS bf16x8*)(lds + PG8_SB(b, h) + boff + n * 2048 + k * 1024); } while (0)
; #define PG8_MMA(ai, bj, At, Bt) do { __builtin_amdgcn_s_setprio(1); _Pragma("unroll") for (int m = 0; m < 4; ++m) _Pragma("unroll") for (int n = 0; n < 2; ++n) _Pragma("unroll") for (int k = 0; k < 2; ++k) \
;         acc[ai][bj][m][n] = __builtin_amdgcn_mfma_f32_16x16x32_bf16(Bt[n][k], At[m][k], acc[ai][bj][m][n], 0, 0, 0); __builtin_amdgcn_s_setprio(0); } while (0)
; #define PG8_WAIT_V(n) asm volatile("s_waitcnt vmcnt(" #n ")" ::: "memory")
; #define PG8_WAIT_L(n) asm volatile("s_waitcnt lgkmcnt(" #n ")" ::: "memory")
; #define PG8_BAR __builtin_amdgcn_s_barrier()
; #define PG8_SCHED __builtin_amdgcn_sched_barrier(0)
; template <class Epi, class Sched, bool ALIGN_EPI = false, bool SP2 = false>
; __device__ __forceinline__ void gemm_phase(PG8_LAS unsigned char* lds, const Gemm g, const Sched& S, const Epi& E) {
;     ...
;             PG8_WAIT_V(8); PG8_WAIT_L(0); PG8_BAR; PG8_MMA(1, 0, At, B0); PG8_MMA(1, 1, At, B1); PG8_BAR; PG8_SCHED;
;             PG8_LDB(B0, 1, 0); PG8_LDB(B1, 1, 1); PG8_SCHED; PG8_LDA(At, 1, 0); PG8_STAGE(PG8_SA(0, 1), a2 + hstepA, voffA);
;             PG8_WAIT_V(8); PG8_WAIT_L(0); PG8_BAR; PG8_MMA(0, 0, At, B0); PG8_MMA(0, 1, At, B1); PG8_BAR; PG8_SCHED;
	s_setprio 1
	v_mfma_f32_16x16x32_bf16 v[60:63], v[128:131], v[170:173], v[60:63]
	v_mfma_f32_16x16x32_bf16 v[56:59], v[146:149], v[170:173], v[56:59]
	v_mfma_f32_16x16x32_bf16 v[44:47], v[128:131], v[184:187], v[44:47]
	v_mfma_f32_16x16x32_bf16 v[40:43], v[146:149], v[184:187], v[40:43]
	v_mfma_f32_16x16x32_bf16 v[28:31], v[128:131], v[200:203], v[28:31]
	v_mfma_f32_16x16x32_bf16 v[24:27], v[146:149], v[200:203], v[24:27]
	v_mfma_f32_16x16x32_bf16 v[12:15], v[128:131], v[208:211], v[12:15]
	v_mfma_f32_16x16x32_bf16 v[8:11], v[146:149], v[208:211], v[8:11]
	v_mfma_f32_16x16x32_bf16 v[60:63], v[132:135], v[180:183], v[60:63]
	v_mfma_f32_16x16x32_bf16 v[56:59], v[150:153], v[180:183], v[56:59]
	v_mfma_f32_16x16x32_bf16 v[44:47], v[132:135], v[188:191], v[44:47]
	v_mfma_f32_16x16x32_bf16 v[40:43], v[150:153], v[188:191], v[40:43]
	v_mfma_f32_16x16x32_bf16 v[28:31], v[132:135], v[204:207], v[28:31]
	v_mfma_f32_16x16x32_bf16 v[24:27], v[150:153], v[204:207], v[24:27]
	v_mfma_f32_16x16x32_bf16 v[12:15], v[132:135], v[212:215], v[12:15]
	v_mfma_f32_16x16x32_bf16 v[8:11], v[150:153], v[212:215], v[8:11]
	v_mfma_f32_16x16x32_bf16 v[52:55], v[154:157], v[170:173], v[52:55]
	v_mfma_f32_16x16x32_bf16 v[48:51], v[162:165], v[170:173], v[48:51]
	v_mfma_f32_16x16x32_bf16 v[36:39], v[154:157], v[184:187], v[36:39]
	v_mfma_f32_16x16x32_bf16 v[32:35], v[162:165], v[184:187], v[32:35]
	v_mfma_f32_16x16x32_bf16 v[20:23], v[154:157], v[200:203], v[20:23]
	v_mfma_f32_16x16x32_bf16 v[16:19], v[162:165], v[200:203], v[16:19]
	v_mfma_f32_16x16x32_bf16 v[4:7], v[154:157], v[208:211], v[4:7]
	v_mfma_f32_16x16x32_bf16 v[0:3], v[162:165], v[208:211], v[0:3]
	v_mfma_f32_16x16x32_bf16 v[52:55], v[158:161], v[180:183], v[52:55]
	v_mfma_f32_16x16x32_bf16 v[48:51], v[166:169], v[180:183], v[48:51]
	v_mfma_f32_16x16x32_bf16 v[36:39], v[158:161], v[188:191], v[36:39]
	v_mfma_f32_16x16x32_bf16 v[32:35], v[166:169], v[188:191], v[32:35]
	v_mfma_f32_16x16x32_bf16 v[20:23], v[158:161], v[204:207], v[20:23]
	v_mfma_f32_16x16x32_bf16 v[16:19], v[166:169], v[204:207], v[16:19]
	v_mfma_f32_16x16x32_bf16 v[4:7], v[158:161], v[212:215], v[4:7]
	v_mfma_f32_16x16x32_bf16 v[0:3], v[166:169], v[212:215], v[0:3]
	s_setprio 0
	s_barrier
	s_add_i32 s74, 0, 0x18000
	s_add_i32 s75, 0, 0x1c000
	v_add_u32_e32 v150, s74, v178
	v_add_u32_e32 v166, s75, v178
	ds_read_b128 v[128:131], v150
	ds_read_b128 v[132:135], v150 offset:1024
	ds_read_b128 v[146:149], v150 offset:2048
	ds_read_b128 v[150:153], v150 offset:3072
	ds_read_b128 v[154:157], v166
	ds_read_b128 v[158:161], v166 offset:1024
	ds_read_b128 v[162:165], v166 offset:2048
	ds_read_b128 v[166:169], v166 offset:3072
	s_add_u32 s44, s44, s82
	s_addc_u32 s45, s45, 0
	s_mov_b32 m0, s11
	v_lshl_add_u64 v[236:237], s[44:45], 0, v[136:137]
	ds_read_b128 v[170:173], v179 offset:32768
	ds_read_b128 v[180:183], v179 offset:33792
	ds_read_b128 v[184:187], v179 offset:34816
	ds_read_b128 v[188:191], v179 offset:35840
	ds_read_b128 v[200:203], v179 offset:36864
	ds_read_b128 v[204:207], v179 offset:37888
	ds_read_b128 v[208:211], v179 offset:38912
	ds_read_b128 v[212:215], v179 offset:39936
	global_load_lds_dwordx4 v[236:237], off
	v_lshl_add_u64 v[236:237], s[44:45], 0, v[138:139]
	s_mov_b32 m0, s12
	s_nop 0
	global_load_lds_dwordx4 v[236:237], off
	s_waitcnt vmcnt(8)
	s_waitcnt lgkmcnt(0)
	s_barrier
	s_setprio 1
	v_mfma_f32_16x16x32_bf16 v[120:123], v[128:131], v[170:173], v[120:123]
	v_mfma_f32_16x16x32_bf16 v[124:127], v[146:149], v[170:173], v[124:127]
	v_mfma_f32_16x16x32_bf16 v[108:111], v[128:131], v[184:187], v[108:111]
	v_mfma_f32_16x16x32_bf16 v[104:107], v[146:149], v[184:187], v[104:107]
	v_mfma_f32_16x16x32_bf16 v[92:95], v[128:131], v[200:203], v[92:95]
	v_mfma_f32_16x16x32_bf16 v[88:91], v[146:149], v[200:203], v[88:91]
	v_mfma_f32_16x16x32_bf16 v[76:79], v[128:131], v[208:211], v[76:79]
	v_mfma_f32_16x16x32_bf16 v[72:75], v[146:149], v[208:211], v[72:75]
	v_mfma_f32_16x16x32_bf16 v[120:123], v[132:135], v[180:183], v[120:123]
	v_mfma_f32_16x16x32_bf16 v[124:127], v[150:153], v[180:183], v[124:127]
	v_mfma_f32_16x16x32_bf16 v[108:111], v[132:135], v[188:191], v[108:111]
	v_mfma_f32_16x16x32_bf16 v[104:107], v[150:153], v[188:191], v[104:107]
	v_mfma_f32_16x16x32_bf16 v[92:95], v[132:135], v[204:207], v[92:95]
	v_mfma_f32_16x16x32_bf16 v[88:91], v[150:153], v[204:207], v[88:91]
	v_mfma_f32_16x16x32_bf16 v[76:79], v[132:135], v[212:215], v[76:79]
	v_mfma_f32_16x16x32_bf16 v[72:75], v[150:153], v[212:215], v[72:75]
	v_mfma_f32_16x16x32_bf16 v[116:119], v[154:157], v[170:173], v[116:119]
	v_mfma_f32_16x16x32_bf16 v[112:115], v[162:165], v[170:173], v[112:115]
	v_mfma_f32_16x16x32_bf16 v[100:103], v[154:157], v[184:187], v[100:103]
	v_mfma_f32_16x16x32_bf16 v[96:99], v[162:165], v[184:187], v[96:99]
	v_mfma_f32_16x16x32_bf16 v[84:87], v[154:157], v[200:203], v[84:87]
	v_mfma_f32_16x16x32_bf16 v[80:83], v[162:165], v[200:203], v[80:83]
	v_mfma_f32_16x16x32_bf16 v[68:71], v[154:157], v[208:211], v[68:71]
	v_mfma_f32_16x16x32_bf16 v[64:67], v[162:165], v[208:211], v[64:67]
	v_mfma_f32_16x16x32_bf16 v[116:119], v[158:161], v[180:183], v[116:119]
	v_mfma_f32_16x16x32_bf16 v[112:115], v[166:169], v[180:183], v[112:115]
	v_mfma_f32_16x16x32_bf16 v[100:103], v[158:161], v[188:191], v[100:103]
	v_mfma_f32_16x16x32_bf16 v[96:99], v[166:169], v[188:191], v[96:99]
	v_mfma_f32_16x16x32_bf16 v[84:87], v[158:161], v[204:207], v[84:87]
	v_mfma_f32_16x16x32_bf16 v[80:83], v[166:169], v[204:207], v[80:83]
	v_mfma_f32_16x16x32_bf16 v[68:71], v[158:161], v[212:215], v[68:71]
	v_mfma_f32_16x16x32_bf16 v[64:67], v[166:169], v[212:215], v[64:67]
	s_setprio 0
	s_barrier
; #define PG8_STAGE(bufoff, gbase, voff) do { _Pragma("unroll") for (int _i = 0; _i < 2; ++_i) \
;         __builtin_amdgcn_global_load_lds((const unsigned*)((const char*)(gbase) + (voff)[_i]), (PG8_LAS unsigned*)(lds + (bufoff) + ldsw + _i * 8192), 16, 0, 0); } while (0)
; #define PG8_LDA(dst, b, h) do { _Pragma("unroll") for (int m = 0; m < 4; ++m) _Pragma("unroll") for (int k = 0; k < 2; ++k) dst[m][k] = *(const PG8_LAS bf16x8*)(lds + PG8_SA(b, h) + aoff + m * 2048 + k * 1024); } while (0)
; #define PG8_MMA(ai, bj, At, Bt) do { __builtin_amdgcn_s_setprio(1); _Pragma("unroll") for (int m = 0; m < 4; ++m) _Pragma("unroll") for (int n = 0; n < 2; ++n) _Pragma("unroll") for (int k = 0; k < 2; ++k) \
;         acc[ai][bj][m][n] = __builtin_amdgcn_mfma_f32_16x16x32_bf16(Bt[n][k], At[m][k], acc[ai][bj][m][n], 0, 0, 0); __builtin_amdgcn_s_setprio(0); } while (0)
; #define PG8_WAIT_V(n) asm volatile("s_waitcnt vmcnt(" #n ")" ::: "memory")
; #define PG8_WAIT_L(n) asm volatile("s_waitcnt lgkmcnt(" #n ")" ::: "memory")
; #define PG8_BAR __builtin_amdgcn_s_barrier()
; #define PG8_SCHED __builtin_amdgcn_sched_barrier(0)
; template <class Epi, class Sched, bool ALIGN_EPI = false, bool SP2 = false>
; __device__ __forceinline__ void gemm_phase(PG8_LAS unsigned char* lds, const Gemm g, const Sched& S, const Epi& E) {
;     ...
;         for (int t = 0; t < nt; t += 2) {
;     ...
;             PG8_LDA(At, 1, 1); PG8_STAGE(PG8_SB(1, 0), b3, voffB); PG8_STAGE(PG8_SB(1, 1), b3 + hstepB, voffB); PG8_STAGE(PG8_SA(1, 0), a3, voffA);
;             PG8_WAIT_V(8); PG8_WAIT_L(0); PG8_BAR; PG8_MMA(1, 0, At, B0); PG8_MMA(1, 1, At, B1); PG8_BAR; PG8_SCHED;
	s_add_i32 s44, s74, s8
	v_lshl_add_u64 v[174:175], v[174:175], 0, s[26:27]
	s_mov_b32 m0, s44
	ds_read_b128 v[170:173], v179 offset:49152
	ds_read_b128 v[180:183], v179 offset:50176
	ds_read_b128 v[184:187], v179 offset:51200
	ds_read_b128 v[188:191], v179 offset:52224
	ds_read_b128 v[200:203], v179 offset:53248
	ds_read_b128 v[204:207], v179 offset:54272
	ds_read_b128 v[208:211], v179 offset:55296
	ds_read_b128 v[212:215], v179 offset:56320
	global_load_lds_dwordx4 v[174:175], off
	v_lshl_add_u64 v[174:175], v[192:193], 0, s[26:27]
	s_add_i32 m0, s44, 0x2000
	s_add_i32 s44, s75, s8
	global_load_lds_dwordx4 v[174:175], off
	v_lshl_add_u64 v[174:175], v[228:229], 0, s[26:27]
	s_mov_b32 m0, s44
	s_nop 0
	global_load_lds_dwordx4 v[174:175], off
	v_lshl_add_u64 v[174:175], v[230:231], 0, s[26:27]
	s_add_i32 m0, s44, 0x2000
	s_nop 0
	global_load_lds_dwordx4 v[174:175], off
	v_lshl_add_u64 v[174:175], v[232:233], 0, s[26:27]
	s_mov_b32 m0, s64
	s_nop 0
	global_load_lds_dwordx4 v[174:175], off
	v_lshl_add_u64 v[174:175], v[234:235], 0, s[26:27]
	s_mov_b32 m0, s14
	s_nop 0
	global_load_lds_dwordx4 v[174:175], off
	s_waitcnt vmcnt(8)
	s_waitcnt lgkmcnt(0)
	s_barrier
	s_setprio 1
	v_mfma_f32_16x16x32_bf16 v[60:63], v[128:131], v[170:173], v[60:63]
	v_mfma_f32_16x16x32_bf16 v[56:59], v[146:149], v[170:173], v[56:59]
	v_mfma_f32_16x16x32_bf16 v[44:47], v[128:131], v[184:187], v[44:47]
	v_mfma_f32_16x16x32_bf16 v[40:43], v[146:149], v[184:187], v[40:43]
	v_mfma_f32_16x16x32_bf16 v[28:31], v[128:131], v[200:203], v[28:31]
	v_mfma_f32_16x16x32_bf16 v[24:27], v[146:149], v[200:203], v[24:27]
	v_mfma_f32_16x16x32_bf16 v[12:15], v[128:131], v[208:211], v[12:15]
	v_mfma_f32_16x16x32_bf16 v[8:11], v[146:149], v[208:211], v[8:11]
	v_mfma_f32_16x16x32_bf16 v[60:63], v[132:135], v[180:183], v[60:63]
	v_mfma_f32_16x16x32_bf16 v[56:59], v[150:153], v[180:183], v[56:59]
	v_mfma_f32_16x16x32_bf16 v[44:47], v[132:135], v[188:191], v[44:47]
	v_mfma_f32_16x16x32_bf16 v[40:43], v[150:153], v[188:191], v[40:43]
	v_mfma_f32_16x16x32_bf16 v[28:31], v[132:135], v[204:207], v[28:31]
	v_mfma_f32_16x16x32_bf16 v[24:27], v[150:153], v[204:207], v[24:27]
	v_mfma_f32_16x16x32_bf16 v[12:15], v[132:135], v[212:215], v[12:15]
	v_mfma_f32_16x16x32_bf16 v[8:11], v[150:153], v[212:215], v[8:11]
	v_mfma_f32_16x16x32_bf16 v[52:55], v[154:157], v[170:173], v[52:55]
	v_mfma_f32_16x16x32_bf16 v[48:51], v[162:165], v[170:173], v[48:51]
	v_mfma_f32_16x16x32_bf16 v[36:39], v[154:157], v[184:187], v[36:39]
	v_mfma_f32_16x16x32_bf16 v[32:35], v[162:165], v[184:187], v[32:35]
	v_mfma_f32_16x16x32_bf16 v[20:23], v[154:157], v[200:203], v[20:23]
	v_mfma_f32_16x16x32_bf16 v[16:19], v[162:165], v[200:203], v[16:19]
	v_mfma_f32_16x16x32_bf16 v[4:7], v[154:157], v[208:211], v[4:7]
	v_mfma_f32_16x16x32_bf16 v[0:3], v[162:165], v[208:211], v[0:3]
	v_mfma_f32_16x16x32_bf16 v[52:55], v[158:161], v[180:183], v[52:55]
	v_mfma_f32_16x16x32_bf16 v[48:51], v[166:169], v[180:183], v[48:51]
	v_mfma_f32_16x16x32_bf16 v[36:39], v[158:161], v[188:191], v[36:39]
	v_mfma_f32_16x16x32_bf16 v[32:35], v[166:169], v[188:191], v[32:35]
	v_mfma_f32_16x16x32_bf16 v[20:23], v[158:161], v[204:207], v[20:23]
	v_mfma_f32_16x16x32_bf16 v[16:19], v[166:169], v[204:207], v[16:19]
	v_mfma_f32_16x16x32_bf16 v[4:7], v[158:161], v[212:215], v[4:7]
	v_mfma_f32_16x16x32_bf16 v[0:3], v[166:169], v[212:215], v[0:3]
	s_setprio 0
	s_barrier
	s_add_u32 s42, s42, 0x100
	s_addc_u32 s43, s43, 0
	s_add_u32 s63, s63, 0x100
	s_addc_u32 s69, s69, 0
	s_cmp_ge_i32 s79, s13
	s_mov_b32 s44, s79
	s_cbranch_scc0 .LBB0_1218

; #define PG8_STAGE(bufoff, gbase, voff) do { _Pragma("unroll") for (int _i = 0; _i < 2; ++_i) \
;         __builtin_amdgcn_global_load_lds((const unsigned*)((const char*)(gbase) + (voff)[_i]), (PG8_LAS unsigned*)(lds + (bufoff) + ldsw + _i * 8192), 16, 0, 0); } while (0)
; #define PG8_LDA(dst, b, h) do { _Pragma("unroll") for (int m = 0; m < 4; ++m) _Pragma("unroll") for (int k = 0; k < 2; ++k) dst[m][k] = *(const PG8_LAS bf16x8*)(lds + PG8_SA(b, h) + aoff + m * 2048 + k * 1024); } while (0)
; #define PG8_LDB(dst, b, h) do { _Pragma("unroll") for (int n = 0; n < 2; ++n) _Pragma("unroll") for (int k = 0; k < 2; ++k) dst[n][k] = *(const PG8_LAS bf16x8*)(lds + PG8_SB(b, h) + boff + n * 2048 + k * 1024); } while (0)
; #define PG8_MMA(ai, bj, At, Bt) do { __builtin_amdgcn_s_setprio(1); _Pragma("unroll") for (int m = 0; m < 4; ++m) _Pragma("unroll") for (int n = 0; n < 2; ++n) _Pragma("unroll") for (int k = 0; k < 2; ++k) \
;         acc[ai][bj][m][n] = __builtin_amdgcn_mfma_f32_16x16x32_bf16(Bt[n][k], At[m][k], acc[ai][bj][m][n], 0, 0, 0); __builtin_amdgcn_s_setprio(0); } while (0)
; #define PG8_WAIT_V(n) asm volatile("s_waitcnt vmcnt(" #n ")" ::: "memory")
; #define PG8_WAIT_L(n) asm volatile("s_waitcnt lgkmcnt(" #n ")" ::: "memory")
; template <class Epi, class Sched, bool ALIGN_EPI = false, bool SP2 = false>
; __device__ __forceinline__ void gemm_phase(PG8_LAS unsigned char* lds, const Gemm g, const Sched& S, const Epi& E) {
;     ...
;             const bool last = (t == nt - 2);
;             const char* a1 = cA + (size_t)(t + 1) * kstep;
;             const char* a2 = last ? nA : cA + (size_t)(t + 2) * kstep; const char* b2 = last ? nB : cB + (size_t)(t + 2) * kstep;
;             const char* a3 = a2 + kstep; const char* b3 = b2 + kstep;
;             if (last && has_next) S.a_ready(nxt);
;             if constexpr (SP2) {
;             PG8_LDB(B0, 0, 0); PG8_LDB(B1, 0, 1); PG8_SCHED; PG8_LDA(At, 0, 0); PG8_STAGE(PG8_SA(1, 1), a1 + hstepA, voffA);
;             PG8_WAIT_V(8); PG8_WAIT_L(0); PG8_BAR; PG8_MMA(0, 0, At, B0); PG8_MMA(0, 1, At, B1); PG8_BAR; PG8_SCHED;
;             PG8_LDA(At, 0, 1); PG8_STAGE(PG8_SB(0, 0), b2, voffB); PG8_STAGE(PG8_SB(0, 1), b2 + hstepB, voffB); PG8_STAGE(PG8_SA(0, 0), a2, voffA);
;             PG8_WAIT_V(8); PG8_WAIT_L(0); PG8_BAR; PG8_MMA(1, 0, At, B0); PG8_MMA(1, 1, At, B1); PG8_BAR; PG8_SCHED;
.LBB0_1463:
	s_add_i32 s86, s84, 2
	s_add_u32 s74, s40, 0x80
	s_addc_u32 s75, s41, 0
	s_add_i32 s87, 0, 0x10000
	s_cmp_eq_u32 s29, s84
	s_cselect_b32 s85, s77, s75
	s_cselect_b32 s84, s76, s74
	s_cselect_b32 s89, s83, s79
	s_cselect_b32 s88, s82, s78
	s_add_i32 s74, 0, 0x14000
	v_add_u32_e32 v140, s87, v166
	v_add_u32_e32 v144, s74, v166
	ds_read_b128 v[128:131], v140
	ds_read_b128 v[132:135], v140 offset:1024
	ds_read_b128 v[136:139], v140 offset:2048
	ds_read_b128 v[140:143], v140 offset:3072
	ds_read_b128 v[156:159], v144
	ds_read_b128 v[160:163], v144 offset:1024
	ds_read_b128 v[168:171], v144 offset:2048
	ds_read_b128 v[172:175], v144 offset:3072
	v_lshl_add_u64 v[144:145], s[40:41], 0, v[152:153]
	s_add_i32 m0, s8, 0xc000
	ds_read_b128 v[176:179], v167
	ds_read_b128 v[180:183], v167 offset:1024
	ds_read_b128 v[184:187], v167 offset:2048
	ds_read_b128 v[188:191], v167 offset:3072
	ds_read_b128 v[200:203], v167 offset:4096
	ds_read_b128 v[204:207], v167 offset:5120
	ds_read_b128 v[208:211], v167 offset:6144
	ds_read_b128 v[212:215], v167 offset:7168
	global_load_lds_dwordx4 v[144:145], off
	v_lshl_add_u64 v[144:145], s[40:41], 0, v[154:155]
	s_add_i32 m0, s8, 0xe000
	s_nop 0
	global_load_lds_dwordx4 v[144:145], off
	s_waitcnt vmcnt(8)
	s_waitcnt lgkmcnt(0)
	s_barrier
	s_setprio 1
	v_mfma_f32_16x16x32_bf16 v[124:127], v[128:131], v[176:179], v[124:127]
	v_mfma_f32_16x16x32_bf16 v[120:123], v[136:139], v[176:179], v[120:123]
	v_mfma_f32_16x16x32_bf16 v[116:119], v[128:131], v[184:187], v[116:119]
	v_mfma_f32_16x16x32_bf16 v[112:115], v[136:139], v[184:187], v[112:115]
	v_mfma_f32_16x16x32_bf16 v[108:111], v[128:131], v[200:203], v[108:111]
	v_mfma_f32_16x16x32_bf16 v[104:107], v[136:139], v[200:203], v[104:107]
	v_mfma_f32_16x16x32_bf16 v[100:103], v[128:131], v[208:211], v[100:103]
	v_mfma_f32_16x16x32_bf16 v[96:99], v[136:139], v[208:211], v[96:99]
	v_mfma_f32_16x16x32_bf16 v[124:127], v[132:135], v[180:183], v[124:127]
	v_mfma_f32_16x16x32_bf16 v[120:123], v[140:143], v[180:183], v[120:123]
	v_mfma_f32_16x16x32_bf16 v[116:119], v[132:135], v[188:191], v[116:119]
	v_mfma_f32_16x16x32_bf16 v[112:115], v[140:143], v[188:191], v[112:115]
	v_mfma_f32_16x16x32_bf16 v[108:111], v[132:135], v[204:207], v[108:111]
	v_mfma_f32_16x16x32_bf16 v[104:107], v[140:143], v[204:207], v[104:107]
	v_mfma_f32_16x16x32_bf16 v[100:103], v[132:135], v[212:215], v[100:103]
	v_mfma_f32_16x16x32_bf16 v[96:99], v[140:143], v[212:215], v[96:99]
	v_mfma_f32_16x16x32_bf16 v[60:63], v[156:159], v[176:179], v[60:63]
	v_mfma_f32_16x16x32_bf16 v[56:59], v[168:171], v[176:179], v[56:59]
	v_mfma_f32_16x16x32_bf16 v[52:55], v[156:159], v[184:187], v[52:55]
	v_mfma_f32_16x16x32_bf16 v[48:51], v[168:171], v[184:187], v[48:51]
	v_mfma_f32_16x16x32_bf16 v[44:47], v[156:159], v[200:203], v[44:47]
	v_mfma_f32_16x16x32_bf16 v[40:43], v[168:171], v[200:203], v[40:43]
	v_mfma_f32_16x16x32_bf16 v[36:39], v[156:159], v[208:211], v[36:39]
	v_mfma_f32_16x16x32_bf16 v[32:35], v[168:171], v[208:211], v[32:35]
	v_mfma_f32_16x16x32_bf16 v[60:63], v[160:163], v[180:183], v[60:63]
	v_mfma_f32_16x16x32_bf16 v[56:59], v[172:175], v[180:183], v[56:59]
	v_mfma_f32_16x16x32_bf16 v[52:55], v[160:163], v[188:191], v[52:55]
	v_mfma_f32_16x16x32_bf16 v[48:51], v[172:175], v[188:191], v[48:51]
	v_mfma_f32_16x16x32_bf16 v[44:47], v[160:163], v[204:207], v[44:47]
	v_mfma_f32_16x16x32_bf16 v[40:43], v[172:175], v[204:207], v[40:43]
	v_mfma_f32_16x16x32_bf16 v[36:39], v[160:163], v[212:215], v[36:39]
	v_mfma_f32_16x16x32_bf16 v[32:35], v[172:175], v[212:215], v[32:35]
	s_setprio 0
	s_barrier
	s_add_i32 s75, s87, s3
	v_lshl_add_u64 v[144:145], s[88:89], 0, v[194:195]
	s_mov_b32 m0, s75
	ds_read_b128 v[176:179], v167 offset:16384
	ds_read_b128 v[180:183], v167 offset:17408
	ds_read_b128 v[184:187], v167 offset:18432
	ds_read_b128 v[188:191], v167 offset:19456
	ds_read_b128 v[200:203], v167 offset:20480
	ds_read_b128 v[204:207], v167 offset:21504
	ds_read_b128 v[208:211], v167 offset:22528
	ds_read_b128 v[212:215], v167 offset:23552
	global_load_lds_dwordx4 v[144:145], off
	s_add_i32 m0, s75, 0x2000
	v_lshl_add_u64 v[192:193], s[88:89], 0, v[146:147]
	s_add_u32 s88, s88, s80
	s_addc_u32 s89, s89, 0
	s_add_i32 s74, s74, s3
	global_load_lds_dwordx4 v[192:193], off
	v_lshl_add_u64 v[228:229], s[88:89], 0, v[194:195]
	s_mov_b32 m0, s74
	v_lshl_add_u64 v[230:231], s[88:89], 0, v[146:147]
	global_load_lds_dwordx4 v[228:229], off
	s_add_i32 m0, s74, 0x2000
	v_lshl_add_u64 v[232:233], s[84:85], 0, v[150:151]
	global_load_lds_dwordx4 v[230:231], off
	s_mov_b32 m0, s8
	v_lshl_add_u64 v[234:235], s[84:85], 0, v[148:149]
	global_load_lds_dwordx4 v[232:233], off
	s_mov_b32 m0, s9
	s_nop 0
	global_load_lds_dwordx4 v[234:235], off
	s_waitcnt vmcnt(8)
	s_waitcnt lgkmcnt(0)
	s_barrier
; #define PG8_STAGE(bufoff, gbase, voff) do { _Pragma("unroll") for (int _i = 0; _i < 2; ++_i) \
;         __builtin_amdgcn_global_load_lds((const unsigned*)((const char*)(gbase) + (voff)[_i]), (PG8_LAS unsigned*)(lds + (bufoff) + ldsw + _i * 8192), 16, 0, 0); } while (0)
; #define PG8_LDA(dst, b, h) do { _Pragma("unroll") for (int m = 0; m < 4; ++m) _Pragma("unroll") for (int k = 0; k < 2; ++k) dst[m][k] = *(const PG8_LAS bf16x8*)(lds + PG8_SA(b, h) + aoff + m * 2048 + k * 1024); } while (0)
; #define PG8_LDB(dst, b, h) do { _Pragma("unroll") for (int n = 0; n < 2; ++n) _Pragma("unroll") for (int k = 0; k < 2; ++k) dst[n][k] = *(const PG8_LAS bf16x8*)(lds + PG8_SB(b, h) + boff + n * 2048 + k * 1024); } while (0)
; #define PG8_MMA(ai, bj, At, Bt) do { __builtin_amdgcn_s_setprio(1); _Pragma("unroll") for (int m = 0; m < 4; ++m) _Pragma("unroll") for (int n = 0; n < 2; ++n) _Pragma("unroll") for (int k = 0; k < 2; ++k) \
;         acc[ai][bj][m][n] = __builtin_amdgcn_mfma_f32_16x16x32_bf16(Bt[n][k], At[m][k], acc[ai][bj][m][n], 0, 0, 0); __builtin_amdgcn_s_setprio(0); } while (0)
; #define PG8_WAIT_V(n) asm volatile("s_waitcnt vmcnt(" #n ")" ::: "memory")
; #define PG8_WAIT_L(n) asm volatile("s_waitcnt lgkmcnt(" #n ")" ::: "memory")
; #define PG8_BAR __builtin_amdgcn_s_barrier()
; #define PG8_SCHED __builtin_amdgcn_sched_barrier(0)
; template <class Epi, class Sched, bool ALIGN_EPI = false, bool SP2 = false>
; __device__ __forceinline__ void gemm_phase(PG8_LAS unsigned char* lds, const Gemm g, const Sched& S, const Epi& E) {
;     ...
;             PG8_WAIT_V(8); PG8_WAIT_L(0); PG8_BAR; PG8_MMA(1, 0, At, B0); PG8_MMA(1, 1, At, B1); PG8_BAR; PG8_SCHED;
;             PG8_LDB(B0, 1, 0); PG8_LDB(B1, 1, 1); PG8_SCHED; PG8_LDA(At, 1, 0); PG8_STAGE(PG8_SA(0, 1), a2 + hstepA, voffA);
;             PG8_WAIT_V(8); PG8_WAIT_L(0); PG8_BAR; PG8_MMA(0, 0, At, B0); PG8_MMA(0, 1, At, B1); PG8_BAR; PG8_SCHED;
	s_setprio 1
	v_mfma_f32_16x16x32_bf16 v[92:95], v[128:131], v[176:179], v[92:95]
	v_mfma_f32_16x16x32_bf16 v[88:91], v[136:139], v[176:179], v[88:91]
	v_mfma_f32_16x16x32_bf16 v[84:87], v[128:131], v[184:187], v[84:87]
	v_mfma_f32_16x16x32_bf16 v[80:83], v[136:139], v[184:187], v[80:83]
	v_mfma_f32_16x16x32_bf16 v[76:79], v[128:131], v[200:203], v[76:79]
	v_mfma_f32_16x16x32_bf16 v[72:75], v[136:139], v[200:203], v[72:75]
	v_mfma_f32_16x16x32_bf16 v[68:71], v[128:131], v[208:211], v[68:71]
	v_mfma_f32_16x16x32_bf16 v[64:67], v[136:139], v[208:211], v[64:67]
	v_mfma_f32_16x16x32_bf16 v[92:95], v[132:135], v[180:183], v[92:95]
	v_mfma_f32_16x16x32_bf16 v[88:91], v[140:143], v[180:183], v[88:91]
	v_mfma_f32_16x16x32_bf16 v[84:87], v[132:135], v[188:191], v[84:87]
	v_mfma_f32_16x16x32_bf16 v[80:83], v[140:143], v[188:191], v[80:83]
	v_mfma_f32_16x16x32_bf16 v[76:79], v[132:135], v[204:207], v[76:79]
	v_mfma_f32_16x16x32_bf16 v[72:75], v[140:143], v[204:207], v[72:75]
	v_mfma_f32_16x16x32_bf16 v[68:71], v[132:135], v[212:215], v[68:71]
	v_mfma_f32_16x16x32_bf16 v[64:67], v[140:143], v[212:215], v[64:67]
	v_mfma_f32_16x16x32_bf16 v[28:31], v[156:159], v[176:179], v[28:31]
	v_mfma_f32_16x16x32_bf16 v[24:27], v[168:171], v[176:179], v[24:27]
	v_mfma_f32_16x16x32_bf16 v[20:23], v[156:159], v[184:187], v[20:23]
	v_mfma_f32_16x16x32_bf16 v[16:19], v[168:171], v[184:187], v[16:19]
	v_mfma_f32_16x16x32_bf16 v[12:15], v[156:159], v[200:203], v[12:15]
	v_mfma_f32_16x16x32_bf16 v[8:11], v[168:171], v[200:203], v[8:11]
	v_mfma_f32_16x16x32_bf16 v[4:7], v[156:159], v[208:211], v[4:7]
	v_mfma_f32_16x16x32_bf16 v[0:3], v[168:171], v[208:211], v[0:3]
	v_mfma_f32_16x16x32_bf16 v[28:31], v[160:163], v[180:183], v[28:31]
	v_mfma_f32_16x16x32_bf16 v[24:27], v[172:175], v[180:183], v[24:27]
	v_mfma_f32_16x16x32_bf16 v[20:23], v[160:163], v[188:191], v[20:23]
	v_mfma_f32_16x16x32_bf16 v[16:19], v[172:175], v[188:191], v[16:19]
	v_mfma_f32_16x16x32_bf16 v[12:15], v[160:163], v[204:207], v[12:15]
	v_mfma_f32_16x16x32_bf16 v[8:11], v[172:175], v[204:207], v[8:11]
	v_mfma_f32_16x16x32_bf16 v[4:7], v[160:163], v[212:215], v[4:7]
	v_mfma_f32_16x16x32_bf16 v[0:3], v[172:175], v[212:215], v[0:3]
	s_setprio 0
	s_barrier
	s_add_i32 s74, 0, 0x18000
	s_add_i32 s75, 0, 0x1c000
	v_add_u32_e32 v140, s74, v166
	v_add_u32_e32 v172, s75, v166
	ds_read_b128 v[128:131], v140
	ds_read_b128 v[132:135], v140 offset:1024
	ds_read_b128 v[136:139], v140 offset:2048
	ds_read_b128 v[140:143], v140 offset:3072
	ds_read_b128 v[156:159], v172
	ds_read_b128 v[160:163], v172 offset:1024
	ds_read_b128 v[168:171], v172 offset:2048
	ds_read_b128 v[172:175], v172 offset:3072
	s_add_u32 s84, s84, s80
	s_addc_u32 s85, s85, 0
	s_mov_b32 m0, s10
	v_lshl_add_u64 v[236:237], s[84:85], 0, v[150:151]
	ds_read_b128 v[176:179], v167 offset:32768
	ds_read_b128 v[180:183], v167 offset:33792
	ds_read_b128 v[184:187], v167 offset:34816
	ds_read_b128 v[188:191], v167 offset:35840
	ds_read_b128 v[200:203], v167 offset:36864
	ds_read_b128 v[204:207], v167 offset:37888
	ds_read_b128 v[208:211], v167 offset:38912
	ds_read_b128 v[212:215], v167 offset:39936
	global_load_lds_dwordx4 v[236:237], off
	v_lshl_add_u64 v[236:237], s[84:85], 0, v[148:149]
	s_mov_b32 m0, s11
	s_nop 0
	global_load_lds_dwordx4 v[236:237], off
	s_waitcnt vmcnt(8)
	s_waitcnt lgkmcnt(0)
	s_barrier
	s_setprio 1
	v_mfma_f32_16x16x32_bf16 v[124:127], v[128:131], v[176:179], v[124:127]
	v_mfma_f32_16x16x32_bf16 v[120:123], v[136:139], v[176:179], v[120:123]
	v_mfma_f32_16x16x32_bf16 v[116:119], v[128:131], v[184:187], v[116:119]
	v_mfma_f32_16x16x32_bf16 v[112:115], v[136:139], v[184:187], v[112:115]
	v_mfma_f32_16x16x32_bf16 v[108:111], v[128:131], v[200:203], v[108:111]
	v_mfma_f32_16x16x32_bf16 v[104:107], v[136:139], v[200:203], v[104:107]
	v_mfma_f32_16x16x32_bf16 v[100:103], v[128:131], v[208:211], v[100:103]
	v_mfma_f32_16x16x32_bf16 v[96:99], v[136:139], v[208:211], v[96:99]
	v_mfma_f32_16x16x32_bf16 v[124:127], v[132:135], v[180:183], v[124:127]
	v_mfma_f32_16x16x32_bf16 v[120:123], v[140:143], v[180:183], v[120:123]
	v_mfma_f32_16x16x32_bf16 v[116:119], v[132:135], v[188:191], v[116:119]
	v_mfma_f32_16x16x32_bf16 v[112:115], v[140:143], v[188:191], v[112:115]
	v_mfma_f32_16x16x32_bf16 v[108:111], v[132:135], v[204:207], v[108:111]
	v_mfma_f32_16x16x32_bf16 v[104:107], v[140:143], v[204:207], v[104:107]
	v_mfma_f32_16x16x32_bf16 v[100:103], v[132:135], v[212:215], v[100:103]
	v_mfma_f32_16x16x32_bf16 v[96:99], v[140:143], v[212:215], v[96:99]
	v_mfma_f32_16x16x32_bf16 v[60:63], v[156:159], v[176:179], v[60:63]
	v_mfma_f32_16x16x32_bf16 v[56:59], v[168:171], v[176:179], v[56:59]
	v_mfma_f32_16x16x32_bf16 v[52:55], v[156:159], v[184:187], v[52:55]
	v_mfma_f32_16x16x32_bf16 v[48:51], v[168:171], v[184:187], v[48:51]
	v_mfma_f32_16x16x32_bf16 v[44:47], v[156:159], v[200:203], v[44:47]
	v_mfma_f32_16x16x32_bf16 v[40:43], v[168:171], v[200:203], v[40:43]
	v_mfma_f32_16x16x32_bf16 v[36:39], v[156:159], v[208:211], v[36:39]
	v_mfma_f32_16x16x32_bf16 v[32:35], v[168:171], v[208:211], v[32:35]
	v_mfma_f32_16x16x32_bf16 v[60:63], v[160:163], v[180:183], v[60:63]
	v_mfma_f32_16x16x32_bf16 v[56:59], v[172:175], v[180:183], v[56:59]
	v_mfma_f32_16x16x32_bf16 v[52:55], v[160:163], v[188:191], v[52:55]
	v_mfma_f32_16x16x32_bf16 v[48:51], v[172:175], v[188:191], v[48:51]
	v_mfma_f32_16x16x32_bf16 v[44:47], v[160:163], v[204:207], v[44:47]
	v_mfma_f32_16x16x32_bf16 v[40:43], v[172:175], v[204:207], v[40:43]
	v_mfma_f32_16x16x32_bf16 v[36:39], v[160:163], v[212:215], v[36:39]
	v_mfma_f32_16x16x32_bf16 v[32:35], v[172:175], v[212:215], v[32:35]
	s_setprio 0
	s_barrier
; #define PG8_STAGE(bufoff, gbase, voff) do { _Pragma("unroll") for (int _i = 0; _i < 2; ++_i) \
;         __builtin_amdgcn_global_load_lds((const unsigned*)((const char*)(gbase) + (voff)[_i]), (PG8_LAS unsigned*)(lds + (bufoff) + ldsw + _i * 8192), 16, 0, 0); } while (0)
; #define PG8_LDA(dst, b, h) do { _Pragma("unroll") for (int m = 0; m < 4; ++m) _Pragma("unroll") for (int k = 0; k < 2; ++k) dst[m][k] = *(const PG8_LAS bf16x8*)(lds + PG8_SA(b, h) + aoff + m * 2048 + k * 1024); } while (0)
; #define PG8_MMA(ai, bj, At, Bt) do { __builtin_amdgcn_s_setprio(1); _Pragma("unroll") for (int m = 0; m < 4; ++m) _Pragma("unroll") for (int n = 0; n < 2; ++n) _Pragma("unroll") for (int k = 0; k < 2; ++k) \
;         acc[ai][bj][m][n] = __builtin_amdgcn_mfma_f32_16x16x32_bf16(Bt[n][k], At[m][k], acc[ai][bj][m][n], 0, 0, 0); __builtin_amdgcn_s_setprio(0); } while (0)
; #define PG8_WAIT_V(n) asm volatile("s_waitcnt vmcnt(" #n ")" ::: "memory")
; #define PG8_WAIT_L(n) asm volatile("s_waitcnt lgkmcnt(" #n ")" ::: "memory")
; #define PG8_BAR __builtin_amdgcn_s_barrier()
; #define PG8_SCHED __builtin_amdgcn_sched_barrier(0)
; template <class Epi, class Sched, bool ALIGN_EPI = false, bool SP2 = false>
; __device__ __forceinline__ void gemm_phase(PG8_LAS unsigned char* lds, const Gemm g, const Sched& S, const Epi& E) {
;     ...
;         for (int t = 0; t < nt; t += 2) {
;     ...
;             PG8_LDA(At, 1, 1); PG8_STAGE(PG8_SB(1, 0), b3, voffB); PG8_STAGE(PG8_SB(1, 1), b3 + hstepB, voffB); PG8_STAGE(PG8_SA(1, 0), a3, voffA);
;             PG8_WAIT_V(8); PG8_WAIT_L(0); PG8_BAR; PG8_MMA(1, 0, At, B0); PG8_MMA(1, 1, At, B1); PG8_BAR; PG8_SCHED;
	s_add_i32 s74, s74, s3
	v_lshl_add_u64 v[144:145], v[144:145], 0, s[26:27]
	s_mov_b32 m0, s74
	ds_read_b128 v[176:179], v167 offset:49152
	ds_read_b128 v[180:183], v167 offset:50176
	ds_read_b128 v[184:187], v167 offset:51200
	ds_read_b128 v[188:191], v167 offset:52224
	ds_read_b128 v[200:203], v167 offset:53248
	ds_read_b128 v[204:207], v167 offset:54272
	ds_read_b128 v[208:211], v167 offset:55296
	ds_read_b128 v[212:215], v167 offset:56320
	global_load_lds_dwordx4 v[144:145], off
	v_lshl_add_u64 v[144:145], v[192:193], 0, s[26:27]
	s_add_i32 m0, s74, 0x2000
	s_add_i32 s74, s75, s3
	global_load_lds_dwordx4 v[144:145], off
	v_lshl_add_u64 v[144:145], v[228:229], 0, s[26:27]
	s_mov_b32 m0, s74
	s_nop 0
	global_load_lds_dwordx4 v[144:145], off
	v_lshl_add_u64 v[144:145], v[230:231], 0, s[26:27]
	s_add_i32 m0, s74, 0x2000
	s_nop 0
	global_load_lds_dwordx4 v[144:145], off
	v_lshl_add_u64 v[144:145], v[232:233], 0, s[26:27]
	s_mov_b32 m0, s17
	s_nop 0
	global_load_lds_dwordx4 v[144:145], off
	v_lshl_add_u64 v[144:145], v[234:235], 0, s[26:27]
	s_mov_b32 m0, s28
	s_nop 0
	global_load_lds_dwordx4 v[144:145], off
	s_waitcnt vmcnt(8)
	s_waitcnt lgkmcnt(0)
	s_barrier
	s_setprio 1
	v_mfma_f32_16x16x32_bf16 v[92:95], v[128:131], v[176:179], v[92:95]
	v_mfma_f32_16x16x32_bf16 v[88:91], v[136:139], v[176:179], v[88:91]
	v_mfma_f32_16x16x32_bf16 v[84:87], v[128:131], v[184:187], v[84:87]
	v_mfma_f32_16x16x32_bf16 v[80:83], v[136:139], v[184:187], v[80:83]
	v_mfma_f32_16x16x32_bf16 v[76:79], v[128:131], v[200:203], v[76:79]
	v_mfma_f32_16x16x32_bf16 v[72:75], v[136:139], v[200:203], v[72:75]
	v_mfma_f32_16x16x32_bf16 v[68:71], v[128:131], v[208:211], v[68:71]
	v_mfma_f32_16x16x32_bf16 v[64:67], v[136:139], v[208:211], v[64:67]
	v_mfma_f32_16x16x32_bf16 v[92:95], v[132:135], v[180:183], v[92:95]
	v_mfma_f32_16x16x32_bf16 v[88:91], v[140:143], v[180:183], v[88:91]
	v_mfma_f32_16x16x32_bf16 v[84:87], v[132:135], v[188:191], v[84:87]
	v_mfma_f32_16x16x32_bf16 v[80:83], v[140:143], v[188:191], v[80:83]
	v_mfma_f32_16x16x32_bf16 v[76:79], v[132:135], v[204:207], v[76:79]
	v_mfma_f32_16x16x32_bf16 v[72:75], v[140:143], v[204:207], v[72:75]
	v_mfma_f32_16x16x32_bf16 v[68:71], v[132:135], v[212:215], v[68:71]
	v_mfma_f32_16x16x32_bf16 v[64:67], v[140:143], v[212:215], v[64:67]
	v_mfma_f32_16x16x32_bf16 v[28:31], v[156:159], v[176:179], v[28:31]
	v_mfma_f32_16x16x32_bf16 v[24:27], v[168:171], v[176:179], v[24:27]
	v_mfma_f32_16x16x32_bf16 v[20:23], v[156:159], v[184:187], v[20:23]
	v_mfma_f32_16x16x32_bf16 v[16:19], v[168:171], v[184:187], v[16:19]
	v_mfma_f32_16x16x32_bf16 v[12:15], v[156:159], v[200:203], v[12:15]
	v_mfma_f32_16x16x32_bf16 v[8:11], v[168:171], v[200:203], v[8:11]
	v_mfma_f32_16x16x32_bf16 v[4:7], v[156:159], v[208:211], v[4:7]
	v_mfma_f32_16x16x32_bf16 v[0:3], v[168:171], v[208:211], v[0:3]
	v_mfma_f32_16x16x32_bf16 v[28:31], v[160:163], v[180:183], v[28:31]
	v_mfma_f32_16x16x32_bf16 v[24:27], v[172:175], v[180:183], v[24:27]
	v_mfma_f32_16x16x32_bf16 v[20:23], v[160:163], v[188:191], v[20:23]
	v_mfma_f32_16x16x32_bf16 v[16:19], v[172:175], v[188:191], v[16:19]
	v_mfma_f32_16x16x32_bf16 v[12:15], v[160:163], v[204:207], v[12:15]
	v_mfma_f32_16x16x32_bf16 v[8:11], v[172:175], v[204:207], v[8:11]
	v_mfma_f32_16x16x32_bf16 v[4:7], v[160:163], v[212:215], v[4:7]
	v_mfma_f32_16x16x32_bf16 v[0:3], v[172:175], v[212:215], v[0:3]
	s_setprio 0
	s_barrier
	s_add_u32 s40, s40, 0x100
	s_addc_u32 s41, s41, 0
	s_add_u32 s78, s78, 0x100
	s_addc_u32 s79, s79, 0
	s_cmp_ge_i32 s86, s14
	s_mov_b32 s84, s86
	s_cbranch_scc0 .LBB0_1463

; #define PG8_STAGE(bufoff, gbase, voff) do { _Pragma("unroll") for (int _i = 0; _i < 2; ++_i) \
;         __builtin_amdgcn_global_load_lds((const unsigned*)((const char*)(gbase) + (voff)[_i]), (PG8_LAS unsigned*)(lds + (bufoff) + ldsw + _i * 8192), 16, 0, 0); } while (0)
; #define PG8_LDA(dst, b, h) do { _Pragma("unroll") for (int m = 0; m < 4; ++m) _Pragma("unroll") for (int k = 0; k < 2; ++k) dst[m][k] = *(const PG8_LAS bf16x8*)(lds + PG8_SA(b, h) + aoff + m * 2048 + k * 1024); } while (0)
; #define PG8_LDB(dst, b, h) do { _Pragma("unroll") for (int n = 0; n < 2; ++n) _Pragma("unroll") for (int k = 0; k < 2; ++k) dst[n][k] = *(const PG8_LAS bf16x8*)(lds + PG8_SB(b, h) + boff + n * 2048 + k * 1024); } while (0)
; #define PG8_MMA(ai, bj, At, Bt) do { __builtin_amdgcn_s_setprio(1); _Pragma("unroll") for (int m = 0; m < 4; ++m) _Pragma("unroll") for (int n = 0; n < 2; ++n) _Pragma("unroll") for (int k = 0; k < 2; ++k) \
;         acc[ai][bj][m][n] = __builtin_amdgcn_mfma_f32_16x16x32_bf16(Bt[n][k], At[m][k], acc[ai][bj][m][n], 0, 0, 0); __builtin_amdgcn_s_setprio(0); } while (0)
; #define PG8_WAIT_V(n) asm volatile("s_waitcnt vmcnt(" #n ")" ::: "memory")
; #define PG8_WAIT_L(n) asm volatile("s_waitcnt lgkmcnt(" #n ")" ::: "memory")
; template <class Epi, class Sched, bool ALIGN_EPI = false, bool SP2 = false>
; __device__ __forceinline__ void gemm_phase(PG8_LAS unsigned char* lds, const Gemm g, const Sched& S, const Epi& E) {
;     ...
;             const bool last = (t == nt - 2);
;             const char* a1 = cA + (size_t)(t + 1) * kstep;
;             const char* a2 = last ? nA : cA + (size_t)(t + 2) * kstep; const char* b2 = last ? nB : cB + (size_t)(t + 2) * kstep;
;             const char* a3 = a2 + kstep; const char* b3 = b2 + kstep;
;             if (last && has_next) S.a_ready(nxt);
;             if constexpr (SP2) {
;             PG8_LDB(B0, 0, 0); PG8_LDB(B1, 0, 1); PG8_SCHED; PG8_LDA(At, 0, 0); PG8_STAGE(PG8_SA(1, 1), a1 + hstepA, voffA);
;             PG8_WAIT_V(8); PG8_WAIT_L(0); PG8_BAR; PG8_MMA(0, 0, At, B0); PG8_MMA(0, 1, At, B1); PG8_BAR; PG8_SCHED;
;             PG8_LDA(At, 0, 1); PG8_STAGE(PG8_SB(0, 0), b2, voffB); PG8_STAGE(PG8_SB(0, 1), b2 + hstepB, voffB); PG8_STAGE(PG8_SA(0, 0), a2, voffA);
;             PG8_WAIT_V(8); PG8_WAIT_L(0); PG8_BAR; PG8_MMA(1, 0, At, B0); PG8_MMA(1, 1, At, B1); PG8_BAR; PG8_SCHED;
.LBB0_1493:
	s_add_i32 s81, s79, 2
	s_add_u32 s74, s84, 0x80
	s_addc_u32 s75, s85, 0
	s_add_i32 s90, 0, 0x10000
	s_cmp_eq_u32 s28, s79
	s_cselect_b32 s87, s47, s75
	s_cselect_b32 s86, s46, s74
	s_cselect_b32 s89, s83, s78
	s_cselect_b32 s88, s82, s64
	s_add_i32 s74, 0, 0x14000
	v_add_u32_e32 v140, s90, v164
	v_add_u32_e32 v144, s74, v164
	ds_read_b128 v[128:131], v140
	ds_read_b128 v[132:135], v140 offset:1024
	ds_read_b128 v[136:139], v140 offset:2048
	ds_read_b128 v[140:143], v140 offset:3072
	ds_read_b128 v[156:159], v144
	ds_read_b128 v[166:169], v144 offset:1024
	ds_read_b128 v[170:173], v144 offset:2048
	ds_read_b128 v[174:177], v144 offset:3072
	v_lshl_add_u64 v[144:145], s[84:85], 0, v[152:153]
	s_add_i32 m0, s2, 0xc000
	ds_read_b128 v[178:181], v165
	ds_read_b128 v[182:185], v165 offset:1024
	ds_read_b128 v[186:189], v165 offset:2048
	ds_read_b128 v[190:193], v165 offset:3072
	ds_read_b128 v[200:203], v165 offset:4096
	ds_read_b128 v[204:207], v165 offset:5120
	ds_read_b128 v[208:211], v165 offset:6144
	ds_read_b128 v[212:215], v165 offset:7168
	global_load_lds_dwordx4 v[144:145], off
	v_lshl_add_u64 v[144:145], s[84:85], 0, v[154:155]
	s_add_i32 m0, s2, 0xe000
	s_nop 0
	global_load_lds_dwordx4 v[144:145], off
	s_waitcnt vmcnt(8)
	s_waitcnt lgkmcnt(0)
	s_barrier
	s_setprio 1
	v_mfma_f32_16x16x32_bf16 v[124:127], v[128:131], v[178:181], v[124:127]
	v_mfma_f32_16x16x32_bf16 v[120:123], v[136:139], v[178:181], v[120:123]
	v_mfma_f32_16x16x32_bf16 v[116:119], v[128:131], v[186:189], v[116:119]
	v_mfma_f32_16x16x32_bf16 v[112:115], v[136:139], v[186:189], v[112:115]
	v_mfma_f32_16x16x32_bf16 v[108:111], v[128:131], v[200:203], v[108:111]
	v_mfma_f32_16x16x32_bf16 v[104:107], v[136:139], v[200:203], v[104:107]
	v_mfma_f32_16x16x32_bf16 v[100:103], v[128:131], v[208:211], v[100:103]
	v_mfma_f32_16x16x32_bf16 v[96:99], v[136:139], v[208:211], v[96:99]
	v_mfma_f32_16x16x32_bf16 v[124:127], v[132:135], v[182:185], v[124:127]
	v_mfma_f32_16x16x32_bf16 v[120:123], v[140:143], v[182:185], v[120:123]
	v_mfma_f32_16x16x32_bf16 v[116:119], v[132:135], v[190:193], v[116:119]
	v_mfma_f32_16x16x32_bf16 v[112:115], v[140:143], v[190:193], v[112:115]
	v_mfma_f32_16x16x32_bf16 v[108:111], v[132:135], v[204:207], v[108:111]
	v_mfma_f32_16x16x32_bf16 v[104:107], v[140:143], v[204:207], v[104:107]
	v_mfma_f32_16x16x32_bf16 v[100:103], v[132:135], v[212:215], v[100:103]
	v_mfma_f32_16x16x32_bf16 v[96:99], v[140:143], v[212:215], v[96:99]
	v_mfma_f32_16x16x32_bf16 v[60:63], v[156:159], v[178:181], v[60:63]
	v_mfma_f32_16x16x32_bf16 v[56:59], v[170:173], v[178:181], v[56:59]
	v_mfma_f32_16x16x32_bf16 v[52:55], v[156:159], v[186:189], v[52:55]
	v_mfma_f32_16x16x32_bf16 v[48:51], v[170:173], v[186:189], v[48:51]
	v_mfma_f32_16x16x32_bf16 v[44:47], v[156:159], v[200:203], v[44:47]
	v_mfma_f32_16x16x32_bf16 v[40:43], v[170:173], v[200:203], v[40:43]
	v_mfma_f32_16x16x32_bf16 v[36:39], v[156:159], v[208:211], v[36:39]
	v_mfma_f32_16x16x32_bf16 v[32:35], v[170:173], v[208:211], v[32:35]
	v_mfma_f32_16x16x32_bf16 v[60:63], v[166:169], v[182:185], v[60:63]
	v_mfma_f32_16x16x32_bf16 v[56:59], v[174:177], v[182:185], v[56:59]
	v_mfma_f32_16x16x32_bf16 v[52:55], v[166:169], v[190:193], v[52:55]
	v_mfma_f32_16x16x32_bf16 v[48:51], v[174:177], v[190:193], v[48:51]
	v_mfma_f32_16x16x32_bf16 v[44:47], v[166:169], v[204:207], v[44:47]
	v_mfma_f32_16x16x32_bf16 v[40:43], v[174:177], v[204:207], v[40:43]
	v_mfma_f32_16x16x32_bf16 v[36:39], v[166:169], v[212:215], v[36:39]
	v_mfma_f32_16x16x32_bf16 v[32:35], v[174:177], v[212:215], v[32:35]
	s_setprio 0
	s_barrier
	s_add_i32 s75, s90, s9
	v_lshl_add_u64 v[144:145], s[88:89], 0, v[194:195]
	s_mov_b32 m0, s75
	ds_read_b128 v[178:181], v165 offset:16384
	ds_read_b128 v[182:185], v165 offset:17408
	ds_read_b128 v[186:189], v165 offset:18432
	ds_read_b128 v[190:193], v165 offset:19456
	ds_read_b128 v[200:203], v165 offset:20480
	ds_read_b128 v[204:207], v165 offset:21504
	ds_read_b128 v[208:211], v165 offset:22528
	ds_read_b128 v[212:215], v165 offset:23552
	global_load_lds_dwordx4 v[144:145], off
	s_add_i32 m0, s75, 0x2000
	v_lshl_add_u64 v[160:161], s[88:89], 0, v[146:147]
	s_add_u32 s88, s88, s80
	s_addc_u32 s89, s89, 0
	s_add_i32 s74, s74, s9
	global_load_lds_dwordx4 v[160:161], off
	v_lshl_add_u64 v[228:229], s[88:89], 0, v[194:195]
	s_mov_b32 m0, s74
	v_lshl_add_u64 v[230:231], s[88:89], 0, v[146:147]
	global_load_lds_dwordx4 v[228:229], off
	s_add_i32 m0, s74, 0x2000
	v_lshl_add_u64 v[232:233], s[86:87], 0, v[150:151]
	global_load_lds_dwordx4 v[230:231], off
	s_mov_b32 m0, s2
	v_lshl_add_u64 v[234:235], s[86:87], 0, v[148:149]
	global_load_lds_dwordx4 v[232:233], off
	s_mov_b32 m0, s10
	s_nop 0
	global_load_lds_dwordx4 v[234:235], off
	s_waitcnt vmcnt(8)
	s_waitcnt lgkmcnt(0)
	s_barrier
; #define PG8_STAGE(bufoff, gbase, voff) do { _Pragma("unroll") for (int _i = 0; _i < 2; ++_i) \
;         __builtin_amdgcn_global_load_lds((const unsigned*)((const char*)(gbase) + (voff)[_i]), (PG8_LAS unsigned*)(lds + (bufoff) + ldsw + _i * 8192), 16, 0, 0); } while (0)
; #define PG8_LDA(dst, b, h) do { _Pragma("unroll") for (int m = 0; m < 4; ++m) _Pragma("unroll") for (int k = 0; k < 2; ++k) dst[m][k] = *(const PG8_LAS bf16x8*)(lds + PG8_SA(b, h) + aoff + m * 2048 + k * 1024); } while (0)
; #define PG8_LDB(dst, b, h) do { _Pragma("unroll") for (int n = 0; n < 2; ++n) _Pragma("unroll") for (int k = 0; k < 2; ++k) dst[n][k] = *(const PG8_LAS bf16x8*)(lds + PG8_SB(b, h) + boff + n * 2048 + k * 1024); } while (0)
; #define PG8_MMA(ai, bj, At, Bt) do { __builtin_amdgcn_s_setprio(1); _Pragma("unroll") for (int m = 0; m < 4; ++m) _Pragma("unroll") for (int n = 0; n < 2; ++n) _Pragma("unroll") for (int k = 0; k < 2; ++k) \
;         acc[ai][bj][m][n] = __builtin_amdgcn_mfma_f32_16x16x32_bf16(Bt[n][k], At[m][k], acc[ai][bj][m][n], 0, 0, 0); __builtin_amdgcn_s_setprio(0); } while (0)
; #define PG8_WAIT_V(n) asm volatile("s_waitcnt vmcnt(" #n ")" ::: "memory")
; #define PG8_WAIT_L(n) asm volatile("s_waitcnt lgkmcnt(" #n ")" ::: "memory")
; #define PG8_BAR __builtin_amdgcn_s_barrier()
; #define PG8_SCHED __builtin_amdgcn_sched_barrier(0)
; template <class Epi, class Sched, bool ALIGN_EPI = false, bool SP2 = false>
; __device__ __forceinline__ void gemm_phase(PG8_LAS unsigned char* lds, const Gemm g, const Sched& S, const Epi& E) {
;     ...
;             PG8_WAIT_V(8); PG8_WAIT_L(0); PG8_BAR; PG8_MMA(1, 0, At, B0); PG8_MMA(1, 1, At, B1); PG8_BAR; PG8_SCHED;
;             PG8_LDB(B0, 1, 0); PG8_LDB(B1, 1, 1); PG8_SCHED; PG8_LDA(At, 1, 0); PG8_STAGE(PG8_SA(0, 1), a2 + hstepA, voffA);
;             PG8_WAIT_V(8); PG8_WAIT_L(0); PG8_BAR; PG8_MMA(0, 0, At, B0); PG8_MMA(0, 1, At, B1); PG8_BAR; PG8_SCHED;
	s_setprio 1
	v_mfma_f32_16x16x32_bf16 v[92:95], v[128:131], v[178:181], v[92:95]
	v_mfma_f32_16x16x32_bf16 v[88:91], v[136:139], v[178:181], v[88:91]
	v_mfma_f32_16x16x32_bf16 v[84:87], v[128:131], v[186:189], v[84:87]
	v_mfma_f32_16x16x32_bf16 v[80:83], v[136:139], v[186:189], v[80:83]
	v_mfma_f32_16x16x32_bf16 v[76:79], v[128:131], v[200:203], v[76:79]
	v_mfma_f32_16x16x32_bf16 v[72:75], v[136:139], v[200:203], v[72:75]
	v_mfma_f32_16x16x32_bf16 v[68:71], v[128:131], v[208:211], v[68:71]
	v_mfma_f32_16x16x32_bf16 v[64:67], v[136:139], v[208:211], v[64:67]
	v_mfma_f32_16x16x32_bf16 v[92:95], v[132:135], v[182:185], v[92:95]
	v_mfma_f32_16x16x32_bf16 v[88:91], v[140:143], v[182:185], v[88:91]
	v_mfma_f32_16x16x32_bf16 v[84:87], v[132:135], v[190:193], v[84:87]
	v_mfma_f32_16x16x32_bf16 v[80:83], v[140:143], v[190:193], v[80:83]
	v_mfma_f32_16x16x32_bf16 v[76:79], v[132:135], v[204:207], v[76:79]
	v_mfma_f32_16x16x32_bf16 v[72:75], v[140:143], v[204:207], v[72:75]
	v_mfma_f32_16x16x32_bf16 v[68:71], v[132:135], v[212:215], v[68:71]
	v_mfma_f32_16x16x32_bf16 v[64:67], v[140:143], v[212:215], v[64:67]
	v_mfma_f32_16x16x32_bf16 v[28:31], v[156:159], v[178:181], v[28:31]
	v_mfma_f32_16x16x32_bf16 v[24:27], v[170:173], v[178:181], v[24:27]
	v_mfma_f32_16x16x32_bf16 v[20:23], v[156:159], v[186:189], v[20:23]
	v_mfma_f32_16x16x32_bf16 v[16:19], v[170:173], v[186:189], v[16:19]
	v_mfma_f32_16x16x32_bf16 v[12:15], v[156:159], v[200:203], v[12:15]
	v_mfma_f32_16x16x32_bf16 v[8:11], v[170:173], v[200:203], v[8:11]
	v_mfma_f32_16x16x32_bf16 v[4:7], v[156:159], v[208:211], v[4:7]
	v_mfma_f32_16x16x32_bf16 v[0:3], v[170:173], v[208:211], v[0:3]
	v_mfma_f32_16x16x32_bf16 v[28:31], v[166:169], v[182:185], v[28:31]
	v_mfma_f32_16x16x32_bf16 v[24:27], v[174:177], v[182:185], v[24:27]
	v_mfma_f32_16x16x32_bf16 v[20:23], v[166:169], v[190:193], v[20:23]
	v_mfma_f32_16x16x32_bf16 v[16:19], v[174:177], v[190:193], v[16:19]
	v_mfma_f32_16x16x32_bf16 v[12:15], v[166:169], v[204:207], v[12:15]
	v_mfma_f32_16x16x32_bf16 v[8:11], v[174:177], v[204:207], v[8:11]
	v_mfma_f32_16x16x32_bf16 v[4:7], v[166:169], v[212:215], v[4:7]
	v_mfma_f32_16x16x32_bf16 v[0:3], v[174:177], v[212:215], v[0:3]
	s_setprio 0
	s_barrier
	s_add_i32 s74, 0, 0x18000
	s_add_i32 s75, 0, 0x1c000
	v_add_u32_e32 v140, s74, v164
	v_add_u32_e32 v174, s75, v164
	ds_read_b128 v[128:131], v140
	ds_read_b128 v[132:135], v140 offset:1024
	ds_read_b128 v[136:139], v140 offset:2048
	ds_read_b128 v[140:143], v140 offset:3072
	ds_read_b128 v[156:159], v174
	ds_read_b128 v[166:169], v174 offset:1024
	ds_read_b128 v[170:173], v174 offset:2048
	ds_read_b128 v[174:177], v174 offset:3072
	s_add_u32 s86, s86, s80
	s_addc_u32 s87, s87, 0
	s_mov_b32 m0, s11
	v_lshl_add_u64 v[236:237], s[86:87], 0, v[150:151]
	ds_read_b128 v[178:181], v165 offset:32768
	ds_read_b128 v[182:185], v165 offset:33792
	ds_read_b128 v[186:189], v165 offset:34816
	ds_read_b128 v[190:193], v165 offset:35840
	ds_read_b128 v[200:203], v165 offset:36864
	ds_read_b128 v[204:207], v165 offset:37888
	ds_read_b128 v[208:211], v165 offset:38912
	ds_read_b128 v[212:215], v165 offset:39936
	global_load_lds_dwordx4 v[236:237], off
	v_lshl_add_u64 v[236:237], s[86:87], 0, v[148:149]
	s_mov_b32 m0, s12
	s_nop 0
	global_load_lds_dwordx4 v[236:237], off
	s_waitcnt vmcnt(8)
	s_waitcnt lgkmcnt(0)
	s_barrier
	s_setprio 1
	v_mfma_f32_16x16x32_bf16 v[124:127], v[128:131], v[178:181], v[124:127]
	v_mfma_f32_16x16x32_bf16 v[120:123], v[136:139], v[178:181], v[120:123]
	v_mfma_f32_16x16x32_bf16 v[116:119], v[128:131], v[186:189], v[116:119]
	v_mfma_f32_16x16x32_bf16 v[112:115], v[136:139], v[186:189], v[112:115]
	v_mfma_f32_16x16x32_bf16 v[108:111], v[128:131], v[200:203], v[108:111]
	v_mfma_f32_16x16x32_bf16 v[104:107], v[136:139], v[200:203], v[104:107]
	v_mfma_f32_16x16x32_bf16 v[100:103], v[128:131], v[208:211], v[100:103]
	v_mfma_f32_16x16x32_bf16 v[96:99], v[136:139], v[208:211], v[96:99]
	v_mfma_f32_16x16x32_bf16 v[124:127], v[132:135], v[182:185], v[124:127]
	v_mfma_f32_16x16x32_bf16 v[120:123], v[140:143], v[182:185], v[120:123]
	v_mfma_f32_16x16x32_bf16 v[116:119], v[132:135], v[190:193], v[116:119]
	v_mfma_f32_16x16x32_bf16 v[112:115], v[140:143], v[190:193], v[112:115]
	v_mfma_f32_16x16x32_bf16 v[108:111], v[132:135], v[204:207], v[108:111]
	v_mfma_f32_16x16x32_bf16 v[104:107], v[140:143], v[204:207], v[104:107]
	v_mfma_f32_16x16x32_bf16 v[100:103], v[132:135], v[212:215], v[100:103]
	v_mfma_f32_16x16x32_bf16 v[96:99], v[140:143], v[212:215], v[96:99]
	v_mfma_f32_16x16x32_bf16 v[60:63], v[156:159], v[178:181], v[60:63]
	v_mfma_f32_16x16x32_bf16 v[56:59], v[170:173], v[178:181], v[56:59]
	v_mfma_f32_16x16x32_bf16 v[52:55], v[156:159], v[186:189], v[52:55]
	v_mfma_f32_16x16x32_bf16 v[48:51], v[170:173], v[186:189], v[48:51]
	v_mfma_f32_16x16x32_bf16 v[44:47], v[156:159], v[200:203], v[44:47]
	v_mfma_f32_16x16x32_bf16 v[40:43], v[170:173], v[200:203], v[40:43]
	v_mfma_f32_16x16x32_bf16 v[36:39], v[156:159], v[208:211], v[36:39]
	v_mfma_f32_16x16x32_bf16 v[32:35], v[170:173], v[208:211], v[32:35]
	v_mfma_f32_16x16x32_bf16 v[60:63], v[166:169], v[182:185], v[60:63]
	v_mfma_f32_16x16x32_bf16 v[56:59], v[174:177], v[182:185], v[56:59]
	v_mfma_f32_16x16x32_bf16 v[52:55], v[166:169], v[190:193], v[52:55]
	v_mfma_f32_16x16x32_bf16 v[48:51], v[174:177], v[190:193], v[48:51]
	v_mfma_f32_16x16x32_bf16 v[44:47], v[166:169], v[204:207], v[44:47]
	v_mfma_f32_16x16x32_bf16 v[40:43], v[174:177], v[204:207], v[40:43]
	v_mfma_f32_16x16x32_bf16 v[36:39], v[166:169], v[212:215], v[36:39]
	v_mfma_f32_16x16x32_bf16 v[32:35], v[174:177], v[212:215], v[32:35]
	s_setprio 0
	s_barrier
; #define PG8_STAGE(bufoff, gbase, voff) do { _Pragma("unroll") for (int _i = 0; _i < 2; ++_i) \
;         __builtin_amdgcn_global_load_lds((const unsigned*)((const char*)(gbase) + (voff)[_i]), (PG8_LAS unsigned*)(lds + (bufoff) + ldsw + _i * 8192), 16, 0, 0); } while (0)
; #define PG8_LDA(dst, b, h) do { _Pragma("unroll") for (int m = 0; m < 4; ++m) _Pragma("unroll") for (int k = 0; k < 2; ++k) dst[m][k] = *(const PG8_LAS bf16x8*)(lds + PG8_SA(b, h) + aoff + m * 2048 + k * 1024); } while (0)
; #define PG8_MMA(ai, bj, At, Bt) do { __builtin_amdgcn_s_setprio(1); _Pragma("unroll") for (int m = 0; m < 4; ++m) _Pragma("unroll") for (int n = 0; n < 2; ++n) _Pragma("unroll") for (int k = 0; k < 2; ++k) \
;         acc[ai][bj][m][n] = __builtin_amdgcn_mfma_f32_16x16x32_bf16(Bt[n][k], At[m][k], acc[ai][bj][m][n], 0, 0, 0); __builtin_amdgcn_s_setprio(0); } while (0)
; #define PG8_WAIT_V(n) asm volatile("s_waitcnt vmcnt(" #n ")" ::: "memory")
; #define PG8_WAIT_L(n) asm volatile("s_waitcnt lgkmcnt(" #n ")" ::: "memory")
; #define PG8_BAR __builtin_amdgcn_s_barrier()
; #define PG8_SCHED __builtin_amdgcn_sched_barrier(0)
; template <class Epi, class Sched, bool ALIGN_EPI = false, bool SP2 = false>
; __device__ __forceinline__ void gemm_phase(PG8_LAS unsigned char* lds, const Gemm g, const Sched& S, const Epi& E) {
;     ...
;         for (int t = 0; t < nt; t += 2) {
;     ...
;             PG8_LDA(At, 1, 1); PG8_STAGE(PG8_SB(1, 0), b3, voffB); PG8_STAGE(PG8_SB(1, 1), b3 + hstepB, voffB); PG8_STAGE(PG8_SA(1, 0), a3, voffA);
;             PG8_WAIT_V(8); PG8_WAIT_L(0); PG8_BAR; PG8_MMA(1, 0, At, B0); PG8_MMA(1, 1, At, B1); PG8_BAR; PG8_SCHED;
	s_add_i32 s74, s74, s9
	v_lshl_add_u64 v[144:145], v[144:145], 0, s[26:27]
	s_mov_b32 m0, s74
	ds_read_b128 v[178:181], v165 offset:49152
	ds_read_b128 v[182:185], v165 offset:50176
	ds_read_b128 v[186:189], v165 offset:51200
	ds_read_b128 v[190:193], v165 offset:52224
	ds_read_b128 v[200:203], v165 offset:53248
	ds_read_b128 v[204:207], v165 offset:54272
	ds_read_b128 v[208:211], v165 offset:55296
	ds_read_b128 v[212:215], v165 offset:56320
	global_load_lds_dwordx4 v[144:145], off
	v_lshl_add_u64 v[144:145], v[160:161], 0, s[26:27]
	s_add_i32 m0, s74, 0x2000
	s_add_i32 s74, s75, s9
	global_load_lds_dwordx4 v[144:145], off
	v_lshl_add_u64 v[144:145], v[228:229], 0, s[26:27]
	s_mov_b32 m0, s74
	s_nop 0
	global_load_lds_dwordx4 v[144:145], off
	v_lshl_add_u64 v[144:145], v[230:231], 0, s[26:27]
	s_add_i32 m0, s74, 0x2000
	s_nop 0
	global_load_lds_dwordx4 v[144:145], off
	v_lshl_add_u64 v[144:145], v[232:233], 0, s[26:27]
	s_mov_b32 m0, s16
	s_nop 0
	global_load_lds_dwordx4 v[144:145], off
	v_lshl_add_u64 v[144:145], v[234:235], 0, s[26:27]
	s_mov_b32 m0, s17
	s_nop 0
	global_load_lds_dwordx4 v[144:145], off
	s_waitcnt vmcnt(8)
	s_waitcnt lgkmcnt(0)
	s_barrier
	s_setprio 1
	v_mfma_f32_16x16x32_bf16 v[92:95], v[128:131], v[178:181], v[92:95]
	v_mfma_f32_16x16x32_bf16 v[88:91], v[136:139], v[178:181], v[88:91]
	v_mfma_f32_16x16x32_bf16 v[84:87], v[128:131], v[186:189], v[84:87]
	v_mfma_f32_16x16x32_bf16 v[80:83], v[136:139], v[186:189], v[80:83]
	v_mfma_f32_16x16x32_bf16 v[76:79], v[128:131], v[200:203], v[76:79]
	v_mfma_f32_16x16x32_bf16 v[72:75], v[136:139], v[200:203], v[72:75]
	v_mfma_f32_16x16x32_bf16 v[68:71], v[128:131], v[208:211], v[68:71]
	v_mfma_f32_16x16x32_bf16 v[64:67], v[136:139], v[208:211], v[64:67]
	v_mfma_f32_16x16x32_bf16 v[92:95], v[132:135], v[182:185], v[92:95]
	v_mfma_f32_16x16x32_bf16 v[88:91], v[140:143], v[182:185], v[88:91]
	v_mfma_f32_16x16x32_bf16 v[84:87], v[132:135], v[190:193], v[84:87]
	v_mfma_f32_16x16x32_bf16 v[80:83], v[140:143], v[190:193], v[80:83]
	v_mfma_f32_16x16x32_bf16 v[76:79], v[132:135], v[204:207], v[76:79]
	v_mfma_f32_16x16x32_bf16 v[72:75], v[140:143], v[204:207], v[72:75]
	v_mfma_f32_16x16x32_bf16 v[68:71], v[132:135], v[212:215], v[68:71]
	v_mfma_f32_16x16x32_bf16 v[64:67], v[140:143], v[212:215], v[64:67]
	v_mfma_f32_16x16x32_bf16 v[28:31], v[156:159], v[178:181], v[28:31]
	v_mfma_f32_16x16x32_bf16 v[24:27], v[170:173], v[178:181], v[24:27]
	v_mfma_f32_16x16x32_bf16 v[20:23], v[156:159], v[186:189], v[20:23]
	v_mfma_f32_16x16x32_bf16 v[16:19], v[170:173], v[186:189], v[16:19]
	v_mfma_f32_16x16x32_bf16 v[12:15], v[156:159], v[200:203], v[12:15]
	v_mfma_f32_16x16x32_bf16 v[8:11], v[170:173], v[200:203], v[8:11]
	v_mfma_f32_16x16x32_bf16 v[4:7], v[156:159], v[208:211], v[4:7]
	v_mfma_f32_16x16x32_bf16 v[0:3], v[170:173], v[208:211], v[0:3]
	v_mfma_f32_16x16x32_bf16 v[28:31], v[166:169], v[182:185], v[28:31]
	v_mfma_f32_16x16x32_bf16 v[24:27], v[174:177], v[182:185], v[24:27]
	v_mfma_f32_16x16x32_bf16 v[20:23], v[166:169], v[190:193], v[20:23]
	v_mfma_f32_16x16x32_bf16 v[16:19], v[174:177], v[190:193], v[16:19]
	v_mfma_f32_16x16x32_bf16 v[12:15], v[166:169], v[204:207], v[12:15]
	v_mfma_f32_16x16x32_bf16 v[8:11], v[174:177], v[204:207], v[8:11]
	v_mfma_f32_16x16x32_bf16 v[4:7], v[166:169], v[212:215], v[4:7]
	v_mfma_f32_16x16x32_bf16 v[0:3], v[174:177], v[212:215], v[0:3]
	s_setprio 0
	s_barrier
	s_add_u32 s84, s84, 0x100
	s_addc_u32 s85, s85, 0
	s_add_u32 s64, s64, 0x100
	s_addc_u32 s78, s78, 0
	s_cmp_ge_i32 s81, s13
	s_mov_b32 s79, s81
	s_cbranch_scc0 .LBB0_1493

; #define PG8_STAGE(bufoff, gbase, voff) do { _Pragma("unroll") for (int _i = 0; _i < 2; ++_i) \
;         __builtin_amdgcn_global_load_lds((const unsigned*)((const char*)(gbase) + (voff)[_i]), (PG8_LAS unsigned*)(lds + (bufoff) + ldsw + _i * 8192), 16, 0, 0); } while (0)
; #define PG8_LDA(dst, b, h) do { _Pragma("unroll") for (int m = 0; m < 4; ++m) _Pragma("unroll") for (int k = 0; k < 2; ++k) dst[m][k] = *(const PG8_LAS bf16x8*)(lds + PG8_SA(b, h) + aoff + m * 2048 + k * 1024); } while (0)
; #define PG8_LDB(dst, b, h) do { _Pragma("unroll") for (int n = 0; n < 2; ++n) _Pragma("unroll") for (int k = 0; k < 2; ++k) dst[n][k] = *(const PG8_LAS bf16x8*)(lds + PG8_SB(b, h) + boff + n * 2048 + k * 1024); } while (0)
; #define PG8_MMA(ai, bj, At, Bt) do { __builtin_amdgcn_s_setprio(1); _Pragma("unroll") for (int m = 0; m < 4; ++m) _Pragma("unroll") for (int n = 0; n < 2; ++n) _Pragma("unroll") for (int k = 0; k < 2; ++k) \
;         acc[ai][bj][m][n] = __builtin_amdgcn_mfma_f32_16x16x32_bf16(Bt[n][k], At[m][k], acc[ai][bj][m][n], 0, 0, 0); __builtin_amdgcn_s_setprio(0); } while (0)
; #define PG8_WAIT_V(n) asm volatile("s_waitcnt vmcnt(" #n ")" ::: "memory")
; #define PG8_WAIT_L(n) asm volatile("s_waitcnt lgkmcnt(" #n ")" ::: "memory")
; template <class Epi, class Sched, bool ALIGN_EPI = false, bool SP2 = false>
; __device__ __forceinline__ void gemm_phase(PG8_LAS unsigned char* lds, const Gemm g, const Sched& S, const Epi& E) {
;     ...
;             const bool last = (t == nt - 2);
;             const char* a1 = cA + (size_t)(t + 1) * kstep;
;             const char* a2 = last ? nA : cA + (size_t)(t + 2) * kstep; const char* b2 = last ? nB : cB + (size_t)(t + 2) * kstep;
;             const char* a3 = a2 + kstep; const char* b3 = b2 + kstep;
;             if (last && has_next) S.a_ready(nxt);
;             if constexpr (SP2) {
;             PG8_LDB(B0, 0, 0); PG8_LDB(B1, 0, 1); PG8_SCHED; PG8_LDA(At, 0, 0); PG8_STAGE(PG8_SA(1, 1), a1 + hstepA, voffA);
;             PG8_WAIT_V(8); PG8_WAIT_L(0); PG8_BAR; PG8_MMA(0, 0, At, B0); PG8_MMA(0, 1, At, B1); PG8_BAR; PG8_SCHED;
;             PG8_LDA(At, 0, 1); PG8_STAGE(PG8_SB(0, 0), b2, voffB); PG8_STAGE(PG8_SB(0, 1), b2 + hstepB, voffB); PG8_STAGE(PG8_SA(0, 0), a2, voffA);
;             PG8_WAIT_V(8); PG8_WAIT_L(0); PG8_BAR; PG8_MMA(1, 0, At, B0); PG8_MMA(1, 1, At, B1); PG8_BAR; PG8_SCHED;
.LBB0_1626:
	s_add_i32 s78, s69, 2
	s_add_u32 s74, s86, 0xfffc0080
	s_addc_u32 s75, s87, -1
	s_add_i32 s79, 0, 0x10000
	s_cmp_eq_u32 s33, s69
	s_cselect_b32 s91, s53, s75
	s_cselect_b32 s90, s58, s74
	v_add_u32_e32 v138, s79, v142
	s_cselect_b32 s89, s59, s64
	s_cselect_b32 s88, s61, s63
	s_add_i32 s69, 0, 0x14000
	ds_read_b128 v[144:147], v138
	ds_read_b128 v[148:151], v138 offset:1024
	ds_read_b128 v[152:155], v138 offset:2048
	ds_read_b128 v[156:159], v138 offset:3072
	v_add_u32_e32 v138, s69, v142
	ds_read_b128 v[160:163], v138
	ds_read_b128 v[164:167], v138 offset:1024
	ds_read_b128 v[168:171], v138 offset:2048
	ds_read_b128 v[172:175], v138 offset:3072
	v_lshl_add_u64 v[138:139], s[86:87], 0, v[134:135]
	s_add_i32 m0, s12, 0xc000
	ds_read_b128 v[176:179], v143
	ds_read_b128 v[180:183], v143 offset:1024
	ds_read_b128 v[184:187], v143 offset:2048
	ds_read_b128 v[188:191], v143 offset:3072
	ds_read_b128 v[200:203], v143 offset:4096
	ds_read_b128 v[204:207], v143 offset:5120
	ds_read_b128 v[208:211], v143 offset:6144
	ds_read_b128 v[212:215], v143 offset:7168
	global_load_lds_dwordx4 v[138:139], off
	v_lshl_add_u64 v[138:139], s[86:87], 0, v[136:137]
	s_add_i32 m0, s12, 0xe000
	s_nop 0
	global_load_lds_dwordx4 v[138:139], off
	s_waitcnt vmcnt(8)
	s_waitcnt lgkmcnt(0)
	s_barrier
	s_setprio 1
	v_mfma_f32_16x16x32_bf16 v[120:123], v[144:147], v[176:179], v[120:123]
	v_mfma_f32_16x16x32_bf16 v[124:127], v[152:155], v[176:179], v[124:127]
	v_mfma_f32_16x16x32_bf16 v[108:111], v[144:147], v[184:187], v[108:111]
	v_mfma_f32_16x16x32_bf16 v[104:107], v[152:155], v[184:187], v[104:107]
	v_mfma_f32_16x16x32_bf16 v[92:95], v[144:147], v[200:203], v[92:95]
	v_mfma_f32_16x16x32_bf16 v[88:91], v[152:155], v[200:203], v[88:91]
	v_mfma_f32_16x16x32_bf16 v[76:79], v[144:147], v[208:211], v[76:79]
	v_mfma_f32_16x16x32_bf16 v[72:75], v[152:155], v[208:211], v[72:75]
	v_mfma_f32_16x16x32_bf16 v[120:123], v[148:151], v[180:183], v[120:123]
	v_mfma_f32_16x16x32_bf16 v[124:127], v[156:159], v[180:183], v[124:127]
	v_mfma_f32_16x16x32_bf16 v[108:111], v[148:151], v[188:191], v[108:111]
	v_mfma_f32_16x16x32_bf16 v[104:107], v[156:159], v[188:191], v[104:107]
	v_mfma_f32_16x16x32_bf16 v[92:95], v[148:151], v[204:207], v[92:95]
	v_mfma_f32_16x16x32_bf16 v[88:91], v[156:159], v[204:207], v[88:91]
	v_mfma_f32_16x16x32_bf16 v[76:79], v[148:151], v[212:215], v[76:79]
	v_mfma_f32_16x16x32_bf16 v[72:75], v[156:159], v[212:215], v[72:75]
	v_mfma_f32_16x16x32_bf16 v[116:119], v[160:163], v[176:179], v[116:119]
	v_mfma_f32_16x16x32_bf16 v[112:115], v[168:171], v[176:179], v[112:115]
	v_mfma_f32_16x16x32_bf16 v[100:103], v[160:163], v[184:187], v[100:103]
	v_mfma_f32_16x16x32_bf16 v[96:99], v[168:171], v[184:187], v[96:99]
	v_mfma_f32_16x16x32_bf16 v[84:87], v[160:163], v[200:203], v[84:87]
	v_mfma_f32_16x16x32_bf16 v[80:83], v[168:171], v[200:203], v[80:83]
	v_mfma_f32_16x16x32_bf16 v[68:71], v[160:163], v[208:211], v[68:71]
	v_mfma_f32_16x16x32_bf16 v[64:67], v[168:171], v[208:211], v[64:67]
	v_mfma_f32_16x16x32_bf16 v[116:119], v[164:167], v[180:183], v[116:119]
	v_mfma_f32_16x16x32_bf16 v[112:115], v[172:175], v[180:183], v[112:115]
	v_mfma_f32_16x16x32_bf16 v[100:103], v[164:167], v[188:191], v[100:103]
	v_mfma_f32_16x16x32_bf16 v[96:99], v[172:175], v[188:191], v[96:99]
	v_mfma_f32_16x16x32_bf16 v[84:87], v[164:167], v[204:207], v[84:87]
	v_mfma_f32_16x16x32_bf16 v[80:83], v[172:175], v[204:207], v[80:83]
	v_mfma_f32_16x16x32_bf16 v[68:71], v[164:167], v[212:215], v[68:71]
	v_mfma_f32_16x16x32_bf16 v[64:67], v[172:175], v[212:215], v[64:67]
	s_setprio 0
	s_barrier
	s_add_i32 s74, s79, s9
	v_lshl_add_u64 v[138:139], s[88:89], 0, v[194:195]
	s_mov_b32 m0, s74
	ds_read_b128 v[176:179], v143 offset:16384
	ds_read_b128 v[180:183], v143 offset:17408
	ds_read_b128 v[184:187], v143 offset:18432
	ds_read_b128 v[188:191], v143 offset:19456
	ds_read_b128 v[200:203], v143 offset:20480
	ds_read_b128 v[204:207], v143 offset:21504
	ds_read_b128 v[208:211], v143 offset:22528
	ds_read_b128 v[212:215], v143 offset:23552
	global_load_lds_dwordx4 v[138:139], off
	s_add_i32 m0, s74, 0x2000
	s_add_u32 s92, s88, 0x40000
	v_lshl_add_u64 v[192:193], s[88:89], 0, v[128:129]
	s_addc_u32 s93, s89, 0
	s_add_i32 s69, s69, s9
	global_load_lds_dwordx4 v[192:193], off
	v_lshl_add_u64 v[228:229], s[92:93], 0, v[194:195]
	s_mov_b32 m0, s69
	v_lshl_add_u64 v[230:231], s[90:91], 0, v[130:131]
	global_load_lds_dwordx4 v[228:229], off
	v_lshl_add_u64 v[228:229], s[92:93], 0, v[128:129]
	s_add_i32 m0, s69, 0x2000
	s_nop 0
	global_load_lds_dwordx4 v[228:229], off
	v_lshl_add_u64 v[228:229], s[90:91], 0, v[132:133]
	s_mov_b32 m0, s12
	s_nop 0
	global_load_lds_dwordx4 v[228:229], off
	s_mov_b32 m0, s13
	s_nop 0
	global_load_lds_dwordx4 v[230:231], off
	s_waitcnt vmcnt(8)
	s_waitcnt lgkmcnt(0)
	s_barrier
; #define PG8_STAGE(bufoff, gbase, voff) do { _Pragma("unroll") for (int _i = 0; _i < 2; ++_i) \
;         __builtin_amdgcn_global_load_lds((const unsigned*)((const char*)(gbase) + (voff)[_i]), (PG8_LAS unsigned*)(lds + (bufoff) + ldsw + _i * 8192), 16, 0, 0); } while (0)
; #define PG8_LDA(dst, b, h) do { _Pragma("unroll") for (int m = 0; m < 4; ++m) _Pragma("unroll") for (int k = 0; k < 2; ++k) dst[m][k] = *(const PG8_LAS bf16x8*)(lds + PG8_SA(b, h) + aoff + m * 2048 + k * 1024); } while (0)
; #define PG8_LDB(dst, b, h) do { _Pragma("unroll") for (int n = 0; n < 2; ++n) _Pragma("unroll") for (int k = 0; k < 2; ++k) dst[n][k] = *(const PG8_LAS bf16x8*)(lds + PG8_SB(b, h) + boff + n * 2048 + k * 1024); } while (0)
; #define PG8_MMA(ai, bj, At, Bt) do { __builtin_amdgcn_s_setprio(1); _Pragma("unroll") for (int m = 0; m < 4; ++m) _Pragma("unroll") for (int n = 0; n < 2; ++n) _Pragma("unroll") for (int k = 0; k < 2; ++k) \
;         acc[ai][bj][m][n] = __builtin_amdgcn_mfma_f32_16x16x32_bf16(Bt[n][k], At[m][k], acc[ai][bj][m][n], 0, 0, 0); __builtin_amdgcn_s_setprio(0); } while (0)
; #define PG8_WAIT_V(n) asm volatile("s_waitcnt vmcnt(" #n ")" ::: "memory")
; #define PG8_WAIT_L(n) asm volatile("s_waitcnt lgkmcnt(" #n ")" ::: "memory")
; #define PG8_BAR __builtin_amdgcn_s_barrier()
; #define PG8_SCHED __builtin_amdgcn_sched_barrier(0)
; template <class Epi, class Sched, bool ALIGN_EPI = false, bool SP2 = false>
; __device__ __forceinline__ void gemm_phase(PG8_LAS unsigned char* lds, const Gemm g, const Sched& S, const Epi& E) {
;     ...
;             PG8_WAIT_V(8); PG8_WAIT_L(0); PG8_BAR; PG8_MMA(1, 0, At, B0); PG8_MMA(1, 1, At, B1); PG8_BAR; PG8_SCHED;
;             PG8_LDB(B0, 1, 0); PG8_LDB(B1, 1, 1); PG8_SCHED; PG8_LDA(At, 1, 0); PG8_STAGE(PG8_SA(0, 1), a2 + hstepA, voffA);
;             PG8_WAIT_V(8); PG8_WAIT_L(0); PG8_BAR; PG8_MMA(0, 0, At, B0); PG8_MMA(0, 1, At, B1); PG8_BAR; PG8_SCHED;
	s_setprio 1
	v_mfma_f32_16x16x32_bf16 v[60:63], v[144:147], v[176:179], v[60:63]
	v_mfma_f32_16x16x32_bf16 v[56:59], v[152:155], v[176:179], v[56:59]
	v_mfma_f32_16x16x32_bf16 v[44:47], v[144:147], v[184:187], v[44:47]
	v_mfma_f32_16x16x32_bf16 v[40:43], v[152:155], v[184:187], v[40:43]
	v_mfma_f32_16x16x32_bf16 v[28:31], v[144:147], v[200:203], v[28:31]
	v_mfma_f32_16x16x32_bf16 v[24:27], v[152:155], v[200:203], v[24:27]
	v_mfma_f32_16x16x32_bf16 v[12:15], v[144:147], v[208:211], v[12:15]
	v_mfma_f32_16x16x32_bf16 v[8:11], v[152:155], v[208:211], v[8:11]
	v_mfma_f32_16x16x32_bf16 v[60:63], v[148:151], v[180:183], v[60:63]
	v_mfma_f32_16x16x32_bf16 v[56:59], v[156:159], v[180:183], v[56:59]
	v_mfma_f32_16x16x32_bf16 v[44:47], v[148:151], v[188:191], v[44:47]
	v_mfma_f32_16x16x32_bf16 v[40:43], v[156:159], v[188:191], v[40:43]
	v_mfma_f32_16x16x32_bf16 v[28:31], v[148:151], v[204:207], v[28:31]
	v_mfma_f32_16x16x32_bf16 v[24:27], v[156:159], v[204:207], v[24:27]
	v_mfma_f32_16x16x32_bf16 v[12:15], v[148:151], v[212:215], v[12:15]
	v_mfma_f32_16x16x32_bf16 v[8:11], v[156:159], v[212:215], v[8:11]
	v_mfma_f32_16x16x32_bf16 v[52:55], v[160:163], v[176:179], v[52:55]
	v_mfma_f32_16x16x32_bf16 v[48:51], v[168:171], v[176:179], v[48:51]
	v_mfma_f32_16x16x32_bf16 v[36:39], v[160:163], v[184:187], v[36:39]
	v_mfma_f32_16x16x32_bf16 v[32:35], v[168:171], v[184:187], v[32:35]
	v_mfma_f32_16x16x32_bf16 v[20:23], v[160:163], v[200:203], v[20:23]
	v_mfma_f32_16x16x32_bf16 v[16:19], v[168:171], v[200:203], v[16:19]
	v_mfma_f32_16x16x32_bf16 v[4:7], v[160:163], v[208:211], v[4:7]
	v_mfma_f32_16x16x32_bf16 v[0:3], v[168:171], v[208:211], v[0:3]
	v_mfma_f32_16x16x32_bf16 v[52:55], v[164:167], v[180:183], v[52:55]
	v_mfma_f32_16x16x32_bf16 v[48:51], v[172:175], v[180:183], v[48:51]
	v_mfma_f32_16x16x32_bf16 v[36:39], v[164:167], v[188:191], v[36:39]
	v_mfma_f32_16x16x32_bf16 v[32:35], v[172:175], v[188:191], v[32:35]
	v_mfma_f32_16x16x32_bf16 v[20:23], v[164:167], v[204:207], v[20:23]
	v_mfma_f32_16x16x32_bf16 v[16:19], v[172:175], v[204:207], v[16:19]
	v_mfma_f32_16x16x32_bf16 v[4:7], v[164:167], v[212:215], v[4:7]
	v_mfma_f32_16x16x32_bf16 v[0:3], v[172:175], v[212:215], v[0:3]
	s_setprio 0
	s_barrier
	s_add_i32 s69, 0, 0x18000
	s_add_i32 s74, 0, 0x1c000
	v_add_u32_e32 v156, s69, v142
	v_add_u32_e32 v172, s74, v142
	ds_read_b128 v[144:147], v156
	ds_read_b128 v[148:151], v156 offset:1024
	ds_read_b128 v[152:155], v156 offset:2048
	ds_read_b128 v[156:159], v156 offset:3072
	ds_read_b128 v[160:163], v172
	ds_read_b128 v[164:167], v172 offset:1024
	ds_read_b128 v[168:171], v172 offset:2048
	ds_read_b128 v[172:175], v172 offset:3072
	s_add_u32 s90, s90, 0x40000
	s_addc_u32 s91, s91, 0
	s_mov_b32 m0, s14
	v_lshl_add_u64 v[232:233], s[90:91], 0, v[132:133]
	ds_read_b128 v[176:179], v143 offset:32768
	ds_read_b128 v[180:183], v143 offset:33792
	ds_read_b128 v[184:187], v143 offset:34816
	ds_read_b128 v[188:191], v143 offset:35840
	ds_read_b128 v[200:203], v143 offset:36864
	ds_read_b128 v[204:207], v143 offset:37888
	ds_read_b128 v[208:211], v143 offset:38912
	ds_read_b128 v[212:215], v143 offset:39936
	global_load_lds_dwordx4 v[232:233], off
	v_lshl_add_u64 v[232:233], s[90:91], 0, v[130:131]
	s_mov_b32 m0, s15
	s_nop 0
	global_load_lds_dwordx4 v[232:233], off
	s_waitcnt vmcnt(8)
	s_waitcnt lgkmcnt(0)
	s_barrier
	s_setprio 1
	v_mfma_f32_16x16x32_bf16 v[120:123], v[144:147], v[176:179], v[120:123]
	v_mfma_f32_16x16x32_bf16 v[124:127], v[152:155], v[176:179], v[124:127]
	v_mfma_f32_16x16x32_bf16 v[108:111], v[144:147], v[184:187], v[108:111]
	v_mfma_f32_16x16x32_bf16 v[104:107], v[152:155], v[184:187], v[104:107]
	v_mfma_f32_16x16x32_bf16 v[92:95], v[144:147], v[200:203], v[92:95]
	v_mfma_f32_16x16x32_bf16 v[88:91], v[152:155], v[200:203], v[88:91]
	v_mfma_f32_16x16x32_bf16 v[76:79], v[144:147], v[208:211], v[76:79]
	v_mfma_f32_16x16x32_bf16 v[72:75], v[152:155], v[208:211], v[72:75]
	v_mfma_f32_16x16x32_bf16 v[120:123], v[148:151], v[180:183], v[120:123]
	v_mfma_f32_16x16x32_bf16 v[124:127], v[156:159], v[180:183], v[124:127]
	v_mfma_f32_16x16x32_bf16 v[108:111], v[148:151], v[188:191], v[108:111]
	v_mfma_f32_16x16x32_bf16 v[104:107], v[156:159], v[188:191], v[104:107]
	v_mfma_f32_16x16x32_bf16 v[92:95], v[148:151], v[204:207], v[92:95]
	v_mfma_f32_16x16x32_bf16 v[88:91], v[156:159], v[204:207], v[88:91]
	v_mfma_f32_16x16x32_bf16 v[76:79], v[148:151], v[212:215], v[76:79]
	v_mfma_f32_16x16x32_bf16 v[72:75], v[156:159], v[212:215], v[72:75]
	v_mfma_f32_16x16x32_bf16 v[116:119], v[160:163], v[176:179], v[116:119]
	v_mfma_f32_16x16x32_bf16 v[112:115], v[168:171], v[176:179], v[112:115]
	v_mfma_f32_16x16x32_bf16 v[100:103], v[160:163], v[184:187], v[100:103]
	v_mfma_f32_16x16x32_bf16 v[96:99], v[168:171], v[184:187], v[96:99]
	v_mfma_f32_16x16x32_bf16 v[84:87], v[160:163], v[200:203], v[84:87]
	v_mfma_f32_16x16x32_bf16 v[80:83], v[168:171], v[200:203], v[80:83]
	v_mfma_f32_16x16x32_bf16 v[68:71], v[160:163], v[208:211], v[68:71]
	v_mfma_f32_16x16x32_bf16 v[64:67], v[168:171], v[208:211], v[64:67]
	v_mfma_f32_16x16x32_bf16 v[116:119], v[164:167], v[180:183], v[116:119]
	v_mfma_f32_16x16x32_bf16 v[112:115], v[172:175], v[180:183], v[112:115]
	v_mfma_f32_16x16x32_bf16 v[100:103], v[164:167], v[188:191], v[100:103]
	v_mfma_f32_16x16x32_bf16 v[96:99], v[172:175], v[188:191], v[96:99]
	v_mfma_f32_16x16x32_bf16 v[84:87], v[164:167], v[204:207], v[84:87]
	v_mfma_f32_16x16x32_bf16 v[80:83], v[172:175], v[204:207], v[80:83]
	v_mfma_f32_16x16x32_bf16 v[68:71], v[164:167], v[212:215], v[68:71]
	v_mfma_f32_16x16x32_bf16 v[64:67], v[172:175], v[212:215], v[64:67]
	s_setprio 0
	s_barrier
; #define PG8_STAGE(bufoff, gbase, voff) do { _Pragma("unroll") for (int _i = 0; _i < 2; ++_i) \
;         __builtin_amdgcn_global_load_lds((const unsigned*)((const char*)(gbase) + (voff)[_i]), (PG8_LAS unsigned*)(lds + (bufoff) + ldsw + _i * 8192), 16, 0, 0); } while (0)
; #define PG8_LDA(dst, b, h) do { _Pragma("unroll") for (int m = 0; m < 4; ++m) _Pragma("unroll") for (int k = 0; k < 2; ++k) dst[m][k] = *(const PG8_LAS bf16x8*)(lds + PG8_SA(b, h) + aoff + m * 2048 + k * 1024); } while (0)
; #define PG8_MMA(ai, bj, At, Bt) do { __builtin_amdgcn_s_setprio(1); _Pragma("unroll") for (int m = 0; m < 4; ++m) _Pragma("unroll") for (int n = 0; n < 2; ++n) _Pragma("unroll") for (int k = 0; k < 2; ++k) \
;         acc[ai][bj][m][n] = __builtin_amdgcn_mfma_f32_16x16x32_bf16(Bt[n][k], At[m][k], acc[ai][bj][m][n], 0, 0, 0); __builtin_amdgcn_s_setprio(0); } while (0)
; #define PG8_WAIT_V(n) asm volatile("s_waitcnt vmcnt(" #n ")" ::: "memory")
; #define PG8_WAIT_L(n) asm volatile("s_waitcnt lgkmcnt(" #n ")" ::: "memory")
; #define PG8_BAR __builtin_amdgcn_s_barrier()
; #define PG8_SCHED __builtin_amdgcn_sched_barrier(0)
; template <class Epi, class Sched, bool ALIGN_EPI = false, bool SP2 = false>
; __device__ __forceinline__ void gemm_phase(PG8_LAS unsigned char* lds, const Gemm g, const Sched& S, const Epi& E) {
;     ...
;         for (int t = 0; t < nt; t += 2) {
;     ...
;             PG8_LDA(At, 1, 1); PG8_STAGE(PG8_SB(1, 0), b3, voffB); PG8_STAGE(PG8_SB(1, 1), b3 + hstepB, voffB); PG8_STAGE(PG8_SA(1, 0), a3, voffA);
;             PG8_WAIT_V(8); PG8_WAIT_L(0); PG8_BAR; PG8_MMA(1, 0, At, B0); PG8_MMA(1, 1, At, B1); PG8_BAR; PG8_SCHED;
	s_add_i32 s69, s69, s9
	v_lshl_add_u64 v[138:139], v[138:139], 0, s[26:27]
	s_mov_b32 m0, s69
	ds_read_b128 v[176:179], v143 offset:49152
	ds_read_b128 v[180:183], v143 offset:50176
	ds_read_b128 v[184:187], v143 offset:51200
	ds_read_b128 v[188:191], v143 offset:52224
	ds_read_b128 v[200:203], v143 offset:53248
	ds_read_b128 v[204:207], v143 offset:54272
	ds_read_b128 v[208:211], v143 offset:55296
	ds_read_b128 v[212:215], v143 offset:56320
	global_load_lds_dwordx4 v[138:139], off
	s_add_i32 m0, s69, 0x2000
	s_add_u32 s88, s88, 0x40080
	v_lshl_add_u64 v[138:139], v[192:193], 0, s[26:27]
	s_addc_u32 s89, s89, 0
	s_add_i32 s69, s74, s9
	global_load_lds_dwordx4 v[138:139], off
	v_lshl_add_u64 v[138:139], s[88:89], 0, v[194:195]
	s_mov_b32 m0, s69
	s_nop 0
	global_load_lds_dwordx4 v[138:139], off
	v_lshl_add_u64 v[138:139], s[88:89], 0, v[128:129]
	s_add_i32 m0, s69, 0x2000
	s_nop 0
	global_load_lds_dwordx4 v[138:139], off
	v_lshl_add_u64 v[138:139], v[228:229], 0, s[26:27]
	s_mov_b32 m0, s28
	s_nop 0
	global_load_lds_dwordx4 v[138:139], off
	v_lshl_add_u64 v[138:139], v[230:231], 0, s[26:27]
	s_mov_b32 m0, s29
	s_nop 0
	global_load_lds_dwordx4 v[138:139], off
	s_waitcnt vmcnt(8)
	s_waitcnt lgkmcnt(0)
	s_barrier
	s_setprio 1
	v_mfma_f32_16x16x32_bf16 v[60:63], v[144:147], v[176:179], v[60:63]
	v_mfma_f32_16x16x32_bf16 v[56:59], v[152:155], v[176:179], v[56:59]
	v_mfma_f32_16x16x32_bf16 v[44:47], v[144:147], v[184:187], v[44:47]
	v_mfma_f32_16x16x32_bf16 v[40:43], v[152:155], v[184:187], v[40:43]
	v_mfma_f32_16x16x32_bf16 v[28:31], v[144:147], v[200:203], v[28:31]
	v_mfma_f32_16x16x32_bf16 v[24:27], v[152:155], v[200:203], v[24:27]
	v_mfma_f32_16x16x32_bf16 v[12:15], v[144:147], v[208:211], v[12:15]
	v_mfma_f32_16x16x32_bf16 v[8:11], v[152:155], v[208:211], v[8:11]
	v_mfma_f32_16x16x32_bf16 v[60:63], v[148:151], v[180:183], v[60:63]
	v_mfma_f32_16x16x32_bf16 v[56:59], v[156:159], v[180:183], v[56:59]
	v_mfma_f32_16x16x32_bf16 v[44:47], v[148:151], v[188:191], v[44:47]
	v_mfma_f32_16x16x32_bf16 v[40:43], v[156:159], v[188:191], v[40:43]
	v_mfma_f32_16x16x32_bf16 v[28:31], v[148:151], v[204:207], v[28:31]
	v_mfma_f32_16x16x32_bf16 v[24:27], v[156:159], v[204:207], v[24:27]
	v_mfma_f32_16x16x32_bf16 v[12:15], v[148:151], v[212:215], v[12:15]
	v_mfma_f32_16x16x32_bf16 v[8:11], v[156:159], v[212:215], v[8:11]
	v_mfma_f32_16x16x32_bf16 v[52:55], v[160:163], v[176:179], v[52:55]
	v_mfma_f32_16x16x32_bf16 v[48:51], v[168:171], v[176:179], v[48:51]
	v_mfma_f32_16x16x32_bf16 v[36:39], v[160:163], v[184:187], v[36:39]
	v_mfma_f32_16x16x32_bf16 v[32:35], v[168:171], v[184:187], v[32:35]
	v_mfma_f32_16x16x32_bf16 v[20:23], v[160:163], v[200:203], v[20:23]
	v_mfma_f32_16x16x32_bf16 v[16:19], v[168:171], v[200:203], v[16:19]
	v_mfma_f32_16x16x32_bf16 v[4:7], v[160:163], v[208:211], v[4:7]
	v_mfma_f32_16x16x32_bf16 v[0:3], v[168:171], v[208:211], v[0:3]
	v_mfma_f32_16x16x32_bf16 v[52:55], v[164:167], v[180:183], v[52:55]
	v_mfma_f32_16x16x32_bf16 v[48:51], v[172:175], v[180:183], v[48:51]
	v_mfma_f32_16x16x32_bf16 v[36:39], v[164:167], v[188:191], v[36:39]
	v_mfma_f32_16x16x32_bf16 v[32:35], v[172:175], v[188:191], v[32:35]
	v_mfma_f32_16x16x32_bf16 v[20:23], v[164:167], v[204:207], v[20:23]
	v_mfma_f32_16x16x32_bf16 v[16:19], v[172:175], v[204:207], v[16:19]
	v_mfma_f32_16x16x32_bf16 v[4:7], v[164:167], v[212:215], v[4:7]
	v_mfma_f32_16x16x32_bf16 v[0:3], v[172:175], v[212:215], v[0:3]
	s_setprio 0
	s_barrier
	s_add_u32 s86, s86, 0x100
	s_addc_u32 s87, s87, 0
	s_add_u32 s63, s63, 0x100
	s_addc_u32 s64, s64, 0
	s_cmp_ge_i32 s78, s16
	s_mov_b32 s69, s78
	s_cbranch_scc0 .LBB0_1626

; #define PG8_STAGE(bufoff, gbase, voff) do { _Pragma("unroll") for (int _i = 0; _i < 2; ++_i) \
;         __builtin_amdgcn_global_load_lds((const unsigned*)((const char*)(gbase) + (voff)[_i]), (PG8_LAS unsigned*)(lds + (bufoff) + ldsw + _i * 8192), 16, 0, 0); } while (0)
; #define PG8_LDA(dst, b, h) do { _Pragma("unroll") for (int m = 0; m < 4; ++m) _Pragma("unroll") for (int k = 0; k < 2; ++k) dst[m][k] = *(const PG8_LAS bf16x8*)(lds + PG8_SA(b, h) + aoff + m * 2048 + k * 1024); } while (0)
; #define PG8_LDB(dst, b, h) do { _Pragma("unroll") for (int n = 0; n < 2; ++n) _Pragma("unroll") for (int k = 0; k < 2; ++k) dst[n][k] = *(const PG8_LAS bf16x8*)(lds + PG8_SB(b, h) + boff + n * 2048 + k * 1024); } while (0)
; #define PG8_MMA(ai, bj, At, Bt) do { __builtin_amdgcn_s_setprio(1); _Pragma("unroll") for (int m = 0; m < 4; ++m) _Pragma("unroll") for (int n = 0; n < 2; ++n) _Pragma("unroll") for (int k = 0; k < 2; ++k) \
;         acc[ai][bj][m][n] = __builtin_amdgcn_mfma_f32_16x16x32_bf16(Bt[n][k], At[m][k], acc[ai][bj][m][n], 0, 0, 0); __builtin_amdgcn_s_setprio(0); } while (0)
; #define PG8_WAIT_V(n) asm volatile("s_waitcnt vmcnt(" #n ")" ::: "memory")
; #define PG8_WAIT_L(n) asm volatile("s_waitcnt lgkmcnt(" #n ")" ::: "memory")
; template <class Epi, class Sched, bool ALIGN_EPI = false, bool SP2 = false>
; __device__ __forceinline__ void gemm_phase(PG8_LAS unsigned char* lds, const Gemm g, const Sched& S, const Epi& E) {
;     ...
;             const bool last = (t == nt - 2);
;             const char* a1 = cA + (size_t)(t + 1) * kstep;
;             const char* a2 = last ? nA : cA + (size_t)(t + 2) * kstep; const char* b2 = last ? nB : cB + (size_t)(t + 2) * kstep;
;             const char* a3 = a2 + kstep; const char* b3 = b2 + kstep;
;             if (last && has_next) S.a_ready(nxt);
;             if constexpr (SP2) {
;             PG8_LDB(B0, 0, 0); PG8_LDB(B1, 0, 1); PG8_SCHED; PG8_LDA(At, 0, 0); PG8_STAGE(PG8_SA(1, 1), a1 + hstepA, voffA);
;             PG8_WAIT_V(8); PG8_WAIT_L(0); PG8_BAR; PG8_MMA(0, 0, At, B0); PG8_MMA(0, 1, At, B1); PG8_BAR; PG8_SCHED;
;             PG8_LDA(At, 0, 1); PG8_STAGE(PG8_SB(0, 0), b2, voffB); PG8_STAGE(PG8_SB(0, 1), b2 + hstepB, voffB); PG8_STAGE(PG8_SA(0, 0), a2, voffA);
;             PG8_WAIT_V(8); PG8_WAIT_L(0); PG8_BAR; PG8_MMA(1, 0, At, B0); PG8_MMA(1, 1, At, B1); PG8_BAR; PG8_SCHED;
.LBB0_1699:
	s_add_i32 s80, s68, 2
	s_add_u32 s69, s62, 0xfff00080
	s_addc_u32 s74, s63, -1
	s_add_i32 s75, 0, 0x10000
	s_cmp_eq_u32 s28, s68
	s_cselect_b32 s77, s45, s74
	s_cselect_b32 s76, s47, s69
	s_cselect_b32 s69, s59, s79
	s_cselect_b32 s68, s64, s78
	s_add_i32 s74, 0, 0x14000
	v_add_u32_e32 v150, s75, v168
	v_add_u32_e32 v170, s74, v168
	ds_read_b128 v[138:141], v150
	ds_read_b128 v[142:145], v150 offset:1024
	ds_read_b128 v[146:149], v150 offset:2048
	ds_read_b128 v[150:153], v150 offset:3072
	ds_read_b128 v[154:157], v170
	ds_read_b128 v[158:161], v170 offset:1024
	ds_read_b128 v[162:165], v170 offset:2048
	ds_read_b128 v[170:173], v170 offset:3072
	v_lshl_add_u64 v[212:213], s[62:63], 0, v[134:135]
	s_add_i32 m0, s3, 0xc000
	ds_read_b128 v[174:177], v169
	ds_read_b128 v[178:181], v169 offset:1024
	ds_read_b128 v[182:185], v169 offset:2048
	ds_read_b128 v[186:189], v169 offset:3072
	ds_read_b128 v[190:193], v169 offset:4096
	ds_read_b128 v[200:203], v169 offset:5120
	ds_read_b128 v[204:207], v169 offset:6144
	ds_read_b128 v[208:211], v169 offset:7168
	global_load_lds_dwordx4 v[212:213], off
	v_lshl_add_u64 v[212:213], s[62:63], 0, v[136:137]
	s_add_i32 m0, s3, 0xe000
	s_nop 0
	global_load_lds_dwordx4 v[212:213], off
	s_waitcnt vmcnt(8)
	s_waitcnt lgkmcnt(0)
	s_barrier
	s_setprio 1
	v_mfma_f32_16x16x32_bf16 v[124:127], v[138:141], v[174:177], v[124:127]
	v_mfma_f32_16x16x32_bf16 v[120:123], v[146:149], v[174:177], v[120:123]
	v_mfma_f32_16x16x32_bf16 v[116:119], v[138:141], v[182:185], v[116:119]
	v_mfma_f32_16x16x32_bf16 v[112:115], v[146:149], v[182:185], v[112:115]
	v_mfma_f32_16x16x32_bf16 v[108:111], v[138:141], v[190:193], v[108:111]
	v_mfma_f32_16x16x32_bf16 v[104:107], v[146:149], v[190:193], v[104:107]
	v_mfma_f32_16x16x32_bf16 v[100:103], v[138:141], v[204:207], v[100:103]
	v_mfma_f32_16x16x32_bf16 v[96:99], v[146:149], v[204:207], v[96:99]
	v_mfma_f32_16x16x32_bf16 v[124:127], v[142:145], v[178:181], v[124:127]
	v_mfma_f32_16x16x32_bf16 v[120:123], v[150:153], v[178:181], v[120:123]
	v_mfma_f32_16x16x32_bf16 v[116:119], v[142:145], v[186:189], v[116:119]
	v_mfma_f32_16x16x32_bf16 v[112:115], v[150:153], v[186:189], v[112:115]
	v_mfma_f32_16x16x32_bf16 v[108:111], v[142:145], v[200:203], v[108:111]
	v_mfma_f32_16x16x32_bf16 v[104:107], v[150:153], v[200:203], v[104:107]
	v_mfma_f32_16x16x32_bf16 v[100:103], v[142:145], v[208:211], v[100:103]
	v_mfma_f32_16x16x32_bf16 v[96:99], v[150:153], v[208:211], v[96:99]
	v_mfma_f32_16x16x32_bf16 v[92:95], v[154:157], v[174:177], v[92:95]
	v_mfma_f32_16x16x32_bf16 v[84:87], v[162:165], v[174:177], v[84:87]
	v_mfma_f32_16x16x32_bf16 v[76:79], v[154:157], v[182:185], v[76:79]
	v_mfma_f32_16x16x32_bf16 v[68:71], v[162:165], v[182:185], v[68:71]
	v_mfma_f32_16x16x32_bf16 v[60:63], v[154:157], v[190:193], v[60:63]
	v_mfma_f32_16x16x32_bf16 v[52:55], v[162:165], v[190:193], v[52:55]
	v_mfma_f32_16x16x32_bf16 v[44:47], v[154:157], v[204:207], v[44:47]
	v_mfma_f32_16x16x32_bf16 v[36:39], v[162:165], v[204:207], v[36:39]
	v_mfma_f32_16x16x32_bf16 v[92:95], v[158:161], v[178:181], v[92:95]
	v_mfma_f32_16x16x32_bf16 v[84:87], v[170:173], v[178:181], v[84:87]
	v_mfma_f32_16x16x32_bf16 v[76:79], v[158:161], v[186:189], v[76:79]
	v_mfma_f32_16x16x32_bf16 v[68:71], v[170:173], v[186:189], v[68:71]
	v_mfma_f32_16x16x32_bf16 v[60:63], v[158:161], v[200:203], v[60:63]
	v_mfma_f32_16x16x32_bf16 v[52:55], v[170:173], v[200:203], v[52:55]
	v_mfma_f32_16x16x32_bf16 v[44:47], v[158:161], v[208:211], v[44:47]
	v_mfma_f32_16x16x32_bf16 v[36:39], v[170:173], v[208:211], v[36:39]
	s_setprio 0
	s_barrier
	s_add_i32 s75, s75, s2
	v_lshl_add_u64 v[212:213], s[68:69], 0, v[194:195]
	s_mov_b32 m0, s75
	ds_read_b128 v[174:177], v169 offset:16384
	ds_read_b128 v[178:181], v169 offset:17408
	ds_read_b128 v[182:185], v169 offset:18432
	ds_read_b128 v[186:189], v169 offset:19456
	ds_read_b128 v[190:193], v169 offset:20480
	ds_read_b128 v[200:203], v169 offset:21504
	ds_read_b128 v[204:207], v169 offset:22528
	ds_read_b128 v[208:211], v169 offset:23552
	global_load_lds_dwordx4 v[212:213], off
	s_add_i32 m0, s75, 0x2000
	s_add_u32 s82, s68, 0x100000
	v_lshl_add_u64 v[214:215], s[68:69], 0, v[128:129]
	s_addc_u32 s83, s69, 0
	s_add_i32 s74, s74, s2
	global_load_lds_dwordx4 v[214:215], off
	v_lshl_add_u64 v[228:229], s[82:83], 0, v[194:195]
	s_mov_b32 m0, s74
	v_lshl_add_u64 v[230:231], s[76:77], 0, v[130:131]
	global_load_lds_dwordx4 v[228:229], off
	v_lshl_add_u64 v[228:229], s[82:83], 0, v[128:129]
	s_add_i32 m0, s74, 0x2000
	s_nop 0
	global_load_lds_dwordx4 v[228:229], off
	v_lshl_add_u64 v[228:229], s[76:77], 0, v[132:133]
	s_mov_b32 m0, s3
	s_nop 0
	global_load_lds_dwordx4 v[228:229], off
	s_mov_b32 m0, s8
	s_nop 0
	global_load_lds_dwordx4 v[230:231], off
	s_waitcnt vmcnt(8)
	s_waitcnt lgkmcnt(0)
	s_barrier
; #define PG8_STAGE(bufoff, gbase, voff) do { _Pragma("unroll") for (int _i = 0; _i < 2; ++_i) \
;         __builtin_amdgcn_global_load_lds((const unsigned*)((const char*)(gbase) + (voff)[_i]), (PG8_LAS unsigned*)(lds + (bufoff) + ldsw + _i * 8192), 16, 0, 0); } while (0)
; #define PG8_LDA(dst, b, h) do { _Pragma("unroll") for (int m = 0; m < 4; ++m) _Pragma("unroll") for (int k = 0; k < 2; ++k) dst[m][k] = *(const PG8_LAS bf16x8*)(lds + PG8_SA(b, h) + aoff + m * 2048 + k * 1024); } while (0)
; #define PG8_LDB(dst, b, h) do { _Pragma("unroll") for (int n = 0; n < 2; ++n) _Pragma("unroll") for (int k = 0; k < 2; ++k) dst[n][k] = *(const PG8_LAS bf16x8*)(lds + PG8_SB(b, h) + boff + n * 2048 + k * 1024); } while (0)
; #define PG8_MMA(ai, bj, At, Bt) do { __builtin_amdgcn_s_setprio(1); _Pragma("unroll") for (int m = 0; m < 4; ++m) _Pragma("unroll") for (int n = 0; n < 2; ++n) _Pragma("unroll") for (int k = 0; k < 2; ++k) \
;         acc[ai][bj][m][n] = __builtin_amdgcn_mfma_f32_16x16x32_bf16(Bt[n][k], At[m][k], acc[ai][bj][m][n], 0, 0, 0); __builtin_amdgcn_s_setprio(0); } while (0)
; #define PG8_WAIT_V(n) asm volatile("s_waitcnt vmcnt(" #n ")" ::: "memory")
; #define PG8_WAIT_L(n) asm volatile("s_waitcnt lgkmcnt(" #n ")" ::: "memory")
; #define PG8_BAR __builtin_amdgcn_s_barrier()
; #define PG8_SCHED __builtin_amdgcn_sched_barrier(0)
; template <class Epi, class Sched, bool ALIGN_EPI = false, bool SP2 = false>
; __device__ __forceinline__ void gemm_phase(PG8_LAS unsigned char* lds, const Gemm g, const Sched& S, const Epi& E) {
;     ...
;             PG8_WAIT_V(8); PG8_WAIT_L(0); PG8_BAR; PG8_MMA(0, 0, At, B0); PG8_MMA(0, 1, At, B1); PG8_BAR; PG8_SCHED;
;             PG8_LDA(At, 0, 1); PG8_STAGE(PG8_SB(0, 0), b2, voffB); PG8_STAGE(PG8_SB(0, 1), b2 + hstepB, voffB); PG8_STAGE(PG8_SA(0, 0), a2, voffA);
;             PG8_WAIT_V(8); PG8_WAIT_L(0); PG8_BAR; PG8_MMA(1, 0, At, B0); PG8_MMA(1, 1, At, B1); PG8_BAR; PG8_SCHED;
;             PG8_LDB(B0, 1, 0); PG8_LDB(B1, 1, 1); PG8_SCHED; PG8_LDA(At, 1, 0); PG8_STAGE(PG8_SA(0, 1), a2 + hstepA, voffA);
;             PG8_WAIT_V(8); PG8_WAIT_L(0); PG8_BAR; PG8_MMA(0, 0, At, B0); PG8_MMA(0, 1, At, B1); PG8_BAR; PG8_SCHED;
	s_setprio 1
	v_mfma_f32_16x16x32_bf16 v[88:91], v[138:141], v[174:177], v[88:91]
	v_mfma_f32_16x16x32_bf16 v[80:83], v[146:149], v[174:177], v[80:83]
	v_mfma_f32_16x16x32_bf16 v[72:75], v[138:141], v[182:185], v[72:75]
	v_mfma_f32_16x16x32_bf16 v[64:67], v[146:149], v[182:185], v[64:67]
	v_mfma_f32_16x16x32_bf16 v[56:59], v[138:141], v[190:193], v[56:59]
	v_mfma_f32_16x16x32_bf16 v[48:51], v[146:149], v[190:193], v[48:51]
	v_mfma_f32_16x16x32_bf16 v[40:43], v[138:141], v[204:207], v[40:43]
	v_mfma_f32_16x16x32_bf16 v[32:35], v[146:149], v[204:207], v[32:35]
	v_mfma_f32_16x16x32_bf16 v[88:91], v[142:145], v[178:181], v[88:91]
	v_mfma_f32_16x16x32_bf16 v[80:83], v[150:153], v[178:181], v[80:83]
	v_mfma_f32_16x16x32_bf16 v[72:75], v[142:145], v[186:189], v[72:75]
	v_mfma_f32_16x16x32_bf16 v[64:67], v[150:153], v[186:189], v[64:67]
	v_mfma_f32_16x16x32_bf16 v[56:59], v[142:145], v[200:203], v[56:59]
	v_mfma_f32_16x16x32_bf16 v[48:51], v[150:153], v[200:203], v[48:51]
	v_mfma_f32_16x16x32_bf16 v[40:43], v[142:145], v[208:211], v[40:43]
	v_mfma_f32_16x16x32_bf16 v[32:35], v[150:153], v[208:211], v[32:35]
	v_mfma_f32_16x16x32_bf16 v[28:31], v[154:157], v[174:177], v[28:31]
	v_mfma_f32_16x16x32_bf16 v[24:27], v[162:165], v[174:177], v[24:27]
	v_mfma_f32_16x16x32_bf16 v[20:23], v[154:157], v[182:185], v[20:23]
	v_mfma_f32_16x16x32_bf16 v[16:19], v[162:165], v[182:185], v[16:19]
	v_mfma_f32_16x16x32_bf16 v[12:15], v[154:157], v[190:193], v[12:15]
	v_mfma_f32_16x16x32_bf16 v[8:11], v[162:165], v[190:193], v[8:11]
	v_mfma_f32_16x16x32_bf16 v[4:7], v[154:157], v[204:207], v[4:7]
	v_mfma_f32_16x16x32_bf16 v[0:3], v[162:165], v[204:207], v[0:3]
	v_mfma_f32_16x16x32_bf16 v[28:31], v[158:161], v[178:181], v[28:31]
	v_mfma_f32_16x16x32_bf16 v[24:27], v[170:173], v[178:181], v[24:27]
	v_mfma_f32_16x16x32_bf16 v[20:23], v[158:161], v[186:189], v[20:23]
	v_mfma_f32_16x16x32_bf16 v[16:19], v[170:173], v[186:189], v[16:19]
	v_mfma_f32_16x16x32_bf16 v[12:15], v[158:161], v[200:203], v[12:15]
	v_mfma_f32_16x16x32_bf16 v[8:11], v[170:173], v[200:203], v[8:11]
	v_mfma_f32_16x16x32_bf16 v[4:7], v[158:161], v[208:211], v[4:7]
	v_mfma_f32_16x16x32_bf16 v[0:3], v[170:173], v[208:211], v[0:3]
	s_setprio 0
	s_barrier
	s_add_i32 s74, 0, 0x18000
	s_add_i32 s75, 0, 0x1c000
	v_add_u32_e32 v150, s74, v168
	v_add_u32_e32 v170, s75, v168
	ds_read_b128 v[138:141], v150
	ds_read_b128 v[142:145], v150 offset:1024
	ds_read_b128 v[146:149], v150 offset:2048
	ds_read_b128 v[150:153], v150 offset:3072
	ds_read_b128 v[154:157], v170
	ds_read_b128 v[158:161], v170 offset:1024
	ds_read_b128 v[162:165], v170 offset:2048
	ds_read_b128 v[170:173], v170 offset:3072
	s_add_u32 s76, s76, 0x100000
	s_addc_u32 s77, s77, 0
	s_mov_b32 m0, s9
	v_lshl_add_u64 v[232:233], s[76:77], 0, v[132:133]
	ds_read_b128 v[174:177], v169 offset:32768
	ds_read_b128 v[178:181], v169 offset:33792
	ds_read_b128 v[182:185], v169 offset:34816
	ds_read_b128 v[186:189], v169 offset:35840
	ds_read_b128 v[190:193], v169 offset:36864
	ds_read_b128 v[200:203], v169 offset:37888
	ds_read_b128 v[204:207], v169 offset:38912
	ds_read_b128 v[208:211], v169 offset:39936
	global_load_lds_dwordx4 v[232:233], off
	v_lshl_add_u64 v[232:233], s[76:77], 0, v[130:131]
	s_mov_b32 m0, s10
	s_nop 0
	global_load_lds_dwordx4 v[232:233], off
	s_waitcnt vmcnt(8)
	s_waitcnt lgkmcnt(0)
	s_barrier
	s_setprio 1
	v_mfma_f32_16x16x32_bf16 v[124:127], v[138:141], v[174:177], v[124:127]
	v_mfma_f32_16x16x32_bf16 v[120:123], v[146:149], v[174:177], v[120:123]
	v_mfma_f32_16x16x32_bf16 v[116:119], v[138:141], v[182:185], v[116:119]
	v_mfma_f32_16x16x32_bf16 v[112:115], v[146:149], v[182:185], v[112:115]
	v_mfma_f32_16x16x32_bf16 v[108:111], v[138:141], v[190:193], v[108:111]
	v_mfma_f32_16x16x32_bf16 v[104:107], v[146:149], v[190:193], v[104:107]
	v_mfma_f32_16x16x32_bf16 v[100:103], v[138:141], v[204:207], v[100:103]
	v_mfma_f32_16x16x32_bf16 v[96:99], v[146:149], v[204:207], v[96:99]
	v_mfma_f32_16x16x32_bf16 v[124:127], v[142:145], v[178:181], v[124:127]
	v_mfma_f32_16x16x32_bf16 v[120:123], v[150:153], v[178:181], v[120:123]
	v_mfma_f32_16x16x32_bf16 v[116:119], v[142:145], v[186:189], v[116:119]
	v_mfma_f32_16x16x32_bf16 v[112:115], v[150:153], v[186:189], v[112:115]
	v_mfma_f32_16x16x32_bf16 v[108:111], v[142:145], v[200:203], v[108:111]
	v_mfma_f32_16x16x32_bf16 v[104:107], v[150:153], v[200:203], v[104:107]
	v_mfma_f32_16x16x32_bf16 v[100:103], v[142:145], v[208:211], v[100:103]
	v_mfma_f32_16x16x32_bf16 v[96:99], v[150:153], v[208:211], v[96:99]
	v_mfma_f32_16x16x32_bf16 v[92:95], v[154:157], v[174:177], v[92:95]
	v_mfma_f32_16x16x32_bf16 v[84:87], v[162:165], v[174:177], v[84:87]
	v_mfma_f32_16x16x32_bf16 v[76:79], v[154:157], v[182:185], v[76:79]
	v_mfma_f32_16x16x32_bf16 v[68:71], v[162:165], v[182:185], v[68:71]
	v_mfma_f32_16x16x32_bf16 v[60:63], v[154:157], v[190:193], v[60:63]
	v_mfma_f32_16x16x32_bf16 v[52:55], v[162:165], v[190:193], v[52:55]
	v_mfma_f32_16x16x32_bf16 v[44:47], v[154:157], v[204:207], v[44:47]
	v_mfma_f32_16x16x32_bf16 v[36:39], v[162:165], v[204:207], v[36:39]
	v_mfma_f32_16x16x32_bf16 v[92:95], v[158:161], v[178:181], v[92:95]
	v_mfma_f32_16x16x32_bf16 v[84:87], v[170:173], v[178:181], v[84:87]
	v_mfma_f32_16x16x32_bf16 v[76:79], v[158:161], v[186:189], v[76:79]
	v_mfma_f32_16x16x32_bf16 v[68:71], v[170:173], v[186:189], v[68:71]
	v_mfma_f32_16x16x32_bf16 v[60:63], v[158:161], v[200:203], v[60:63]
	v_mfma_f32_16x16x32_bf16 v[52:55], v[170:173], v[200:203], v[52:55]
	v_mfma_f32_16x16x32_bf16 v[44:47], v[158:161], v[208:211], v[44:47]
	v_mfma_f32_16x16x32_bf16 v[36:39], v[170:173], v[208:211], v[36:39]
	s_setprio 0
	s_barrier
; #define PG8_STAGE(bufoff, gbase, voff) do { _Pragma("unroll") for (int _i = 0; _i < 2; ++_i) \
;         __builtin_amdgcn_global_load_lds((const unsigned*)((const char*)(gbase) + (voff)[_i]), (PG8_LAS unsigned*)(lds + (bufoff) + ldsw + _i * 8192), 16, 0, 0); } while (0)
; #define PG8_LDA(dst, b, h) do { _Pragma("unroll") for (int m = 0; m < 4; ++m) _Pragma("unroll") for (int k = 0; k < 2; ++k) dst[m][k] = *(const PG8_LAS bf16x8*)(lds + PG8_SA(b, h) + aoff + m * 2048 + k * 1024); } while (0)
; #define PG8_MMA(ai, bj, At, Bt) do { __builtin_amdgcn_s_setprio(1); _Pragma("unroll") for (int m = 0; m < 4; ++m) _Pragma("unroll") for (int n = 0; n < 2; ++n) _Pragma("unroll") for (int k = 0; k < 2; ++k) \
;         acc[ai][bj][m][n] = __builtin_amdgcn_mfma_f32_16x16x32_bf16(Bt[n][k], At[m][k], acc[ai][bj][m][n], 0, 0, 0); __builtin_amdgcn_s_setprio(0); } while (0)
; #define PG8_WAIT_V(n) asm volatile("s_waitcnt vmcnt(" #n ")" ::: "memory")
; #define PG8_WAIT_L(n) asm volatile("s_waitcnt lgkmcnt(" #n ")" ::: "memory")
; #define PG8_BAR __builtin_amdgcn_s_barrier()
; #define PG8_SCHED __builtin_amdgcn_sched_barrier(0)
; template <class Epi, class Sched, bool ALIGN_EPI = false, bool SP2 = false>
; __device__ __forceinline__ void gemm_phase(PG8_LAS unsigned char* lds, const Gemm g, const Sched& S, const Epi& E) {
;     ...
;         for (int t = 0; t < nt; t += 2) {
;     ...
;             PG8_LDA(At, 1, 1); PG8_STAGE(PG8_SB(1, 0), b3, voffB); PG8_STAGE(PG8_SB(1, 1), b3 + hstepB, voffB); PG8_STAGE(PG8_SA(1, 0), a3, voffA);
;             PG8_WAIT_V(8); PG8_WAIT_L(0); PG8_BAR; PG8_MMA(1, 0, At, B0); PG8_MMA(1, 1, At, B1); PG8_BAR; PG8_SCHED;
;     ...
;         if constexpr (!Epi::AFTER_DRAIN) { Unit ce = cur; int fr_ = fr, fq_ = fq; asm volatile("" : "+s"(ce.pm), "+s"(ce.pn), "+v"(fr_), "+v"(fq_)); E(acc, ce, wr, wc, fr_, fq_); S.done(cur); }
	s_add_i32 s74, s74, s2
	v_lshl_add_u64 v[212:213], v[212:213], 0, s[26:27]
	s_mov_b32 m0, s74
	ds_read_b128 v[174:177], v169 offset:49152
	ds_read_b128 v[178:181], v169 offset:50176
	ds_read_b128 v[182:185], v169 offset:51200
	ds_read_b128 v[186:189], v169 offset:52224
	ds_read_b128 v[190:193], v169 offset:53248
	ds_read_b128 v[200:203], v169 offset:54272
	ds_read_b128 v[204:207], v169 offset:55296
	ds_read_b128 v[208:211], v169 offset:56320
	global_load_lds_dwordx4 v[212:213], off
	s_add_i32 m0, s74, 0x2000
	s_add_u32 s68, s68, 0x100080
	v_lshl_add_u64 v[212:213], v[214:215], 0, s[26:27]
	s_addc_u32 s69, s69, 0
	s_add_i32 s74, s75, s2
	global_load_lds_dwordx4 v[212:213], off
	v_lshl_add_u64 v[212:213], s[68:69], 0, v[194:195]
	s_mov_b32 m0, s74
	s_nop 0
	global_load_lds_dwordx4 v[212:213], off
	v_lshl_add_u64 v[212:213], s[68:69], 0, v[128:129]
	s_add_i32 m0, s74, 0x2000
	s_nop 0
	global_load_lds_dwordx4 v[212:213], off
	v_lshl_add_u64 v[212:213], v[228:229], 0, s[26:27]
	s_mov_b32 m0, s16
	s_nop 0
	global_load_lds_dwordx4 v[212:213], off
	v_lshl_add_u64 v[212:213], v[230:231], 0, s[26:27]
	s_mov_b32 m0, s17
	s_nop 0
	global_load_lds_dwordx4 v[212:213], off
	s_waitcnt vmcnt(8)
	s_waitcnt lgkmcnt(0)
	s_barrier
	s_setprio 1
	v_mfma_f32_16x16x32_bf16 v[88:91], v[138:141], v[174:177], v[88:91]
	v_mfma_f32_16x16x32_bf16 v[80:83], v[146:149], v[174:177], v[80:83]
	v_mfma_f32_16x16x32_bf16 v[72:75], v[138:141], v[182:185], v[72:75]
	v_mfma_f32_16x16x32_bf16 v[64:67], v[146:149], v[182:185], v[64:67]
	v_mfma_f32_16x16x32_bf16 v[56:59], v[138:141], v[190:193], v[56:59]
	v_mfma_f32_16x16x32_bf16 v[48:51], v[146:149], v[190:193], v[48:51]
	v_mfma_f32_16x16x32_bf16 v[40:43], v[138:141], v[204:207], v[40:43]
	v_mfma_f32_16x16x32_bf16 v[32:35], v[146:149], v[204:207], v[32:35]
	v_mfma_f32_16x16x32_bf16 v[88:91], v[142:145], v[178:181], v[88:91]
	v_mfma_f32_16x16x32_bf16 v[80:83], v[150:153], v[178:181], v[80:83]
	v_mfma_f32_16x16x32_bf16 v[72:75], v[142:145], v[186:189], v[72:75]
	v_mfma_f32_16x16x32_bf16 v[64:67], v[150:153], v[186:189], v[64:67]
	v_mfma_f32_16x16x32_bf16 v[56:59], v[142:145], v[200:203], v[56:59]
	v_mfma_f32_16x16x32_bf16 v[48:51], v[150:153], v[200:203], v[48:51]
	v_mfma_f32_16x16x32_bf16 v[40:43], v[142:145], v[208:211], v[40:43]
	v_mfma_f32_16x16x32_bf16 v[32:35], v[150:153], v[208:211], v[32:35]
	v_mfma_f32_16x16x32_bf16 v[28:31], v[154:157], v[174:177], v[28:31]
	v_mfma_f32_16x16x32_bf16 v[24:27], v[162:165], v[174:177], v[24:27]
	v_mfma_f32_16x16x32_bf16 v[20:23], v[154:157], v[182:185], v[20:23]
	v_mfma_f32_16x16x32_bf16 v[16:19], v[162:165], v[182:185], v[16:19]
	v_mfma_f32_16x16x32_bf16 v[12:15], v[154:157], v[190:193], v[12:15]
	v_mfma_f32_16x16x32_bf16 v[8:11], v[162:165], v[190:193], v[8:11]
	v_mfma_f32_16x16x32_bf16 v[4:7], v[154:157], v[204:207], v[4:7]
	v_mfma_f32_16x16x32_bf16 v[0:3], v[162:165], v[204:207], v[0:3]
	v_mfma_f32_16x16x32_bf16 v[28:31], v[158:161], v[178:181], v[28:31]
	v_mfma_f32_16x16x32_bf16 v[24:27], v[170:173], v[178:181], v[24:27]
	v_mfma_f32_16x16x32_bf16 v[20:23], v[158:161], v[186:189], v[20:23]
	v_mfma_f32_16x16x32_bf16 v[16:19], v[170:173], v[186:189], v[16:19]
	v_mfma_f32_16x16x32_bf16 v[12:15], v[158:161], v[200:203], v[12:15]
	v_mfma_f32_16x16x32_bf16 v[8:11], v[170:173], v[200:203], v[8:11]
	v_mfma_f32_16x16x32_bf16 v[4:7], v[158:161], v[208:211], v[4:7]
	v_mfma_f32_16x16x32_bf16 v[0:3], v[170:173], v[208:211], v[0:3]
	s_setprio 0
	s_barrier
	s_add_u32 s62, s62, 0x100
	s_addc_u32 s63, s63, 0
	s_add_u32 s78, s78, 0x100
	s_addc_u32 s79, s79, 0
	s_cmp_ge_i32 s80, s13
	s_mov_b32 s68, s80
	s_cbranch_scc0 .LBB0_1699
	v_pk_add_f32 v[158:159], v[126:127], 0 op_sel_hi:[1,0]
	v_pk_add_f32 v[160:161], v[124:125], 0 op_sel_hi:[1,0]
	v_pk_add_f32 v[162:163], v[122:123], 0 op_sel_hi:[1,0]
	v_pk_add_f32 v[164:165], v[120:121], 0 op_sel_hi:[1,0]
	v_pk_add_f32 v[150:151], v[118:119], 0 op_sel_hi:[1,0]
	v_pk_add_f32 v[152:153], v[116:117], 0 op_sel_hi:[1,0]
	v_pk_add_f32 v[154:155], v[114:115], 0 op_sel_hi:[1,0]
	v_pk_add_f32 v[156:157], v[112:113], 0 op_sel_hi:[1,0]
	v_pk_add_f32 v[142:143], v[110:111], 0 op_sel_hi:[1,0]
	v_pk_add_f32 v[144:145], v[108:109], 0 op_sel_hi:[1,0]
	v_pk_add_f32 v[146:147], v[106:107], 0 op_sel_hi:[1,0]
	v_pk_add_f32 v[148:149], v[104:105], 0 op_sel_hi:[1,0]
	v_pk_add_f32 v[124:125], v[102:103], 0 op_sel_hi:[1,0]
	v_pk_add_f32 v[126:127], v[100:101], 0 op_sel_hi:[1,0]
	v_pk_add_f32 v[138:139], v[98:99], 0 op_sel_hi:[1,0]
	v_pk_add_f32 v[140:141], v[96:97], 0 op_sel_hi:[1,0]
	v_pk_add_f32 v[116:117], v[90:91], 0 op_sel_hi:[1,0]
	v_pk_add_f32 v[118:119], v[88:89], 0 op_sel_hi:[1,0]
	v_pk_add_f32 v[120:121], v[82:83], 0 op_sel_hi:[1,0]
	v_pk_add_f32 v[122:123], v[80:81], 0 op_sel_hi:[1,0]
	v_pk_add_f32 v[108:109], v[74:75], 0 op_sel_hi:[1,0]
	v_pk_add_f32 v[110:111], v[72:73], 0 op_sel_hi:[1,0]
	v_pk_add_f32 v[112:113], v[66:67], 0 op_sel_hi:[1,0]
	v_pk_add_f32 v[114:115], v[64:65], 0 op_sel_hi:[1,0]
	v_pk_add_f32 v[100:101], v[58:59], 0 op_sel_hi:[1,0]
	v_pk_add_f32 v[102:103], v[56:57], 0 op_sel_hi:[1,0]
	v_pk_add_f32 v[104:105], v[50:51], 0 op_sel_hi:[1,0]
	v_pk_add_f32 v[106:107], v[48:49], 0 op_sel_hi:[1,0]
	v_pk_add_f32 v[88:89], v[42:43], 0 op_sel_hi:[1,0]
	v_pk_add_f32 v[90:91], v[40:41], 0 op_sel_hi:[1,0]
	v_pk_add_f32 v[96:97], v[34:35], 0 op_sel_hi:[1,0]
	v_pk_add_f32 v[98:99], v[32:33], 0 op_sel_hi:[1,0]
	v_pk_add_f32 v[72:73], v[94:95], 0 op_sel_hi:[1,0]
	v_pk_add_f32 v[74:75], v[92:93], 0 op_sel_hi:[1,0]
	v_pk_add_f32 v[80:81], v[86:87], 0 op_sel_hi:[1,0]
	v_pk_add_f32 v[82:83], v[84:85], 0 op_sel_hi:[1,0]
	v_pk_add_f32 v[56:57], v[78:79], 0 op_sel_hi:[1,0]
	v_pk_add_f32 v[58:59], v[76:77], 0 op_sel_hi:[1,0]
	v_pk_add_f32 v[64:65], v[70:71], 0 op_sel_hi:[1,0]
	v_pk_add_f32 v[66:67], v[68:69], 0 op_sel_hi:[1,0]
	v_pk_add_f32 v[48:49], v[62:63], 0 op_sel_hi:[1,0]
	v_pk_add_f32 v[50:51], v[60:61], 0 op_sel_hi:[1,0]
	v_pk_add_f32 v[54:55], v[54:55], 0 op_sel_hi:[1,0]
	v_pk_add_f32 v[52:53], v[52:53], 0 op_sel_hi:[1,0]
	v_pk_add_f32 v[40:41], v[46:47], 0 op_sel_hi:[1,0]
	v_pk_add_f32 v[42:43], v[44:45], 0 op_sel_hi:[1,0]
	v_pk_add_f32 v[44:45], v[38:39], 0 op_sel_hi:[1,0]
	v_pk_add_f32 v[46:47], v[36:37], 0 op_sel_hi:[1,0]
	v_pk_add_f32 v[32:33], v[30:31], 0 op_sel_hi:[1,0]
	v_pk_add_f32 v[34:35], v[28:29], 0 op_sel_hi:[1,0]
	v_pk_add_f32 v[36:37], v[26:27], 0 op_sel_hi:[1,0]
	v_pk_add_f32 v[38:39], v[24:25], 0 op_sel_hi:[1,0]
	v_pk_add_f32 v[24:25], v[22:23], 0 op_sel_hi:[1,0]
	v_pk_add_f32 v[26:27], v[20:21], 0 op_sel_hi:[1,0]
	v_pk_add_f32 v[28:29], v[18:19], 0 op_sel_hi:[1,0]
	v_pk_add_f32 v[30:31], v[16:17], 0 op_sel_hi:[1,0]
	v_pk_add_f32 v[20:21], v[14:15], 0 op_sel_hi:[1,0]
	v_pk_add_f32 v[22:23], v[12:13], 0 op_sel_hi:[1,0]
	v_pk_add_f32 v[10:11], v[10:11], 0 op_sel_hi:[1,0]
	v_pk_add_f32 v[8:9], v[8:9], 0 op_sel_hi:[1,0]
	v_pk_add_f32 v[18:19], v[6:7], 0 op_sel_hi:[1,0]
	v_pk_add_f32 v[16:17], v[4:5], 0 op_sel_hi:[1,0]
	v_pk_add_f32 v[14:15], v[2:3], 0 op_sel_hi:[1,0]
	v_pk_add_f32 v[12:13], v[0:1], 0 op_sel_hi:[1,0]

; #define PG8_STAGE(bufoff, gbase, voff) do { _Pragma("unroll") for (int _i = 0; _i < 2; ++_i) \
;         __builtin_amdgcn_global_load_lds((const unsigned*)((const char*)(gbase) + (voff)[_i]), (PG8_LAS unsigned*)(lds + (bufoff) + ldsw + _i * 8192), 16, 0, 0); } while (0)
; #define PG8_LDA(dst, b, h) do { _Pragma("unroll") for (int m = 0; m < 4; ++m) _Pragma("unroll") for (int k = 0; k < 2; ++k) dst[m][k] = *(const PG8_LAS bf16x8*)(lds + PG8_SA(b, h) + aoff + m * 2048 + k * 1024); } while (0)
; #define PG8_LDB(dst, b, h) do { _Pragma("unroll") for (int n = 0; n < 2; ++n) _Pragma("unroll") for (int k = 0; k < 2; ++k) dst[n][k] = *(const PG8_LAS bf16x8*)(lds + PG8_SB(b, h) + boff + n * 2048 + k * 1024); } while (0)
; #define PG8_MMA(ai, bj, At, Bt) do { __builtin_amdgcn_s_setprio(1); _Pragma("unroll") for (int m = 0; m < 4; ++m) _Pragma("unroll") for (int n = 0; n < 2; ++n) _Pragma("unroll") for (int k = 0; k < 2; ++k) \
;         acc[ai][bj][m][n] = __builtin_amdgcn_mfma_f32_16x16x32_bf16(Bt[n][k], At[m][k], acc[ai][bj][m][n], 0, 0, 0); __builtin_amdgcn_s_setprio(0); } while (0)
; #define PG8_WAIT_V(n) asm volatile("s_waitcnt vmcnt(" #n ")" ::: "memory")
; #define PG8_WAIT_L(n) asm volatile("s_waitcnt lgkmcnt(" #n ")" ::: "memory")
; #define PG8_BAR __builtin_amdgcn_s_barrier()
; #define PG8_SCHED __builtin_amdgcn_sched_barrier(0)
; template <class Epi, class Sched, bool ALIGN_EPI = false, bool SP2 = false>
; __device__ __forceinline__ void gemm_phase(PG8_LAS unsigned char* lds, const Gemm g, const Sched& S, const Epi& E) {
;     ...
;             const bool last = (t == nt - 2);
;             const char* a1 = cA + (size_t)(t + 1) * kstep;
;             const char* a2 = last ? nA : cA + (size_t)(t + 2) * kstep; const char* b2 = last ? nB : cB + (size_t)(t + 2) * kstep;
;             const char* a3 = a2 + kstep; const char* b3 = b2 + kstep;
;             if (last && has_next) S.a_ready(nxt);
;             if constexpr (SP2) {
;             PG8_LDB(B0, 0, 0); PG8_LDB(B1, 0, 1); PG8_SCHED; PG8_LDA(At, 0, 0); PG8_STAGE(PG8_SA(1, 1), a1 + hstepA, voffA);
;             PG8_WAIT_V(8); PG8_WAIT_L(0); PG8_BAR; PG8_MMA(0, 0, At, B0); PG8_MMA(0, 1, At, B1); PG8_BAR; PG8_SCHED;
;             PG8_LDA(At, 0, 1); PG8_STAGE(PG8_SB(0, 0), b2, voffB); PG8_STAGE(PG8_SB(0, 1), b2 + hstepB, voffB); PG8_STAGE(PG8_SA(0, 0), a2, voffA);
.LBB0_1726:
	s_add_i32 s64, s59, 2
	s_add_u32 s62, s52, 0xfff00080
	s_addc_u32 s63, s53, -1
	s_add_i32 s74, 0, 0x10000
	s_cmp_eq_u32 s16, s59
	s_cselect_b32 s69, s41, s63
	s_cselect_b32 s68, s40, s62
	s_cselect_b32 s63, s49, s58
	s_cselect_b32 s62, s48, s47
	s_add_i32 s59, 0, 0x14000
	v_add_u32_e32 v150, s74, v172
	v_add_u32_e32 v166, s59, v172
	ds_read_b128 v[138:141], v150
	ds_read_b128 v[142:145], v150 offset:1024
	ds_read_b128 v[146:149], v150 offset:2048
	ds_read_b128 v[150:153], v150 offset:3072
	ds_read_b128 v[154:157], v166
	ds_read_b128 v[158:161], v166 offset:1024
	ds_read_b128 v[162:165], v166 offset:2048
	ds_read_b128 v[166:169], v166 offset:3072
	v_lshl_add_u64 v[212:213], s[52:53], 0, v[134:135]
	s_add_i32 m0, s3, 0xc000
	ds_read_b128 v[174:177], v173
	ds_read_b128 v[178:181], v173 offset:1024
	ds_read_b128 v[182:185], v173 offset:2048
	ds_read_b128 v[186:189], v173 offset:3072
	ds_read_b128 v[190:193], v173 offset:4096
	ds_read_b128 v[200:203], v173 offset:5120
	ds_read_b128 v[204:207], v173 offset:6144
	ds_read_b128 v[208:211], v173 offset:7168
	global_load_lds_dwordx4 v[212:213], off
	v_lshl_add_u64 v[212:213], s[52:53], 0, v[136:137]
	s_add_i32 m0, s3, 0xe000
	s_nop 0
	global_load_lds_dwordx4 v[212:213], off
	s_waitcnt vmcnt(8)
	s_waitcnt lgkmcnt(0)
	s_barrier
	s_setprio 1
	v_mfma_f32_16x16x32_bf16 v[124:127], v[138:141], v[174:177], v[124:127]
	v_mfma_f32_16x16x32_bf16 v[120:123], v[146:149], v[174:177], v[120:123]
	v_mfma_f32_16x16x32_bf16 v[116:119], v[138:141], v[182:185], v[116:119]
	v_mfma_f32_16x16x32_bf16 v[112:115], v[146:149], v[182:185], v[112:115]
	v_mfma_f32_16x16x32_bf16 v[108:111], v[138:141], v[190:193], v[108:111]
	v_mfma_f32_16x16x32_bf16 v[104:107], v[146:149], v[190:193], v[104:107]
	v_mfma_f32_16x16x32_bf16 v[100:103], v[138:141], v[204:207], v[100:103]
	v_mfma_f32_16x16x32_bf16 v[96:99], v[146:149], v[204:207], v[96:99]
	v_mfma_f32_16x16x32_bf16 v[124:127], v[142:145], v[178:181], v[124:127]
	v_mfma_f32_16x16x32_bf16 v[120:123], v[150:153], v[178:181], v[120:123]
	v_mfma_f32_16x16x32_bf16 v[116:119], v[142:145], v[186:189], v[116:119]
	v_mfma_f32_16x16x32_bf16 v[112:115], v[150:153], v[186:189], v[112:115]
	v_mfma_f32_16x16x32_bf16 v[108:111], v[142:145], v[200:203], v[108:111]
	v_mfma_f32_16x16x32_bf16 v[104:107], v[150:153], v[200:203], v[104:107]
	v_mfma_f32_16x16x32_bf16 v[100:103], v[142:145], v[208:211], v[100:103]
	v_mfma_f32_16x16x32_bf16 v[96:99], v[150:153], v[208:211], v[96:99]
	v_mfma_f32_16x16x32_bf16 v[92:95], v[154:157], v[174:177], v[92:95]
	v_mfma_f32_16x16x32_bf16 v[84:87], v[162:165], v[174:177], v[84:87]
	v_mfma_f32_16x16x32_bf16 v[76:79], v[154:157], v[182:185], v[76:79]
	v_mfma_f32_16x16x32_bf16 v[68:71], v[162:165], v[182:185], v[68:71]
	v_mfma_f32_16x16x32_bf16 v[60:63], v[154:157], v[190:193], v[60:63]
	v_mfma_f32_16x16x32_bf16 v[52:55], v[162:165], v[190:193], v[52:55]
	v_mfma_f32_16x16x32_bf16 v[44:47], v[154:157], v[204:207], v[44:47]
	v_mfma_f32_16x16x32_bf16 v[36:39], v[162:165], v[204:207], v[36:39]
	v_mfma_f32_16x16x32_bf16 v[92:95], v[158:161], v[178:181], v[92:95]
	v_mfma_f32_16x16x32_bf16 v[84:87], v[166:169], v[178:181], v[84:87]
	v_mfma_f32_16x16x32_bf16 v[76:79], v[158:161], v[186:189], v[76:79]
	v_mfma_f32_16x16x32_bf16 v[68:71], v[166:169], v[186:189], v[68:71]
	v_mfma_f32_16x16x32_bf16 v[60:63], v[158:161], v[200:203], v[60:63]
	v_mfma_f32_16x16x32_bf16 v[52:55], v[166:169], v[200:203], v[52:55]
	v_mfma_f32_16x16x32_bf16 v[44:47], v[158:161], v[208:211], v[44:47]
	v_mfma_f32_16x16x32_bf16 v[36:39], v[166:169], v[208:211], v[36:39]
	s_setprio 0
	s_barrier
	s_add_i32 s74, s74, s2
	v_lshl_add_u64 v[212:213], s[62:63], 0, v[194:195]
	s_mov_b32 m0, s74
	ds_read_b128 v[174:177], v173 offset:16384
	ds_read_b128 v[178:181], v173 offset:17408
	ds_read_b128 v[182:185], v173 offset:18432
	ds_read_b128 v[186:189], v173 offset:19456
	ds_read_b128 v[190:193], v173 offset:20480
	ds_read_b128 v[200:203], v173 offset:21504
	ds_read_b128 v[204:207], v173 offset:22528
	ds_read_b128 v[208:211], v173 offset:23552
	global_load_lds_dwordx4 v[212:213], off
	s_add_i32 m0, s74, 0x2000
	s_add_u32 s76, s62, 0x100000
	v_lshl_add_u64 v[214:215], s[62:63], 0, v[128:129]
	s_addc_u32 s77, s63, 0
	s_add_i32 s59, s59, s2
	global_load_lds_dwordx4 v[214:215], off
	v_lshl_add_u64 v[228:229], s[76:77], 0, v[194:195]
	s_mov_b32 m0, s59
	v_lshl_add_u64 v[230:231], s[68:69], 0, v[130:131]
	global_load_lds_dwordx4 v[228:229], off
	v_lshl_add_u64 v[228:229], s[76:77], 0, v[128:129]
	s_add_i32 m0, s59, 0x2000
	s_nop 0
	global_load_lds_dwordx4 v[228:229], off
	v_lshl_add_u64 v[228:229], s[68:69], 0, v[132:133]
	s_mov_b32 m0, s3
	s_nop 0
	global_load_lds_dwordx4 v[228:229], off
	s_mov_b32 m0, s8
	s_nop 0
	global_load_lds_dwordx4 v[230:231], off
	s_waitcnt vmcnt(8)
	s_waitcnt lgkmcnt(0)
	s_barrier
; #define PG8_STAGE(bufoff, gbase, voff) do { _Pragma("unroll") for (int _i = 0; _i < 2; ++_i) \
;         __builtin_amdgcn_global_load_lds((const unsigned*)((const char*)(gbase) + (voff)[_i]), (PG8_LAS unsigned*)(lds + (bufoff) + ldsw + _i * 8192), 16, 0, 0); } while (0)
; #define PG8_LDA(dst, b, h) do { _Pragma("unroll") for (int m = 0; m < 4; ++m) _Pragma("unroll") for (int k = 0; k < 2; ++k) dst[m][k] = *(const PG8_LAS bf16x8*)(lds + PG8_SA(b, h) + aoff + m * 2048 + k * 1024); } while (0)
; #define PG8_LDB(dst, b, h) do { _Pragma("unroll") for (int n = 0; n < 2; ++n) _Pragma("unroll") for (int k = 0; k < 2; ++k) dst[n][k] = *(const PG8_LAS bf16x8*)(lds + PG8_SB(b, h) + boff + n * 2048 + k * 1024); } while (0)
; #define PG8_MMA(ai, bj, At, Bt) do { __builtin_amdgcn_s_setprio(1); _Pragma("unroll") for (int m = 0; m < 4; ++m) _Pragma("unroll") for (int n = 0; n < 2; ++n) _Pragma("unroll") for (int k = 0; k < 2; ++k) \
;         acc[ai][bj][m][n] = __builtin_amdgcn_mfma_f32_16x16x32_bf16(Bt[n][k], At[m][k], acc[ai][bj][m][n], 0, 0, 0); __builtin_amdgcn_s_setprio(0); } while (0)
; #define PG8_WAIT_V(n) asm volatile("s_waitcnt vmcnt(" #n ")" ::: "memory")
; #define PG8_WAIT_L(n) asm volatile("s_waitcnt lgkmcnt(" #n ")" ::: "memory")
; #define PG8_BAR __builtin_amdgcn_s_barrier()
; #define PG8_SCHED __builtin_amdgcn_sched_barrier(0)
; template <class Epi, class Sched, bool ALIGN_EPI = false, bool SP2 = false>
; __device__ __forceinline__ void gemm_phase(PG8_LAS unsigned char* lds, const Gemm g, const Sched& S, const Epi& E) {
;     ...
;             PG8_WAIT_V(8); PG8_WAIT_L(0); PG8_BAR; PG8_MMA(1, 0, At, B0); PG8_MMA(1, 1, At, B1); PG8_BAR; PG8_SCHED;
;             PG8_LDB(B0, 1, 0); PG8_LDB(B1, 1, 1); PG8_SCHED; PG8_LDA(At, 1, 0); PG8_STAGE(PG8_SA(0, 1), a2 + hstepA, voffA);
;             PG8_WAIT_V(8); PG8_WAIT_L(0); PG8_BAR; PG8_MMA(0, 0, At, B0); PG8_MMA(0, 1, At, B1); PG8_BAR; PG8_SCHED;
	s_setprio 1
	v_mfma_f32_16x16x32_bf16 v[88:91], v[138:141], v[174:177], v[88:91]
	v_mfma_f32_16x16x32_bf16 v[80:83], v[146:149], v[174:177], v[80:83]
	v_mfma_f32_16x16x32_bf16 v[72:75], v[138:141], v[182:185], v[72:75]
	v_mfma_f32_16x16x32_bf16 v[64:67], v[146:149], v[182:185], v[64:67]
	v_mfma_f32_16x16x32_bf16 v[56:59], v[138:141], v[190:193], v[56:59]
	v_mfma_f32_16x16x32_bf16 v[48:51], v[146:149], v[190:193], v[48:51]
	v_mfma_f32_16x16x32_bf16 v[40:43], v[138:141], v[204:207], v[40:43]
	v_mfma_f32_16x16x32_bf16 v[32:35], v[146:149], v[204:207], v[32:35]
	v_mfma_f32_16x16x32_bf16 v[88:91], v[142:145], v[178:181], v[88:91]
	v_mfma_f32_16x16x32_bf16 v[80:83], v[150:153], v[178:181], v[80:83]
	v_mfma_f32_16x16x32_bf16 v[72:75], v[142:145], v[186:189], v[72:75]
	v_mfma_f32_16x16x32_bf16 v[64:67], v[150:153], v[186:189], v[64:67]
	v_mfma_f32_16x16x32_bf16 v[56:59], v[142:145], v[200:203], v[56:59]
	v_mfma_f32_16x16x32_bf16 v[48:51], v[150:153], v[200:203], v[48:51]
	v_mfma_f32_16x16x32_bf16 v[40:43], v[142:145], v[208:211], v[40:43]
	v_mfma_f32_16x16x32_bf16 v[32:35], v[150:153], v[208:211], v[32:35]
	v_mfma_f32_16x16x32_bf16 v[28:31], v[154:157], v[174:177], v[28:31]
	v_mfma_f32_16x16x32_bf16 v[24:27], v[162:165], v[174:177], v[24:27]
	v_mfma_f32_16x16x32_bf16 v[20:23], v[154:157], v[182:185], v[20:23]
	v_mfma_f32_16x16x32_bf16 v[16:19], v[162:165], v[182:185], v[16:19]
	v_mfma_f32_16x16x32_bf16 v[12:15], v[154:157], v[190:193], v[12:15]
	v_mfma_f32_16x16x32_bf16 v[8:11], v[162:165], v[190:193], v[8:11]
	v_mfma_f32_16x16x32_bf16 v[4:7], v[154:157], v[204:207], v[4:7]
	v_mfma_f32_16x16x32_bf16 v[0:3], v[162:165], v[204:207], v[0:3]
	v_mfma_f32_16x16x32_bf16 v[28:31], v[158:161], v[178:181], v[28:31]
	v_mfma_f32_16x16x32_bf16 v[24:27], v[166:169], v[178:181], v[24:27]
	v_mfma_f32_16x16x32_bf16 v[20:23], v[158:161], v[186:189], v[20:23]
	v_mfma_f32_16x16x32_bf16 v[16:19], v[166:169], v[186:189], v[16:19]
	v_mfma_f32_16x16x32_bf16 v[12:15], v[158:161], v[200:203], v[12:15]
	v_mfma_f32_16x16x32_bf16 v[8:11], v[166:169], v[200:203], v[8:11]
	v_mfma_f32_16x16x32_bf16 v[4:7], v[158:161], v[208:211], v[4:7]
	v_mfma_f32_16x16x32_bf16 v[0:3], v[166:169], v[208:211], v[0:3]
	s_setprio 0
	s_barrier
	s_add_i32 s59, 0, 0x18000
	s_add_i32 s74, 0, 0x1c000
	v_add_u32_e32 v150, s59, v172
	v_add_u32_e32 v166, s74, v172
	ds_read_b128 v[138:141], v150
	ds_read_b128 v[142:145], v150 offset:1024
	ds_read_b128 v[146:149], v150 offset:2048
	ds_read_b128 v[150:153], v150 offset:3072
	ds_read_b128 v[154:157], v166
	ds_read_b128 v[158:161], v166 offset:1024
	ds_read_b128 v[162:165], v166 offset:2048
	ds_read_b128 v[166:169], v166 offset:3072
	s_add_u32 s68, s68, 0x100000
	s_addc_u32 s69, s69, 0
	s_mov_b32 m0, s9
	v_lshl_add_u64 v[232:233], s[68:69], 0, v[132:133]
	ds_read_b128 v[174:177], v173 offset:32768
	ds_read_b128 v[178:181], v173 offset:33792
	ds_read_b128 v[182:185], v173 offset:34816
	ds_read_b128 v[186:189], v173 offset:35840
	ds_read_b128 v[190:193], v173 offset:36864
	ds_read_b128 v[200:203], v173 offset:37888
	ds_read_b128 v[204:207], v173 offset:38912
	ds_read_b128 v[208:211], v173 offset:39936
	global_load_lds_dwordx4 v[232:233], off
	v_lshl_add_u64 v[232:233], s[68:69], 0, v[130:131]
	s_mov_b32 m0, s10
	s_nop 0
	global_load_lds_dwordx4 v[232:233], off
	s_waitcnt vmcnt(8)
	s_waitcnt lgkmcnt(0)
	s_barrier
	s_setprio 1
	v_mfma_f32_16x16x32_bf16 v[124:127], v[138:141], v[174:177], v[124:127]
	v_mfma_f32_16x16x32_bf16 v[120:123], v[146:149], v[174:177], v[120:123]
	v_mfma_f32_16x16x32_bf16 v[116:119], v[138:141], v[182:185], v[116:119]
	v_mfma_f32_16x16x32_bf16 v[112:115], v[146:149], v[182:185], v[112:115]
	v_mfma_f32_16x16x32_bf16 v[108:111], v[138:141], v[190:193], v[108:111]
	v_mfma_f32_16x16x32_bf16 v[104:107], v[146:149], v[190:193], v[104:107]
	v_mfma_f32_16x16x32_bf16 v[100:103], v[138:141], v[204:207], v[100:103]
	v_mfma_f32_16x16x32_bf16 v[96:99], v[146:149], v[204:207], v[96:99]
	v_mfma_f32_16x16x32_bf16 v[124:127], v[142:145], v[178:181], v[124:127]
	v_mfma_f32_16x16x32_bf16 v[120:123], v[150:153], v[178:181], v[120:123]
	v_mfma_f32_16x16x32_bf16 v[116:119], v[142:145], v[186:189], v[116:119]
	v_mfma_f32_16x16x32_bf16 v[112:115], v[150:153], v[186:189], v[112:115]
	v_mfma_f32_16x16x32_bf16 v[108:111], v[142:145], v[200:203], v[108:111]
	v_mfma_f32_16x16x32_bf16 v[104:107], v[150:153], v[200:203], v[104:107]
	v_mfma_f32_16x16x32_bf16 v[100:103], v[142:145], v[208:211], v[100:103]
	v_mfma_f32_16x16x32_bf16 v[96:99], v[150:153], v[208:211], v[96:99]
	v_mfma_f32_16x16x32_bf16 v[92:95], v[154:157], v[174:177], v[92:95]
	v_mfma_f32_16x16x32_bf16 v[84:87], v[162:165], v[174:177], v[84:87]
	v_mfma_f32_16x16x32_bf16 v[76:79], v[154:157], v[182:185], v[76:79]
	v_mfma_f32_16x16x32_bf16 v[68:71], v[162:165], v[182:185], v[68:71]
	v_mfma_f32_16x16x32_bf16 v[60:63], v[154:157], v[190:193], v[60:63]
	v_mfma_f32_16x16x32_bf16 v[52:55], v[162:165], v[190:193], v[52:55]
	v_mfma_f32_16x16x32_bf16 v[44:47], v[154:157], v[204:207], v[44:47]
	v_mfma_f32_16x16x32_bf16 v[36:39], v[162:165], v[204:207], v[36:39]
	v_mfma_f32_16x16x32_bf16 v[92:95], v[158:161], v[178:181], v[92:95]
	v_mfma_f32_16x16x32_bf16 v[84:87], v[166:169], v[178:181], v[84:87]
	v_mfma_f32_16x16x32_bf16 v[76:79], v[158:161], v[186:189], v[76:79]
	v_mfma_f32_16x16x32_bf16 v[68:71], v[166:169], v[186:189], v[68:71]
	v_mfma_f32_16x16x32_bf16 v[60:63], v[158:161], v[200:203], v[60:63]
	v_mfma_f32_16x16x32_bf16 v[52:55], v[166:169], v[200:203], v[52:55]
	v_mfma_f32_16x16x32_bf16 v[44:47], v[158:161], v[208:211], v[44:47]
	v_mfma_f32_16x16x32_bf16 v[36:39], v[166:169], v[208:211], v[36:39]
	s_setprio 0
	s_barrier
; #define PG8_STAGE(bufoff, gbase, voff) do { _Pragma("unroll") for (int _i = 0; _i < 2; ++_i) \
;         __builtin_amdgcn_global_load_lds((const unsigned*)((const char*)(gbase) + (voff)[_i]), (PG8_LAS unsigned*)(lds + (bufoff) + ldsw + _i * 8192), 16, 0, 0); } while (0)
; #define PG8_LDA(dst, b, h) do { _Pragma("unroll") for (int m = 0; m < 4; ++m) _Pragma("unroll") for (int k = 0; k < 2; ++k) dst[m][k] = *(const PG8_LAS bf16x8*)(lds + PG8_SA(b, h) + aoff + m * 2048 + k * 1024); } while (0)
; #define PG8_MMA(ai, bj, At, Bt) do { __builtin_amdgcn_s_setprio(1); _Pragma("unroll") for (int m = 0; m < 4; ++m) _Pragma("unroll") for (int n = 0; n < 2; ++n) _Pragma("unroll") for (int k = 0; k < 2; ++k) \
;         acc[ai][bj][m][n] = __builtin_amdgcn_mfma_f32_16x16x32_bf16(Bt[n][k], At[m][k], acc[ai][bj][m][n], 0, 0, 0); __builtin_amdgcn_s_setprio(0); } while (0)
; #define PG8_WAIT_V(n) asm volatile("s_waitcnt vmcnt(" #n ")" ::: "memory")
; #define PG8_WAIT_L(n) asm volatile("s_waitcnt lgkmcnt(" #n ")" ::: "memory")
; #define PG8_BAR __builtin_amdgcn_s_barrier()
; #define PG8_SCHED __builtin_amdgcn_sched_barrier(0)
; template <class Epi, class Sched, bool ALIGN_EPI = false, bool SP2 = false>
; __device__ __forceinline__ void gemm_phase(PG8_LAS unsigned char* lds, const Gemm g, const Sched& S, const Epi& E) {
;     ...
;         for (int t = 0; t < nt; t += 2) {
;     ...
;             PG8_LDA(At, 1, 1); PG8_STAGE(PG8_SB(1, 0), b3, voffB); PG8_STAGE(PG8_SB(1, 1), b3 + hstepB, voffB); PG8_STAGE(PG8_SA(1, 0), a3, voffA);
;             PG8_WAIT_V(8); PG8_WAIT_L(0); PG8_BAR; PG8_MMA(1, 0, At, B0); PG8_MMA(1, 1, At, B1); PG8_BAR; PG8_SCHED;
;     ...
;         if constexpr (!Epi::AFTER_DRAIN) { Unit ce = cur; int fr_ = fr, fq_ = fq; asm volatile("" : "+s"(ce.pm), "+s"(ce.pn), "+v"(fr_), "+v"(fq_)); E(acc, ce, wr, wc, fr_, fq_); S.done(cur); }
	s_add_i32 s59, s59, s2
	v_lshl_add_u64 v[212:213], v[212:213], 0, s[26:27]
	s_mov_b32 m0, s59
	ds_read_b128 v[174:177], v173 offset:49152
	ds_read_b128 v[178:181], v173 offset:50176
	ds_read_b128 v[182:185], v173 offset:51200
	ds_read_b128 v[186:189], v173 offset:52224
	ds_read_b128 v[190:193], v173 offset:53248
	ds_read_b128 v[200:203], v173 offset:54272
	ds_read_b128 v[204:207], v173 offset:55296
	ds_read_b128 v[208:211], v173 offset:56320
	global_load_lds_dwordx4 v[212:213], off
	s_add_i32 m0, s59, 0x2000
	s_add_u32 s62, s62, 0x100080
	v_lshl_add_u64 v[212:213], v[214:215], 0, s[26:27]
	s_addc_u32 s63, s63, 0
	s_add_i32 s59, s74, s2
	global_load_lds_dwordx4 v[212:213], off
	v_lshl_add_u64 v[212:213], s[62:63], 0, v[194:195]
	s_mov_b32 m0, s59
	s_nop 0
	global_load_lds_dwordx4 v[212:213], off
	v_lshl_add_u64 v[212:213], s[62:63], 0, v[128:129]
	s_add_i32 m0, s59, 0x2000
	s_nop 0
	global_load_lds_dwordx4 v[212:213], off
	v_lshl_add_u64 v[212:213], v[228:229], 0, s[26:27]
	s_mov_b32 m0, s14
	s_nop 0
	global_load_lds_dwordx4 v[212:213], off
	v_lshl_add_u64 v[212:213], v[230:231], 0, s[26:27]
	s_mov_b32 m0, s15
	s_nop 0
	global_load_lds_dwordx4 v[212:213], off
	s_waitcnt vmcnt(8)
	s_waitcnt lgkmcnt(0)
	s_barrier
	s_setprio 1
	v_mfma_f32_16x16x32_bf16 v[88:91], v[138:141], v[174:177], v[88:91]
	v_mfma_f32_16x16x32_bf16 v[80:83], v[146:149], v[174:177], v[80:83]
	v_mfma_f32_16x16x32_bf16 v[72:75], v[138:141], v[182:185], v[72:75]
	v_mfma_f32_16x16x32_bf16 v[64:67], v[146:149], v[182:185], v[64:67]
	v_mfma_f32_16x16x32_bf16 v[56:59], v[138:141], v[190:193], v[56:59]
	v_mfma_f32_16x16x32_bf16 v[48:51], v[146:149], v[190:193], v[48:51]
	v_mfma_f32_16x16x32_bf16 v[40:43], v[138:141], v[204:207], v[40:43]
	v_mfma_f32_16x16x32_bf16 v[32:35], v[146:149], v[204:207], v[32:35]
	v_mfma_f32_16x16x32_bf16 v[88:91], v[142:145], v[178:181], v[88:91]
	v_mfma_f32_16x16x32_bf16 v[80:83], v[150:153], v[178:181], v[80:83]
	v_mfma_f32_16x16x32_bf16 v[72:75], v[142:145], v[186:189], v[72:75]
	v_mfma_f32_16x16x32_bf16 v[64:67], v[150:153], v[186:189], v[64:67]
	v_mfma_f32_16x16x32_bf16 v[56:59], v[142:145], v[200:203], v[56:59]
	v_mfma_f32_16x16x32_bf16 v[48:51], v[150:153], v[200:203], v[48:51]
	v_mfma_f32_16x16x32_bf16 v[40:43], v[142:145], v[208:211], v[40:43]
	v_mfma_f32_16x16x32_bf16 v[32:35], v[150:153], v[208:211], v[32:35]
	v_mfma_f32_16x16x32_bf16 v[28:31], v[154:157], v[174:177], v[28:31]
	v_mfma_f32_16x16x32_bf16 v[24:27], v[162:165], v[174:177], v[24:27]
	v_mfma_f32_16x16x32_bf16 v[20:23], v[154:157], v[182:185], v[20:23]
	v_mfma_f32_16x16x32_bf16 v[16:19], v[162:165], v[182:185], v[16:19]
	v_mfma_f32_16x16x32_bf16 v[12:15], v[154:157], v[190:193], v[12:15]
	v_mfma_f32_16x16x32_bf16 v[8:11], v[162:165], v[190:193], v[8:11]
	v_mfma_f32_16x16x32_bf16 v[4:7], v[154:157], v[204:207], v[4:7]
	v_mfma_f32_16x16x32_bf16 v[0:3], v[162:165], v[204:207], v[0:3]
	v_mfma_f32_16x16x32_bf16 v[28:31], v[158:161], v[178:181], v[28:31]
	v_mfma_f32_16x16x32_bf16 v[24:27], v[166:169], v[178:181], v[24:27]
	v_mfma_f32_16x16x32_bf16 v[20:23], v[158:161], v[186:189], v[20:23]
	v_mfma_f32_16x16x32_bf16 v[16:19], v[166:169], v[186:189], v[16:19]
	v_mfma_f32_16x16x32_bf16 v[12:15], v[158:161], v[200:203], v[12:15]
	v_mfma_f32_16x16x32_bf16 v[8:11], v[166:169], v[200:203], v[8:11]
	v_mfma_f32_16x16x32_bf16 v[4:7], v[158:161], v[208:211], v[4:7]
	v_mfma_f32_16x16x32_bf16 v[0:3], v[166:169], v[208:211], v[0:3]
	s_setprio 0
	s_barrier
	s_add_u32 s52, s52, 0x100
	s_addc_u32 s53, s53, 0
	s_add_u32 s47, s47, 0x100
	s_addc_u32 s58, s58, 0
	s_cmp_ge_i32 s64, s11
	s_mov_b32 s59, s64
	s_cbranch_scc0 .LBB0_1726
	v_pk_add_f32 v[126:127], v[126:127], 0 op_sel_hi:[1,0]
	v_pk_add_f32 v[124:125], v[124:125], 0 op_sel_hi:[1,0]
	v_pk_add_f32 v[122:123], v[122:123], 0 op_sel_hi:[1,0]
	v_pk_add_f32 v[120:121], v[120:121], 0 op_sel_hi:[1,0]
	v_pk_add_f32 v[118:119], v[118:119], 0 op_sel_hi:[1,0]
	v_pk_add_f32 v[116:117], v[116:117], 0 op_sel_hi:[1,0]
	v_pk_add_f32 v[114:115], v[114:115], 0 op_sel_hi:[1,0]
	v_pk_add_f32 v[112:113], v[112:113], 0 op_sel_hi:[1,0]
	v_pk_add_f32 v[110:111], v[110:111], 0 op_sel_hi:[1,0]
	v_pk_add_f32 v[108:109], v[108:109], 0 op_sel_hi:[1,0]
	v_pk_add_f32 v[106:107], v[106:107], 0 op_sel_hi:[1,0]
	v_pk_add_f32 v[104:105], v[104:105], 0 op_sel_hi:[1,0]
	v_pk_add_f32 v[102:103], v[102:103], 0 op_sel_hi:[1,0]
	v_pk_add_f32 v[100:101], v[100:101], 0 op_sel_hi:[1,0]
	v_pk_add_f32 v[98:99], v[98:99], 0 op_sel_hi:[1,0]
	v_pk_add_f32 v[96:97], v[96:97], 0 op_sel_hi:[1,0]
	v_pk_add_f32 v[140:141], v[90:91], 0 op_sel_hi:[1,0]
	v_pk_add_f32 v[144:145], v[88:89], 0 op_sel_hi:[1,0]
	v_pk_add_f32 v[138:139], v[82:83], 0 op_sel_hi:[1,0]
	v_pk_add_f32 v[142:143], v[80:81], 0 op_sel_hi:[1,0]
	v_pk_add_f32 v[148:149], v[74:75], 0 op_sel_hi:[1,0]
	v_pk_add_f32 v[152:153], v[72:73], 0 op_sel_hi:[1,0]
	v_pk_add_f32 v[146:147], v[66:67], 0 op_sel_hi:[1,0]
	v_pk_add_f32 v[150:151], v[64:65], 0 op_sel_hi:[1,0]
	v_pk_add_f32 v[156:157], v[58:59], 0 op_sel_hi:[1,0]
	v_pk_add_f32 v[160:161], v[56:57], 0 op_sel_hi:[1,0]
	v_pk_add_f32 v[154:155], v[50:51], 0 op_sel_hi:[1,0]
	v_pk_add_f32 v[158:159], v[48:49], 0 op_sel_hi:[1,0]
	v_pk_add_f32 v[162:163], v[42:43], 0 op_sel_hi:[1,0]
	v_pk_add_f32 v[166:167], v[40:41], 0 op_sel_hi:[1,0]
	v_pk_add_f32 v[164:165], v[34:35], 0 op_sel_hi:[1,0]
	v_pk_add_f32 v[168:169], v[32:33], 0 op_sel_hi:[1,0]
	v_pk_add_f32 v[90:91], v[94:95], 0 op_sel_hi:[1,0]
	v_pk_add_f32 v[88:89], v[92:93], 0 op_sel_hi:[1,0]
	v_pk_add_f32 v[82:83], v[86:87], 0 op_sel_hi:[1,0]
	v_pk_add_f32 v[80:81], v[84:85], 0 op_sel_hi:[1,0]
	v_pk_add_f32 v[74:75], v[78:79], 0 op_sel_hi:[1,0]
	v_pk_add_f32 v[72:73], v[76:77], 0 op_sel_hi:[1,0]
	v_pk_add_f32 v[66:67], v[70:71], 0 op_sel_hi:[1,0]
	v_pk_add_f32 v[64:65], v[68:69], 0 op_sel_hi:[1,0]
	v_pk_add_f32 v[58:59], v[62:63], 0 op_sel_hi:[1,0]
	v_pk_add_f32 v[56:57], v[60:61], 0 op_sel_hi:[1,0]
	v_pk_add_f32 v[50:51], v[54:55], 0 op_sel_hi:[1,0]
	v_pk_add_f32 v[48:49], v[52:53], 0 op_sel_hi:[1,0]
	v_pk_add_f32 v[42:43], v[46:47], 0 op_sel_hi:[1,0]
	v_pk_add_f32 v[40:41], v[44:45], 0 op_sel_hi:[1,0]
	v_pk_add_f32 v[34:35], v[38:39], 0 op_sel_hi:[1,0]
	v_pk_add_f32 v[32:33], v[36:37], 0 op_sel_hi:[1,0]
	v_pk_add_f32 v[46:47], v[30:31], 0 op_sel_hi:[1,0]
	v_pk_add_f32 v[44:45], v[28:29], 0 op_sel_hi:[1,0]
	v_pk_add_f32 v[38:39], v[26:27], 0 op_sel_hi:[1,0]
	v_pk_add_f32 v[36:37], v[24:25], 0 op_sel_hi:[1,0]
	v_pk_add_f32 v[30:31], v[22:23], 0 op_sel_hi:[1,0]
	v_pk_add_f32 v[28:29], v[20:21], 0 op_sel_hi:[1,0]
	v_pk_add_f32 v[26:27], v[18:19], 0 op_sel_hi:[1,0]
	v_pk_add_f32 v[24:25], v[16:17], 0 op_sel_hi:[1,0]
	v_pk_add_f32 v[22:23], v[14:15], 0 op_sel_hi:[1,0]
	v_pk_add_f32 v[20:21], v[12:13], 0 op_sel_hi:[1,0]
	v_pk_add_f32 v[18:19], v[10:11], 0 op_sel_hi:[1,0]
	v_pk_add_f32 v[16:17], v[8:9], 0 op_sel_hi:[1,0]
	v_pk_add_f32 v[14:15], v[6:7], 0 op_sel_hi:[1,0]
	v_pk_add_f32 v[12:13], v[4:5], 0 op_sel_hi:[1,0]
	v_pk_add_f32 v[10:11], v[2:3], 0 op_sel_hi:[1,0]
	v_pk_add_f32 v[8:9], v[0:1], 0 op_sel_hi:[1,0]
